# c19: c16 with the early segment barrier 4 MFMAs (two same-D pairs) before the segment end instead of 2
# baseline (speedup 1.0000x reference)
.LBB0_343:
	s_ashr_i32 s11, s10, 31
	s_lshl_b64 s[12:13], s[10:11], 20
	s_add_u32 s12, s26, s12
	s_addc_u32 s13, s27, s13
	s_and_b64 s[14:15], s[2:3], exec
	s_cselect_b32 s11, s13, s21
	s_cselect_b32 s75, s12, s20
	s_ashr_i32 s9, s8, 31
	s_lshl_b64 s[14:15], s[8:9], 20
	s_add_u32 s14, s28, s14
	s_addc_u32 s15, s29, s15
	s_and_b64 s[22:23], s[2:3], exec
	s_cselect_b32 s9, s15, s19
	s_cselect_b32 s76, s14, s18
	s_add_u32 s77, s18, 0x100
	s_addc_u32 s78, s19, 0
	s_add_u32 s18, s20, 0x80080
	s_addc_u32 s19, s21, 0
	s_add_u32 s79, s20, 0x100
	s_addc_u32 s80, s21, 0
	s_mov_b32 s81, -2
	ds_read_b128 v[148:151], v143
	ds_read_b128 v[152:155], v143 offset:1024
	ds_read_b128 v[156:159], v143 offset:2048
	ds_read_b128 v[160:163], v143 offset:3072
	ds_read_b128 v[164:167], v144
	ds_read_b128 v[168:171], v144 offset:1024
	ds_read_b128 v[172:175], v144 offset:2048
	ds_read_b128 v[176:179], v144 offset:3072
	s_cmp_eq_u32 s81, 28
	s_cselect_b32 s21, s9, s78
	s_cselect_b32 s20, s76, s77
	s_cselect_b32 s23, s11, s80
	s_cselect_b32 s22, s75, s79
	ds_read_b128 v[180:183], v145
	ds_read_b128 v[184:187], v145 offset:1024
	ds_read_b128 v[188:191], v145 offset:2048
	ds_read_b128 v[192:195], v145 offset:3072
	ds_read_b128 v[196:199], v145 offset:4096
	ds_read_b128 v[200:203], v145 offset:5120
	ds_read_b128 v[204:207], v145 offset:6144
	ds_read_b128 v[208:211], v145 offset:7168
	s_add_u32 s82, s18, 0xfff80000
	s_addc_u32 s83, s19, -1
	s_mov_b32 s86, m0
	s_mov_b32 m0, s64
	s_nop 0
	global_load_lds_dwordx4 v138, s[82:83]
	s_mov_b32 m0, s86
	s_nop 0
	s_mov_b32 s86, m0
	s_mov_b32 m0, s67
	s_nop 0
	global_load_lds_dwordx4 v140, s[82:83]
	s_mov_b32 m0, s86
	s_mov_b32 s82, m0
	s_mov_b32 m0, s65
	s_nop 0
	global_load_lds_dwordx4 v138, s[18:19]
	s_mov_b32 m0, s82
	s_nop 0
	s_mov_b32 s82, m0
	s_mov_b32 m0, s73
	s_nop 0
	global_load_lds_dwordx4 v140, s[18:19]
	s_mov_b32 m0, s82
	s_waitcnt vmcnt(8)
	s_waitcnt lgkmcnt(0)
	s_barrier
	s_setprio 1
	s_waitcnt lgkmcnt(7)
	v_mfma_f32_16x16x32_bf16 v[126:129], v[148:151], v[180:183], 0
	v_mfma_f32_16x16x32_bf16 v[126:129], v[152:155], v[184:187], v[126:129]
	s_waitcnt lgkmcnt(5)
	v_mfma_f32_16x16x32_bf16 v[122:125], v[156:159], v[180:183], 0
	v_mfma_f32_16x16x32_bf16 v[122:125], v[160:163], v[184:187], v[122:125]
	s_waitcnt lgkmcnt(3)
	v_mfma_f32_16x16x32_bf16 v[106:109], v[156:159], v[188:191], 0
	v_mfma_f32_16x16x32_bf16 v[106:109], v[160:163], v[192:195], v[106:109]
	s_waitcnt lgkmcnt(1)
	v_mfma_f32_16x16x32_bf16 v[110:113], v[148:151], v[188:191], 0
	v_mfma_f32_16x16x32_bf16 v[110:113], v[152:155], v[192:195], v[110:113]
	v_mfma_f32_16x16x32_bf16 v[94:97], v[148:151], v[196:199], 0
	v_mfma_f32_16x16x32_bf16 v[94:97], v[152:155], v[200:203], v[94:97]
	v_mfma_f32_16x16x32_bf16 v[90:93], v[156:159], v[196:199], 0
	v_mfma_f32_16x16x32_bf16 v[90:93], v[160:163], v[200:203], v[90:93]
	v_mfma_f32_16x16x32_bf16 v[74:77], v[156:159], v[204:207], 0
	v_mfma_f32_16x16x32_bf16 v[74:77], v[160:163], v[208:211], v[74:77]
	s_waitcnt lgkmcnt(0)
	v_mfma_f32_16x16x32_bf16 v[78:81], v[148:151], v[204:207], 0
	v_mfma_f32_16x16x32_bf16 v[78:81], v[152:155], v[208:211], v[78:81]
	s_setprio 0
	s_setprio 1
	v_mfma_f32_16x16x32_bf16 v[118:121], v[164:167], v[180:183], 0
	v_mfma_f32_16x16x32_bf16 v[118:121], v[168:171], v[184:187], v[118:121]
	v_mfma_f32_16x16x32_bf16 v[114:117], v[172:175], v[180:183], 0
	v_mfma_f32_16x16x32_bf16 v[114:117], v[176:179], v[184:187], v[114:117]
	v_mfma_f32_16x16x32_bf16 v[98:101], v[172:175], v[188:191], 0
	v_mfma_f32_16x16x32_bf16 v[98:101], v[176:179], v[192:195], v[98:101]
	v_mfma_f32_16x16x32_bf16 v[102:105], v[164:167], v[188:191], 0
	v_mfma_f32_16x16x32_bf16 v[102:105], v[168:171], v[192:195], v[102:105]
	v_mfma_f32_16x16x32_bf16 v[86:89], v[164:167], v[196:199], 0
	v_mfma_f32_16x16x32_bf16 v[86:89], v[168:171], v[200:203], v[86:89]
	v_mfma_f32_16x16x32_bf16 v[82:85], v[172:175], v[196:199], 0
	v_mfma_f32_16x16x32_bf16 v[82:85], v[176:179], v[200:203], v[82:85]
	s_setprio 2
	s_barrier
	v_mfma_f32_16x16x32_bf16 v[66:69], v[172:175], v[204:207], 0
	v_mfma_f32_16x16x32_bf16 v[66:69], v[176:179], v[208:211], v[66:69]
	v_mfma_f32_16x16x32_bf16 v[70:73], v[164:167], v[204:207], 0
	v_mfma_f32_16x16x32_bf16 v[70:73], v[168:171], v[208:211], v[70:73]
	s_setprio 0
	ds_read_b128 v[180:183], v145 offset:16384
	ds_read_b128 v[184:187], v145 offset:17408
	ds_read_b128 v[188:191], v145 offset:18432
	ds_read_b128 v[192:195], v145 offset:19456
	ds_read_b128 v[196:199], v145 offset:20480
	ds_read_b128 v[200:203], v145 offset:21504
	ds_read_b128 v[204:207], v145 offset:22528
	ds_read_b128 v[208:211], v145 offset:23552
	s_mov_b32 s82, m0
	s_mov_b32 m0, s35
	s_nop 0
	global_load_lds_dwordx4 v139, s[20:21]
	s_mov_b32 m0, s82
	s_nop 0
	s_mov_b32 s82, m0
	s_mov_b32 m0, s36
	s_nop 0
	global_load_lds_dwordx4 v141, s[20:21]
	s_mov_b32 m0, s82
	s_add_u32 s82, s20, 0x80000
	s_addc_u32 s83, s21, 0
	s_mov_b32 s86, m0
	s_mov_b32 m0, s37
	s_nop 0
	global_load_lds_dwordx4 v139, s[82:83]
	s_mov_b32 m0, s86
	s_nop 0
	s_mov_b32 s86, m0
	s_mov_b32 m0, s42
	s_nop 0
	global_load_lds_dwordx4 v141, s[82:83]
	s_mov_b32 m0, s86
	s_waitcnt vmcnt(4)
	s_waitcnt lgkmcnt(0)
	s_barrier
	s_setprio 1
	s_waitcnt lgkmcnt(7)
	v_mfma_f32_16x16x32_bf16 v[62:65], v[148:151], v[180:183], 0
	v_mfma_f32_16x16x32_bf16 v[62:65], v[152:155], v[184:187], v[62:65]
	s_waitcnt lgkmcnt(5)
	v_mfma_f32_16x16x32_bf16 v[58:61], v[156:159], v[180:183], 0
	v_mfma_f32_16x16x32_bf16 v[58:61], v[160:163], v[184:187], v[58:61]
	s_waitcnt lgkmcnt(3)
	v_mfma_f32_16x16x32_bf16 v[42:45], v[156:159], v[188:191], 0
	v_mfma_f32_16x16x32_bf16 v[42:45], v[160:163], v[192:195], v[42:45]
	s_waitcnt lgkmcnt(1)
	v_mfma_f32_16x16x32_bf16 v[46:49], v[148:151], v[188:191], 0
	v_mfma_f32_16x16x32_bf16 v[46:49], v[152:155], v[192:195], v[46:49]
	v_mfma_f32_16x16x32_bf16 v[30:33], v[148:151], v[196:199], 0
	v_mfma_f32_16x16x32_bf16 v[30:33], v[152:155], v[200:203], v[30:33]
	v_mfma_f32_16x16x32_bf16 v[26:29], v[156:159], v[196:199], 0
	v_mfma_f32_16x16x32_bf16 v[26:29], v[160:163], v[200:203], v[26:29]
	v_mfma_f32_16x16x32_bf16 v[10:13], v[156:159], v[204:207], 0
	v_mfma_f32_16x16x32_bf16 v[10:13], v[160:163], v[208:211], v[10:13]
	s_waitcnt lgkmcnt(0)
	v_mfma_f32_16x16x32_bf16 v[14:17], v[148:151], v[204:207], 0
	v_mfma_f32_16x16x32_bf16 v[14:17], v[152:155], v[208:211], v[14:17]
	s_setprio 0
	s_setprio 1
	v_mfma_f32_16x16x32_bf16 v[54:57], v[164:167], v[180:183], 0
	v_mfma_f32_16x16x32_bf16 v[54:57], v[168:171], v[184:187], v[54:57]
	v_mfma_f32_16x16x32_bf16 v[50:53], v[172:175], v[180:183], 0
	v_mfma_f32_16x16x32_bf16 v[50:53], v[176:179], v[184:187], v[50:53]
	v_mfma_f32_16x16x32_bf16 v[34:37], v[172:175], v[188:191], 0
	v_mfma_f32_16x16x32_bf16 v[34:37], v[176:179], v[192:195], v[34:37]
	v_mfma_f32_16x16x32_bf16 v[38:41], v[164:167], v[188:191], 0
	v_mfma_f32_16x16x32_bf16 v[38:41], v[168:171], v[192:195], v[38:41]
	v_mfma_f32_16x16x32_bf16 v[22:25], v[164:167], v[196:199], 0
	v_mfma_f32_16x16x32_bf16 v[22:25], v[168:171], v[200:203], v[22:25]
	v_mfma_f32_16x16x32_bf16 v[18:21], v[172:175], v[196:199], 0
	v_mfma_f32_16x16x32_bf16 v[18:21], v[176:179], v[200:203], v[18:21]
	s_setprio 2
	s_barrier
	v_mfma_f32_16x16x32_bf16 v[2:5], v[172:175], v[204:207], 0
	v_mfma_f32_16x16x32_bf16 v[2:5], v[176:179], v[208:211], v[2:5]
	v_mfma_f32_16x16x32_bf16 v[6:9], v[164:167], v[204:207], 0
	v_mfma_f32_16x16x32_bf16 v[6:9], v[168:171], v[208:211], v[6:9]
	s_setprio 0
	ds_read_b128 v[148:151], v146
	ds_read_b128 v[152:155], v146 offset:1024
	ds_read_b128 v[156:159], v146 offset:2048
	ds_read_b128 v[160:163], v146 offset:3072
	ds_read_b128 v[164:167], v147
	ds_read_b128 v[168:171], v147 offset:1024
	ds_read_b128 v[172:175], v147 offset:2048
	ds_read_b128 v[176:179], v147 offset:3072
	ds_read_b128 v[180:183], v145 offset:32768
	ds_read_b128 v[184:187], v145 offset:33792
	ds_read_b128 v[188:191], v145 offset:34816
	ds_read_b128 v[192:195], v145 offset:35840
	ds_read_b128 v[196:199], v145 offset:36864
	ds_read_b128 v[200:203], v145 offset:37888
	ds_read_b128 v[204:207], v145 offset:38912
	ds_read_b128 v[208:211], v145 offset:39936
	s_mov_b32 s82, m0
	s_mov_b32 m0, s31
	s_nop 0
	global_load_lds_dwordx4 v138, s[22:23]
	s_mov_b32 m0, s82
	s_nop 0
	s_mov_b32 s82, m0
	s_mov_b32 m0, s43
	s_nop 0
	global_load_lds_dwordx4 v140, s[22:23]
	s_mov_b32 m0, s82
	s_add_u32 s22, s22, 0x80000
	s_addc_u32 s23, s23, 0
	s_mov_b32 s82, m0
	s_mov_b32 m0, s46
	s_nop 0
	global_load_lds_dwordx4 v138, s[22:23]
	s_mov_b32 m0, s82
	s_nop 0
	s_mov_b32 s82, m0
	s_mov_b32 m0, s47
	s_nop 0
	global_load_lds_dwordx4 v140, s[22:23]
	s_mov_b32 m0, s82
	s_waitcnt vmcnt(8)
	s_waitcnt lgkmcnt(0)
	s_barrier
	s_setprio 1
	s_waitcnt lgkmcnt(7)
	v_mfma_f32_16x16x32_bf16 v[126:129], v[148:151], v[180:183], v[126:129]
	v_mfma_f32_16x16x32_bf16 v[126:129], v[152:155], v[184:187], v[126:129]
	s_waitcnt lgkmcnt(5)
	v_mfma_f32_16x16x32_bf16 v[122:125], v[156:159], v[180:183], v[122:125]
	v_mfma_f32_16x16x32_bf16 v[122:125], v[160:163], v[184:187], v[122:125]
	s_waitcnt lgkmcnt(3)
	v_mfma_f32_16x16x32_bf16 v[106:109], v[156:159], v[188:191], v[106:109]
	v_mfma_f32_16x16x32_bf16 v[106:109], v[160:163], v[192:195], v[106:109]
	s_waitcnt lgkmcnt(1)
	v_mfma_f32_16x16x32_bf16 v[110:113], v[148:151], v[188:191], v[110:113]
	v_mfma_f32_16x16x32_bf16 v[110:113], v[152:155], v[192:195], v[110:113]
	v_mfma_f32_16x16x32_bf16 v[94:97], v[148:151], v[196:199], v[94:97]
	v_mfma_f32_16x16x32_bf16 v[94:97], v[152:155], v[200:203], v[94:97]
	v_mfma_f32_16x16x32_bf16 v[90:93], v[156:159], v[196:199], v[90:93]
	v_mfma_f32_16x16x32_bf16 v[90:93], v[160:163], v[200:203], v[90:93]
	v_mfma_f32_16x16x32_bf16 v[74:77], v[156:159], v[204:207], v[74:77]
	v_mfma_f32_16x16x32_bf16 v[74:77], v[160:163], v[208:211], v[74:77]
	s_waitcnt lgkmcnt(0)
	v_mfma_f32_16x16x32_bf16 v[78:81], v[148:151], v[204:207], v[78:81]
	v_mfma_f32_16x16x32_bf16 v[78:81], v[152:155], v[208:211], v[78:81]
	s_setprio 0
	s_setprio 1
	v_mfma_f32_16x16x32_bf16 v[118:121], v[164:167], v[180:183], v[118:121]
	v_mfma_f32_16x16x32_bf16 v[118:121], v[168:171], v[184:187], v[118:121]
	v_mfma_f32_16x16x32_bf16 v[114:117], v[172:175], v[180:183], v[114:117]
	v_mfma_f32_16x16x32_bf16 v[114:117], v[176:179], v[184:187], v[114:117]
	v_mfma_f32_16x16x32_bf16 v[98:101], v[172:175], v[188:191], v[98:101]
	v_mfma_f32_16x16x32_bf16 v[98:101], v[176:179], v[192:195], v[98:101]
	v_mfma_f32_16x16x32_bf16 v[102:105], v[164:167], v[188:191], v[102:105]
	v_mfma_f32_16x16x32_bf16 v[102:105], v[168:171], v[192:195], v[102:105]
	v_mfma_f32_16x16x32_bf16 v[86:89], v[164:167], v[196:199], v[86:89]
	v_mfma_f32_16x16x32_bf16 v[86:89], v[168:171], v[200:203], v[86:89]
	v_mfma_f32_16x16x32_bf16 v[82:85], v[172:175], v[196:199], v[82:85]
	v_mfma_f32_16x16x32_bf16 v[82:85], v[176:179], v[200:203], v[82:85]
	s_setprio 2
	s_barrier
	v_mfma_f32_16x16x32_bf16 v[66:69], v[172:175], v[204:207], v[66:69]
	v_mfma_f32_16x16x32_bf16 v[66:69], v[176:179], v[208:211], v[66:69]
	v_mfma_f32_16x16x32_bf16 v[70:73], v[164:167], v[204:207], v[70:73]
	v_mfma_f32_16x16x32_bf16 v[70:73], v[168:171], v[208:211], v[70:73]
	s_setprio 0
	ds_read_b128 v[180:183], v145 offset:49152
	ds_read_b128 v[184:187], v145 offset:50176
	ds_read_b128 v[188:191], v145 offset:51200
	ds_read_b128 v[192:195], v145 offset:52224
	ds_read_b128 v[196:199], v145 offset:53248
	ds_read_b128 v[200:203], v145 offset:54272
	ds_read_b128 v[204:207], v145 offset:55296
	ds_read_b128 v[208:211], v145 offset:56320
	s_add_u32 s22, s20, 0x80
	s_addc_u32 s23, s21, 0
	s_mov_b32 s82, m0
	s_mov_b32 m0, s48
	s_nop 0
	global_load_lds_dwordx4 v139, s[22:23]
	s_mov_b32 m0, s82
	s_add_u32 s20, s20, 0x80080
	s_mov_b32 s82, m0
	s_mov_b32 m0, s49
	s_nop 0
	global_load_lds_dwordx4 v141, s[22:23]
	s_mov_b32 m0, s82
	s_addc_u32 s21, s21, 0
	s_mov_b32 s22, m0
	s_mov_b32 m0, s56
	s_nop 0
	global_load_lds_dwordx4 v139, s[20:21]
	s_mov_b32 m0, s22
	s_nop 0
	s_mov_b32 s22, m0
	s_mov_b32 m0, s57
	s_nop 0
	global_load_lds_dwordx4 v141, s[20:21]
	s_mov_b32 m0, s22
	s_waitcnt vmcnt(4)
	s_waitcnt lgkmcnt(0)
	s_barrier
	s_setprio 1
	s_waitcnt lgkmcnt(7)
	v_mfma_f32_16x16x32_bf16 v[62:65], v[148:151], v[180:183], v[62:65]
	v_mfma_f32_16x16x32_bf16 v[62:65], v[152:155], v[184:187], v[62:65]
	s_waitcnt lgkmcnt(5)
	v_mfma_f32_16x16x32_bf16 v[58:61], v[156:159], v[180:183], v[58:61]
	v_mfma_f32_16x16x32_bf16 v[58:61], v[160:163], v[184:187], v[58:61]
	s_waitcnt lgkmcnt(3)
	v_mfma_f32_16x16x32_bf16 v[42:45], v[156:159], v[188:191], v[42:45]
	v_mfma_f32_16x16x32_bf16 v[42:45], v[160:163], v[192:195], v[42:45]
	s_waitcnt lgkmcnt(1)
	v_mfma_f32_16x16x32_bf16 v[46:49], v[148:151], v[188:191], v[46:49]
	v_mfma_f32_16x16x32_bf16 v[46:49], v[152:155], v[192:195], v[46:49]
	v_mfma_f32_16x16x32_bf16 v[30:33], v[148:151], v[196:199], v[30:33]
	v_mfma_f32_16x16x32_bf16 v[30:33], v[152:155], v[200:203], v[30:33]
	v_mfma_f32_16x16x32_bf16 v[26:29], v[156:159], v[196:199], v[26:29]
	v_mfma_f32_16x16x32_bf16 v[26:29], v[160:163], v[200:203], v[26:29]
	v_mfma_f32_16x16x32_bf16 v[10:13], v[156:159], v[204:207], v[10:13]
	v_mfma_f32_16x16x32_bf16 v[10:13], v[160:163], v[208:211], v[10:13]
	s_waitcnt lgkmcnt(0)
	v_mfma_f32_16x16x32_bf16 v[14:17], v[148:151], v[204:207], v[14:17]
	v_mfma_f32_16x16x32_bf16 v[14:17], v[152:155], v[208:211], v[14:17]
	s_setprio 0
	s_setprio 1
	v_mfma_f32_16x16x32_bf16 v[54:57], v[164:167], v[180:183], v[54:57]
	v_mfma_f32_16x16x32_bf16 v[54:57], v[168:171], v[184:187], v[54:57]
	v_mfma_f32_16x16x32_bf16 v[50:53], v[172:175], v[180:183], v[50:53]
	v_mfma_f32_16x16x32_bf16 v[50:53], v[176:179], v[184:187], v[50:53]
	v_mfma_f32_16x16x32_bf16 v[34:37], v[172:175], v[188:191], v[34:37]
	v_mfma_f32_16x16x32_bf16 v[34:37], v[176:179], v[192:195], v[34:37]
	v_mfma_f32_16x16x32_bf16 v[38:41], v[164:167], v[188:191], v[38:41]
	v_mfma_f32_16x16x32_bf16 v[38:41], v[168:171], v[192:195], v[38:41]
	v_mfma_f32_16x16x32_bf16 v[22:25], v[164:167], v[196:199], v[22:25]
	v_mfma_f32_16x16x32_bf16 v[22:25], v[168:171], v[200:203], v[22:25]
	v_mfma_f32_16x16x32_bf16 v[18:21], v[172:175], v[196:199], v[18:21]
	v_mfma_f32_16x16x32_bf16 v[18:21], v[176:179], v[200:203], v[18:21]
	s_setprio 2
	s_barrier
	v_mfma_f32_16x16x32_bf16 v[2:5], v[172:175], v[204:207], v[2:5]
	v_mfma_f32_16x16x32_bf16 v[2:5], v[176:179], v[208:211], v[2:5]
	v_mfma_f32_16x16x32_bf16 v[6:9], v[164:167], v[204:207], v[6:9]
	v_mfma_f32_16x16x32_bf16 v[6:9], v[168:171], v[208:211], v[6:9]
	s_setprio 0
	s_add_i32 s81, s81, 2
	s_add_u32 s77, s77, 0x100
	s_addc_u32 s78, s78, 0
	s_add_u32 s18, s18, 0x100
	s_addc_u32 s19, s19, 0
	s_add_u32 s79, s79, 0x100
	s_addc_u32 s80, s80, 0
	s_cmp_gt_u32 s81, 29
	.p2align 6
.LBB0_344:
	ds_read_b128 v[148:151], v143
	ds_read_b128 v[152:155], v143 offset:1024
	ds_read_b128 v[156:159], v143 offset:2048
	ds_read_b128 v[160:163], v143 offset:3072
	ds_read_b128 v[164:167], v144
	ds_read_b128 v[168:171], v144 offset:1024
	ds_read_b128 v[172:175], v144 offset:2048
	ds_read_b128 v[176:179], v144 offset:3072
	s_cmp_eq_u32 s81, 28
	s_cselect_b32 s21, s9, s78
	s_cselect_b32 s20, s76, s77
	s_cselect_b32 s23, s11, s80
	s_cselect_b32 s22, s75, s79
	ds_read_b128 v[180:183], v145
	ds_read_b128 v[184:187], v145 offset:1024
	ds_read_b128 v[188:191], v145 offset:2048
	ds_read_b128 v[192:195], v145 offset:3072
	ds_read_b128 v[196:199], v145 offset:4096
	ds_read_b128 v[200:203], v145 offset:5120
	ds_read_b128 v[204:207], v145 offset:6144
	ds_read_b128 v[208:211], v145 offset:7168
	s_add_u32 s82, s18, 0xfff80000
	s_addc_u32 s83, s19, -1
	s_mov_b32 s86, m0
	s_mov_b32 m0, s64
	s_nop 0
	global_load_lds_dwordx4 v138, s[82:83]
	s_mov_b32 m0, s86
	s_nop 0
	s_mov_b32 s86, m0
	s_mov_b32 m0, s67
	s_nop 0
	global_load_lds_dwordx4 v140, s[82:83]
	s_mov_b32 m0, s86
	s_mov_b32 s82, m0
	s_mov_b32 m0, s65
	s_nop 0
	global_load_lds_dwordx4 v138, s[18:19]
	s_mov_b32 m0, s82
	s_nop 0
	s_mov_b32 s82, m0
	s_mov_b32 m0, s73
	s_nop 0
	global_load_lds_dwordx4 v140, s[18:19]
	s_mov_b32 m0, s82
	s_waitcnt vmcnt(8)
	s_waitcnt lgkmcnt(0)
	s_barrier
	s_setprio 1
	s_waitcnt lgkmcnt(7)
	v_mfma_f32_16x16x32_bf16 v[126:129], v[148:151], v[180:183], v[126:129]
	v_mfma_f32_16x16x32_bf16 v[126:129], v[152:155], v[184:187], v[126:129]
	s_waitcnt lgkmcnt(5)
	v_mfma_f32_16x16x32_bf16 v[122:125], v[156:159], v[180:183], v[122:125]
	v_mfma_f32_16x16x32_bf16 v[122:125], v[160:163], v[184:187], v[122:125]
	s_waitcnt lgkmcnt(3)
	v_mfma_f32_16x16x32_bf16 v[106:109], v[156:159], v[188:191], v[106:109]
	v_mfma_f32_16x16x32_bf16 v[106:109], v[160:163], v[192:195], v[106:109]
	s_waitcnt lgkmcnt(1)
	v_mfma_f32_16x16x32_bf16 v[110:113], v[148:151], v[188:191], v[110:113]
	v_mfma_f32_16x16x32_bf16 v[110:113], v[152:155], v[192:195], v[110:113]
	v_mfma_f32_16x16x32_bf16 v[94:97], v[148:151], v[196:199], v[94:97]
	v_mfma_f32_16x16x32_bf16 v[94:97], v[152:155], v[200:203], v[94:97]
	v_mfma_f32_16x16x32_bf16 v[90:93], v[156:159], v[196:199], v[90:93]
	v_mfma_f32_16x16x32_bf16 v[90:93], v[160:163], v[200:203], v[90:93]
	v_mfma_f32_16x16x32_bf16 v[74:77], v[156:159], v[204:207], v[74:77]
	v_mfma_f32_16x16x32_bf16 v[74:77], v[160:163], v[208:211], v[74:77]
	s_waitcnt lgkmcnt(0)
	v_mfma_f32_16x16x32_bf16 v[78:81], v[148:151], v[204:207], v[78:81]
	v_mfma_f32_16x16x32_bf16 v[78:81], v[152:155], v[208:211], v[78:81]
	s_setprio 0
	s_setprio 1
	v_mfma_f32_16x16x32_bf16 v[118:121], v[164:167], v[180:183], v[118:121]
	v_mfma_f32_16x16x32_bf16 v[118:121], v[168:171], v[184:187], v[118:121]
	v_mfma_f32_16x16x32_bf16 v[114:117], v[172:175], v[180:183], v[114:117]
	v_mfma_f32_16x16x32_bf16 v[114:117], v[176:179], v[184:187], v[114:117]
	v_mfma_f32_16x16x32_bf16 v[98:101], v[172:175], v[188:191], v[98:101]
	v_mfma_f32_16x16x32_bf16 v[98:101], v[176:179], v[192:195], v[98:101]
	v_mfma_f32_16x16x32_bf16 v[102:105], v[164:167], v[188:191], v[102:105]
	v_mfma_f32_16x16x32_bf16 v[102:105], v[168:171], v[192:195], v[102:105]
	v_mfma_f32_16x16x32_bf16 v[86:89], v[164:167], v[196:199], v[86:89]
	v_mfma_f32_16x16x32_bf16 v[86:89], v[168:171], v[200:203], v[86:89]
	v_mfma_f32_16x16x32_bf16 v[82:85], v[172:175], v[196:199], v[82:85]
	v_mfma_f32_16x16x32_bf16 v[82:85], v[176:179], v[200:203], v[82:85]
	s_setprio 2
	s_barrier
	v_mfma_f32_16x16x32_bf16 v[66:69], v[172:175], v[204:207], v[66:69]
	v_mfma_f32_16x16x32_bf16 v[66:69], v[176:179], v[208:211], v[66:69]
	v_mfma_f32_16x16x32_bf16 v[70:73], v[164:167], v[204:207], v[70:73]
	v_mfma_f32_16x16x32_bf16 v[70:73], v[168:171], v[208:211], v[70:73]
	s_setprio 0
	ds_read_b128 v[180:183], v145 offset:16384
	ds_read_b128 v[184:187], v145 offset:17408
	ds_read_b128 v[188:191], v145 offset:18432
	ds_read_b128 v[192:195], v145 offset:19456
	ds_read_b128 v[196:199], v145 offset:20480
	ds_read_b128 v[200:203], v145 offset:21504
	ds_read_b128 v[204:207], v145 offset:22528
	ds_read_b128 v[208:211], v145 offset:23552
	s_mov_b32 s82, m0
	s_mov_b32 m0, s35
	s_nop 0
	global_load_lds_dwordx4 v139, s[20:21]
	s_mov_b32 m0, s82
	s_nop 0
	s_mov_b32 s82, m0
	s_mov_b32 m0, s36
	s_nop 0
	global_load_lds_dwordx4 v141, s[20:21]
	s_mov_b32 m0, s82
	s_add_u32 s82, s20, 0x80000
	s_addc_u32 s83, s21, 0
	s_mov_b32 s86, m0
	s_mov_b32 m0, s37
	s_nop 0
	global_load_lds_dwordx4 v139, s[82:83]
	s_mov_b32 m0, s86
	s_nop 0
	s_mov_b32 s86, m0
	s_mov_b32 m0, s42
	s_nop 0
	global_load_lds_dwordx4 v141, s[82:83]
	s_mov_b32 m0, s86
	s_waitcnt vmcnt(4)
	s_waitcnt lgkmcnt(0)
	s_barrier
	s_setprio 1
	s_waitcnt lgkmcnt(7)
	v_mfma_f32_16x16x32_bf16 v[62:65], v[148:151], v[180:183], v[62:65]
	v_mfma_f32_16x16x32_bf16 v[62:65], v[152:155], v[184:187], v[62:65]
	s_waitcnt lgkmcnt(5)
	v_mfma_f32_16x16x32_bf16 v[58:61], v[156:159], v[180:183], v[58:61]
	v_mfma_f32_16x16x32_bf16 v[58:61], v[160:163], v[184:187], v[58:61]
	s_waitcnt lgkmcnt(3)
	v_mfma_f32_16x16x32_bf16 v[42:45], v[156:159], v[188:191], v[42:45]
	v_mfma_f32_16x16x32_bf16 v[42:45], v[160:163], v[192:195], v[42:45]
	s_waitcnt lgkmcnt(1)
	v_mfma_f32_16x16x32_bf16 v[46:49], v[148:151], v[188:191], v[46:49]
	v_mfma_f32_16x16x32_bf16 v[46:49], v[152:155], v[192:195], v[46:49]
	v_mfma_f32_16x16x32_bf16 v[30:33], v[148:151], v[196:199], v[30:33]
	v_mfma_f32_16x16x32_bf16 v[30:33], v[152:155], v[200:203], v[30:33]
	v_mfma_f32_16x16x32_bf16 v[26:29], v[156:159], v[196:199], v[26:29]
	v_mfma_f32_16x16x32_bf16 v[26:29], v[160:163], v[200:203], v[26:29]
	v_mfma_f32_16x16x32_bf16 v[10:13], v[156:159], v[204:207], v[10:13]
	v_mfma_f32_16x16x32_bf16 v[10:13], v[160:163], v[208:211], v[10:13]
	s_waitcnt lgkmcnt(0)
	v_mfma_f32_16x16x32_bf16 v[14:17], v[148:151], v[204:207], v[14:17]
	v_mfma_f32_16x16x32_bf16 v[14:17], v[152:155], v[208:211], v[14:17]
	s_setprio 0
	s_setprio 1
	v_mfma_f32_16x16x32_bf16 v[54:57], v[164:167], v[180:183], v[54:57]
	v_mfma_f32_16x16x32_bf16 v[54:57], v[168:171], v[184:187], v[54:57]
	v_mfma_f32_16x16x32_bf16 v[50:53], v[172:175], v[180:183], v[50:53]
	v_mfma_f32_16x16x32_bf16 v[50:53], v[176:179], v[184:187], v[50:53]
	v_mfma_f32_16x16x32_bf16 v[34:37], v[172:175], v[188:191], v[34:37]
	v_mfma_f32_16x16x32_bf16 v[34:37], v[176:179], v[192:195], v[34:37]
	v_mfma_f32_16x16x32_bf16 v[38:41], v[164:167], v[188:191], v[38:41]
	v_mfma_f32_16x16x32_bf16 v[38:41], v[168:171], v[192:195], v[38:41]
	v_mfma_f32_16x16x32_bf16 v[22:25], v[164:167], v[196:199], v[22:25]
	v_mfma_f32_16x16x32_bf16 v[22:25], v[168:171], v[200:203], v[22:25]
	v_mfma_f32_16x16x32_bf16 v[18:21], v[172:175], v[196:199], v[18:21]
	v_mfma_f32_16x16x32_bf16 v[18:21], v[176:179], v[200:203], v[18:21]
	s_setprio 2
	s_barrier
	v_mfma_f32_16x16x32_bf16 v[2:5], v[172:175], v[204:207], v[2:5]
	v_mfma_f32_16x16x32_bf16 v[2:5], v[176:179], v[208:211], v[2:5]
	v_mfma_f32_16x16x32_bf16 v[6:9], v[164:167], v[204:207], v[6:9]
	v_mfma_f32_16x16x32_bf16 v[6:9], v[168:171], v[208:211], v[6:9]
	s_setprio 0
	ds_read_b128 v[148:151], v146
	ds_read_b128 v[152:155], v146 offset:1024
	ds_read_b128 v[156:159], v146 offset:2048
	ds_read_b128 v[160:163], v146 offset:3072
	ds_read_b128 v[164:167], v147
	ds_read_b128 v[168:171], v147 offset:1024
	ds_read_b128 v[172:175], v147 offset:2048
	ds_read_b128 v[176:179], v147 offset:3072
	ds_read_b128 v[180:183], v145 offset:32768
	ds_read_b128 v[184:187], v145 offset:33792
	ds_read_b128 v[188:191], v145 offset:34816
	ds_read_b128 v[192:195], v145 offset:35840
	ds_read_b128 v[196:199], v145 offset:36864
	ds_read_b128 v[200:203], v145 offset:37888
	ds_read_b128 v[204:207], v145 offset:38912
	ds_read_b128 v[208:211], v145 offset:39936
	s_mov_b32 s82, m0
	s_mov_b32 m0, s31
	s_nop 0
	global_load_lds_dwordx4 v138, s[22:23]
	s_mov_b32 m0, s82
	s_nop 0
	s_mov_b32 s82, m0
	s_mov_b32 m0, s43
	s_nop 0
	global_load_lds_dwordx4 v140, s[22:23]
	s_mov_b32 m0, s82
	s_add_u32 s22, s22, 0x80000
	s_addc_u32 s23, s23, 0
	s_mov_b32 s82, m0
	s_mov_b32 m0, s46
	s_nop 0
	global_load_lds_dwordx4 v138, s[22:23]
	s_mov_b32 m0, s82
	s_nop 0
	s_mov_b32 s82, m0
	s_mov_b32 m0, s47
	s_nop 0
	global_load_lds_dwordx4 v140, s[22:23]
	s_mov_b32 m0, s82
	s_waitcnt vmcnt(8)
	s_waitcnt lgkmcnt(0)
	s_barrier
	s_setprio 1
	s_waitcnt lgkmcnt(7)
	v_mfma_f32_16x16x32_bf16 v[126:129], v[148:151], v[180:183], v[126:129]
	v_mfma_f32_16x16x32_bf16 v[126:129], v[152:155], v[184:187], v[126:129]
	s_waitcnt lgkmcnt(5)
	v_mfma_f32_16x16x32_bf16 v[122:125], v[156:159], v[180:183], v[122:125]
	v_mfma_f32_16x16x32_bf16 v[122:125], v[160:163], v[184:187], v[122:125]
	s_waitcnt lgkmcnt(3)
	v_mfma_f32_16x16x32_bf16 v[106:109], v[156:159], v[188:191], v[106:109]
	v_mfma_f32_16x16x32_bf16 v[106:109], v[160:163], v[192:195], v[106:109]
	s_waitcnt lgkmcnt(1)
	v_mfma_f32_16x16x32_bf16 v[110:113], v[148:151], v[188:191], v[110:113]
	v_mfma_f32_16x16x32_bf16 v[110:113], v[152:155], v[192:195], v[110:113]
	v_mfma_f32_16x16x32_bf16 v[94:97], v[148:151], v[196:199], v[94:97]
	v_mfma_f32_16x16x32_bf16 v[94:97], v[152:155], v[200:203], v[94:97]
	v_mfma_f32_16x16x32_bf16 v[90:93], v[156:159], v[196:199], v[90:93]
	v_mfma_f32_16x16x32_bf16 v[90:93], v[160:163], v[200:203], v[90:93]
	v_mfma_f32_16x16x32_bf16 v[74:77], v[156:159], v[204:207], v[74:77]
	v_mfma_f32_16x16x32_bf16 v[74:77], v[160:163], v[208:211], v[74:77]
	s_waitcnt lgkmcnt(0)
	v_mfma_f32_16x16x32_bf16 v[78:81], v[148:151], v[204:207], v[78:81]
	v_mfma_f32_16x16x32_bf16 v[78:81], v[152:155], v[208:211], v[78:81]
	s_setprio 0
	s_setprio 1
	v_mfma_f32_16x16x32_bf16 v[118:121], v[164:167], v[180:183], v[118:121]
	v_mfma_f32_16x16x32_bf16 v[118:121], v[168:171], v[184:187], v[118:121]
	v_mfma_f32_16x16x32_bf16 v[114:117], v[172:175], v[180:183], v[114:117]
	v_mfma_f32_16x16x32_bf16 v[114:117], v[176:179], v[184:187], v[114:117]
	v_mfma_f32_16x16x32_bf16 v[98:101], v[172:175], v[188:191], v[98:101]
	v_mfma_f32_16x16x32_bf16 v[98:101], v[176:179], v[192:195], v[98:101]
	v_mfma_f32_16x16x32_bf16 v[102:105], v[164:167], v[188:191], v[102:105]
	v_mfma_f32_16x16x32_bf16 v[102:105], v[168:171], v[192:195], v[102:105]
	v_mfma_f32_16x16x32_bf16 v[86:89], v[164:167], v[196:199], v[86:89]
	v_mfma_f32_16x16x32_bf16 v[86:89], v[168:171], v[200:203], v[86:89]
	v_mfma_f32_16x16x32_bf16 v[82:85], v[172:175], v[196:199], v[82:85]
	v_mfma_f32_16x16x32_bf16 v[82:85], v[176:179], v[200:203], v[82:85]
	s_setprio 2
	s_barrier
	v_mfma_f32_16x16x32_bf16 v[66:69], v[172:175], v[204:207], v[66:69]
	v_mfma_f32_16x16x32_bf16 v[66:69], v[176:179], v[208:211], v[66:69]
	v_mfma_f32_16x16x32_bf16 v[70:73], v[164:167], v[204:207], v[70:73]
	v_mfma_f32_16x16x32_bf16 v[70:73], v[168:171], v[208:211], v[70:73]
	s_setprio 0
	ds_read_b128 v[180:183], v145 offset:49152
	ds_read_b128 v[184:187], v145 offset:50176
	ds_read_b128 v[188:191], v145 offset:51200
	ds_read_b128 v[192:195], v145 offset:52224
	ds_read_b128 v[196:199], v145 offset:53248
	ds_read_b128 v[200:203], v145 offset:54272
	ds_read_b128 v[204:207], v145 offset:55296
	ds_read_b128 v[208:211], v145 offset:56320
	s_add_u32 s22, s20, 0x80
	s_addc_u32 s23, s21, 0
	s_mov_b32 s82, m0
	s_mov_b32 m0, s48
	s_nop 0
	global_load_lds_dwordx4 v139, s[22:23]
	s_mov_b32 m0, s82
	s_add_u32 s20, s20, 0x80080
	s_mov_b32 s82, m0
	s_mov_b32 m0, s49
	s_nop 0
	global_load_lds_dwordx4 v141, s[22:23]
	s_mov_b32 m0, s82
	s_addc_u32 s21, s21, 0
	s_mov_b32 s22, m0
	s_mov_b32 m0, s56
	s_nop 0
	global_load_lds_dwordx4 v139, s[20:21]
	s_mov_b32 m0, s22
	s_nop 0
	s_mov_b32 s22, m0
	s_mov_b32 m0, s57
	s_nop 0
	global_load_lds_dwordx4 v141, s[20:21]
	s_mov_b32 m0, s22
	s_waitcnt vmcnt(4)
	s_waitcnt lgkmcnt(0)
	s_barrier
	s_setprio 1
	s_waitcnt lgkmcnt(7)
	v_mfma_f32_16x16x32_bf16 v[62:65], v[148:151], v[180:183], v[62:65]
	v_mfma_f32_16x16x32_bf16 v[62:65], v[152:155], v[184:187], v[62:65]
	s_waitcnt lgkmcnt(5)
	v_mfma_f32_16x16x32_bf16 v[58:61], v[156:159], v[180:183], v[58:61]
	v_mfma_f32_16x16x32_bf16 v[58:61], v[160:163], v[184:187], v[58:61]
	s_waitcnt lgkmcnt(3)
	v_mfma_f32_16x16x32_bf16 v[42:45], v[156:159], v[188:191], v[42:45]
	v_mfma_f32_16x16x32_bf16 v[42:45], v[160:163], v[192:195], v[42:45]
	s_waitcnt lgkmcnt(1)
	v_mfma_f32_16x16x32_bf16 v[46:49], v[148:151], v[188:191], v[46:49]
	v_mfma_f32_16x16x32_bf16 v[46:49], v[152:155], v[192:195], v[46:49]
	v_mfma_f32_16x16x32_bf16 v[30:33], v[148:151], v[196:199], v[30:33]
	v_mfma_f32_16x16x32_bf16 v[30:33], v[152:155], v[200:203], v[30:33]
	v_mfma_f32_16x16x32_bf16 v[26:29], v[156:159], v[196:199], v[26:29]
	v_mfma_f32_16x16x32_bf16 v[26:29], v[160:163], v[200:203], v[26:29]
	v_mfma_f32_16x16x32_bf16 v[10:13], v[156:159], v[204:207], v[10:13]
	v_mfma_f32_16x16x32_bf16 v[10:13], v[160:163], v[208:211], v[10:13]
	s_waitcnt lgkmcnt(0)
	v_mfma_f32_16x16x32_bf16 v[14:17], v[148:151], v[204:207], v[14:17]
	v_mfma_f32_16x16x32_bf16 v[14:17], v[152:155], v[208:211], v[14:17]
	s_setprio 0
	s_setprio 1
	v_mfma_f32_16x16x32_bf16 v[54:57], v[164:167], v[180:183], v[54:57]
	v_mfma_f32_16x16x32_bf16 v[54:57], v[168:171], v[184:187], v[54:57]
	v_mfma_f32_16x16x32_bf16 v[50:53], v[172:175], v[180:183], v[50:53]
	v_mfma_f32_16x16x32_bf16 v[50:53], v[176:179], v[184:187], v[50:53]
	v_mfma_f32_16x16x32_bf16 v[34:37], v[172:175], v[188:191], v[34:37]
	v_mfma_f32_16x16x32_bf16 v[34:37], v[176:179], v[192:195], v[34:37]
	v_mfma_f32_16x16x32_bf16 v[38:41], v[164:167], v[188:191], v[38:41]
	v_mfma_f32_16x16x32_bf16 v[38:41], v[168:171], v[192:195], v[38:41]
	v_mfma_f32_16x16x32_bf16 v[22:25], v[164:167], v[196:199], v[22:25]
	v_mfma_f32_16x16x32_bf16 v[22:25], v[168:171], v[200:203], v[22:25]
	v_mfma_f32_16x16x32_bf16 v[18:21], v[172:175], v[196:199], v[18:21]
	v_mfma_f32_16x16x32_bf16 v[18:21], v[176:179], v[200:203], v[18:21]
	s_setprio 2
	s_barrier
	v_mfma_f32_16x16x32_bf16 v[2:5], v[172:175], v[204:207], v[2:5]
	v_mfma_f32_16x16x32_bf16 v[2:5], v[176:179], v[208:211], v[2:5]
	v_mfma_f32_16x16x32_bf16 v[6:9], v[164:167], v[204:207], v[6:9]
	v_mfma_f32_16x16x32_bf16 v[6:9], v[168:171], v[208:211], v[6:9]
	s_setprio 0
	s_add_i32 s81, s81, 2
	s_add_u32 s77, s77, 0x100
	s_addc_u32 s78, s78, 0
	s_add_u32 s18, s18, 0x100
	s_addc_u32 s19, s19, 0
	s_add_u32 s79, s79, 0x100
	s_addc_u32 s80, s80, 0
	s_cmp_gt_u32 s81, 29
	s_cbranch_scc0 .LBB0_344
	s_and_b64 vcc, exec, s[6:7]
	s_cbranch_vccz .LBB0_347
	s_barrier

.LBB0_472:
	s_ashr_i32 s13, s12, 31
	s_lshl_b64 s[14:15], s[12:13], 15
	s_add_u32 s14, s28, s14
	s_addc_u32 s15, s29, s15
	s_and_b64 s[16:17], s[2:3], exec
	s_cselect_b32 s13, s15, s23
	s_cselect_b32 s76, s14, s22
	s_ashr_i32 s11, s10, 31
	s_lshl_b64 s[16:17], s[10:11], 15
	s_add_u32 s16, s30, s16
	s_addc_u32 s17, s31, s17
	s_and_b64 s[24:25], s[2:3], exec
	s_cselect_b32 s11, s17, s21
	s_cselect_b32 s77, s16, s20
	s_add_u32 s78, s20, 0x80000
	s_addc_u32 s79, s21, 0
	s_add_u32 s20, s22, 0x204000
	s_addc_u32 s21, s23, 0
	s_add_u32 s80, s22, 0x400000
	s_addc_u32 s81, s23, 0
	s_mov_b32 s82, -2
	s_waitcnt vmcnt(25)
	s_waitcnt vmcnt(24)
	s_waitcnt vmcnt(23)
	s_waitcnt vmcnt(22)
	s_waitcnt vmcnt(21)
	s_waitcnt vmcnt(20)
	s_waitcnt vmcnt(15)
	s_waitcnt vmcnt(14)
	s_waitcnt vmcnt(13)
	s_waitcnt vmcnt(12)
	s_waitcnt vmcnt(7)
	s_waitcnt vmcnt(6)
	s_waitcnt vmcnt(5)
	s_waitcnt vmcnt(4)
	s_waitcnt vmcnt(3)
	s_waitcnt vmcnt(2)
	s_waitcnt vmcnt(1)
	s_waitcnt vmcnt(0)
	ds_read_b128 v[134:137], v161
	ds_read_b128 v[138:141], v161 offset:1024
	ds_read_b128 v[142:145], v161 offset:2048
	ds_read_b128 v[146:149], v161 offset:3072
	ds_read_b128 v[150:153], v162
	ds_read_b128 v[166:169], v162 offset:1024
	ds_read_b128 v[170:173], v162 offset:2048
	ds_read_b128 v[174:177], v162 offset:3072
	s_cmpk_eq_i32 s82, 0x52
	s_cselect_b32 s23, s11, s79
	s_cselect_b32 s22, s77, s78
	s_cselect_b32 s25, s13, s81
	s_cselect_b32 s24, s76, s80
	ds_read_b128 v[178:181], v163
	ds_read_b128 v[182:185], v163 offset:1024
	ds_read_b128 v[186:189], v163 offset:2048
	ds_read_b128 v[190:193], v163 offset:3072
	ds_read_b128 v[194:197], v163 offset:4096
	ds_read_b128 v[198:201], v163 offset:5120
	ds_read_b128 v[202:205], v163 offset:6144
	ds_read_b128 v[206:209], v163 offset:7168
	s_add_u32 s86, s20, 0xffffc000
	s_addc_u32 s87, s21, -1
	s_mov_b32 s83, m0
	s_mov_b32 m0, s65
	s_nop 0
	global_load_lds_dwordx4 v1, s[86:87]
	s_mov_b32 m0, s83
	s_nop 0
	s_mov_b32 s83, m0
	s_mov_b32 m0, s67
	s_nop 0
	global_load_lds_dwordx4 v157, s[86:87]
	s_mov_b32 m0, s83
	s_nop 0
	s_mov_b32 s83, m0
	s_mov_b32 m0, s66
	s_nop 0
	global_load_lds_dwordx4 v1, s[20:21]
	s_mov_b32 m0, s83
	s_nop 0
	s_mov_b32 s83, m0
	s_mov_b32 m0, s73
	s_nop 0
	global_load_lds_dwordx4 v157, s[20:21]
	s_mov_b32 m0, s83
	s_waitcnt vmcnt(8)
	s_waitcnt lgkmcnt(0)
	s_barrier
	s_setprio 1
	s_waitcnt lgkmcnt(7)
	v_mfma_f32_16x16x32_bf16 v[126:129], v[134:137], v[178:181], 0
	v_mfma_f32_16x16x32_bf16 v[126:129], v[138:141], v[182:185], v[126:129]
	s_waitcnt lgkmcnt(5)
	v_mfma_f32_16x16x32_bf16 v[122:125], v[142:145], v[178:181], 0
	v_mfma_f32_16x16x32_bf16 v[122:125], v[146:149], v[182:185], v[122:125]
	s_waitcnt lgkmcnt(3)
	v_mfma_f32_16x16x32_bf16 v[114:117], v[142:145], v[186:189], 0
	v_mfma_f32_16x16x32_bf16 v[114:117], v[146:149], v[190:193], v[114:117]
	s_waitcnt lgkmcnt(1)
	v_mfma_f32_16x16x32_bf16 v[118:121], v[134:137], v[186:189], 0
	v_mfma_f32_16x16x32_bf16 v[118:121], v[138:141], v[190:193], v[118:121]
	v_mfma_f32_16x16x32_bf16 v[102:105], v[134:137], v[194:197], 0
	v_mfma_f32_16x16x32_bf16 v[102:105], v[138:141], v[198:201], v[102:105]
	v_mfma_f32_16x16x32_bf16 v[94:97], v[142:145], v[194:197], 0
	v_mfma_f32_16x16x32_bf16 v[94:97], v[146:149], v[198:201], v[94:97]
	v_mfma_f32_16x16x32_bf16 v[78:81], v[142:145], v[202:205], 0
	v_mfma_f32_16x16x32_bf16 v[78:81], v[146:149], v[206:209], v[78:81]
	s_waitcnt lgkmcnt(0)
	v_mfma_f32_16x16x32_bf16 v[86:89], v[134:137], v[202:205], 0
	v_mfma_f32_16x16x32_bf16 v[86:89], v[138:141], v[206:209], v[86:89]
	s_setprio 0
	s_setprio 1
	v_mfma_f32_16x16x32_bf16 v[110:113], v[150:153], v[178:181], 0
	v_mfma_f32_16x16x32_bf16 v[110:113], v[166:169], v[182:185], v[110:113]
	v_mfma_f32_16x16x32_bf16 v[106:109], v[170:173], v[178:181], 0
	v_mfma_f32_16x16x32_bf16 v[106:109], v[174:177], v[182:185], v[106:109]
	v_mfma_f32_16x16x32_bf16 v[90:93], v[170:173], v[186:189], 0
	v_mfma_f32_16x16x32_bf16 v[90:93], v[174:177], v[190:193], v[90:93]
	v_mfma_f32_16x16x32_bf16 v[98:101], v[150:153], v[186:189], 0
	v_mfma_f32_16x16x32_bf16 v[98:101], v[166:169], v[190:193], v[98:101]
	v_mfma_f32_16x16x32_bf16 v[82:85], v[150:153], v[194:197], 0
	v_mfma_f32_16x16x32_bf16 v[82:85], v[166:169], v[198:201], v[82:85]
	v_mfma_f32_16x16x32_bf16 v[74:77], v[170:173], v[194:197], 0
	v_mfma_f32_16x16x32_bf16 v[74:77], v[174:177], v[198:201], v[74:77]
	s_setprio 2
	s_barrier
	v_mfma_f32_16x16x32_bf16 v[66:69], v[170:173], v[202:205], 0
	v_mfma_f32_16x16x32_bf16 v[66:69], v[174:177], v[206:209], v[66:69]
	v_mfma_f32_16x16x32_bf16 v[70:73], v[150:153], v[202:205], 0
	v_mfma_f32_16x16x32_bf16 v[70:73], v[166:169], v[206:209], v[70:73]
	s_setprio 0
	ds_read_b128 v[178:181], v163 offset:16384
	ds_read_b128 v[182:185], v163 offset:17408
	ds_read_b128 v[186:189], v163 offset:18432
	ds_read_b128 v[190:193], v163 offset:19456
	ds_read_b128 v[194:197], v163 offset:20480
	ds_read_b128 v[198:201], v163 offset:21504
	ds_read_b128 v[202:205], v163 offset:22528
	ds_read_b128 v[206:209], v163 offset:23552
	s_mov_b32 s83, m0
	s_mov_b32 m0, s19
	s_nop 0
	global_load_lds_dwordx4 v156, s[22:23]
	s_mov_b32 m0, s83
	s_add_u32 s86, s22, 0x4000
	s_mov_b32 s83, m0
	s_mov_b32 m0, s35
	s_nop 0
	global_load_lds_dwordx4 v158, s[22:23]
	s_mov_b32 m0, s83
	s_addc_u32 s87, s23, 0
	s_mov_b32 s83, m0
	s_mov_b32 m0, s36
	s_nop 0
	global_load_lds_dwordx4 v156, s[86:87]
	s_mov_b32 m0, s83
	s_nop 0
	s_mov_b32 s83, m0
	s_mov_b32 m0, s37
	s_nop 0
	global_load_lds_dwordx4 v158, s[86:87]
	s_mov_b32 m0, s83
	s_waitcnt vmcnt(4)
	s_waitcnt lgkmcnt(0)
	s_barrier
	s_setprio 1
	s_waitcnt lgkmcnt(7)
	v_mfma_f32_16x16x32_bf16 v[62:65], v[134:137], v[178:181], 0
	v_mfma_f32_16x16x32_bf16 v[62:65], v[138:141], v[182:185], v[62:65]
	s_waitcnt lgkmcnt(5)
	v_mfma_f32_16x16x32_bf16 v[58:61], v[142:145], v[178:181], 0
	v_mfma_f32_16x16x32_bf16 v[58:61], v[146:149], v[182:185], v[58:61]
	s_waitcnt lgkmcnt(3)
	v_mfma_f32_16x16x32_bf16 v[46:49], v[142:145], v[186:189], 0
	v_mfma_f32_16x16x32_bf16 v[46:49], v[146:149], v[190:193], v[46:49]
	s_waitcnt lgkmcnt(1)
	v_mfma_f32_16x16x32_bf16 v[54:57], v[134:137], v[186:189], 0
	v_mfma_f32_16x16x32_bf16 v[54:57], v[138:141], v[190:193], v[54:57]
	v_mfma_f32_16x16x32_bf16 v[38:41], v[134:137], v[194:197], 0
	v_mfma_f32_16x16x32_bf16 v[38:41], v[138:141], v[198:201], v[38:41]
	v_mfma_f32_16x16x32_bf16 v[30:33], v[142:145], v[194:197], 0
	v_mfma_f32_16x16x32_bf16 v[30:33], v[146:149], v[198:201], v[30:33]
	v_mfma_f32_16x16x32_bf16 v[14:17], v[142:145], v[202:205], 0
	v_mfma_f32_16x16x32_bf16 v[14:17], v[146:149], v[206:209], v[14:17]
	s_waitcnt lgkmcnt(0)
	v_mfma_f32_16x16x32_bf16 v[22:25], v[134:137], v[202:205], 0
	v_mfma_f32_16x16x32_bf16 v[22:25], v[138:141], v[206:209], v[22:25]
	s_setprio 0
	s_setprio 1
	v_mfma_f32_16x16x32_bf16 v[50:53], v[150:153], v[178:181], 0
	v_mfma_f32_16x16x32_bf16 v[50:53], v[166:169], v[182:185], v[50:53]
	v_mfma_f32_16x16x32_bf16 v[42:45], v[170:173], v[178:181], 0
	v_mfma_f32_16x16x32_bf16 v[42:45], v[174:177], v[182:185], v[42:45]
	v_mfma_f32_16x16x32_bf16 v[26:29], v[170:173], v[186:189], 0
	v_mfma_f32_16x16x32_bf16 v[26:29], v[174:177], v[190:193], v[26:29]
	v_mfma_f32_16x16x32_bf16 v[34:37], v[150:153], v[186:189], 0
	v_mfma_f32_16x16x32_bf16 v[34:37], v[166:169], v[190:193], v[34:37]
	v_mfma_f32_16x16x32_bf16 v[18:21], v[150:153], v[194:197], 0
	v_mfma_f32_16x16x32_bf16 v[18:21], v[166:169], v[198:201], v[18:21]
	v_mfma_f32_16x16x32_bf16 v[10:13], v[170:173], v[194:197], 0
	v_mfma_f32_16x16x32_bf16 v[10:13], v[174:177], v[198:201], v[10:13]
	s_setprio 2
	s_barrier
	v_mfma_f32_16x16x32_bf16 v[2:5], v[170:173], v[202:205], 0
	v_mfma_f32_16x16x32_bf16 v[2:5], v[174:177], v[206:209], v[2:5]
	v_mfma_f32_16x16x32_bf16 v[6:9], v[150:153], v[202:205], 0
	v_mfma_f32_16x16x32_bf16 v[6:9], v[166:169], v[206:209], v[6:9]
	s_setprio 0
	ds_read_b128 v[134:137], v164
	ds_read_b128 v[138:141], v164 offset:1024
	ds_read_b128 v[142:145], v164 offset:2048
	ds_read_b128 v[146:149], v164 offset:3072
	ds_read_b128 v[150:153], v165
	ds_read_b128 v[166:169], v165 offset:1024
	ds_read_b128 v[170:173], v165 offset:2048
	ds_read_b128 v[174:177], v165 offset:3072
	ds_read_b128 v[178:181], v163 offset:32768
	ds_read_b128 v[182:185], v163 offset:33792
	ds_read_b128 v[186:189], v163 offset:34816
	ds_read_b128 v[190:193], v163 offset:35840
	ds_read_b128 v[194:197], v163 offset:36864
	ds_read_b128 v[198:201], v163 offset:37888
	ds_read_b128 v[202:205], v163 offset:38912
	ds_read_b128 v[206:209], v163 offset:39936
	s_mov_b32 s83, m0
	s_mov_b32 m0, s34
	s_nop 0
	global_load_lds_dwordx4 v1, s[24:25]
	s_mov_b32 m0, s83
	s_nop 0
	s_mov_b32 s83, m0
	s_mov_b32 m0, s42
	s_nop 0
	global_load_lds_dwordx4 v157, s[24:25]
	s_mov_b32 m0, s83
	s_add_u32 s24, s24, 0x4000
	s_addc_u32 s25, s25, 0
	s_mov_b32 s83, m0
	s_mov_b32 m0, s43
	s_nop 0
	global_load_lds_dwordx4 v1, s[24:25]
	s_mov_b32 m0, s83
	s_nop 0
	s_mov_b32 s83, m0
	s_mov_b32 m0, s46
	s_nop 0
	global_load_lds_dwordx4 v157, s[24:25]
	s_mov_b32 m0, s83
	s_waitcnt vmcnt(8)
	s_waitcnt lgkmcnt(0)
	s_barrier
	s_setprio 1
	s_waitcnt lgkmcnt(7)
	v_mfma_f32_16x16x32_bf16 v[126:129], v[134:137], v[178:181], v[126:129]
	v_mfma_f32_16x16x32_bf16 v[126:129], v[138:141], v[182:185], v[126:129]
	s_waitcnt lgkmcnt(5)
	v_mfma_f32_16x16x32_bf16 v[122:125], v[142:145], v[178:181], v[122:125]
	v_mfma_f32_16x16x32_bf16 v[122:125], v[146:149], v[182:185], v[122:125]
	s_waitcnt lgkmcnt(3)
	v_mfma_f32_16x16x32_bf16 v[114:117], v[142:145], v[186:189], v[114:117]
	v_mfma_f32_16x16x32_bf16 v[114:117], v[146:149], v[190:193], v[114:117]
	s_waitcnt lgkmcnt(1)
	v_mfma_f32_16x16x32_bf16 v[118:121], v[134:137], v[186:189], v[118:121]
	v_mfma_f32_16x16x32_bf16 v[118:121], v[138:141], v[190:193], v[118:121]
	v_mfma_f32_16x16x32_bf16 v[102:105], v[134:137], v[194:197], v[102:105]
	v_mfma_f32_16x16x32_bf16 v[102:105], v[138:141], v[198:201], v[102:105]
	v_mfma_f32_16x16x32_bf16 v[94:97], v[142:145], v[194:197], v[94:97]
	v_mfma_f32_16x16x32_bf16 v[94:97], v[146:149], v[198:201], v[94:97]
	v_mfma_f32_16x16x32_bf16 v[78:81], v[142:145], v[202:205], v[78:81]
	v_mfma_f32_16x16x32_bf16 v[78:81], v[146:149], v[206:209], v[78:81]
	s_waitcnt lgkmcnt(0)
	v_mfma_f32_16x16x32_bf16 v[86:89], v[134:137], v[202:205], v[86:89]
	v_mfma_f32_16x16x32_bf16 v[86:89], v[138:141], v[206:209], v[86:89]
	s_setprio 0
	s_setprio 1
	v_mfma_f32_16x16x32_bf16 v[110:113], v[150:153], v[178:181], v[110:113]
	v_mfma_f32_16x16x32_bf16 v[110:113], v[166:169], v[182:185], v[110:113]
	v_mfma_f32_16x16x32_bf16 v[106:109], v[170:173], v[178:181], v[106:109]
	v_mfma_f32_16x16x32_bf16 v[106:109], v[174:177], v[182:185], v[106:109]
	v_mfma_f32_16x16x32_bf16 v[90:93], v[170:173], v[186:189], v[90:93]
	v_mfma_f32_16x16x32_bf16 v[90:93], v[174:177], v[190:193], v[90:93]
	v_mfma_f32_16x16x32_bf16 v[98:101], v[150:153], v[186:189], v[98:101]
	v_mfma_f32_16x16x32_bf16 v[98:101], v[166:169], v[190:193], v[98:101]
	v_mfma_f32_16x16x32_bf16 v[82:85], v[150:153], v[194:197], v[82:85]
	v_mfma_f32_16x16x32_bf16 v[82:85], v[166:169], v[198:201], v[82:85]
	v_mfma_f32_16x16x32_bf16 v[74:77], v[170:173], v[194:197], v[74:77]
	v_mfma_f32_16x16x32_bf16 v[74:77], v[174:177], v[198:201], v[74:77]
	s_setprio 2
	s_barrier
	v_mfma_f32_16x16x32_bf16 v[66:69], v[170:173], v[202:205], v[66:69]
	v_mfma_f32_16x16x32_bf16 v[66:69], v[174:177], v[206:209], v[66:69]
	v_mfma_f32_16x16x32_bf16 v[70:73], v[150:153], v[202:205], v[70:73]
	v_mfma_f32_16x16x32_bf16 v[70:73], v[166:169], v[206:209], v[70:73]
	s_setprio 0
	ds_read_b128 v[178:181], v163 offset:49152
	ds_read_b128 v[182:185], v163 offset:50176
	ds_read_b128 v[186:189], v163 offset:51200
	ds_read_b128 v[190:193], v163 offset:52224
	ds_read_b128 v[194:197], v163 offset:53248
	ds_read_b128 v[198:201], v163 offset:54272
	ds_read_b128 v[202:205], v163 offset:55296
	ds_read_b128 v[206:209], v163 offset:56320
	s_add_u32 s24, s22, 0x40000
	s_addc_u32 s25, s23, 0
	s_mov_b32 s83, m0
	s_mov_b32 m0, s47
	s_nop 0
	global_load_lds_dwordx4 v156, s[24:25]
	s_mov_b32 m0, s83
	s_add_u32 s22, s22, 0x44000
	s_mov_b32 s83, m0
	s_mov_b32 m0, s48
	s_nop 0
	global_load_lds_dwordx4 v158, s[24:25]
	s_mov_b32 m0, s83
	s_addc_u32 s23, s23, 0
	s_mov_b32 s24, m0
	s_mov_b32 m0, s49
	s_nop 0
	global_load_lds_dwordx4 v156, s[22:23]
	s_mov_b32 m0, s24
	s_nop 0
	s_mov_b32 s24, m0
	s_mov_b32 m0, s56
	s_nop 0
	global_load_lds_dwordx4 v158, s[22:23]
	s_mov_b32 m0, s24
	s_waitcnt vmcnt(4)
	s_waitcnt lgkmcnt(0)
	s_barrier
	s_setprio 1
	s_waitcnt lgkmcnt(7)
	v_mfma_f32_16x16x32_bf16 v[62:65], v[134:137], v[178:181], v[62:65]
	v_mfma_f32_16x16x32_bf16 v[62:65], v[138:141], v[182:185], v[62:65]
	s_waitcnt lgkmcnt(5)
	v_mfma_f32_16x16x32_bf16 v[58:61], v[142:145], v[178:181], v[58:61]
	v_mfma_f32_16x16x32_bf16 v[58:61], v[146:149], v[182:185], v[58:61]
	s_waitcnt lgkmcnt(3)
	v_mfma_f32_16x16x32_bf16 v[46:49], v[142:145], v[186:189], v[46:49]
	v_mfma_f32_16x16x32_bf16 v[46:49], v[146:149], v[190:193], v[46:49]
	s_waitcnt lgkmcnt(1)
	v_mfma_f32_16x16x32_bf16 v[54:57], v[134:137], v[186:189], v[54:57]
	v_mfma_f32_16x16x32_bf16 v[54:57], v[138:141], v[190:193], v[54:57]
	v_mfma_f32_16x16x32_bf16 v[38:41], v[134:137], v[194:197], v[38:41]
	v_mfma_f32_16x16x32_bf16 v[38:41], v[138:141], v[198:201], v[38:41]
	v_mfma_f32_16x16x32_bf16 v[30:33], v[142:145], v[194:197], v[30:33]
	v_mfma_f32_16x16x32_bf16 v[30:33], v[146:149], v[198:201], v[30:33]
	v_mfma_f32_16x16x32_bf16 v[14:17], v[142:145], v[202:205], v[14:17]
	v_mfma_f32_16x16x32_bf16 v[14:17], v[146:149], v[206:209], v[14:17]
	s_waitcnt lgkmcnt(0)
	v_mfma_f32_16x16x32_bf16 v[22:25], v[134:137], v[202:205], v[22:25]
	v_mfma_f32_16x16x32_bf16 v[22:25], v[138:141], v[206:209], v[22:25]
	s_setprio 0
	s_setprio 1
	v_mfma_f32_16x16x32_bf16 v[50:53], v[150:153], v[178:181], v[50:53]
	v_mfma_f32_16x16x32_bf16 v[50:53], v[166:169], v[182:185], v[50:53]
	v_mfma_f32_16x16x32_bf16 v[42:45], v[170:173], v[178:181], v[42:45]
	v_mfma_f32_16x16x32_bf16 v[42:45], v[174:177], v[182:185], v[42:45]
	v_mfma_f32_16x16x32_bf16 v[26:29], v[170:173], v[186:189], v[26:29]
	v_mfma_f32_16x16x32_bf16 v[26:29], v[174:177], v[190:193], v[26:29]
	v_mfma_f32_16x16x32_bf16 v[34:37], v[150:153], v[186:189], v[34:37]
	v_mfma_f32_16x16x32_bf16 v[34:37], v[166:169], v[190:193], v[34:37]
	v_mfma_f32_16x16x32_bf16 v[18:21], v[150:153], v[194:197], v[18:21]
	v_mfma_f32_16x16x32_bf16 v[18:21], v[166:169], v[198:201], v[18:21]
	v_mfma_f32_16x16x32_bf16 v[10:13], v[170:173], v[194:197], v[10:13]
	v_mfma_f32_16x16x32_bf16 v[10:13], v[174:177], v[198:201], v[10:13]
	s_setprio 2
	s_barrier
	v_mfma_f32_16x16x32_bf16 v[2:5], v[170:173], v[202:205], v[2:5]
	v_mfma_f32_16x16x32_bf16 v[2:5], v[174:177], v[206:209], v[2:5]
	v_mfma_f32_16x16x32_bf16 v[6:9], v[150:153], v[202:205], v[6:9]
	v_mfma_f32_16x16x32_bf16 v[6:9], v[166:169], v[206:209], v[6:9]
	s_setprio 0
	s_add_i32 s82, s82, 2
	s_add_u32 s78, s78, 0x80000
	s_addc_u32 s79, s79, 0
	s_add_u32 s20, s20, 0x400000
	s_addc_u32 s21, s21, 0
	s_add_u32 s80, s80, 0x400000
	s_addc_u32 s81, s81, 0
	s_cmpk_gt_u32 s82, 0x53
	.p2align 6
.LBB0_473:
	ds_read_b128 v[134:137], v161
	ds_read_b128 v[138:141], v161 offset:1024
	ds_read_b128 v[142:145], v161 offset:2048
	ds_read_b128 v[146:149], v161 offset:3072
	ds_read_b128 v[150:153], v162
	ds_read_b128 v[166:169], v162 offset:1024
	ds_read_b128 v[170:173], v162 offset:2048
	ds_read_b128 v[174:177], v162 offset:3072
	s_cmpk_eq_i32 s82, 0x52
	s_cselect_b32 s23, s11, s79
	s_cselect_b32 s22, s77, s78
	s_cselect_b32 s25, s13, s81
	s_cselect_b32 s24, s76, s80
	ds_read_b128 v[178:181], v163
	ds_read_b128 v[182:185], v163 offset:1024
	ds_read_b128 v[186:189], v163 offset:2048
	ds_read_b128 v[190:193], v163 offset:3072
	ds_read_b128 v[194:197], v163 offset:4096
	ds_read_b128 v[198:201], v163 offset:5120
	ds_read_b128 v[202:205], v163 offset:6144
	ds_read_b128 v[206:209], v163 offset:7168
	s_add_u32 s86, s20, 0xffffc000
	s_addc_u32 s87, s21, -1
	s_mov_b32 s83, m0
	s_mov_b32 m0, s65
	s_nop 0
	global_load_lds_dwordx4 v1, s[86:87]
	s_mov_b32 m0, s83
	s_nop 0
	s_mov_b32 s83, m0
	s_mov_b32 m0, s67
	s_nop 0
	global_load_lds_dwordx4 v157, s[86:87]
	s_mov_b32 m0, s83
	s_nop 0
	s_mov_b32 s83, m0
	s_mov_b32 m0, s66
	s_nop 0
	global_load_lds_dwordx4 v1, s[20:21]
	s_mov_b32 m0, s83
	s_nop 0
	s_mov_b32 s83, m0
	s_mov_b32 m0, s73
	s_nop 0
	global_load_lds_dwordx4 v157, s[20:21]
	s_mov_b32 m0, s83
	s_waitcnt vmcnt(8)
	s_waitcnt lgkmcnt(0)
	s_barrier
	s_setprio 1
	s_waitcnt lgkmcnt(7)
	v_mfma_f32_16x16x32_bf16 v[126:129], v[134:137], v[178:181], v[126:129]
	v_mfma_f32_16x16x32_bf16 v[126:129], v[138:141], v[182:185], v[126:129]
	s_waitcnt lgkmcnt(5)
	v_mfma_f32_16x16x32_bf16 v[122:125], v[142:145], v[178:181], v[122:125]
	v_mfma_f32_16x16x32_bf16 v[122:125], v[146:149], v[182:185], v[122:125]
	s_waitcnt lgkmcnt(3)
	v_mfma_f32_16x16x32_bf16 v[114:117], v[142:145], v[186:189], v[114:117]
	v_mfma_f32_16x16x32_bf16 v[114:117], v[146:149], v[190:193], v[114:117]
	s_waitcnt lgkmcnt(1)
	v_mfma_f32_16x16x32_bf16 v[118:121], v[134:137], v[186:189], v[118:121]
	v_mfma_f32_16x16x32_bf16 v[118:121], v[138:141], v[190:193], v[118:121]
	v_mfma_f32_16x16x32_bf16 v[102:105], v[134:137], v[194:197], v[102:105]
	v_mfma_f32_16x16x32_bf16 v[102:105], v[138:141], v[198:201], v[102:105]
	v_mfma_f32_16x16x32_bf16 v[94:97], v[142:145], v[194:197], v[94:97]
	v_mfma_f32_16x16x32_bf16 v[94:97], v[146:149], v[198:201], v[94:97]
	v_mfma_f32_16x16x32_bf16 v[78:81], v[142:145], v[202:205], v[78:81]
	v_mfma_f32_16x16x32_bf16 v[78:81], v[146:149], v[206:209], v[78:81]
	s_waitcnt lgkmcnt(0)
	v_mfma_f32_16x16x32_bf16 v[86:89], v[134:137], v[202:205], v[86:89]
	v_mfma_f32_16x16x32_bf16 v[86:89], v[138:141], v[206:209], v[86:89]
	s_setprio 0
	s_setprio 1
	v_mfma_f32_16x16x32_bf16 v[110:113], v[150:153], v[178:181], v[110:113]
	v_mfma_f32_16x16x32_bf16 v[110:113], v[166:169], v[182:185], v[110:113]
	v_mfma_f32_16x16x32_bf16 v[106:109], v[170:173], v[178:181], v[106:109]
	v_mfma_f32_16x16x32_bf16 v[106:109], v[174:177], v[182:185], v[106:109]
	v_mfma_f32_16x16x32_bf16 v[90:93], v[170:173], v[186:189], v[90:93]
	v_mfma_f32_16x16x32_bf16 v[90:93], v[174:177], v[190:193], v[90:93]
	v_mfma_f32_16x16x32_bf16 v[98:101], v[150:153], v[186:189], v[98:101]
	v_mfma_f32_16x16x32_bf16 v[98:101], v[166:169], v[190:193], v[98:101]
	v_mfma_f32_16x16x32_bf16 v[82:85], v[150:153], v[194:197], v[82:85]
	v_mfma_f32_16x16x32_bf16 v[82:85], v[166:169], v[198:201], v[82:85]
	v_mfma_f32_16x16x32_bf16 v[74:77], v[170:173], v[194:197], v[74:77]
	v_mfma_f32_16x16x32_bf16 v[74:77], v[174:177], v[198:201], v[74:77]
	s_setprio 2
	s_barrier
	v_mfma_f32_16x16x32_bf16 v[66:69], v[170:173], v[202:205], v[66:69]
	v_mfma_f32_16x16x32_bf16 v[66:69], v[174:177], v[206:209], v[66:69]
	v_mfma_f32_16x16x32_bf16 v[70:73], v[150:153], v[202:205], v[70:73]
	v_mfma_f32_16x16x32_bf16 v[70:73], v[166:169], v[206:209], v[70:73]
	s_setprio 0
	ds_read_b128 v[178:181], v163 offset:16384
	ds_read_b128 v[182:185], v163 offset:17408
	ds_read_b128 v[186:189], v163 offset:18432
	ds_read_b128 v[190:193], v163 offset:19456
	ds_read_b128 v[194:197], v163 offset:20480
	ds_read_b128 v[198:201], v163 offset:21504
	ds_read_b128 v[202:205], v163 offset:22528
	ds_read_b128 v[206:209], v163 offset:23552
	s_mov_b32 s83, m0
	s_mov_b32 m0, s19
	s_nop 0
	global_load_lds_dwordx4 v156, s[22:23]
	s_mov_b32 m0, s83
	s_add_u32 s86, s22, 0x4000
	s_mov_b32 s83, m0
	s_mov_b32 m0, s35
	s_nop 0
	global_load_lds_dwordx4 v158, s[22:23]
	s_mov_b32 m0, s83
	s_addc_u32 s87, s23, 0
	s_mov_b32 s83, m0
	s_mov_b32 m0, s36
	s_nop 0
	global_load_lds_dwordx4 v156, s[86:87]
	s_mov_b32 m0, s83
	s_nop 0
	s_mov_b32 s83, m0
	s_mov_b32 m0, s37
	s_nop 0
	global_load_lds_dwordx4 v158, s[86:87]
	s_mov_b32 m0, s83
	s_waitcnt vmcnt(4)
	s_waitcnt lgkmcnt(0)
	s_barrier
	s_setprio 1
	s_waitcnt lgkmcnt(7)
	v_mfma_f32_16x16x32_bf16 v[62:65], v[134:137], v[178:181], v[62:65]
	v_mfma_f32_16x16x32_bf16 v[62:65], v[138:141], v[182:185], v[62:65]
	s_waitcnt lgkmcnt(5)
	v_mfma_f32_16x16x32_bf16 v[58:61], v[142:145], v[178:181], v[58:61]
	v_mfma_f32_16x16x32_bf16 v[58:61], v[146:149], v[182:185], v[58:61]
	s_waitcnt lgkmcnt(3)
	v_mfma_f32_16x16x32_bf16 v[46:49], v[142:145], v[186:189], v[46:49]
	v_mfma_f32_16x16x32_bf16 v[46:49], v[146:149], v[190:193], v[46:49]
	s_waitcnt lgkmcnt(1)
	v_mfma_f32_16x16x32_bf16 v[54:57], v[134:137], v[186:189], v[54:57]
	v_mfma_f32_16x16x32_bf16 v[54:57], v[138:141], v[190:193], v[54:57]
	v_mfma_f32_16x16x32_bf16 v[38:41], v[134:137], v[194:197], v[38:41]
	v_mfma_f32_16x16x32_bf16 v[38:41], v[138:141], v[198:201], v[38:41]
	v_mfma_f32_16x16x32_bf16 v[30:33], v[142:145], v[194:197], v[30:33]
	v_mfma_f32_16x16x32_bf16 v[30:33], v[146:149], v[198:201], v[30:33]
	v_mfma_f32_16x16x32_bf16 v[14:17], v[142:145], v[202:205], v[14:17]
	v_mfma_f32_16x16x32_bf16 v[14:17], v[146:149], v[206:209], v[14:17]
	s_waitcnt lgkmcnt(0)
	v_mfma_f32_16x16x32_bf16 v[22:25], v[134:137], v[202:205], v[22:25]
	v_mfma_f32_16x16x32_bf16 v[22:25], v[138:141], v[206:209], v[22:25]
	s_setprio 0
	s_setprio 1
	v_mfma_f32_16x16x32_bf16 v[50:53], v[150:153], v[178:181], v[50:53]
	v_mfma_f32_16x16x32_bf16 v[50:53], v[166:169], v[182:185], v[50:53]
	v_mfma_f32_16x16x32_bf16 v[42:45], v[170:173], v[178:181], v[42:45]
	v_mfma_f32_16x16x32_bf16 v[42:45], v[174:177], v[182:185], v[42:45]
	v_mfma_f32_16x16x32_bf16 v[26:29], v[170:173], v[186:189], v[26:29]
	v_mfma_f32_16x16x32_bf16 v[26:29], v[174:177], v[190:193], v[26:29]
	v_mfma_f32_16x16x32_bf16 v[34:37], v[150:153], v[186:189], v[34:37]
	v_mfma_f32_16x16x32_bf16 v[34:37], v[166:169], v[190:193], v[34:37]
	v_mfma_f32_16x16x32_bf16 v[18:21], v[150:153], v[194:197], v[18:21]
	v_mfma_f32_16x16x32_bf16 v[18:21], v[166:169], v[198:201], v[18:21]
	v_mfma_f32_16x16x32_bf16 v[10:13], v[170:173], v[194:197], v[10:13]
	v_mfma_f32_16x16x32_bf16 v[10:13], v[174:177], v[198:201], v[10:13]
	s_setprio 2
	s_barrier
	v_mfma_f32_16x16x32_bf16 v[2:5], v[170:173], v[202:205], v[2:5]
	v_mfma_f32_16x16x32_bf16 v[2:5], v[174:177], v[206:209], v[2:5]
	v_mfma_f32_16x16x32_bf16 v[6:9], v[150:153], v[202:205], v[6:9]
	v_mfma_f32_16x16x32_bf16 v[6:9], v[166:169], v[206:209], v[6:9]
	s_setprio 0
	ds_read_b128 v[134:137], v164
	ds_read_b128 v[138:141], v164 offset:1024
	ds_read_b128 v[142:145], v164 offset:2048
	ds_read_b128 v[146:149], v164 offset:3072
	ds_read_b128 v[150:153], v165
	ds_read_b128 v[166:169], v165 offset:1024
	ds_read_b128 v[170:173], v165 offset:2048
	ds_read_b128 v[174:177], v165 offset:3072
	ds_read_b128 v[178:181], v163 offset:32768
	ds_read_b128 v[182:185], v163 offset:33792
	ds_read_b128 v[186:189], v163 offset:34816
	ds_read_b128 v[190:193], v163 offset:35840
	ds_read_b128 v[194:197], v163 offset:36864
	ds_read_b128 v[198:201], v163 offset:37888
	ds_read_b128 v[202:205], v163 offset:38912
	ds_read_b128 v[206:209], v163 offset:39936
	s_mov_b32 s83, m0
	s_mov_b32 m0, s34
	s_nop 0
	global_load_lds_dwordx4 v1, s[24:25]
	s_mov_b32 m0, s83
	s_nop 0
	s_mov_b32 s83, m0
	s_mov_b32 m0, s42
	s_nop 0
	global_load_lds_dwordx4 v157, s[24:25]
	s_mov_b32 m0, s83
	s_add_u32 s24, s24, 0x4000
	s_addc_u32 s25, s25, 0
	s_mov_b32 s83, m0
	s_mov_b32 m0, s43
	s_nop 0
	global_load_lds_dwordx4 v1, s[24:25]
	s_mov_b32 m0, s83
	s_nop 0
	s_mov_b32 s83, m0
	s_mov_b32 m0, s46
	s_nop 0
	global_load_lds_dwordx4 v157, s[24:25]
	s_mov_b32 m0, s83
	s_waitcnt vmcnt(8)
	s_waitcnt lgkmcnt(0)
	s_barrier
	s_setprio 1
	s_waitcnt lgkmcnt(7)
	v_mfma_f32_16x16x32_bf16 v[126:129], v[134:137], v[178:181], v[126:129]
	v_mfma_f32_16x16x32_bf16 v[126:129], v[138:141], v[182:185], v[126:129]
	s_waitcnt lgkmcnt(5)
	v_mfma_f32_16x16x32_bf16 v[122:125], v[142:145], v[178:181], v[122:125]
	v_mfma_f32_16x16x32_bf16 v[122:125], v[146:149], v[182:185], v[122:125]
	s_waitcnt lgkmcnt(3)
	v_mfma_f32_16x16x32_bf16 v[114:117], v[142:145], v[186:189], v[114:117]
	v_mfma_f32_16x16x32_bf16 v[114:117], v[146:149], v[190:193], v[114:117]
	s_waitcnt lgkmcnt(1)
	v_mfma_f32_16x16x32_bf16 v[118:121], v[134:137], v[186:189], v[118:121]
	v_mfma_f32_16x16x32_bf16 v[118:121], v[138:141], v[190:193], v[118:121]
	v_mfma_f32_16x16x32_bf16 v[102:105], v[134:137], v[194:197], v[102:105]
	v_mfma_f32_16x16x32_bf16 v[102:105], v[138:141], v[198:201], v[102:105]
	v_mfma_f32_16x16x32_bf16 v[94:97], v[142:145], v[194:197], v[94:97]
	v_mfma_f32_16x16x32_bf16 v[94:97], v[146:149], v[198:201], v[94:97]
	v_mfma_f32_16x16x32_bf16 v[78:81], v[142:145], v[202:205], v[78:81]
	v_mfma_f32_16x16x32_bf16 v[78:81], v[146:149], v[206:209], v[78:81]
	s_waitcnt lgkmcnt(0)
	v_mfma_f32_16x16x32_bf16 v[86:89], v[134:137], v[202:205], v[86:89]
	v_mfma_f32_16x16x32_bf16 v[86:89], v[138:141], v[206:209], v[86:89]
	s_setprio 0
	s_setprio 1
	v_mfma_f32_16x16x32_bf16 v[110:113], v[150:153], v[178:181], v[110:113]
	v_mfma_f32_16x16x32_bf16 v[110:113], v[166:169], v[182:185], v[110:113]
	v_mfma_f32_16x16x32_bf16 v[106:109], v[170:173], v[178:181], v[106:109]
	v_mfma_f32_16x16x32_bf16 v[106:109], v[174:177], v[182:185], v[106:109]
	v_mfma_f32_16x16x32_bf16 v[90:93], v[170:173], v[186:189], v[90:93]
	v_mfma_f32_16x16x32_bf16 v[90:93], v[174:177], v[190:193], v[90:93]
	v_mfma_f32_16x16x32_bf16 v[98:101], v[150:153], v[186:189], v[98:101]
	v_mfma_f32_16x16x32_bf16 v[98:101], v[166:169], v[190:193], v[98:101]
	v_mfma_f32_16x16x32_bf16 v[82:85], v[150:153], v[194:197], v[82:85]
	v_mfma_f32_16x16x32_bf16 v[82:85], v[166:169], v[198:201], v[82:85]
	v_mfma_f32_16x16x32_bf16 v[74:77], v[170:173], v[194:197], v[74:77]
	v_mfma_f32_16x16x32_bf16 v[74:77], v[174:177], v[198:201], v[74:77]
	s_setprio 2
	s_barrier
	v_mfma_f32_16x16x32_bf16 v[66:69], v[170:173], v[202:205], v[66:69]
	v_mfma_f32_16x16x32_bf16 v[66:69], v[174:177], v[206:209], v[66:69]
	v_mfma_f32_16x16x32_bf16 v[70:73], v[150:153], v[202:205], v[70:73]
	v_mfma_f32_16x16x32_bf16 v[70:73], v[166:169], v[206:209], v[70:73]
	s_setprio 0
	ds_read_b128 v[178:181], v163 offset:49152
	ds_read_b128 v[182:185], v163 offset:50176
	ds_read_b128 v[186:189], v163 offset:51200
	ds_read_b128 v[190:193], v163 offset:52224
	ds_read_b128 v[194:197], v163 offset:53248
	ds_read_b128 v[198:201], v163 offset:54272
	ds_read_b128 v[202:205], v163 offset:55296
	ds_read_b128 v[206:209], v163 offset:56320
	s_add_u32 s24, s22, 0x40000
	s_addc_u32 s25, s23, 0
	s_mov_b32 s83, m0
	s_mov_b32 m0, s47
	s_nop 0
	global_load_lds_dwordx4 v156, s[24:25]
	s_mov_b32 m0, s83
	s_add_u32 s22, s22, 0x44000
	s_mov_b32 s83, m0
	s_mov_b32 m0, s48
	s_nop 0
	global_load_lds_dwordx4 v158, s[24:25]
	s_mov_b32 m0, s83
	s_addc_u32 s23, s23, 0
	s_mov_b32 s24, m0
	s_mov_b32 m0, s49
	s_nop 0
	global_load_lds_dwordx4 v156, s[22:23]
	s_mov_b32 m0, s24
	s_nop 0
	s_mov_b32 s24, m0
	s_mov_b32 m0, s56
	s_nop 0
	global_load_lds_dwordx4 v158, s[22:23]
	s_mov_b32 m0, s24
	s_waitcnt vmcnt(4)
	s_waitcnt lgkmcnt(0)
	s_barrier
	s_setprio 1
	s_waitcnt lgkmcnt(7)
	v_mfma_f32_16x16x32_bf16 v[62:65], v[134:137], v[178:181], v[62:65]
	v_mfma_f32_16x16x32_bf16 v[62:65], v[138:141], v[182:185], v[62:65]
	s_waitcnt lgkmcnt(5)
	v_mfma_f32_16x16x32_bf16 v[58:61], v[142:145], v[178:181], v[58:61]
	v_mfma_f32_16x16x32_bf16 v[58:61], v[146:149], v[182:185], v[58:61]
	s_waitcnt lgkmcnt(3)
	v_mfma_f32_16x16x32_bf16 v[46:49], v[142:145], v[186:189], v[46:49]
	v_mfma_f32_16x16x32_bf16 v[46:49], v[146:149], v[190:193], v[46:49]
	s_waitcnt lgkmcnt(1)
	v_mfma_f32_16x16x32_bf16 v[54:57], v[134:137], v[186:189], v[54:57]
	v_mfma_f32_16x16x32_bf16 v[54:57], v[138:141], v[190:193], v[54:57]
	v_mfma_f32_16x16x32_bf16 v[38:41], v[134:137], v[194:197], v[38:41]
	v_mfma_f32_16x16x32_bf16 v[38:41], v[138:141], v[198:201], v[38:41]
	v_mfma_f32_16x16x32_bf16 v[30:33], v[142:145], v[194:197], v[30:33]
	v_mfma_f32_16x16x32_bf16 v[30:33], v[146:149], v[198:201], v[30:33]
	v_mfma_f32_16x16x32_bf16 v[14:17], v[142:145], v[202:205], v[14:17]
	v_mfma_f32_16x16x32_bf16 v[14:17], v[146:149], v[206:209], v[14:17]
	s_waitcnt lgkmcnt(0)
	v_mfma_f32_16x16x32_bf16 v[22:25], v[134:137], v[202:205], v[22:25]
	v_mfma_f32_16x16x32_bf16 v[22:25], v[138:141], v[206:209], v[22:25]
	s_setprio 0
	s_setprio 1
	v_mfma_f32_16x16x32_bf16 v[50:53], v[150:153], v[178:181], v[50:53]
	v_mfma_f32_16x16x32_bf16 v[50:53], v[166:169], v[182:185], v[50:53]
	v_mfma_f32_16x16x32_bf16 v[42:45], v[170:173], v[178:181], v[42:45]
	v_mfma_f32_16x16x32_bf16 v[42:45], v[174:177], v[182:185], v[42:45]
	v_mfma_f32_16x16x32_bf16 v[26:29], v[170:173], v[186:189], v[26:29]
	v_mfma_f32_16x16x32_bf16 v[26:29], v[174:177], v[190:193], v[26:29]
	v_mfma_f32_16x16x32_bf16 v[34:37], v[150:153], v[186:189], v[34:37]
	v_mfma_f32_16x16x32_bf16 v[34:37], v[166:169], v[190:193], v[34:37]
	v_mfma_f32_16x16x32_bf16 v[18:21], v[150:153], v[194:197], v[18:21]
	v_mfma_f32_16x16x32_bf16 v[18:21], v[166:169], v[198:201], v[18:21]
	v_mfma_f32_16x16x32_bf16 v[10:13], v[170:173], v[194:197], v[10:13]
	v_mfma_f32_16x16x32_bf16 v[10:13], v[174:177], v[198:201], v[10:13]
	s_setprio 2
	s_barrier
	v_mfma_f32_16x16x32_bf16 v[2:5], v[170:173], v[202:205], v[2:5]
	v_mfma_f32_16x16x32_bf16 v[2:5], v[174:177], v[206:209], v[2:5]
	v_mfma_f32_16x16x32_bf16 v[6:9], v[150:153], v[202:205], v[6:9]
	v_mfma_f32_16x16x32_bf16 v[6:9], v[166:169], v[206:209], v[6:9]
	s_setprio 0
	s_add_i32 s82, s82, 2
	s_add_u32 s78, s78, 0x80000
	s_addc_u32 s79, s79, 0
	s_add_u32 s20, s20, 0x400000
	s_addc_u32 s21, s21, 0
	s_add_u32 s80, s80, 0x400000
	s_addc_u32 s81, s81, 0
	s_cmpk_gt_u32 s82, 0x53
	s_cbranch_scc0 .LBB0_473
	s_and_b64 vcc, exec, s[8:9]
	s_cbranch_vccz .LBB0_476
	s_barrier

.LBB0_653:
	s_ashr_i32 s23, s22, 31
	s_lshl_b64 s[24:25], s[22:23], 20
	s_add_u32 s24, s35, s24
	s_addc_u32 s25, s36, s25
	s_and_b64 s[26:27], s[2:3], exec
	s_cselect_b32 s7, s25, s11
	s_cselect_b32 s9, s24, s10
	s_ashr_i32 s21, s20, 31
	s_lshl_b64 s[26:27], s[20:21], 20
	s_add_u32 s26, s37, s26
	s_addc_u32 s27, s40, s27
	s_and_b64 s[28:29], s[2:3], exec
	s_cselect_b32 s21, s27, s5
	s_cselect_b32 s23, s26, s4
	s_add_u32 s30, s4, 0x100
	s_addc_u32 s31, s5, 0
	s_add_u32 s4, s10, 0x80080
	s_addc_u32 s5, s11, 0
	s_add_u32 s33, s10, 0x100
	s_addc_u32 s73, s11, 0
	s_mov_b32 s74, -2
	s_waitcnt vmcnt(25)
	s_waitcnt vmcnt(24)
	s_waitcnt vmcnt(15)
	s_waitcnt vmcnt(14)
	s_waitcnt vmcnt(13)
	s_waitcnt vmcnt(12)
	s_waitcnt vmcnt(11)
	s_waitcnt vmcnt(10)
	s_waitcnt vmcnt(9)
	s_waitcnt vmcnt(8)
	s_waitcnt vmcnt(7)
	s_waitcnt vmcnt(6)
	s_waitcnt vmcnt(5)
	s_waitcnt vmcnt(4)
	s_waitcnt vmcnt(3)
	s_waitcnt vmcnt(2)
	s_waitcnt vmcnt(1)
	s_waitcnt vmcnt(0)
	ds_read_b128 v[130:133], v161
	ds_read_b128 v[138:141], v161 offset:1024
	ds_read_b128 v[142:145], v161 offset:2048
	ds_read_b128 v[146:149], v161 offset:3072
	ds_read_b128 v[150:153], v162
	ds_read_b128 v[168:171], v162 offset:1024
	ds_read_b128 v[172:175], v162 offset:2048
	ds_read_b128 v[176:179], v162 offset:3072
	s_cmp_eq_u32 s74, 28
	s_cselect_b32 s11, s21, s31
	s_cselect_b32 s10, s23, s30
	s_cselect_b32 s29, s7, s73
	s_cselect_b32 s28, s9, s33
	ds_read_b128 v[180:183], v163
	ds_read_b128 v[184:187], v163 offset:1024
	ds_read_b128 v[188:191], v163 offset:2048
	ds_read_b128 v[192:195], v163 offset:3072
	ds_read_b128 v[196:199], v163 offset:4096
	ds_read_b128 v[200:203], v163 offset:5120
	ds_read_b128 v[204:207], v163 offset:6144
	ds_read_b128 v[208:211], v163 offset:7168
	s_add_u32 s76, s4, 0xfff80000
	s_addc_u32 s77, s5, -1
	s_mov_b32 s75, m0
	s_mov_b32 m0, s80
	s_nop 0
	global_load_lds_dwordx4 v1, s[76:77]
	s_mov_b32 m0, s75
	s_nop 0
	s_mov_b32 s75, m0
	s_mov_b32 m0, s82
	s_nop 0
	global_load_lds_dwordx4 v157, s[76:77]
	s_mov_b32 m0, s75
	s_nop 0
	s_mov_b32 s75, m0
	s_mov_b32 m0, s81
	s_nop 0
	global_load_lds_dwordx4 v1, s[4:5]
	s_mov_b32 m0, s75
	s_nop 0
	s_mov_b32 s75, m0
	s_mov_b32 m0, s83
	s_nop 0
	global_load_lds_dwordx4 v157, s[4:5]
	s_mov_b32 m0, s75
	s_waitcnt vmcnt(8)
	s_waitcnt lgkmcnt(0)
	s_barrier
	s_setprio 1
	s_waitcnt lgkmcnt(7)
	v_mfma_f32_16x16x32_bf16 v[126:129], v[130:133], v[180:183], 0
	v_mfma_f32_16x16x32_bf16 v[126:129], v[138:141], v[184:187], v[126:129]
	s_waitcnt lgkmcnt(5)
	v_mfma_f32_16x16x32_bf16 v[122:125], v[142:145], v[180:183], 0
	v_mfma_f32_16x16x32_bf16 v[122:125], v[146:149], v[184:187], v[122:125]
	s_waitcnt lgkmcnt(3)
	v_mfma_f32_16x16x32_bf16 v[106:109], v[142:145], v[188:191], 0
	v_mfma_f32_16x16x32_bf16 v[106:109], v[146:149], v[192:195], v[106:109]
	s_waitcnt lgkmcnt(1)
	v_mfma_f32_16x16x32_bf16 v[110:113], v[130:133], v[188:191], 0
	v_mfma_f32_16x16x32_bf16 v[110:113], v[138:141], v[192:195], v[110:113]
	v_mfma_f32_16x16x32_bf16 v[94:97], v[130:133], v[196:199], 0
	v_mfma_f32_16x16x32_bf16 v[94:97], v[138:141], v[200:203], v[94:97]
	v_mfma_f32_16x16x32_bf16 v[90:93], v[142:145], v[196:199], 0
	v_mfma_f32_16x16x32_bf16 v[90:93], v[146:149], v[200:203], v[90:93]
	v_mfma_f32_16x16x32_bf16 v[74:77], v[142:145], v[204:207], 0
	v_mfma_f32_16x16x32_bf16 v[74:77], v[146:149], v[208:211], v[74:77]
	s_waitcnt lgkmcnt(0)
	v_mfma_f32_16x16x32_bf16 v[78:81], v[130:133], v[204:207], 0
	v_mfma_f32_16x16x32_bf16 v[78:81], v[138:141], v[208:211], v[78:81]
	s_setprio 0
	s_setprio 1
	v_mfma_f32_16x16x32_bf16 v[118:121], v[150:153], v[180:183], 0
	v_mfma_f32_16x16x32_bf16 v[118:121], v[168:171], v[184:187], v[118:121]
	v_mfma_f32_16x16x32_bf16 v[114:117], v[172:175], v[180:183], 0
	v_mfma_f32_16x16x32_bf16 v[114:117], v[176:179], v[184:187], v[114:117]
	v_mfma_f32_16x16x32_bf16 v[98:101], v[172:175], v[188:191], 0
	v_mfma_f32_16x16x32_bf16 v[98:101], v[176:179], v[192:195], v[98:101]
	v_mfma_f32_16x16x32_bf16 v[102:105], v[150:153], v[188:191], 0
	v_mfma_f32_16x16x32_bf16 v[102:105], v[168:171], v[192:195], v[102:105]
	v_mfma_f32_16x16x32_bf16 v[86:89], v[150:153], v[196:199], 0
	v_mfma_f32_16x16x32_bf16 v[86:89], v[168:171], v[200:203], v[86:89]
	v_mfma_f32_16x16x32_bf16 v[82:85], v[172:175], v[196:199], 0
	v_mfma_f32_16x16x32_bf16 v[82:85], v[176:179], v[200:203], v[82:85]
	s_setprio 2
	s_barrier
	v_mfma_f32_16x16x32_bf16 v[66:69], v[172:175], v[204:207], 0
	v_mfma_f32_16x16x32_bf16 v[66:69], v[176:179], v[208:211], v[66:69]
	v_mfma_f32_16x16x32_bf16 v[70:73], v[150:153], v[204:207], 0
	v_mfma_f32_16x16x32_bf16 v[70:73], v[168:171], v[208:211], v[70:73]
	s_setprio 0
	ds_read_b128 v[180:183], v163 offset:16384
	ds_read_b128 v[184:187], v163 offset:17408
	ds_read_b128 v[188:191], v163 offset:18432
	ds_read_b128 v[192:195], v163 offset:19456
	ds_read_b128 v[196:199], v163 offset:20480
	ds_read_b128 v[200:203], v163 offset:21504
	ds_read_b128 v[204:207], v163 offset:22528
	ds_read_b128 v[208:211], v163 offset:23552
	s_mov_b32 s75, m0
	s_mov_b32 m0, s43
	s_nop 0
	global_load_lds_dwordx4 v156, s[10:11]
	s_mov_b32 m0, s75
	s_add_u32 s76, s10, 0x80000
	s_mov_b32 s75, m0
	s_mov_b32 m0, s46
	s_nop 0
	global_load_lds_dwordx4 v158, s[10:11]
	s_mov_b32 m0, s75
	s_addc_u32 s77, s11, 0
	s_mov_b32 s75, m0
	s_mov_b32 m0, s47
	s_nop 0
	global_load_lds_dwordx4 v156, s[76:77]
	s_mov_b32 m0, s75
	s_nop 0
	s_mov_b32 s75, m0
	s_mov_b32 m0, s48
	s_nop 0
	global_load_lds_dwordx4 v158, s[76:77]
	s_mov_b32 m0, s75
	s_waitcnt vmcnt(4)
	s_waitcnt lgkmcnt(0)
	s_barrier
	s_setprio 1
	s_waitcnt lgkmcnt(7)
	v_mfma_f32_16x16x32_bf16 v[62:65], v[130:133], v[180:183], 0
	v_mfma_f32_16x16x32_bf16 v[62:65], v[138:141], v[184:187], v[62:65]
	s_waitcnt lgkmcnt(5)
	v_mfma_f32_16x16x32_bf16 v[58:61], v[142:145], v[180:183], 0
	v_mfma_f32_16x16x32_bf16 v[58:61], v[146:149], v[184:187], v[58:61]
	s_waitcnt lgkmcnt(3)
	v_mfma_f32_16x16x32_bf16 v[42:45], v[142:145], v[188:191], 0
	v_mfma_f32_16x16x32_bf16 v[42:45], v[146:149], v[192:195], v[42:45]
	s_waitcnt lgkmcnt(1)
	v_mfma_f32_16x16x32_bf16 v[46:49], v[130:133], v[188:191], 0
	v_mfma_f32_16x16x32_bf16 v[46:49], v[138:141], v[192:195], v[46:49]
	v_mfma_f32_16x16x32_bf16 v[30:33], v[130:133], v[196:199], 0
	v_mfma_f32_16x16x32_bf16 v[30:33], v[138:141], v[200:203], v[30:33]
	v_mfma_f32_16x16x32_bf16 v[26:29], v[142:145], v[196:199], 0
	v_mfma_f32_16x16x32_bf16 v[26:29], v[146:149], v[200:203], v[26:29]
	v_mfma_f32_16x16x32_bf16 v[10:13], v[142:145], v[204:207], 0
	v_mfma_f32_16x16x32_bf16 v[10:13], v[146:149], v[208:211], v[10:13]
	s_waitcnt lgkmcnt(0)
	v_mfma_f32_16x16x32_bf16 v[14:17], v[130:133], v[204:207], 0
	v_mfma_f32_16x16x32_bf16 v[14:17], v[138:141], v[208:211], v[14:17]
	s_setprio 0
	s_setprio 1
	v_mfma_f32_16x16x32_bf16 v[54:57], v[150:153], v[180:183], 0
	v_mfma_f32_16x16x32_bf16 v[54:57], v[168:171], v[184:187], v[54:57]
	v_mfma_f32_16x16x32_bf16 v[50:53], v[172:175], v[180:183], 0
	v_mfma_f32_16x16x32_bf16 v[50:53], v[176:179], v[184:187], v[50:53]
	v_mfma_f32_16x16x32_bf16 v[34:37], v[172:175], v[188:191], 0
	v_mfma_f32_16x16x32_bf16 v[34:37], v[176:179], v[192:195], v[34:37]
	v_mfma_f32_16x16x32_bf16 v[38:41], v[150:153], v[188:191], 0
	v_mfma_f32_16x16x32_bf16 v[38:41], v[168:171], v[192:195], v[38:41]
	v_mfma_f32_16x16x32_bf16 v[22:25], v[150:153], v[196:199], 0
	v_mfma_f32_16x16x32_bf16 v[22:25], v[168:171], v[200:203], v[22:25]
	v_mfma_f32_16x16x32_bf16 v[18:21], v[172:175], v[196:199], 0
	v_mfma_f32_16x16x32_bf16 v[18:21], v[176:179], v[200:203], v[18:21]
	s_setprio 2
	s_barrier
	v_mfma_f32_16x16x32_bf16 v[2:5], v[172:175], v[204:207], 0
	v_mfma_f32_16x16x32_bf16 v[2:5], v[176:179], v[208:211], v[2:5]
	v_mfma_f32_16x16x32_bf16 v[6:9], v[150:153], v[204:207], 0
	v_mfma_f32_16x16x32_bf16 v[6:9], v[168:171], v[208:211], v[6:9]
	s_setprio 0
	ds_read_b128 v[130:133], v164
	ds_read_b128 v[138:141], v164 offset:1024
	ds_read_b128 v[142:145], v164 offset:2048
	ds_read_b128 v[146:149], v164 offset:3072
	ds_read_b128 v[150:153], v165
	ds_read_b128 v[168:171], v165 offset:1024
	ds_read_b128 v[172:175], v165 offset:2048
	ds_read_b128 v[176:179], v165 offset:3072
	ds_read_b128 v[180:183], v163 offset:32768
	ds_read_b128 v[184:187], v163 offset:33792
	ds_read_b128 v[188:191], v163 offset:34816
	ds_read_b128 v[192:195], v163 offset:35840
	ds_read_b128 v[196:199], v163 offset:36864
	ds_read_b128 v[200:203], v163 offset:37888
	ds_read_b128 v[204:207], v163 offset:38912
	ds_read_b128 v[208:211], v163 offset:39936
	s_mov_b32 s75, m0
	s_mov_b32 m0, s42
	s_nop 0
	global_load_lds_dwordx4 v1, s[28:29]
	s_mov_b32 m0, s75
	s_nop 0
	s_mov_b32 s75, m0
	s_mov_b32 m0, s49
	s_nop 0
	global_load_lds_dwordx4 v157, s[28:29]
	s_mov_b32 m0, s75
	s_add_u32 s28, s28, 0x80000
	s_addc_u32 s29, s29, 0
	s_mov_b32 s75, m0
	s_mov_b32 m0, s56
	s_nop 0
	global_load_lds_dwordx4 v1, s[28:29]
	s_mov_b32 m0, s75
	s_nop 0
	s_mov_b32 s75, m0
	s_mov_b32 m0, s57
	s_nop 0
	global_load_lds_dwordx4 v157, s[28:29]
	s_mov_b32 m0, s75
	s_waitcnt vmcnt(8)
	s_waitcnt lgkmcnt(0)
	s_barrier
	s_setprio 1
	s_waitcnt lgkmcnt(7)
	v_mfma_f32_16x16x32_bf16 v[126:129], v[130:133], v[180:183], v[126:129]
	v_mfma_f32_16x16x32_bf16 v[126:129], v[138:141], v[184:187], v[126:129]
	s_waitcnt lgkmcnt(5)
	v_mfma_f32_16x16x32_bf16 v[122:125], v[142:145], v[180:183], v[122:125]
	v_mfma_f32_16x16x32_bf16 v[122:125], v[146:149], v[184:187], v[122:125]
	s_waitcnt lgkmcnt(3)
	v_mfma_f32_16x16x32_bf16 v[106:109], v[142:145], v[188:191], v[106:109]
	v_mfma_f32_16x16x32_bf16 v[106:109], v[146:149], v[192:195], v[106:109]
	s_waitcnt lgkmcnt(1)
	v_mfma_f32_16x16x32_bf16 v[110:113], v[130:133], v[188:191], v[110:113]
	v_mfma_f32_16x16x32_bf16 v[110:113], v[138:141], v[192:195], v[110:113]
	v_mfma_f32_16x16x32_bf16 v[94:97], v[130:133], v[196:199], v[94:97]
	v_mfma_f32_16x16x32_bf16 v[94:97], v[138:141], v[200:203], v[94:97]
	v_mfma_f32_16x16x32_bf16 v[90:93], v[142:145], v[196:199], v[90:93]
	v_mfma_f32_16x16x32_bf16 v[90:93], v[146:149], v[200:203], v[90:93]
	v_mfma_f32_16x16x32_bf16 v[74:77], v[142:145], v[204:207], v[74:77]
	v_mfma_f32_16x16x32_bf16 v[74:77], v[146:149], v[208:211], v[74:77]
	s_waitcnt lgkmcnt(0)
	v_mfma_f32_16x16x32_bf16 v[78:81], v[130:133], v[204:207], v[78:81]
	v_mfma_f32_16x16x32_bf16 v[78:81], v[138:141], v[208:211], v[78:81]
	s_setprio 0
	s_setprio 1
	v_mfma_f32_16x16x32_bf16 v[118:121], v[150:153], v[180:183], v[118:121]
	v_mfma_f32_16x16x32_bf16 v[118:121], v[168:171], v[184:187], v[118:121]
	v_mfma_f32_16x16x32_bf16 v[114:117], v[172:175], v[180:183], v[114:117]
	v_mfma_f32_16x16x32_bf16 v[114:117], v[176:179], v[184:187], v[114:117]
	v_mfma_f32_16x16x32_bf16 v[98:101], v[172:175], v[188:191], v[98:101]
	v_mfma_f32_16x16x32_bf16 v[98:101], v[176:179], v[192:195], v[98:101]
	v_mfma_f32_16x16x32_bf16 v[102:105], v[150:153], v[188:191], v[102:105]
	v_mfma_f32_16x16x32_bf16 v[102:105], v[168:171], v[192:195], v[102:105]
	v_mfma_f32_16x16x32_bf16 v[86:89], v[150:153], v[196:199], v[86:89]
	v_mfma_f32_16x16x32_bf16 v[86:89], v[168:171], v[200:203], v[86:89]
	v_mfma_f32_16x16x32_bf16 v[82:85], v[172:175], v[196:199], v[82:85]
	v_mfma_f32_16x16x32_bf16 v[82:85], v[176:179], v[200:203], v[82:85]
	s_setprio 2
	s_barrier
	v_mfma_f32_16x16x32_bf16 v[66:69], v[172:175], v[204:207], v[66:69]
	v_mfma_f32_16x16x32_bf16 v[66:69], v[176:179], v[208:211], v[66:69]
	v_mfma_f32_16x16x32_bf16 v[70:73], v[150:153], v[204:207], v[70:73]
	v_mfma_f32_16x16x32_bf16 v[70:73], v[168:171], v[208:211], v[70:73]
	s_setprio 0
	ds_read_b128 v[180:183], v163 offset:49152
	ds_read_b128 v[184:187], v163 offset:50176
	ds_read_b128 v[188:191], v163 offset:51200
	ds_read_b128 v[192:195], v163 offset:52224
	ds_read_b128 v[196:199], v163 offset:53248
	ds_read_b128 v[200:203], v163 offset:54272
	ds_read_b128 v[204:207], v163 offset:55296
	ds_read_b128 v[208:211], v163 offset:56320
	s_add_u32 s28, s10, 0x80
	s_addc_u32 s29, s11, 0
	s_mov_b32 s75, m0
	s_mov_b32 m0, s64
	s_nop 0
	global_load_lds_dwordx4 v156, s[28:29]
	s_mov_b32 m0, s75
	s_add_u32 s10, s10, 0x80080
	s_mov_b32 s75, m0
	s_mov_b32 m0, s65
	s_nop 0
	global_load_lds_dwordx4 v158, s[28:29]
	s_mov_b32 m0, s75
	s_addc_u32 s11, s11, 0
	s_mov_b32 s28, m0
	s_mov_b32 m0, s66
	s_nop 0
	global_load_lds_dwordx4 v156, s[10:11]
	s_mov_b32 m0, s28
	s_nop 0
	s_mov_b32 s28, m0
	s_mov_b32 m0, s67
	s_nop 0
	global_load_lds_dwordx4 v158, s[10:11]
	s_mov_b32 m0, s28
	s_waitcnt vmcnt(4)
	s_waitcnt lgkmcnt(0)
	s_barrier
	s_setprio 1
	s_waitcnt lgkmcnt(7)
	v_mfma_f32_16x16x32_bf16 v[62:65], v[130:133], v[180:183], v[62:65]
	v_mfma_f32_16x16x32_bf16 v[62:65], v[138:141], v[184:187], v[62:65]
	s_waitcnt lgkmcnt(5)
	v_mfma_f32_16x16x32_bf16 v[58:61], v[142:145], v[180:183], v[58:61]
	v_mfma_f32_16x16x32_bf16 v[58:61], v[146:149], v[184:187], v[58:61]
	s_waitcnt lgkmcnt(3)
	v_mfma_f32_16x16x32_bf16 v[42:45], v[142:145], v[188:191], v[42:45]
	v_mfma_f32_16x16x32_bf16 v[42:45], v[146:149], v[192:195], v[42:45]
	s_waitcnt lgkmcnt(1)
	v_mfma_f32_16x16x32_bf16 v[46:49], v[130:133], v[188:191], v[46:49]
	v_mfma_f32_16x16x32_bf16 v[46:49], v[138:141], v[192:195], v[46:49]
	v_mfma_f32_16x16x32_bf16 v[30:33], v[130:133], v[196:199], v[30:33]
	v_mfma_f32_16x16x32_bf16 v[30:33], v[138:141], v[200:203], v[30:33]
	v_mfma_f32_16x16x32_bf16 v[26:29], v[142:145], v[196:199], v[26:29]
	v_mfma_f32_16x16x32_bf16 v[26:29], v[146:149], v[200:203], v[26:29]
	v_mfma_f32_16x16x32_bf16 v[10:13], v[142:145], v[204:207], v[10:13]
	v_mfma_f32_16x16x32_bf16 v[10:13], v[146:149], v[208:211], v[10:13]
	s_waitcnt lgkmcnt(0)
	v_mfma_f32_16x16x32_bf16 v[14:17], v[130:133], v[204:207], v[14:17]
	v_mfma_f32_16x16x32_bf16 v[14:17], v[138:141], v[208:211], v[14:17]
	s_setprio 0
	s_setprio 1
	v_mfma_f32_16x16x32_bf16 v[54:57], v[150:153], v[180:183], v[54:57]
	v_mfma_f32_16x16x32_bf16 v[54:57], v[168:171], v[184:187], v[54:57]
	v_mfma_f32_16x16x32_bf16 v[50:53], v[172:175], v[180:183], v[50:53]
	v_mfma_f32_16x16x32_bf16 v[50:53], v[176:179], v[184:187], v[50:53]
	v_mfma_f32_16x16x32_bf16 v[34:37], v[172:175], v[188:191], v[34:37]
	v_mfma_f32_16x16x32_bf16 v[34:37], v[176:179], v[192:195], v[34:37]
	v_mfma_f32_16x16x32_bf16 v[38:41], v[150:153], v[188:191], v[38:41]
	v_mfma_f32_16x16x32_bf16 v[38:41], v[168:171], v[192:195], v[38:41]
	v_mfma_f32_16x16x32_bf16 v[22:25], v[150:153], v[196:199], v[22:25]
	v_mfma_f32_16x16x32_bf16 v[22:25], v[168:171], v[200:203], v[22:25]
	v_mfma_f32_16x16x32_bf16 v[18:21], v[172:175], v[196:199], v[18:21]
	v_mfma_f32_16x16x32_bf16 v[18:21], v[176:179], v[200:203], v[18:21]
	s_setprio 2
	s_barrier
	v_mfma_f32_16x16x32_bf16 v[2:5], v[172:175], v[204:207], v[2:5]
	v_mfma_f32_16x16x32_bf16 v[2:5], v[176:179], v[208:211], v[2:5]
	v_mfma_f32_16x16x32_bf16 v[6:9], v[150:153], v[204:207], v[6:9]
	v_mfma_f32_16x16x32_bf16 v[6:9], v[168:171], v[208:211], v[6:9]
	s_setprio 0
	s_add_i32 s74, s74, 2
	s_add_u32 s30, s30, 0x100
	s_addc_u32 s31, s31, 0
	s_add_u32 s4, s4, 0x100
	s_addc_u32 s5, s5, 0
	s_add_u32 s33, s33, 0x100
	s_addc_u32 s73, s73, 0
	s_cmp_gt_u32 s74, 29
	.p2align 6
.LBB0_654:
	ds_read_b128 v[130:133], v161
	ds_read_b128 v[138:141], v161 offset:1024
	ds_read_b128 v[142:145], v161 offset:2048
	ds_read_b128 v[146:149], v161 offset:3072
	ds_read_b128 v[150:153], v162
	ds_read_b128 v[168:171], v162 offset:1024
	ds_read_b128 v[172:175], v162 offset:2048
	ds_read_b128 v[176:179], v162 offset:3072
	s_cmp_eq_u32 s74, 28
	s_cselect_b32 s11, s21, s31
	s_cselect_b32 s10, s23, s30
	s_cselect_b32 s29, s7, s73
	s_cselect_b32 s28, s9, s33
	ds_read_b128 v[180:183], v163
	ds_read_b128 v[184:187], v163 offset:1024
	ds_read_b128 v[188:191], v163 offset:2048
	ds_read_b128 v[192:195], v163 offset:3072
	ds_read_b128 v[196:199], v163 offset:4096
	ds_read_b128 v[200:203], v163 offset:5120
	ds_read_b128 v[204:207], v163 offset:6144
	ds_read_b128 v[208:211], v163 offset:7168
	s_add_u32 s76, s4, 0xfff80000
	s_addc_u32 s77, s5, -1
	s_mov_b32 s75, m0
	s_mov_b32 m0, s80
	s_nop 0
	global_load_lds_dwordx4 v1, s[76:77]
	s_mov_b32 m0, s75
	s_nop 0
	s_mov_b32 s75, m0
	s_mov_b32 m0, s82
	s_nop 0
	global_load_lds_dwordx4 v157, s[76:77]
	s_mov_b32 m0, s75
	s_nop 0
	s_mov_b32 s75, m0
	s_mov_b32 m0, s81
	s_nop 0
	global_load_lds_dwordx4 v1, s[4:5]
	s_mov_b32 m0, s75
	s_nop 0
	s_mov_b32 s75, m0
	s_mov_b32 m0, s83
	s_nop 0
	global_load_lds_dwordx4 v157, s[4:5]
	s_mov_b32 m0, s75
	s_waitcnt vmcnt(8)
	s_waitcnt lgkmcnt(0)
	s_barrier
	s_setprio 1
	s_waitcnt lgkmcnt(7)
	v_mfma_f32_16x16x32_bf16 v[126:129], v[130:133], v[180:183], v[126:129]
	v_mfma_f32_16x16x32_bf16 v[126:129], v[138:141], v[184:187], v[126:129]
	s_waitcnt lgkmcnt(5)
	v_mfma_f32_16x16x32_bf16 v[122:125], v[142:145], v[180:183], v[122:125]
	v_mfma_f32_16x16x32_bf16 v[122:125], v[146:149], v[184:187], v[122:125]
	s_waitcnt lgkmcnt(3)
	v_mfma_f32_16x16x32_bf16 v[106:109], v[142:145], v[188:191], v[106:109]
	v_mfma_f32_16x16x32_bf16 v[106:109], v[146:149], v[192:195], v[106:109]
	s_waitcnt lgkmcnt(1)
	v_mfma_f32_16x16x32_bf16 v[110:113], v[130:133], v[188:191], v[110:113]
	v_mfma_f32_16x16x32_bf16 v[110:113], v[138:141], v[192:195], v[110:113]
	v_mfma_f32_16x16x32_bf16 v[94:97], v[130:133], v[196:199], v[94:97]
	v_mfma_f32_16x16x32_bf16 v[94:97], v[138:141], v[200:203], v[94:97]
	v_mfma_f32_16x16x32_bf16 v[90:93], v[142:145], v[196:199], v[90:93]
	v_mfma_f32_16x16x32_bf16 v[90:93], v[146:149], v[200:203], v[90:93]
	v_mfma_f32_16x16x32_bf16 v[74:77], v[142:145], v[204:207], v[74:77]
	v_mfma_f32_16x16x32_bf16 v[74:77], v[146:149], v[208:211], v[74:77]
	s_waitcnt lgkmcnt(0)
	v_mfma_f32_16x16x32_bf16 v[78:81], v[130:133], v[204:207], v[78:81]
	v_mfma_f32_16x16x32_bf16 v[78:81], v[138:141], v[208:211], v[78:81]
	s_setprio 0
	s_setprio 1
	v_mfma_f32_16x16x32_bf16 v[118:121], v[150:153], v[180:183], v[118:121]
	v_mfma_f32_16x16x32_bf16 v[118:121], v[168:171], v[184:187], v[118:121]
	v_mfma_f32_16x16x32_bf16 v[114:117], v[172:175], v[180:183], v[114:117]
	v_mfma_f32_16x16x32_bf16 v[114:117], v[176:179], v[184:187], v[114:117]
	v_mfma_f32_16x16x32_bf16 v[98:101], v[172:175], v[188:191], v[98:101]
	v_mfma_f32_16x16x32_bf16 v[98:101], v[176:179], v[192:195], v[98:101]
	v_mfma_f32_16x16x32_bf16 v[102:105], v[150:153], v[188:191], v[102:105]
	v_mfma_f32_16x16x32_bf16 v[102:105], v[168:171], v[192:195], v[102:105]
	v_mfma_f32_16x16x32_bf16 v[86:89], v[150:153], v[196:199], v[86:89]
	v_mfma_f32_16x16x32_bf16 v[86:89], v[168:171], v[200:203], v[86:89]
	v_mfma_f32_16x16x32_bf16 v[82:85], v[172:175], v[196:199], v[82:85]
	v_mfma_f32_16x16x32_bf16 v[82:85], v[176:179], v[200:203], v[82:85]
	s_setprio 2
	s_barrier
	v_mfma_f32_16x16x32_bf16 v[66:69], v[172:175], v[204:207], v[66:69]
	v_mfma_f32_16x16x32_bf16 v[66:69], v[176:179], v[208:211], v[66:69]
	v_mfma_f32_16x16x32_bf16 v[70:73], v[150:153], v[204:207], v[70:73]
	v_mfma_f32_16x16x32_bf16 v[70:73], v[168:171], v[208:211], v[70:73]
	s_setprio 0
	ds_read_b128 v[180:183], v163 offset:16384
	ds_read_b128 v[184:187], v163 offset:17408
	ds_read_b128 v[188:191], v163 offset:18432
	ds_read_b128 v[192:195], v163 offset:19456
	ds_read_b128 v[196:199], v163 offset:20480
	ds_read_b128 v[200:203], v163 offset:21504
	ds_read_b128 v[204:207], v163 offset:22528
	ds_read_b128 v[208:211], v163 offset:23552
	s_mov_b32 s75, m0
	s_mov_b32 m0, s43
	s_nop 0
	global_load_lds_dwordx4 v156, s[10:11]
	s_mov_b32 m0, s75
	s_add_u32 s76, s10, 0x80000
	s_mov_b32 s75, m0
	s_mov_b32 m0, s46
	s_nop 0
	global_load_lds_dwordx4 v158, s[10:11]
	s_mov_b32 m0, s75
	s_addc_u32 s77, s11, 0
	s_mov_b32 s75, m0
	s_mov_b32 m0, s47
	s_nop 0
	global_load_lds_dwordx4 v156, s[76:77]
	s_mov_b32 m0, s75
	s_nop 0
	s_mov_b32 s75, m0
	s_mov_b32 m0, s48
	s_nop 0
	global_load_lds_dwordx4 v158, s[76:77]
	s_mov_b32 m0, s75
	s_waitcnt vmcnt(4)
	s_waitcnt lgkmcnt(0)
	s_barrier
	s_setprio 1
	s_waitcnt lgkmcnt(7)
	v_mfma_f32_16x16x32_bf16 v[62:65], v[130:133], v[180:183], v[62:65]
	v_mfma_f32_16x16x32_bf16 v[62:65], v[138:141], v[184:187], v[62:65]
	s_waitcnt lgkmcnt(5)
	v_mfma_f32_16x16x32_bf16 v[58:61], v[142:145], v[180:183], v[58:61]
	v_mfma_f32_16x16x32_bf16 v[58:61], v[146:149], v[184:187], v[58:61]
	s_waitcnt lgkmcnt(3)
	v_mfma_f32_16x16x32_bf16 v[42:45], v[142:145], v[188:191], v[42:45]
	v_mfma_f32_16x16x32_bf16 v[42:45], v[146:149], v[192:195], v[42:45]
	s_waitcnt lgkmcnt(1)
	v_mfma_f32_16x16x32_bf16 v[46:49], v[130:133], v[188:191], v[46:49]
	v_mfma_f32_16x16x32_bf16 v[46:49], v[138:141], v[192:195], v[46:49]
	v_mfma_f32_16x16x32_bf16 v[30:33], v[130:133], v[196:199], v[30:33]
	v_mfma_f32_16x16x32_bf16 v[30:33], v[138:141], v[200:203], v[30:33]
	v_mfma_f32_16x16x32_bf16 v[26:29], v[142:145], v[196:199], v[26:29]
	v_mfma_f32_16x16x32_bf16 v[26:29], v[146:149], v[200:203], v[26:29]
	v_mfma_f32_16x16x32_bf16 v[10:13], v[142:145], v[204:207], v[10:13]
	v_mfma_f32_16x16x32_bf16 v[10:13], v[146:149], v[208:211], v[10:13]
	s_waitcnt lgkmcnt(0)
	v_mfma_f32_16x16x32_bf16 v[14:17], v[130:133], v[204:207], v[14:17]
	v_mfma_f32_16x16x32_bf16 v[14:17], v[138:141], v[208:211], v[14:17]
	s_setprio 0
	s_setprio 1
	v_mfma_f32_16x16x32_bf16 v[54:57], v[150:153], v[180:183], v[54:57]
	v_mfma_f32_16x16x32_bf16 v[54:57], v[168:171], v[184:187], v[54:57]
	v_mfma_f32_16x16x32_bf16 v[50:53], v[172:175], v[180:183], v[50:53]
	v_mfma_f32_16x16x32_bf16 v[50:53], v[176:179], v[184:187], v[50:53]
	v_mfma_f32_16x16x32_bf16 v[34:37], v[172:175], v[188:191], v[34:37]
	v_mfma_f32_16x16x32_bf16 v[34:37], v[176:179], v[192:195], v[34:37]
	v_mfma_f32_16x16x32_bf16 v[38:41], v[150:153], v[188:191], v[38:41]
	v_mfma_f32_16x16x32_bf16 v[38:41], v[168:171], v[192:195], v[38:41]
	v_mfma_f32_16x16x32_bf16 v[22:25], v[150:153], v[196:199], v[22:25]
	v_mfma_f32_16x16x32_bf16 v[22:25], v[168:171], v[200:203], v[22:25]
	v_mfma_f32_16x16x32_bf16 v[18:21], v[172:175], v[196:199], v[18:21]
	v_mfma_f32_16x16x32_bf16 v[18:21], v[176:179], v[200:203], v[18:21]
	s_setprio 2
	s_barrier
	v_mfma_f32_16x16x32_bf16 v[2:5], v[172:175], v[204:207], v[2:5]
	v_mfma_f32_16x16x32_bf16 v[2:5], v[176:179], v[208:211], v[2:5]
	v_mfma_f32_16x16x32_bf16 v[6:9], v[150:153], v[204:207], v[6:9]
	v_mfma_f32_16x16x32_bf16 v[6:9], v[168:171], v[208:211], v[6:9]
	s_setprio 0
	ds_read_b128 v[130:133], v164
	ds_read_b128 v[138:141], v164 offset:1024
	ds_read_b128 v[142:145], v164 offset:2048
	ds_read_b128 v[146:149], v164 offset:3072
	ds_read_b128 v[150:153], v165
	ds_read_b128 v[168:171], v165 offset:1024
	ds_read_b128 v[172:175], v165 offset:2048
	ds_read_b128 v[176:179], v165 offset:3072
	ds_read_b128 v[180:183], v163 offset:32768
	ds_read_b128 v[184:187], v163 offset:33792
	ds_read_b128 v[188:191], v163 offset:34816
	ds_read_b128 v[192:195], v163 offset:35840
	ds_read_b128 v[196:199], v163 offset:36864
	ds_read_b128 v[200:203], v163 offset:37888
	ds_read_b128 v[204:207], v163 offset:38912
	ds_read_b128 v[208:211], v163 offset:39936
	s_mov_b32 s75, m0
	s_mov_b32 m0, s42
	s_nop 0
	global_load_lds_dwordx4 v1, s[28:29]
	s_mov_b32 m0, s75
	s_nop 0
	s_mov_b32 s75, m0
	s_mov_b32 m0, s49
	s_nop 0
	global_load_lds_dwordx4 v157, s[28:29]
	s_mov_b32 m0, s75
	s_add_u32 s28, s28, 0x80000
	s_addc_u32 s29, s29, 0
	s_mov_b32 s75, m0
	s_mov_b32 m0, s56
	s_nop 0
	global_load_lds_dwordx4 v1, s[28:29]
	s_mov_b32 m0, s75
	s_nop 0
	s_mov_b32 s75, m0
	s_mov_b32 m0, s57
	s_nop 0
	global_load_lds_dwordx4 v157, s[28:29]
	s_mov_b32 m0, s75
	s_waitcnt vmcnt(8)
	s_waitcnt lgkmcnt(0)
	s_barrier
	s_setprio 1
	s_waitcnt lgkmcnt(7)
	v_mfma_f32_16x16x32_bf16 v[126:129], v[130:133], v[180:183], v[126:129]
	v_mfma_f32_16x16x32_bf16 v[126:129], v[138:141], v[184:187], v[126:129]
	s_waitcnt lgkmcnt(5)
	v_mfma_f32_16x16x32_bf16 v[122:125], v[142:145], v[180:183], v[122:125]
	v_mfma_f32_16x16x32_bf16 v[122:125], v[146:149], v[184:187], v[122:125]
	s_waitcnt lgkmcnt(3)
	v_mfma_f32_16x16x32_bf16 v[106:109], v[142:145], v[188:191], v[106:109]
	v_mfma_f32_16x16x32_bf16 v[106:109], v[146:149], v[192:195], v[106:109]
	s_waitcnt lgkmcnt(1)
	v_mfma_f32_16x16x32_bf16 v[110:113], v[130:133], v[188:191], v[110:113]
	v_mfma_f32_16x16x32_bf16 v[110:113], v[138:141], v[192:195], v[110:113]
	v_mfma_f32_16x16x32_bf16 v[94:97], v[130:133], v[196:199], v[94:97]
	v_mfma_f32_16x16x32_bf16 v[94:97], v[138:141], v[200:203], v[94:97]
	v_mfma_f32_16x16x32_bf16 v[90:93], v[142:145], v[196:199], v[90:93]
	v_mfma_f32_16x16x32_bf16 v[90:93], v[146:149], v[200:203], v[90:93]
	v_mfma_f32_16x16x32_bf16 v[74:77], v[142:145], v[204:207], v[74:77]
	v_mfma_f32_16x16x32_bf16 v[74:77], v[146:149], v[208:211], v[74:77]
	s_waitcnt lgkmcnt(0)
	v_mfma_f32_16x16x32_bf16 v[78:81], v[130:133], v[204:207], v[78:81]
	v_mfma_f32_16x16x32_bf16 v[78:81], v[138:141], v[208:211], v[78:81]
	s_setprio 0
	s_setprio 1
	v_mfma_f32_16x16x32_bf16 v[118:121], v[150:153], v[180:183], v[118:121]
	v_mfma_f32_16x16x32_bf16 v[118:121], v[168:171], v[184:187], v[118:121]
	v_mfma_f32_16x16x32_bf16 v[114:117], v[172:175], v[180:183], v[114:117]
	v_mfma_f32_16x16x32_bf16 v[114:117], v[176:179], v[184:187], v[114:117]
	v_mfma_f32_16x16x32_bf16 v[98:101], v[172:175], v[188:191], v[98:101]
	v_mfma_f32_16x16x32_bf16 v[98:101], v[176:179], v[192:195], v[98:101]
	v_mfma_f32_16x16x32_bf16 v[102:105], v[150:153], v[188:191], v[102:105]
	v_mfma_f32_16x16x32_bf16 v[102:105], v[168:171], v[192:195], v[102:105]
	v_mfma_f32_16x16x32_bf16 v[86:89], v[150:153], v[196:199], v[86:89]
	v_mfma_f32_16x16x32_bf16 v[86:89], v[168:171], v[200:203], v[86:89]
	v_mfma_f32_16x16x32_bf16 v[82:85], v[172:175], v[196:199], v[82:85]
	v_mfma_f32_16x16x32_bf16 v[82:85], v[176:179], v[200:203], v[82:85]
	s_setprio 2
	s_barrier
	v_mfma_f32_16x16x32_bf16 v[66:69], v[172:175], v[204:207], v[66:69]
	v_mfma_f32_16x16x32_bf16 v[66:69], v[176:179], v[208:211], v[66:69]
	v_mfma_f32_16x16x32_bf16 v[70:73], v[150:153], v[204:207], v[70:73]
	v_mfma_f32_16x16x32_bf16 v[70:73], v[168:171], v[208:211], v[70:73]
	s_setprio 0
	ds_read_b128 v[180:183], v163 offset:49152
	ds_read_b128 v[184:187], v163 offset:50176
	ds_read_b128 v[188:191], v163 offset:51200
	ds_read_b128 v[192:195], v163 offset:52224
	ds_read_b128 v[196:199], v163 offset:53248
	ds_read_b128 v[200:203], v163 offset:54272
	ds_read_b128 v[204:207], v163 offset:55296
	ds_read_b128 v[208:211], v163 offset:56320
	s_add_u32 s28, s10, 0x80
	s_addc_u32 s29, s11, 0
	s_mov_b32 s75, m0
	s_mov_b32 m0, s64
	s_nop 0
	global_load_lds_dwordx4 v156, s[28:29]
	s_mov_b32 m0, s75
	s_add_u32 s10, s10, 0x80080
	s_mov_b32 s75, m0
	s_mov_b32 m0, s65
	s_nop 0
	global_load_lds_dwordx4 v158, s[28:29]
	s_mov_b32 m0, s75
	s_addc_u32 s11, s11, 0
	s_mov_b32 s28, m0
	s_mov_b32 m0, s66
	s_nop 0
	global_load_lds_dwordx4 v156, s[10:11]
	s_mov_b32 m0, s28
	s_nop 0
	s_mov_b32 s28, m0
	s_mov_b32 m0, s67
	s_nop 0
	global_load_lds_dwordx4 v158, s[10:11]
	s_mov_b32 m0, s28
	s_waitcnt vmcnt(4)
	s_waitcnt lgkmcnt(0)
	s_barrier
	s_setprio 1
	s_waitcnt lgkmcnt(7)
	v_mfma_f32_16x16x32_bf16 v[62:65], v[130:133], v[180:183], v[62:65]
	v_mfma_f32_16x16x32_bf16 v[62:65], v[138:141], v[184:187], v[62:65]
	s_waitcnt lgkmcnt(5)
	v_mfma_f32_16x16x32_bf16 v[58:61], v[142:145], v[180:183], v[58:61]
	v_mfma_f32_16x16x32_bf16 v[58:61], v[146:149], v[184:187], v[58:61]
	s_waitcnt lgkmcnt(3)
	v_mfma_f32_16x16x32_bf16 v[42:45], v[142:145], v[188:191], v[42:45]
	v_mfma_f32_16x16x32_bf16 v[42:45], v[146:149], v[192:195], v[42:45]
	s_waitcnt lgkmcnt(1)
	v_mfma_f32_16x16x32_bf16 v[46:49], v[130:133], v[188:191], v[46:49]
	v_mfma_f32_16x16x32_bf16 v[46:49], v[138:141], v[192:195], v[46:49]
	v_mfma_f32_16x16x32_bf16 v[30:33], v[130:133], v[196:199], v[30:33]
	v_mfma_f32_16x16x32_bf16 v[30:33], v[138:141], v[200:203], v[30:33]
	v_mfma_f32_16x16x32_bf16 v[26:29], v[142:145], v[196:199], v[26:29]
	v_mfma_f32_16x16x32_bf16 v[26:29], v[146:149], v[200:203], v[26:29]
	v_mfma_f32_16x16x32_bf16 v[10:13], v[142:145], v[204:207], v[10:13]
	v_mfma_f32_16x16x32_bf16 v[10:13], v[146:149], v[208:211], v[10:13]
	s_waitcnt lgkmcnt(0)
	v_mfma_f32_16x16x32_bf16 v[14:17], v[130:133], v[204:207], v[14:17]
	v_mfma_f32_16x16x32_bf16 v[14:17], v[138:141], v[208:211], v[14:17]
	s_setprio 0
	s_setprio 1
	v_mfma_f32_16x16x32_bf16 v[54:57], v[150:153], v[180:183], v[54:57]
	v_mfma_f32_16x16x32_bf16 v[54:57], v[168:171], v[184:187], v[54:57]
	v_mfma_f32_16x16x32_bf16 v[50:53], v[172:175], v[180:183], v[50:53]
	v_mfma_f32_16x16x32_bf16 v[50:53], v[176:179], v[184:187], v[50:53]
	v_mfma_f32_16x16x32_bf16 v[34:37], v[172:175], v[188:191], v[34:37]
	v_mfma_f32_16x16x32_bf16 v[34:37], v[176:179], v[192:195], v[34:37]
	v_mfma_f32_16x16x32_bf16 v[38:41], v[150:153], v[188:191], v[38:41]
	v_mfma_f32_16x16x32_bf16 v[38:41], v[168:171], v[192:195], v[38:41]
	v_mfma_f32_16x16x32_bf16 v[22:25], v[150:153], v[196:199], v[22:25]
	v_mfma_f32_16x16x32_bf16 v[22:25], v[168:171], v[200:203], v[22:25]
	v_mfma_f32_16x16x32_bf16 v[18:21], v[172:175], v[196:199], v[18:21]
	v_mfma_f32_16x16x32_bf16 v[18:21], v[176:179], v[200:203], v[18:21]
	s_setprio 2
	s_barrier
	v_mfma_f32_16x16x32_bf16 v[2:5], v[172:175], v[204:207], v[2:5]
	v_mfma_f32_16x16x32_bf16 v[2:5], v[176:179], v[208:211], v[2:5]
	v_mfma_f32_16x16x32_bf16 v[6:9], v[150:153], v[204:207], v[6:9]
	v_mfma_f32_16x16x32_bf16 v[6:9], v[168:171], v[208:211], v[6:9]
	s_setprio 0
	s_add_i32 s74, s74, 2
	s_add_u32 s30, s30, 0x100
	s_addc_u32 s31, s31, 0
	s_add_u32 s4, s4, 0x100
	s_addc_u32 s5, s5, 0
	s_add_u32 s33, s33, 0x100
	s_addc_u32 s73, s73, 0
	s_cmp_gt_u32 s74, 29
	s_cbranch_scc0 .LBB0_654
	s_and_b64 vcc, exec, s[18:19]
	s_cbranch_vccz .LBB0_657
	s_barrier

.LBB0_1052:
	s_ashr_i32 s13, s12, 31
	s_lshl_b64 s[14:15], s[12:13], 20
	s_add_u32 s14, s28, s14
	s_addc_u32 s15, s29, s15
	s_and_b64 s[16:17], s[2:3], exec
	s_cselect_b32 s13, s15, s23
	s_cselect_b32 s67, s14, s22
	s_ashr_i32 s11, s10, 31
	s_lshl_b64 s[16:17], s[10:11], 20
	s_add_u32 s16, s30, s16
	s_addc_u32 s17, s31, s17
	s_and_b64 s[24:25], s[2:3], exec
	s_cselect_b32 s11, s17, s21
	s_cselect_b32 s73, s16, s20
	s_add_u32 s74, s20, 0x100
	s_addc_u32 s75, s21, 0
	s_add_u32 s20, s22, 0x80080
	s_addc_u32 s21, s23, 0
	s_add_u32 s76, s22, 0x100
	s_addc_u32 s77, s23, 0
	s_mov_b32 s78, -2
	s_waitcnt vmcnt(25)
	s_waitcnt vmcnt(24)
	s_waitcnt vmcnt(15)
	s_waitcnt vmcnt(14)
	s_waitcnt vmcnt(13)
	s_waitcnt vmcnt(12)
	s_waitcnt vmcnt(11)
	s_waitcnt vmcnt(10)
	s_waitcnt vmcnt(9)
	s_waitcnt vmcnt(8)
	s_waitcnt vmcnt(7)
	s_waitcnt vmcnt(6)
	s_waitcnt vmcnt(5)
	s_waitcnt vmcnt(4)
	s_waitcnt vmcnt(3)
	s_waitcnt vmcnt(2)
	s_waitcnt vmcnt(1)
	s_waitcnt vmcnt(0)
	ds_read_b128 v[130:133], v181
	ds_read_b128 v[134:137], v181 offset:1024
	ds_read_b128 v[138:141], v181 offset:2048
	ds_read_b128 v[142:145], v181 offset:3072
	ds_read_b128 v[146:149], v182
	ds_read_b128 v[150:153], v182 offset:1024
	ds_read_b128 v[154:157], v182 offset:2048
	ds_read_b128 v[158:161], v182 offset:3072
	s_cmp_eq_u32 s78, 28
	s_cselect_b32 s23, s11, s75
	s_cselect_b32 s22, s73, s74
	s_cselect_b32 s25, s13, s77
	s_cselect_b32 s24, s67, s76
	ds_read_b128 v[166:169], v183
	ds_read_b128 v[170:173], v183 offset:1024
	ds_read_b128 v[186:189], v183 offset:2048
	ds_read_b128 v[190:193], v183 offset:3072
	ds_read_b128 v[194:197], v183 offset:4096
	ds_read_b128 v[198:201], v183 offset:5120
	ds_read_b128 v[202:205], v183 offset:6144
	ds_read_b128 v[206:209], v183 offset:7168
	s_add_u32 s80, s20, 0xfff80000
	s_addc_u32 s81, s21, -1
	s_mov_b32 s79, m0
	s_mov_b32 m0, s58
	s_nop 0
	global_load_lds_dwordx4 v1, s[80:81]
	s_mov_b32 m0, s79
	s_nop 0
	s_mov_b32 s79, m0
	s_mov_b32 m0, s64
	s_nop 0
	global_load_lds_dwordx4 v177, s[80:81]
	s_mov_b32 m0, s79
	s_nop 0
	s_mov_b32 s79, m0
	s_mov_b32 m0, s59
	s_nop 0
	global_load_lds_dwordx4 v1, s[20:21]
	s_mov_b32 m0, s79
	s_nop 0
	s_mov_b32 s79, m0
	s_mov_b32 m0, s65
	s_nop 0
	global_load_lds_dwordx4 v177, s[20:21]
	s_mov_b32 m0, s79
	s_waitcnt vmcnt(8)
	s_waitcnt lgkmcnt(0)
	s_barrier
	s_setprio 1
	s_waitcnt lgkmcnt(7)
	v_mfma_f32_16x16x32_bf16 v[126:129], v[130:133], v[166:169], 0
	v_mfma_f32_16x16x32_bf16 v[126:129], v[134:137], v[170:173], v[126:129]
	s_waitcnt lgkmcnt(5)
	v_mfma_f32_16x16x32_bf16 v[122:125], v[138:141], v[166:169], 0
	v_mfma_f32_16x16x32_bf16 v[122:125], v[142:145], v[170:173], v[122:125]
	s_waitcnt lgkmcnt(3)
	v_mfma_f32_16x16x32_bf16 v[114:117], v[138:141], v[186:189], 0
	v_mfma_f32_16x16x32_bf16 v[114:117], v[142:145], v[190:193], v[114:117]
	s_waitcnt lgkmcnt(1)
	v_mfma_f32_16x16x32_bf16 v[118:121], v[130:133], v[186:189], 0
	v_mfma_f32_16x16x32_bf16 v[118:121], v[134:137], v[190:193], v[118:121]
	v_mfma_f32_16x16x32_bf16 v[94:97], v[130:133], v[194:197], 0
	v_mfma_f32_16x16x32_bf16 v[94:97], v[134:137], v[198:201], v[94:97]
	v_mfma_f32_16x16x32_bf16 v[90:93], v[138:141], v[194:197], 0
	v_mfma_f32_16x16x32_bf16 v[90:93], v[142:145], v[198:201], v[90:93]
	v_mfma_f32_16x16x32_bf16 v[78:81], v[138:141], v[202:205], 0
	v_mfma_f32_16x16x32_bf16 v[78:81], v[142:145], v[206:209], v[78:81]
	s_waitcnt lgkmcnt(0)
	v_mfma_f32_16x16x32_bf16 v[86:89], v[130:133], v[202:205], 0
	v_mfma_f32_16x16x32_bf16 v[86:89], v[134:137], v[206:209], v[86:89]
	s_setprio 0
	s_setprio 1
	v_mfma_f32_16x16x32_bf16 v[110:113], v[146:149], v[166:169], 0
	v_mfma_f32_16x16x32_bf16 v[110:113], v[150:153], v[170:173], v[110:113]
	v_mfma_f32_16x16x32_bf16 v[106:109], v[154:157], v[166:169], 0
	v_mfma_f32_16x16x32_bf16 v[106:109], v[158:161], v[170:173], v[106:109]
	v_mfma_f32_16x16x32_bf16 v[98:101], v[154:157], v[186:189], 0
	v_mfma_f32_16x16x32_bf16 v[98:101], v[158:161], v[190:193], v[98:101]
	v_mfma_f32_16x16x32_bf16 v[102:105], v[146:149], v[186:189], 0
	v_mfma_f32_16x16x32_bf16 v[102:105], v[150:153], v[190:193], v[102:105]
	v_mfma_f32_16x16x32_bf16 v[82:85], v[146:149], v[194:197], 0
	v_mfma_f32_16x16x32_bf16 v[82:85], v[150:153], v[198:201], v[82:85]
	v_mfma_f32_16x16x32_bf16 v[74:77], v[154:157], v[194:197], 0
	v_mfma_f32_16x16x32_bf16 v[74:77], v[158:161], v[198:201], v[74:77]
	s_setprio 2
	s_barrier
	v_mfma_f32_16x16x32_bf16 v[66:69], v[154:157], v[202:205], 0
	v_mfma_f32_16x16x32_bf16 v[66:69], v[158:161], v[206:209], v[66:69]
	v_mfma_f32_16x16x32_bf16 v[70:73], v[146:149], v[202:205], 0
	v_mfma_f32_16x16x32_bf16 v[70:73], v[150:153], v[206:209], v[70:73]
	s_setprio 0
	ds_read_b128 v[166:169], v183 offset:16384
	ds_read_b128 v[170:173], v183 offset:17408
	ds_read_b128 v[186:189], v183 offset:18432
	ds_read_b128 v[190:193], v183 offset:19456
	ds_read_b128 v[194:197], v183 offset:20480
	ds_read_b128 v[198:201], v183 offset:21504
	ds_read_b128 v[202:205], v183 offset:22528
	ds_read_b128 v[206:209], v183 offset:23552
	s_mov_b32 s79, m0
	s_mov_b32 m0, s35
	s_nop 0
	global_load_lds_dwordx4 v176, s[22:23]
	s_mov_b32 m0, s79
	s_add_u32 s80, s22, 0x80000
	s_mov_b32 s79, m0
	s_mov_b32 m0, s36
	s_nop 0
	global_load_lds_dwordx4 v178, s[22:23]
	s_mov_b32 m0, s79
	s_addc_u32 s81, s23, 0
	s_mov_b32 s79, m0
	s_mov_b32 m0, s37
	s_nop 0
	global_load_lds_dwordx4 v176, s[80:81]
	s_mov_b32 m0, s79
	s_nop 0
	s_mov_b32 s79, m0
	s_mov_b32 m0, s40
	s_nop 0
	global_load_lds_dwordx4 v178, s[80:81]
	s_mov_b32 m0, s79
	s_waitcnt vmcnt(4)
	s_waitcnt lgkmcnt(0)
	s_barrier
	s_setprio 1
	s_waitcnt lgkmcnt(7)
	v_mfma_f32_16x16x32_bf16 v[62:65], v[130:133], v[166:169], 0
	v_mfma_f32_16x16x32_bf16 v[62:65], v[134:137], v[170:173], v[62:65]
	s_waitcnt lgkmcnt(5)
	v_mfma_f32_16x16x32_bf16 v[58:61], v[138:141], v[166:169], 0
	v_mfma_f32_16x16x32_bf16 v[58:61], v[142:145], v[170:173], v[58:61]
	s_waitcnt lgkmcnt(3)
	v_mfma_f32_16x16x32_bf16 v[42:45], v[138:141], v[186:189], 0
	v_mfma_f32_16x16x32_bf16 v[42:45], v[142:145], v[190:193], v[42:45]
	s_waitcnt lgkmcnt(1)
	v_mfma_f32_16x16x32_bf16 v[46:49], v[130:133], v[186:189], 0
	v_mfma_f32_16x16x32_bf16 v[46:49], v[134:137], v[190:193], v[46:49]
	v_mfma_f32_16x16x32_bf16 v[30:33], v[130:133], v[194:197], 0
	v_mfma_f32_16x16x32_bf16 v[30:33], v[134:137], v[198:201], v[30:33]
	v_mfma_f32_16x16x32_bf16 v[26:29], v[138:141], v[194:197], 0
	v_mfma_f32_16x16x32_bf16 v[26:29], v[142:145], v[198:201], v[26:29]
	v_mfma_f32_16x16x32_bf16 v[10:13], v[138:141], v[202:205], 0
	v_mfma_f32_16x16x32_bf16 v[10:13], v[142:145], v[206:209], v[10:13]
	s_waitcnt lgkmcnt(0)
	v_mfma_f32_16x16x32_bf16 v[14:17], v[130:133], v[202:205], 0
	v_mfma_f32_16x16x32_bf16 v[14:17], v[134:137], v[206:209], v[14:17]
	s_setprio 0
	s_setprio 1
	v_mfma_f32_16x16x32_bf16 v[54:57], v[146:149], v[166:169], 0
	v_mfma_f32_16x16x32_bf16 v[54:57], v[150:153], v[170:173], v[54:57]
	v_mfma_f32_16x16x32_bf16 v[50:53], v[154:157], v[166:169], 0
	v_mfma_f32_16x16x32_bf16 v[50:53], v[158:161], v[170:173], v[50:53]
	v_mfma_f32_16x16x32_bf16 v[34:37], v[154:157], v[186:189], 0
	v_mfma_f32_16x16x32_bf16 v[34:37], v[158:161], v[190:193], v[34:37]
	v_mfma_f32_16x16x32_bf16 v[38:41], v[146:149], v[186:189], 0
	v_mfma_f32_16x16x32_bf16 v[38:41], v[150:153], v[190:193], v[38:41]
	v_mfma_f32_16x16x32_bf16 v[22:25], v[146:149], v[194:197], 0
	v_mfma_f32_16x16x32_bf16 v[22:25], v[150:153], v[198:201], v[22:25]
	v_mfma_f32_16x16x32_bf16 v[18:21], v[154:157], v[194:197], 0
	v_mfma_f32_16x16x32_bf16 v[18:21], v[158:161], v[198:201], v[18:21]
	s_setprio 2
	s_barrier
	v_mfma_f32_16x16x32_bf16 v[2:5], v[154:157], v[202:205], 0
	v_mfma_f32_16x16x32_bf16 v[2:5], v[158:161], v[206:209], v[2:5]
	v_mfma_f32_16x16x32_bf16 v[6:9], v[146:149], v[202:205], 0
	v_mfma_f32_16x16x32_bf16 v[6:9], v[150:153], v[206:209], v[6:9]
	s_setprio 0
	ds_read_b128 v[130:133], v184
	ds_read_b128 v[134:137], v184 offset:1024
	ds_read_b128 v[138:141], v184 offset:2048
	ds_read_b128 v[142:145], v184 offset:3072
	ds_read_b128 v[146:149], v185
	ds_read_b128 v[150:153], v185 offset:1024
	ds_read_b128 v[154:157], v185 offset:2048
	ds_read_b128 v[158:161], v185 offset:3072
	ds_read_b128 v[166:169], v183 offset:32768
	ds_read_b128 v[170:173], v183 offset:33792
	ds_read_b128 v[186:189], v183 offset:34816
	ds_read_b128 v[190:193], v183 offset:35840
	ds_read_b128 v[194:197], v183 offset:36864
	ds_read_b128 v[198:201], v183 offset:37888
	ds_read_b128 v[202:205], v183 offset:38912
	ds_read_b128 v[206:209], v183 offset:39936
	s_mov_b32 s79, m0
	s_mov_b32 m0, s34
	s_nop 0
	global_load_lds_dwordx4 v1, s[24:25]
	s_mov_b32 m0, s79
	s_nop 0
	s_mov_b32 s79, m0
	s_mov_b32 m0, s41
	s_nop 0
	global_load_lds_dwordx4 v177, s[24:25]
	s_mov_b32 m0, s79
	s_add_u32 s24, s24, 0x80000
	s_addc_u32 s25, s25, 0
	s_mov_b32 s79, m0
	s_mov_b32 m0, s42
	s_nop 0
	global_load_lds_dwordx4 v1, s[24:25]
	s_mov_b32 m0, s79
	s_nop 0
	s_mov_b32 s79, m0
	s_mov_b32 m0, s43
	s_nop 0
	global_load_lds_dwordx4 v177, s[24:25]
	s_mov_b32 m0, s79
	s_waitcnt vmcnt(8)
	s_waitcnt lgkmcnt(0)
	s_barrier
	s_setprio 1
	s_waitcnt lgkmcnt(7)
	v_mfma_f32_16x16x32_bf16 v[126:129], v[130:133], v[166:169], v[126:129]
	v_mfma_f32_16x16x32_bf16 v[126:129], v[134:137], v[170:173], v[126:129]
	s_waitcnt lgkmcnt(5)
	v_mfma_f32_16x16x32_bf16 v[122:125], v[138:141], v[166:169], v[122:125]
	v_mfma_f32_16x16x32_bf16 v[122:125], v[142:145], v[170:173], v[122:125]
	s_waitcnt lgkmcnt(3)
	v_mfma_f32_16x16x32_bf16 v[114:117], v[138:141], v[186:189], v[114:117]
	v_mfma_f32_16x16x32_bf16 v[114:117], v[142:145], v[190:193], v[114:117]
	s_waitcnt lgkmcnt(1)
	v_mfma_f32_16x16x32_bf16 v[118:121], v[130:133], v[186:189], v[118:121]
	v_mfma_f32_16x16x32_bf16 v[118:121], v[134:137], v[190:193], v[118:121]
	v_mfma_f32_16x16x32_bf16 v[94:97], v[130:133], v[194:197], v[94:97]
	v_mfma_f32_16x16x32_bf16 v[94:97], v[134:137], v[198:201], v[94:97]
	v_mfma_f32_16x16x32_bf16 v[90:93], v[138:141], v[194:197], v[90:93]
	v_mfma_f32_16x16x32_bf16 v[90:93], v[142:145], v[198:201], v[90:93]
	v_mfma_f32_16x16x32_bf16 v[78:81], v[138:141], v[202:205], v[78:81]
	v_mfma_f32_16x16x32_bf16 v[78:81], v[142:145], v[206:209], v[78:81]
	s_waitcnt lgkmcnt(0)
	v_mfma_f32_16x16x32_bf16 v[86:89], v[130:133], v[202:205], v[86:89]
	v_mfma_f32_16x16x32_bf16 v[86:89], v[134:137], v[206:209], v[86:89]
	s_setprio 0
	s_setprio 1
	v_mfma_f32_16x16x32_bf16 v[110:113], v[146:149], v[166:169], v[110:113]
	v_mfma_f32_16x16x32_bf16 v[110:113], v[150:153], v[170:173], v[110:113]
	v_mfma_f32_16x16x32_bf16 v[106:109], v[154:157], v[166:169], v[106:109]
	v_mfma_f32_16x16x32_bf16 v[106:109], v[158:161], v[170:173], v[106:109]
	v_mfma_f32_16x16x32_bf16 v[98:101], v[154:157], v[186:189], v[98:101]
	v_mfma_f32_16x16x32_bf16 v[98:101], v[158:161], v[190:193], v[98:101]
	v_mfma_f32_16x16x32_bf16 v[102:105], v[146:149], v[186:189], v[102:105]
	v_mfma_f32_16x16x32_bf16 v[102:105], v[150:153], v[190:193], v[102:105]
	v_mfma_f32_16x16x32_bf16 v[82:85], v[146:149], v[194:197], v[82:85]
	v_mfma_f32_16x16x32_bf16 v[82:85], v[150:153], v[198:201], v[82:85]
	v_mfma_f32_16x16x32_bf16 v[74:77], v[154:157], v[194:197], v[74:77]
	v_mfma_f32_16x16x32_bf16 v[74:77], v[158:161], v[198:201], v[74:77]
	s_setprio 2
	s_barrier
	v_mfma_f32_16x16x32_bf16 v[66:69], v[154:157], v[202:205], v[66:69]
	v_mfma_f32_16x16x32_bf16 v[66:69], v[158:161], v[206:209], v[66:69]
	v_mfma_f32_16x16x32_bf16 v[70:73], v[146:149], v[202:205], v[70:73]
	v_mfma_f32_16x16x32_bf16 v[70:73], v[150:153], v[206:209], v[70:73]
	s_setprio 0
	ds_read_b128 v[166:169], v183 offset:49152
	ds_read_b128 v[170:173], v183 offset:50176
	ds_read_b128 v[186:189], v183 offset:51200
	ds_read_b128 v[190:193], v183 offset:52224
	ds_read_b128 v[194:197], v183 offset:53248
	ds_read_b128 v[198:201], v183 offset:54272
	ds_read_b128 v[202:205], v183 offset:55296
	ds_read_b128 v[206:209], v183 offset:56320
	s_add_u32 s24, s22, 0x80
	s_addc_u32 s25, s23, 0
	s_mov_b32 s79, m0
	s_mov_b32 m0, s46
	s_nop 0
	global_load_lds_dwordx4 v176, s[24:25]
	s_mov_b32 m0, s79
	s_add_u32 s22, s22, 0x80080
	s_mov_b32 s79, m0
	s_mov_b32 m0, s47
	s_nop 0
	global_load_lds_dwordx4 v178, s[24:25]
	s_mov_b32 m0, s79
	s_addc_u32 s23, s23, 0
	s_mov_b32 s24, m0
	s_mov_b32 m0, s48
	s_nop 0
	global_load_lds_dwordx4 v176, s[22:23]
	s_mov_b32 m0, s24
	s_nop 0
	s_mov_b32 s24, m0
	s_mov_b32 m0, s49
	s_nop 0
	global_load_lds_dwordx4 v178, s[22:23]
	s_mov_b32 m0, s24
	s_waitcnt vmcnt(4)
	s_waitcnt lgkmcnt(0)
	s_barrier
	s_setprio 1
	s_waitcnt lgkmcnt(7)
	v_mfma_f32_16x16x32_bf16 v[62:65], v[130:133], v[166:169], v[62:65]
	v_mfma_f32_16x16x32_bf16 v[62:65], v[134:137], v[170:173], v[62:65]
	s_waitcnt lgkmcnt(5)
	v_mfma_f32_16x16x32_bf16 v[58:61], v[138:141], v[166:169], v[58:61]
	v_mfma_f32_16x16x32_bf16 v[58:61], v[142:145], v[170:173], v[58:61]
	s_waitcnt lgkmcnt(3)
	v_mfma_f32_16x16x32_bf16 v[42:45], v[138:141], v[186:189], v[42:45]
	v_mfma_f32_16x16x32_bf16 v[42:45], v[142:145], v[190:193], v[42:45]
	s_waitcnt lgkmcnt(1)
	v_mfma_f32_16x16x32_bf16 v[46:49], v[130:133], v[186:189], v[46:49]
	v_mfma_f32_16x16x32_bf16 v[46:49], v[134:137], v[190:193], v[46:49]
	v_mfma_f32_16x16x32_bf16 v[30:33], v[130:133], v[194:197], v[30:33]
	v_mfma_f32_16x16x32_bf16 v[30:33], v[134:137], v[198:201], v[30:33]
	v_mfma_f32_16x16x32_bf16 v[26:29], v[138:141], v[194:197], v[26:29]
	v_mfma_f32_16x16x32_bf16 v[26:29], v[142:145], v[198:201], v[26:29]
	v_mfma_f32_16x16x32_bf16 v[10:13], v[138:141], v[202:205], v[10:13]
	v_mfma_f32_16x16x32_bf16 v[10:13], v[142:145], v[206:209], v[10:13]
	s_waitcnt lgkmcnt(0)
	v_mfma_f32_16x16x32_bf16 v[14:17], v[130:133], v[202:205], v[14:17]
	v_mfma_f32_16x16x32_bf16 v[14:17], v[134:137], v[206:209], v[14:17]
	s_setprio 0
	s_setprio 1
	v_mfma_f32_16x16x32_bf16 v[54:57], v[146:149], v[166:169], v[54:57]
	v_mfma_f32_16x16x32_bf16 v[54:57], v[150:153], v[170:173], v[54:57]
	v_mfma_f32_16x16x32_bf16 v[50:53], v[154:157], v[166:169], v[50:53]
	v_mfma_f32_16x16x32_bf16 v[50:53], v[158:161], v[170:173], v[50:53]
	v_mfma_f32_16x16x32_bf16 v[34:37], v[154:157], v[186:189], v[34:37]
	v_mfma_f32_16x16x32_bf16 v[34:37], v[158:161], v[190:193], v[34:37]
	v_mfma_f32_16x16x32_bf16 v[38:41], v[146:149], v[186:189], v[38:41]
	v_mfma_f32_16x16x32_bf16 v[38:41], v[150:153], v[190:193], v[38:41]
	v_mfma_f32_16x16x32_bf16 v[22:25], v[146:149], v[194:197], v[22:25]
	v_mfma_f32_16x16x32_bf16 v[22:25], v[150:153], v[198:201], v[22:25]
	v_mfma_f32_16x16x32_bf16 v[18:21], v[154:157], v[194:197], v[18:21]
	v_mfma_f32_16x16x32_bf16 v[18:21], v[158:161], v[198:201], v[18:21]
	s_setprio 2
	s_barrier
	v_mfma_f32_16x16x32_bf16 v[2:5], v[154:157], v[202:205], v[2:5]
	v_mfma_f32_16x16x32_bf16 v[2:5], v[158:161], v[206:209], v[2:5]
	v_mfma_f32_16x16x32_bf16 v[6:9], v[146:149], v[202:205], v[6:9]
	v_mfma_f32_16x16x32_bf16 v[6:9], v[150:153], v[206:209], v[6:9]
	s_setprio 0
	s_add_i32 s78, s78, 2
	s_add_u32 s74, s74, 0x100
	s_addc_u32 s75, s75, 0
	s_add_u32 s20, s20, 0x100
	s_addc_u32 s21, s21, 0
	s_add_u32 s76, s76, 0x100
	s_addc_u32 s77, s77, 0
	s_cmp_gt_u32 s78, 29
	.p2align 6
.LBB0_1053:
	ds_read_b128 v[130:133], v181
	ds_read_b128 v[134:137], v181 offset:1024
	ds_read_b128 v[138:141], v181 offset:2048
	ds_read_b128 v[142:145], v181 offset:3072
	ds_read_b128 v[146:149], v182
	ds_read_b128 v[150:153], v182 offset:1024
	ds_read_b128 v[154:157], v182 offset:2048
	ds_read_b128 v[158:161], v182 offset:3072
	s_cmp_eq_u32 s78, 28
	s_cselect_b32 s23, s11, s75
	s_cselect_b32 s22, s73, s74
	s_cselect_b32 s25, s13, s77
	s_cselect_b32 s24, s67, s76
	ds_read_b128 v[166:169], v183
	ds_read_b128 v[170:173], v183 offset:1024
	ds_read_b128 v[186:189], v183 offset:2048
	ds_read_b128 v[190:193], v183 offset:3072
	ds_read_b128 v[194:197], v183 offset:4096
	ds_read_b128 v[198:201], v183 offset:5120
	ds_read_b128 v[202:205], v183 offset:6144
	ds_read_b128 v[206:209], v183 offset:7168
	s_add_u32 s80, s20, 0xfff80000
	s_addc_u32 s81, s21, -1
	s_mov_b32 s79, m0
	s_mov_b32 m0, s58
	s_nop 0
	global_load_lds_dwordx4 v1, s[80:81]
	s_mov_b32 m0, s79
	s_nop 0
	s_mov_b32 s79, m0
	s_mov_b32 m0, s64
	s_nop 0
	global_load_lds_dwordx4 v177, s[80:81]
	s_mov_b32 m0, s79
	s_nop 0
	s_mov_b32 s79, m0
	s_mov_b32 m0, s59
	s_nop 0
	global_load_lds_dwordx4 v1, s[20:21]
	s_mov_b32 m0, s79
	s_nop 0
	s_mov_b32 s79, m0
	s_mov_b32 m0, s65
	s_nop 0
	global_load_lds_dwordx4 v177, s[20:21]
	s_mov_b32 m0, s79
	s_waitcnt vmcnt(8)
	s_waitcnt lgkmcnt(0)
	s_barrier
	s_setprio 1
	s_waitcnt lgkmcnt(7)
	v_mfma_f32_16x16x32_bf16 v[126:129], v[130:133], v[166:169], v[126:129]
	v_mfma_f32_16x16x32_bf16 v[126:129], v[134:137], v[170:173], v[126:129]
	s_waitcnt lgkmcnt(5)
	v_mfma_f32_16x16x32_bf16 v[122:125], v[138:141], v[166:169], v[122:125]
	v_mfma_f32_16x16x32_bf16 v[122:125], v[142:145], v[170:173], v[122:125]
	s_waitcnt lgkmcnt(3)
	v_mfma_f32_16x16x32_bf16 v[114:117], v[138:141], v[186:189], v[114:117]
	v_mfma_f32_16x16x32_bf16 v[114:117], v[142:145], v[190:193], v[114:117]
	s_waitcnt lgkmcnt(1)
	v_mfma_f32_16x16x32_bf16 v[118:121], v[130:133], v[186:189], v[118:121]
	v_mfma_f32_16x16x32_bf16 v[118:121], v[134:137], v[190:193], v[118:121]
	v_mfma_f32_16x16x32_bf16 v[94:97], v[130:133], v[194:197], v[94:97]
	v_mfma_f32_16x16x32_bf16 v[94:97], v[134:137], v[198:201], v[94:97]
	v_mfma_f32_16x16x32_bf16 v[90:93], v[138:141], v[194:197], v[90:93]
	v_mfma_f32_16x16x32_bf16 v[90:93], v[142:145], v[198:201], v[90:93]
	v_mfma_f32_16x16x32_bf16 v[78:81], v[138:141], v[202:205], v[78:81]
	v_mfma_f32_16x16x32_bf16 v[78:81], v[142:145], v[206:209], v[78:81]
	s_waitcnt lgkmcnt(0)
	v_mfma_f32_16x16x32_bf16 v[86:89], v[130:133], v[202:205], v[86:89]
	v_mfma_f32_16x16x32_bf16 v[86:89], v[134:137], v[206:209], v[86:89]
	s_setprio 0
	s_setprio 1
	v_mfma_f32_16x16x32_bf16 v[110:113], v[146:149], v[166:169], v[110:113]
	v_mfma_f32_16x16x32_bf16 v[110:113], v[150:153], v[170:173], v[110:113]
	v_mfma_f32_16x16x32_bf16 v[106:109], v[154:157], v[166:169], v[106:109]
	v_mfma_f32_16x16x32_bf16 v[106:109], v[158:161], v[170:173], v[106:109]
	v_mfma_f32_16x16x32_bf16 v[98:101], v[154:157], v[186:189], v[98:101]
	v_mfma_f32_16x16x32_bf16 v[98:101], v[158:161], v[190:193], v[98:101]
	v_mfma_f32_16x16x32_bf16 v[102:105], v[146:149], v[186:189], v[102:105]
	v_mfma_f32_16x16x32_bf16 v[102:105], v[150:153], v[190:193], v[102:105]
	v_mfma_f32_16x16x32_bf16 v[82:85], v[146:149], v[194:197], v[82:85]
	v_mfma_f32_16x16x32_bf16 v[82:85], v[150:153], v[198:201], v[82:85]
	v_mfma_f32_16x16x32_bf16 v[74:77], v[154:157], v[194:197], v[74:77]
	v_mfma_f32_16x16x32_bf16 v[74:77], v[158:161], v[198:201], v[74:77]
	s_setprio 2
	s_barrier
	v_mfma_f32_16x16x32_bf16 v[66:69], v[154:157], v[202:205], v[66:69]
	v_mfma_f32_16x16x32_bf16 v[66:69], v[158:161], v[206:209], v[66:69]
	v_mfma_f32_16x16x32_bf16 v[70:73], v[146:149], v[202:205], v[70:73]
	v_mfma_f32_16x16x32_bf16 v[70:73], v[150:153], v[206:209], v[70:73]
	s_setprio 0
	ds_read_b128 v[166:169], v183 offset:16384
	ds_read_b128 v[170:173], v183 offset:17408
	ds_read_b128 v[186:189], v183 offset:18432
	ds_read_b128 v[190:193], v183 offset:19456
	ds_read_b128 v[194:197], v183 offset:20480
	ds_read_b128 v[198:201], v183 offset:21504
	ds_read_b128 v[202:205], v183 offset:22528
	ds_read_b128 v[206:209], v183 offset:23552
	s_mov_b32 s79, m0
	s_mov_b32 m0, s35
	s_nop 0
	global_load_lds_dwordx4 v176, s[22:23]
	s_mov_b32 m0, s79
	s_add_u32 s80, s22, 0x80000
	s_mov_b32 s79, m0
	s_mov_b32 m0, s36
	s_nop 0
	global_load_lds_dwordx4 v178, s[22:23]
	s_mov_b32 m0, s79
	s_addc_u32 s81, s23, 0
	s_mov_b32 s79, m0
	s_mov_b32 m0, s37
	s_nop 0
	global_load_lds_dwordx4 v176, s[80:81]
	s_mov_b32 m0, s79
	s_nop 0
	s_mov_b32 s79, m0
	s_mov_b32 m0, s40
	s_nop 0
	global_load_lds_dwordx4 v178, s[80:81]
	s_mov_b32 m0, s79
	s_waitcnt vmcnt(4)
	s_waitcnt lgkmcnt(0)
	s_barrier
	s_setprio 1
	s_waitcnt lgkmcnt(7)
	v_mfma_f32_16x16x32_bf16 v[62:65], v[130:133], v[166:169], v[62:65]
	v_mfma_f32_16x16x32_bf16 v[62:65], v[134:137], v[170:173], v[62:65]
	s_waitcnt lgkmcnt(5)
	v_mfma_f32_16x16x32_bf16 v[58:61], v[138:141], v[166:169], v[58:61]
	v_mfma_f32_16x16x32_bf16 v[58:61], v[142:145], v[170:173], v[58:61]
	s_waitcnt lgkmcnt(3)
	v_mfma_f32_16x16x32_bf16 v[42:45], v[138:141], v[186:189], v[42:45]
	v_mfma_f32_16x16x32_bf16 v[42:45], v[142:145], v[190:193], v[42:45]
	s_waitcnt lgkmcnt(1)
	v_mfma_f32_16x16x32_bf16 v[46:49], v[130:133], v[186:189], v[46:49]
	v_mfma_f32_16x16x32_bf16 v[46:49], v[134:137], v[190:193], v[46:49]
	v_mfma_f32_16x16x32_bf16 v[30:33], v[130:133], v[194:197], v[30:33]
	v_mfma_f32_16x16x32_bf16 v[30:33], v[134:137], v[198:201], v[30:33]
	v_mfma_f32_16x16x32_bf16 v[26:29], v[138:141], v[194:197], v[26:29]
	v_mfma_f32_16x16x32_bf16 v[26:29], v[142:145], v[198:201], v[26:29]
	v_mfma_f32_16x16x32_bf16 v[10:13], v[138:141], v[202:205], v[10:13]
	v_mfma_f32_16x16x32_bf16 v[10:13], v[142:145], v[206:209], v[10:13]
	s_waitcnt lgkmcnt(0)
	v_mfma_f32_16x16x32_bf16 v[14:17], v[130:133], v[202:205], v[14:17]
	v_mfma_f32_16x16x32_bf16 v[14:17], v[134:137], v[206:209], v[14:17]
	s_setprio 0
	s_setprio 1
	v_mfma_f32_16x16x32_bf16 v[54:57], v[146:149], v[166:169], v[54:57]
	v_mfma_f32_16x16x32_bf16 v[54:57], v[150:153], v[170:173], v[54:57]
	v_mfma_f32_16x16x32_bf16 v[50:53], v[154:157], v[166:169], v[50:53]
	v_mfma_f32_16x16x32_bf16 v[50:53], v[158:161], v[170:173], v[50:53]
	v_mfma_f32_16x16x32_bf16 v[34:37], v[154:157], v[186:189], v[34:37]
	v_mfma_f32_16x16x32_bf16 v[34:37], v[158:161], v[190:193], v[34:37]
	v_mfma_f32_16x16x32_bf16 v[38:41], v[146:149], v[186:189], v[38:41]
	v_mfma_f32_16x16x32_bf16 v[38:41], v[150:153], v[190:193], v[38:41]
	v_mfma_f32_16x16x32_bf16 v[22:25], v[146:149], v[194:197], v[22:25]
	v_mfma_f32_16x16x32_bf16 v[22:25], v[150:153], v[198:201], v[22:25]
	v_mfma_f32_16x16x32_bf16 v[18:21], v[154:157], v[194:197], v[18:21]
	v_mfma_f32_16x16x32_bf16 v[18:21], v[158:161], v[198:201], v[18:21]
	s_setprio 2
	s_barrier
	v_mfma_f32_16x16x32_bf16 v[2:5], v[154:157], v[202:205], v[2:5]
	v_mfma_f32_16x16x32_bf16 v[2:5], v[158:161], v[206:209], v[2:5]
	v_mfma_f32_16x16x32_bf16 v[6:9], v[146:149], v[202:205], v[6:9]
	v_mfma_f32_16x16x32_bf16 v[6:9], v[150:153], v[206:209], v[6:9]
	s_setprio 0
	ds_read_b128 v[130:133], v184
	ds_read_b128 v[134:137], v184 offset:1024
	ds_read_b128 v[138:141], v184 offset:2048
	ds_read_b128 v[142:145], v184 offset:3072
	ds_read_b128 v[146:149], v185
	ds_read_b128 v[150:153], v185 offset:1024
	ds_read_b128 v[154:157], v185 offset:2048
	ds_read_b128 v[158:161], v185 offset:3072
	ds_read_b128 v[166:169], v183 offset:32768
	ds_read_b128 v[170:173], v183 offset:33792
	ds_read_b128 v[186:189], v183 offset:34816
	ds_read_b128 v[190:193], v183 offset:35840
	ds_read_b128 v[194:197], v183 offset:36864
	ds_read_b128 v[198:201], v183 offset:37888
	ds_read_b128 v[202:205], v183 offset:38912
	ds_read_b128 v[206:209], v183 offset:39936
	s_mov_b32 s79, m0
	s_mov_b32 m0, s34
	s_nop 0
	global_load_lds_dwordx4 v1, s[24:25]
	s_mov_b32 m0, s79
	s_nop 0
	s_mov_b32 s79, m0
	s_mov_b32 m0, s41
	s_nop 0
	global_load_lds_dwordx4 v177, s[24:25]
	s_mov_b32 m0, s79
	s_add_u32 s24, s24, 0x80000
	s_addc_u32 s25, s25, 0
	s_mov_b32 s79, m0
	s_mov_b32 m0, s42
	s_nop 0
	global_load_lds_dwordx4 v1, s[24:25]
	s_mov_b32 m0, s79
	s_nop 0
	s_mov_b32 s79, m0
	s_mov_b32 m0, s43
	s_nop 0
	global_load_lds_dwordx4 v177, s[24:25]
	s_mov_b32 m0, s79
	s_waitcnt vmcnt(8)
	s_waitcnt lgkmcnt(0)
	s_barrier
	s_setprio 1
	s_waitcnt lgkmcnt(7)
	v_mfma_f32_16x16x32_bf16 v[126:129], v[130:133], v[166:169], v[126:129]
	v_mfma_f32_16x16x32_bf16 v[126:129], v[134:137], v[170:173], v[126:129]
	s_waitcnt lgkmcnt(5)
	v_mfma_f32_16x16x32_bf16 v[122:125], v[138:141], v[166:169], v[122:125]
	v_mfma_f32_16x16x32_bf16 v[122:125], v[142:145], v[170:173], v[122:125]
	s_waitcnt lgkmcnt(3)
	v_mfma_f32_16x16x32_bf16 v[114:117], v[138:141], v[186:189], v[114:117]
	v_mfma_f32_16x16x32_bf16 v[114:117], v[142:145], v[190:193], v[114:117]
	s_waitcnt lgkmcnt(1)
	v_mfma_f32_16x16x32_bf16 v[118:121], v[130:133], v[186:189], v[118:121]
	v_mfma_f32_16x16x32_bf16 v[118:121], v[134:137], v[190:193], v[118:121]
	v_mfma_f32_16x16x32_bf16 v[94:97], v[130:133], v[194:197], v[94:97]
	v_mfma_f32_16x16x32_bf16 v[94:97], v[134:137], v[198:201], v[94:97]
	v_mfma_f32_16x16x32_bf16 v[90:93], v[138:141], v[194:197], v[90:93]
	v_mfma_f32_16x16x32_bf16 v[90:93], v[142:145], v[198:201], v[90:93]
	v_mfma_f32_16x16x32_bf16 v[78:81], v[138:141], v[202:205], v[78:81]
	v_mfma_f32_16x16x32_bf16 v[78:81], v[142:145], v[206:209], v[78:81]
	s_waitcnt lgkmcnt(0)
	v_mfma_f32_16x16x32_bf16 v[86:89], v[130:133], v[202:205], v[86:89]
	v_mfma_f32_16x16x32_bf16 v[86:89], v[134:137], v[206:209], v[86:89]
	s_setprio 0
	s_setprio 1
	v_mfma_f32_16x16x32_bf16 v[110:113], v[146:149], v[166:169], v[110:113]
	v_mfma_f32_16x16x32_bf16 v[110:113], v[150:153], v[170:173], v[110:113]
	v_mfma_f32_16x16x32_bf16 v[106:109], v[154:157], v[166:169], v[106:109]
	v_mfma_f32_16x16x32_bf16 v[106:109], v[158:161], v[170:173], v[106:109]
	v_mfma_f32_16x16x32_bf16 v[98:101], v[154:157], v[186:189], v[98:101]
	v_mfma_f32_16x16x32_bf16 v[98:101], v[158:161], v[190:193], v[98:101]
	v_mfma_f32_16x16x32_bf16 v[102:105], v[146:149], v[186:189], v[102:105]
	v_mfma_f32_16x16x32_bf16 v[102:105], v[150:153], v[190:193], v[102:105]
	v_mfma_f32_16x16x32_bf16 v[82:85], v[146:149], v[194:197], v[82:85]
	v_mfma_f32_16x16x32_bf16 v[82:85], v[150:153], v[198:201], v[82:85]
	v_mfma_f32_16x16x32_bf16 v[74:77], v[154:157], v[194:197], v[74:77]
	v_mfma_f32_16x16x32_bf16 v[74:77], v[158:161], v[198:201], v[74:77]
	s_setprio 2
	s_barrier
	v_mfma_f32_16x16x32_bf16 v[66:69], v[154:157], v[202:205], v[66:69]
	v_mfma_f32_16x16x32_bf16 v[66:69], v[158:161], v[206:209], v[66:69]
	v_mfma_f32_16x16x32_bf16 v[70:73], v[146:149], v[202:205], v[70:73]
	v_mfma_f32_16x16x32_bf16 v[70:73], v[150:153], v[206:209], v[70:73]
	s_setprio 0
	ds_read_b128 v[166:169], v183 offset:49152
	ds_read_b128 v[170:173], v183 offset:50176
	ds_read_b128 v[186:189], v183 offset:51200
	ds_read_b128 v[190:193], v183 offset:52224
	ds_read_b128 v[194:197], v183 offset:53248
	ds_read_b128 v[198:201], v183 offset:54272
	ds_read_b128 v[202:205], v183 offset:55296
	ds_read_b128 v[206:209], v183 offset:56320
	s_add_u32 s24, s22, 0x80
	s_addc_u32 s25, s23, 0
	s_mov_b32 s79, m0
	s_mov_b32 m0, s46
	s_nop 0
	global_load_lds_dwordx4 v176, s[24:25]
	s_mov_b32 m0, s79
	s_add_u32 s22, s22, 0x80080
	s_mov_b32 s79, m0
	s_mov_b32 m0, s47
	s_nop 0
	global_load_lds_dwordx4 v178, s[24:25]
	s_mov_b32 m0, s79
	s_addc_u32 s23, s23, 0
	s_mov_b32 s24, m0
	s_mov_b32 m0, s48
	s_nop 0
	global_load_lds_dwordx4 v176, s[22:23]
	s_mov_b32 m0, s24
	s_nop 0
	s_mov_b32 s24, m0
	s_mov_b32 m0, s49
	s_nop 0
	global_load_lds_dwordx4 v178, s[22:23]
	s_mov_b32 m0, s24
	s_waitcnt vmcnt(4)
	s_waitcnt lgkmcnt(0)
	s_barrier
	s_setprio 1
	s_waitcnt lgkmcnt(7)
	v_mfma_f32_16x16x32_bf16 v[62:65], v[130:133], v[166:169], v[62:65]
	v_mfma_f32_16x16x32_bf16 v[62:65], v[134:137], v[170:173], v[62:65]
	s_waitcnt lgkmcnt(5)
	v_mfma_f32_16x16x32_bf16 v[58:61], v[138:141], v[166:169], v[58:61]
	v_mfma_f32_16x16x32_bf16 v[58:61], v[142:145], v[170:173], v[58:61]
	s_waitcnt lgkmcnt(3)
	v_mfma_f32_16x16x32_bf16 v[42:45], v[138:141], v[186:189], v[42:45]
	v_mfma_f32_16x16x32_bf16 v[42:45], v[142:145], v[190:193], v[42:45]
	s_waitcnt lgkmcnt(1)
	v_mfma_f32_16x16x32_bf16 v[46:49], v[130:133], v[186:189], v[46:49]
	v_mfma_f32_16x16x32_bf16 v[46:49], v[134:137], v[190:193], v[46:49]
	v_mfma_f32_16x16x32_bf16 v[30:33], v[130:133], v[194:197], v[30:33]
	v_mfma_f32_16x16x32_bf16 v[30:33], v[134:137], v[198:201], v[30:33]
	v_mfma_f32_16x16x32_bf16 v[26:29], v[138:141], v[194:197], v[26:29]
	v_mfma_f32_16x16x32_bf16 v[26:29], v[142:145], v[198:201], v[26:29]
	v_mfma_f32_16x16x32_bf16 v[10:13], v[138:141], v[202:205], v[10:13]
	v_mfma_f32_16x16x32_bf16 v[10:13], v[142:145], v[206:209], v[10:13]
	s_waitcnt lgkmcnt(0)
	v_mfma_f32_16x16x32_bf16 v[14:17], v[130:133], v[202:205], v[14:17]
	v_mfma_f32_16x16x32_bf16 v[14:17], v[134:137], v[206:209], v[14:17]
	s_setprio 0
	s_setprio 1
	v_mfma_f32_16x16x32_bf16 v[54:57], v[146:149], v[166:169], v[54:57]
	v_mfma_f32_16x16x32_bf16 v[54:57], v[150:153], v[170:173], v[54:57]
	v_mfma_f32_16x16x32_bf16 v[50:53], v[154:157], v[166:169], v[50:53]
	v_mfma_f32_16x16x32_bf16 v[50:53], v[158:161], v[170:173], v[50:53]
	v_mfma_f32_16x16x32_bf16 v[34:37], v[154:157], v[186:189], v[34:37]
	v_mfma_f32_16x16x32_bf16 v[34:37], v[158:161], v[190:193], v[34:37]
	v_mfma_f32_16x16x32_bf16 v[38:41], v[146:149], v[186:189], v[38:41]
	v_mfma_f32_16x16x32_bf16 v[38:41], v[150:153], v[190:193], v[38:41]
	v_mfma_f32_16x16x32_bf16 v[22:25], v[146:149], v[194:197], v[22:25]
	v_mfma_f32_16x16x32_bf16 v[22:25], v[150:153], v[198:201], v[22:25]
	v_mfma_f32_16x16x32_bf16 v[18:21], v[154:157], v[194:197], v[18:21]
	v_mfma_f32_16x16x32_bf16 v[18:21], v[158:161], v[198:201], v[18:21]
	s_setprio 2
	s_barrier
	v_mfma_f32_16x16x32_bf16 v[2:5], v[154:157], v[202:205], v[2:5]
	v_mfma_f32_16x16x32_bf16 v[2:5], v[158:161], v[206:209], v[2:5]
	v_mfma_f32_16x16x32_bf16 v[6:9], v[146:149], v[202:205], v[6:9]
	v_mfma_f32_16x16x32_bf16 v[6:9], v[150:153], v[206:209], v[6:9]
	s_setprio 0
	s_add_i32 s78, s78, 2
	s_add_u32 s74, s74, 0x100
	s_addc_u32 s75, s75, 0
	s_add_u32 s20, s20, 0x100
	s_addc_u32 s21, s21, 0
	s_add_u32 s76, s76, 0x100
	s_addc_u32 s77, s77, 0
	s_cmp_gt_u32 s78, 29
	s_cbranch_scc0 .LBB0_1053
	s_and_b64 vcc, exec, s[8:9]
	s_cbranch_vccz .LBB0_1056
	s_barrier

.LBB0_1223:
	s_ashr_i32 s11, s10, 31
	s_lshl_b64 s[12:13], s[10:11], 20
	s_add_u32 s12, s26, s12
	s_addc_u32 s13, s27, s13
	s_and_b64 s[14:15], s[2:3], exec
	s_cselect_b32 s11, s13, s21
	s_cselect_b32 s66, s12, s20
	s_ashr_i32 s9, s8, 31
	s_lshl_b64 s[14:15], s[8:9], 20
	s_add_u32 s14, s28, s14
	s_addc_u32 s15, s29, s15
	s_and_b64 s[22:23], s[2:3], exec
	s_cselect_b32 s9, s15, s19
	s_cselect_b32 s67, s14, s18
	s_add_u32 s73, s18, 0x100
	s_addc_u32 s74, s19, 0
	s_add_u32 s18, s20, 0x80080
	s_addc_u32 s19, s21, 0
	s_add_u32 s75, s20, 0x100
	s_addc_u32 s76, s21, 0
	s_mov_b32 s77, -2
	ds_read_b128 v[148:151], v143
	ds_read_b128 v[152:155], v143 offset:1024
	ds_read_b128 v[156:159], v143 offset:2048
	ds_read_b128 v[160:163], v143 offset:3072
	ds_read_b128 v[164:167], v144
	ds_read_b128 v[168:171], v144 offset:1024
	ds_read_b128 v[172:175], v144 offset:2048
	ds_read_b128 v[176:179], v144 offset:3072
	s_cmp_eq_u32 s77, 28
	s_cselect_b32 s21, s9, s74
	s_cselect_b32 s20, s67, s73
	s_cselect_b32 s23, s11, s76
	s_cselect_b32 s22, s66, s75
	ds_read_b128 v[180:183], v145
	ds_read_b128 v[184:187], v145 offset:1024
	ds_read_b128 v[188:191], v145 offset:2048
	ds_read_b128 v[192:195], v145 offset:3072
	ds_read_b128 v[196:199], v145 offset:4096
	ds_read_b128 v[200:203], v145 offset:5120
	ds_read_b128 v[204:207], v145 offset:6144
	ds_read_b128 v[208:211], v145 offset:7168
	s_add_u32 s78, s18, 0xfff80000
	s_addc_u32 s79, s19, -1
	s_mov_b32 s80, m0
	s_mov_b32 m0, s56
	s_nop 0
	global_load_lds_dwordx4 v138, s[78:79]
	s_mov_b32 m0, s80
	s_nop 0
	s_mov_b32 s80, m0
	s_mov_b32 m0, s59
	s_nop 0
	global_load_lds_dwordx4 v140, s[78:79]
	s_mov_b32 m0, s80
	s_mov_b32 s78, m0
	s_mov_b32 m0, s57
	s_nop 0
	global_load_lds_dwordx4 v138, s[18:19]
	s_mov_b32 m0, s78
	s_nop 0
	s_mov_b32 s78, m0
	s_mov_b32 m0, s64
	s_nop 0
	global_load_lds_dwordx4 v140, s[18:19]
	s_mov_b32 m0, s78
	s_waitcnt vmcnt(8)
	s_waitcnt lgkmcnt(0)
	s_barrier
	s_setprio 1
	s_waitcnt lgkmcnt(7)
	v_mfma_f32_16x16x32_bf16 v[126:129], v[148:151], v[180:183], 0
	v_mfma_f32_16x16x32_bf16 v[126:129], v[152:155], v[184:187], v[126:129]
	s_waitcnt lgkmcnt(5)
	v_mfma_f32_16x16x32_bf16 v[122:125], v[156:159], v[180:183], 0
	v_mfma_f32_16x16x32_bf16 v[122:125], v[160:163], v[184:187], v[122:125]
	s_waitcnt lgkmcnt(3)
	v_mfma_f32_16x16x32_bf16 v[106:109], v[156:159], v[188:191], 0
	v_mfma_f32_16x16x32_bf16 v[106:109], v[160:163], v[192:195], v[106:109]
	s_waitcnt lgkmcnt(1)
	v_mfma_f32_16x16x32_bf16 v[110:113], v[148:151], v[188:191], 0
	v_mfma_f32_16x16x32_bf16 v[110:113], v[152:155], v[192:195], v[110:113]
	v_mfma_f32_16x16x32_bf16 v[94:97], v[148:151], v[196:199], 0
	v_mfma_f32_16x16x32_bf16 v[94:97], v[152:155], v[200:203], v[94:97]
	v_mfma_f32_16x16x32_bf16 v[90:93], v[156:159], v[196:199], 0
	v_mfma_f32_16x16x32_bf16 v[90:93], v[160:163], v[200:203], v[90:93]
	v_mfma_f32_16x16x32_bf16 v[74:77], v[156:159], v[204:207], 0
	v_mfma_f32_16x16x32_bf16 v[74:77], v[160:163], v[208:211], v[74:77]
	s_waitcnt lgkmcnt(0)
	v_mfma_f32_16x16x32_bf16 v[78:81], v[148:151], v[204:207], 0
	v_mfma_f32_16x16x32_bf16 v[78:81], v[152:155], v[208:211], v[78:81]
	s_setprio 0
	s_setprio 1
	v_mfma_f32_16x16x32_bf16 v[118:121], v[164:167], v[180:183], 0
	v_mfma_f32_16x16x32_bf16 v[118:121], v[168:171], v[184:187], v[118:121]
	v_mfma_f32_16x16x32_bf16 v[114:117], v[172:175], v[180:183], 0
	v_mfma_f32_16x16x32_bf16 v[114:117], v[176:179], v[184:187], v[114:117]
	v_mfma_f32_16x16x32_bf16 v[98:101], v[172:175], v[188:191], 0
	v_mfma_f32_16x16x32_bf16 v[98:101], v[176:179], v[192:195], v[98:101]
	v_mfma_f32_16x16x32_bf16 v[102:105], v[164:167], v[188:191], 0
	v_mfma_f32_16x16x32_bf16 v[102:105], v[168:171], v[192:195], v[102:105]
	v_mfma_f32_16x16x32_bf16 v[86:89], v[164:167], v[196:199], 0
	v_mfma_f32_16x16x32_bf16 v[86:89], v[168:171], v[200:203], v[86:89]
	v_mfma_f32_16x16x32_bf16 v[82:85], v[172:175], v[196:199], 0
	v_mfma_f32_16x16x32_bf16 v[82:85], v[176:179], v[200:203], v[82:85]
	s_setprio 2
	s_barrier
	v_mfma_f32_16x16x32_bf16 v[66:69], v[172:175], v[204:207], 0
	v_mfma_f32_16x16x32_bf16 v[66:69], v[176:179], v[208:211], v[66:69]
	v_mfma_f32_16x16x32_bf16 v[70:73], v[164:167], v[204:207], 0
	v_mfma_f32_16x16x32_bf16 v[70:73], v[168:171], v[208:211], v[70:73]
	s_setprio 0
	ds_read_b128 v[180:183], v145 offset:16384
	ds_read_b128 v[184:187], v145 offset:17408
	ds_read_b128 v[188:191], v145 offset:18432
	ds_read_b128 v[192:195], v145 offset:19456
	ds_read_b128 v[196:199], v145 offset:20480
	ds_read_b128 v[200:203], v145 offset:21504
	ds_read_b128 v[204:207], v145 offset:22528
	ds_read_b128 v[208:211], v145 offset:23552
	s_mov_b32 s78, m0
	s_mov_b32 m0, s35
	s_nop 0
	global_load_lds_dwordx4 v139, s[20:21]
	s_mov_b32 m0, s78
	s_nop 0
	s_mov_b32 s78, m0
	s_mov_b32 m0, s36
	s_nop 0
	global_load_lds_dwordx4 v141, s[20:21]
	s_mov_b32 m0, s78
	s_add_u32 s78, s20, 0x80000
	s_addc_u32 s79, s21, 0
	s_mov_b32 s80, m0
	s_mov_b32 m0, s37
	s_nop 0
	global_load_lds_dwordx4 v139, s[78:79]
	s_mov_b32 m0, s80
	s_nop 0
	s_mov_b32 s80, m0
	s_mov_b32 m0, s40
	s_nop 0
	global_load_lds_dwordx4 v141, s[78:79]
	s_mov_b32 m0, s80
	s_waitcnt vmcnt(4)
	s_waitcnt lgkmcnt(0)
	s_barrier
	s_setprio 1
	s_waitcnt lgkmcnt(7)
	v_mfma_f32_16x16x32_bf16 v[62:65], v[148:151], v[180:183], 0
	v_mfma_f32_16x16x32_bf16 v[62:65], v[152:155], v[184:187], v[62:65]
	s_waitcnt lgkmcnt(5)
	v_mfma_f32_16x16x32_bf16 v[58:61], v[156:159], v[180:183], 0
	v_mfma_f32_16x16x32_bf16 v[58:61], v[160:163], v[184:187], v[58:61]
	s_waitcnt lgkmcnt(3)
	v_mfma_f32_16x16x32_bf16 v[42:45], v[156:159], v[188:191], 0
	v_mfma_f32_16x16x32_bf16 v[42:45], v[160:163], v[192:195], v[42:45]
	s_waitcnt lgkmcnt(1)
	v_mfma_f32_16x16x32_bf16 v[46:49], v[148:151], v[188:191], 0
	v_mfma_f32_16x16x32_bf16 v[46:49], v[152:155], v[192:195], v[46:49]
	v_mfma_f32_16x16x32_bf16 v[30:33], v[148:151], v[196:199], 0
	v_mfma_f32_16x16x32_bf16 v[30:33], v[152:155], v[200:203], v[30:33]
	v_mfma_f32_16x16x32_bf16 v[26:29], v[156:159], v[196:199], 0
	v_mfma_f32_16x16x32_bf16 v[26:29], v[160:163], v[200:203], v[26:29]
	v_mfma_f32_16x16x32_bf16 v[10:13], v[156:159], v[204:207], 0
	v_mfma_f32_16x16x32_bf16 v[10:13], v[160:163], v[208:211], v[10:13]
	s_waitcnt lgkmcnt(0)
	v_mfma_f32_16x16x32_bf16 v[14:17], v[148:151], v[204:207], 0
	v_mfma_f32_16x16x32_bf16 v[14:17], v[152:155], v[208:211], v[14:17]
	s_setprio 0
	s_setprio 1
	v_mfma_f32_16x16x32_bf16 v[54:57], v[164:167], v[180:183], 0
	v_mfma_f32_16x16x32_bf16 v[54:57], v[168:171], v[184:187], v[54:57]
	v_mfma_f32_16x16x32_bf16 v[50:53], v[172:175], v[180:183], 0
	v_mfma_f32_16x16x32_bf16 v[50:53], v[176:179], v[184:187], v[50:53]
	v_mfma_f32_16x16x32_bf16 v[34:37], v[172:175], v[188:191], 0
	v_mfma_f32_16x16x32_bf16 v[34:37], v[176:179], v[192:195], v[34:37]
	v_mfma_f32_16x16x32_bf16 v[38:41], v[164:167], v[188:191], 0
	v_mfma_f32_16x16x32_bf16 v[38:41], v[168:171], v[192:195], v[38:41]
	v_mfma_f32_16x16x32_bf16 v[22:25], v[164:167], v[196:199], 0
	v_mfma_f32_16x16x32_bf16 v[22:25], v[168:171], v[200:203], v[22:25]
	v_mfma_f32_16x16x32_bf16 v[18:21], v[172:175], v[196:199], 0
	v_mfma_f32_16x16x32_bf16 v[18:21], v[176:179], v[200:203], v[18:21]
	s_setprio 2
	s_barrier
	v_mfma_f32_16x16x32_bf16 v[2:5], v[172:175], v[204:207], 0
	v_mfma_f32_16x16x32_bf16 v[2:5], v[176:179], v[208:211], v[2:5]
	v_mfma_f32_16x16x32_bf16 v[6:9], v[164:167], v[204:207], 0
	v_mfma_f32_16x16x32_bf16 v[6:9], v[168:171], v[208:211], v[6:9]
	s_setprio 0
	ds_read_b128 v[148:151], v146
	ds_read_b128 v[152:155], v146 offset:1024
	ds_read_b128 v[156:159], v146 offset:2048
	ds_read_b128 v[160:163], v146 offset:3072
	ds_read_b128 v[164:167], v147
	ds_read_b128 v[168:171], v147 offset:1024
	ds_read_b128 v[172:175], v147 offset:2048
	ds_read_b128 v[176:179], v147 offset:3072
	ds_read_b128 v[180:183], v145 offset:32768
	ds_read_b128 v[184:187], v145 offset:33792
	ds_read_b128 v[188:191], v145 offset:34816
	ds_read_b128 v[192:195], v145 offset:35840
	ds_read_b128 v[196:199], v145 offset:36864
	ds_read_b128 v[200:203], v145 offset:37888
	ds_read_b128 v[204:207], v145 offset:38912
	ds_read_b128 v[208:211], v145 offset:39936
	s_mov_b32 s78, m0
	s_mov_b32 m0, s31
	s_nop 0
	global_load_lds_dwordx4 v138, s[22:23]
	s_mov_b32 m0, s78
	s_nop 0
	s_mov_b32 s78, m0
	s_mov_b32 m0, s41
	s_nop 0
	global_load_lds_dwordx4 v140, s[22:23]
	s_mov_b32 m0, s78
	s_add_u32 s22, s22, 0x80000
	s_addc_u32 s23, s23, 0
	s_mov_b32 s78, m0
	s_mov_b32 m0, s42
	s_nop 0
	global_load_lds_dwordx4 v138, s[22:23]
	s_mov_b32 m0, s78
	s_nop 0
	s_mov_b32 s78, m0
	s_mov_b32 m0, s43
	s_nop 0
	global_load_lds_dwordx4 v140, s[22:23]
	s_mov_b32 m0, s78
	s_waitcnt vmcnt(8)
	s_waitcnt lgkmcnt(0)
	s_barrier
	s_setprio 1
	s_waitcnt lgkmcnt(7)
	v_mfma_f32_16x16x32_bf16 v[126:129], v[148:151], v[180:183], v[126:129]
	v_mfma_f32_16x16x32_bf16 v[126:129], v[152:155], v[184:187], v[126:129]
	s_waitcnt lgkmcnt(5)
	v_mfma_f32_16x16x32_bf16 v[122:125], v[156:159], v[180:183], v[122:125]
	v_mfma_f32_16x16x32_bf16 v[122:125], v[160:163], v[184:187], v[122:125]
	s_waitcnt lgkmcnt(3)
	v_mfma_f32_16x16x32_bf16 v[106:109], v[156:159], v[188:191], v[106:109]
	v_mfma_f32_16x16x32_bf16 v[106:109], v[160:163], v[192:195], v[106:109]
	s_waitcnt lgkmcnt(1)
	v_mfma_f32_16x16x32_bf16 v[110:113], v[148:151], v[188:191], v[110:113]
	v_mfma_f32_16x16x32_bf16 v[110:113], v[152:155], v[192:195], v[110:113]
	v_mfma_f32_16x16x32_bf16 v[94:97], v[148:151], v[196:199], v[94:97]
	v_mfma_f32_16x16x32_bf16 v[94:97], v[152:155], v[200:203], v[94:97]
	v_mfma_f32_16x16x32_bf16 v[90:93], v[156:159], v[196:199], v[90:93]
	v_mfma_f32_16x16x32_bf16 v[90:93], v[160:163], v[200:203], v[90:93]
	v_mfma_f32_16x16x32_bf16 v[74:77], v[156:159], v[204:207], v[74:77]
	v_mfma_f32_16x16x32_bf16 v[74:77], v[160:163], v[208:211], v[74:77]
	s_waitcnt lgkmcnt(0)
	v_mfma_f32_16x16x32_bf16 v[78:81], v[148:151], v[204:207], v[78:81]
	v_mfma_f32_16x16x32_bf16 v[78:81], v[152:155], v[208:211], v[78:81]
	s_setprio 0
	s_setprio 1
	v_mfma_f32_16x16x32_bf16 v[118:121], v[164:167], v[180:183], v[118:121]
	v_mfma_f32_16x16x32_bf16 v[118:121], v[168:171], v[184:187], v[118:121]
	v_mfma_f32_16x16x32_bf16 v[114:117], v[172:175], v[180:183], v[114:117]
	v_mfma_f32_16x16x32_bf16 v[114:117], v[176:179], v[184:187], v[114:117]
	v_mfma_f32_16x16x32_bf16 v[98:101], v[172:175], v[188:191], v[98:101]
	v_mfma_f32_16x16x32_bf16 v[98:101], v[176:179], v[192:195], v[98:101]
	v_mfma_f32_16x16x32_bf16 v[102:105], v[164:167], v[188:191], v[102:105]
	v_mfma_f32_16x16x32_bf16 v[102:105], v[168:171], v[192:195], v[102:105]
	v_mfma_f32_16x16x32_bf16 v[86:89], v[164:167], v[196:199], v[86:89]
	v_mfma_f32_16x16x32_bf16 v[86:89], v[168:171], v[200:203], v[86:89]
	v_mfma_f32_16x16x32_bf16 v[82:85], v[172:175], v[196:199], v[82:85]
	v_mfma_f32_16x16x32_bf16 v[82:85], v[176:179], v[200:203], v[82:85]
	s_setprio 2
	s_barrier
	v_mfma_f32_16x16x32_bf16 v[66:69], v[172:175], v[204:207], v[66:69]
	v_mfma_f32_16x16x32_bf16 v[66:69], v[176:179], v[208:211], v[66:69]
	v_mfma_f32_16x16x32_bf16 v[70:73], v[164:167], v[204:207], v[70:73]
	v_mfma_f32_16x16x32_bf16 v[70:73], v[168:171], v[208:211], v[70:73]
	s_setprio 0
	ds_read_b128 v[180:183], v145 offset:49152
	ds_read_b128 v[184:187], v145 offset:50176
	ds_read_b128 v[188:191], v145 offset:51200
	ds_read_b128 v[192:195], v145 offset:52224
	ds_read_b128 v[196:199], v145 offset:53248
	ds_read_b128 v[200:203], v145 offset:54272
	ds_read_b128 v[204:207], v145 offset:55296
	ds_read_b128 v[208:211], v145 offset:56320
	s_add_u32 s22, s20, 0x80
	s_addc_u32 s23, s21, 0
	s_mov_b32 s78, m0
	s_mov_b32 m0, s46
	s_nop 0
	global_load_lds_dwordx4 v139, s[22:23]
	s_mov_b32 m0, s78
	s_add_u32 s20, s20, 0x80080
	s_mov_b32 s78, m0
	s_mov_b32 m0, s47
	s_nop 0
	global_load_lds_dwordx4 v141, s[22:23]
	s_mov_b32 m0, s78
	s_addc_u32 s21, s21, 0
	s_mov_b32 s22, m0
	s_mov_b32 m0, s48
	s_nop 0
	global_load_lds_dwordx4 v139, s[20:21]
	s_mov_b32 m0, s22
	s_nop 0
	s_mov_b32 s22, m0
	s_mov_b32 m0, s49
	s_nop 0
	global_load_lds_dwordx4 v141, s[20:21]
	s_mov_b32 m0, s22
	s_waitcnt vmcnt(4)
	s_waitcnt lgkmcnt(0)
	s_barrier
	s_setprio 1
	s_waitcnt lgkmcnt(7)
	v_mfma_f32_16x16x32_bf16 v[62:65], v[148:151], v[180:183], v[62:65]
	v_mfma_f32_16x16x32_bf16 v[62:65], v[152:155], v[184:187], v[62:65]
	s_waitcnt lgkmcnt(5)
	v_mfma_f32_16x16x32_bf16 v[58:61], v[156:159], v[180:183], v[58:61]
	v_mfma_f32_16x16x32_bf16 v[58:61], v[160:163], v[184:187], v[58:61]
	s_waitcnt lgkmcnt(3)
	v_mfma_f32_16x16x32_bf16 v[42:45], v[156:159], v[188:191], v[42:45]
	v_mfma_f32_16x16x32_bf16 v[42:45], v[160:163], v[192:195], v[42:45]
	s_waitcnt lgkmcnt(1)
	v_mfma_f32_16x16x32_bf16 v[46:49], v[148:151], v[188:191], v[46:49]
	v_mfma_f32_16x16x32_bf16 v[46:49], v[152:155], v[192:195], v[46:49]
	v_mfma_f32_16x16x32_bf16 v[30:33], v[148:151], v[196:199], v[30:33]
	v_mfma_f32_16x16x32_bf16 v[30:33], v[152:155], v[200:203], v[30:33]
	v_mfma_f32_16x16x32_bf16 v[26:29], v[156:159], v[196:199], v[26:29]
	v_mfma_f32_16x16x32_bf16 v[26:29], v[160:163], v[200:203], v[26:29]
	v_mfma_f32_16x16x32_bf16 v[10:13], v[156:159], v[204:207], v[10:13]
	v_mfma_f32_16x16x32_bf16 v[10:13], v[160:163], v[208:211], v[10:13]
	s_waitcnt lgkmcnt(0)
	v_mfma_f32_16x16x32_bf16 v[14:17], v[148:151], v[204:207], v[14:17]
	v_mfma_f32_16x16x32_bf16 v[14:17], v[152:155], v[208:211], v[14:17]
	s_setprio 0
	s_setprio 1
	v_mfma_f32_16x16x32_bf16 v[54:57], v[164:167], v[180:183], v[54:57]
	v_mfma_f32_16x16x32_bf16 v[54:57], v[168:171], v[184:187], v[54:57]
	v_mfma_f32_16x16x32_bf16 v[50:53], v[172:175], v[180:183], v[50:53]
	v_mfma_f32_16x16x32_bf16 v[50:53], v[176:179], v[184:187], v[50:53]
	v_mfma_f32_16x16x32_bf16 v[34:37], v[172:175], v[188:191], v[34:37]
	v_mfma_f32_16x16x32_bf16 v[34:37], v[176:179], v[192:195], v[34:37]
	v_mfma_f32_16x16x32_bf16 v[38:41], v[164:167], v[188:191], v[38:41]
	v_mfma_f32_16x16x32_bf16 v[38:41], v[168:171], v[192:195], v[38:41]
	v_mfma_f32_16x16x32_bf16 v[22:25], v[164:167], v[196:199], v[22:25]
	v_mfma_f32_16x16x32_bf16 v[22:25], v[168:171], v[200:203], v[22:25]
	v_mfma_f32_16x16x32_bf16 v[18:21], v[172:175], v[196:199], v[18:21]
	v_mfma_f32_16x16x32_bf16 v[18:21], v[176:179], v[200:203], v[18:21]
	s_setprio 2
	s_barrier
	v_mfma_f32_16x16x32_bf16 v[2:5], v[172:175], v[204:207], v[2:5]
	v_mfma_f32_16x16x32_bf16 v[2:5], v[176:179], v[208:211], v[2:5]
	v_mfma_f32_16x16x32_bf16 v[6:9], v[164:167], v[204:207], v[6:9]
	v_mfma_f32_16x16x32_bf16 v[6:9], v[168:171], v[208:211], v[6:9]
	s_setprio 0
	s_add_i32 s77, s77, 2
	s_add_u32 s73, s73, 0x100
	s_addc_u32 s74, s74, 0
	s_add_u32 s18, s18, 0x100
	s_addc_u32 s19, s19, 0
	s_add_u32 s75, s75, 0x100
	s_addc_u32 s76, s76, 0
	s_cmp_gt_u32 s77, 29
	.p2align 6
.LBB0_1224:
	ds_read_b128 v[148:151], v143
	ds_read_b128 v[152:155], v143 offset:1024
	ds_read_b128 v[156:159], v143 offset:2048
	ds_read_b128 v[160:163], v143 offset:3072
	ds_read_b128 v[164:167], v144
	ds_read_b128 v[168:171], v144 offset:1024
	ds_read_b128 v[172:175], v144 offset:2048
	ds_read_b128 v[176:179], v144 offset:3072
	s_cmp_eq_u32 s77, 28
	s_cselect_b32 s21, s9, s74
	s_cselect_b32 s20, s67, s73
	s_cselect_b32 s23, s11, s76
	s_cselect_b32 s22, s66, s75
	ds_read_b128 v[180:183], v145
	ds_read_b128 v[184:187], v145 offset:1024
	ds_read_b128 v[188:191], v145 offset:2048
	ds_read_b128 v[192:195], v145 offset:3072
	ds_read_b128 v[196:199], v145 offset:4096
	ds_read_b128 v[200:203], v145 offset:5120
	ds_read_b128 v[204:207], v145 offset:6144
	ds_read_b128 v[208:211], v145 offset:7168
	s_add_u32 s78, s18, 0xfff80000
	s_addc_u32 s79, s19, -1
	s_mov_b32 s80, m0
	s_mov_b32 m0, s56
	s_nop 0
	global_load_lds_dwordx4 v138, s[78:79]
	s_mov_b32 m0, s80
	s_nop 0
	s_mov_b32 s80, m0
	s_mov_b32 m0, s59
	s_nop 0
	global_load_lds_dwordx4 v140, s[78:79]
	s_mov_b32 m0, s80
	s_mov_b32 s78, m0
	s_mov_b32 m0, s57
	s_nop 0
	global_load_lds_dwordx4 v138, s[18:19]
	s_mov_b32 m0, s78
	s_nop 0
	s_mov_b32 s78, m0
	s_mov_b32 m0, s64
	s_nop 0
	global_load_lds_dwordx4 v140, s[18:19]
	s_mov_b32 m0, s78
	s_waitcnt vmcnt(8)
	s_waitcnt lgkmcnt(0)
	s_barrier
	s_setprio 1
	s_waitcnt lgkmcnt(7)
	v_mfma_f32_16x16x32_bf16 v[126:129], v[148:151], v[180:183], v[126:129]
	v_mfma_f32_16x16x32_bf16 v[126:129], v[152:155], v[184:187], v[126:129]
	s_waitcnt lgkmcnt(5)
	v_mfma_f32_16x16x32_bf16 v[122:125], v[156:159], v[180:183], v[122:125]
	v_mfma_f32_16x16x32_bf16 v[122:125], v[160:163], v[184:187], v[122:125]
	s_waitcnt lgkmcnt(3)
	v_mfma_f32_16x16x32_bf16 v[106:109], v[156:159], v[188:191], v[106:109]
	v_mfma_f32_16x16x32_bf16 v[106:109], v[160:163], v[192:195], v[106:109]
	s_waitcnt lgkmcnt(1)
	v_mfma_f32_16x16x32_bf16 v[110:113], v[148:151], v[188:191], v[110:113]
	v_mfma_f32_16x16x32_bf16 v[110:113], v[152:155], v[192:195], v[110:113]
	v_mfma_f32_16x16x32_bf16 v[94:97], v[148:151], v[196:199], v[94:97]
	v_mfma_f32_16x16x32_bf16 v[94:97], v[152:155], v[200:203], v[94:97]
	v_mfma_f32_16x16x32_bf16 v[90:93], v[156:159], v[196:199], v[90:93]
	v_mfma_f32_16x16x32_bf16 v[90:93], v[160:163], v[200:203], v[90:93]
	v_mfma_f32_16x16x32_bf16 v[74:77], v[156:159], v[204:207], v[74:77]
	v_mfma_f32_16x16x32_bf16 v[74:77], v[160:163], v[208:211], v[74:77]
	s_waitcnt lgkmcnt(0)
	v_mfma_f32_16x16x32_bf16 v[78:81], v[148:151], v[204:207], v[78:81]
	v_mfma_f32_16x16x32_bf16 v[78:81], v[152:155], v[208:211], v[78:81]
	s_setprio 0
	s_setprio 1
	v_mfma_f32_16x16x32_bf16 v[118:121], v[164:167], v[180:183], v[118:121]
	v_mfma_f32_16x16x32_bf16 v[118:121], v[168:171], v[184:187], v[118:121]
	v_mfma_f32_16x16x32_bf16 v[114:117], v[172:175], v[180:183], v[114:117]
	v_mfma_f32_16x16x32_bf16 v[114:117], v[176:179], v[184:187], v[114:117]
	v_mfma_f32_16x16x32_bf16 v[98:101], v[172:175], v[188:191], v[98:101]
	v_mfma_f32_16x16x32_bf16 v[98:101], v[176:179], v[192:195], v[98:101]
	v_mfma_f32_16x16x32_bf16 v[102:105], v[164:167], v[188:191], v[102:105]
	v_mfma_f32_16x16x32_bf16 v[102:105], v[168:171], v[192:195], v[102:105]
	v_mfma_f32_16x16x32_bf16 v[86:89], v[164:167], v[196:199], v[86:89]
	v_mfma_f32_16x16x32_bf16 v[86:89], v[168:171], v[200:203], v[86:89]
	v_mfma_f32_16x16x32_bf16 v[82:85], v[172:175], v[196:199], v[82:85]
	v_mfma_f32_16x16x32_bf16 v[82:85], v[176:179], v[200:203], v[82:85]
	s_setprio 2
	s_barrier
	v_mfma_f32_16x16x32_bf16 v[66:69], v[172:175], v[204:207], v[66:69]
	v_mfma_f32_16x16x32_bf16 v[66:69], v[176:179], v[208:211], v[66:69]
	v_mfma_f32_16x16x32_bf16 v[70:73], v[164:167], v[204:207], v[70:73]
	v_mfma_f32_16x16x32_bf16 v[70:73], v[168:171], v[208:211], v[70:73]
	s_setprio 0
	ds_read_b128 v[180:183], v145 offset:16384
	ds_read_b128 v[184:187], v145 offset:17408
	ds_read_b128 v[188:191], v145 offset:18432
	ds_read_b128 v[192:195], v145 offset:19456
	ds_read_b128 v[196:199], v145 offset:20480
	ds_read_b128 v[200:203], v145 offset:21504
	ds_read_b128 v[204:207], v145 offset:22528
	ds_read_b128 v[208:211], v145 offset:23552
	s_mov_b32 s78, m0
	s_mov_b32 m0, s35
	s_nop 0
	global_load_lds_dwordx4 v139, s[20:21]
	s_mov_b32 m0, s78
	s_nop 0
	s_mov_b32 s78, m0
	s_mov_b32 m0, s36
	s_nop 0
	global_load_lds_dwordx4 v141, s[20:21]
	s_mov_b32 m0, s78
	s_add_u32 s78, s20, 0x80000
	s_addc_u32 s79, s21, 0
	s_mov_b32 s80, m0
	s_mov_b32 m0, s37
	s_nop 0
	global_load_lds_dwordx4 v139, s[78:79]
	s_mov_b32 m0, s80
	s_nop 0
	s_mov_b32 s80, m0
	s_mov_b32 m0, s40
	s_nop 0
	global_load_lds_dwordx4 v141, s[78:79]
	s_mov_b32 m0, s80
	s_waitcnt vmcnt(4)
	s_waitcnt lgkmcnt(0)
	s_barrier
	s_setprio 1
	s_waitcnt lgkmcnt(7)
	v_mfma_f32_16x16x32_bf16 v[62:65], v[148:151], v[180:183], v[62:65]
	v_mfma_f32_16x16x32_bf16 v[62:65], v[152:155], v[184:187], v[62:65]
	s_waitcnt lgkmcnt(5)
	v_mfma_f32_16x16x32_bf16 v[58:61], v[156:159], v[180:183], v[58:61]
	v_mfma_f32_16x16x32_bf16 v[58:61], v[160:163], v[184:187], v[58:61]
	s_waitcnt lgkmcnt(3)
	v_mfma_f32_16x16x32_bf16 v[42:45], v[156:159], v[188:191], v[42:45]
	v_mfma_f32_16x16x32_bf16 v[42:45], v[160:163], v[192:195], v[42:45]
	s_waitcnt lgkmcnt(1)
	v_mfma_f32_16x16x32_bf16 v[46:49], v[148:151], v[188:191], v[46:49]
	v_mfma_f32_16x16x32_bf16 v[46:49], v[152:155], v[192:195], v[46:49]
	v_mfma_f32_16x16x32_bf16 v[30:33], v[148:151], v[196:199], v[30:33]
	v_mfma_f32_16x16x32_bf16 v[30:33], v[152:155], v[200:203], v[30:33]
	v_mfma_f32_16x16x32_bf16 v[26:29], v[156:159], v[196:199], v[26:29]
	v_mfma_f32_16x16x32_bf16 v[26:29], v[160:163], v[200:203], v[26:29]
	v_mfma_f32_16x16x32_bf16 v[10:13], v[156:159], v[204:207], v[10:13]
	v_mfma_f32_16x16x32_bf16 v[10:13], v[160:163], v[208:211], v[10:13]
	s_waitcnt lgkmcnt(0)
	v_mfma_f32_16x16x32_bf16 v[14:17], v[148:151], v[204:207], v[14:17]
	v_mfma_f32_16x16x32_bf16 v[14:17], v[152:155], v[208:211], v[14:17]
	s_setprio 0
	s_setprio 1
	v_mfma_f32_16x16x32_bf16 v[54:57], v[164:167], v[180:183], v[54:57]
	v_mfma_f32_16x16x32_bf16 v[54:57], v[168:171], v[184:187], v[54:57]
	v_mfma_f32_16x16x32_bf16 v[50:53], v[172:175], v[180:183], v[50:53]
	v_mfma_f32_16x16x32_bf16 v[50:53], v[176:179], v[184:187], v[50:53]
	v_mfma_f32_16x16x32_bf16 v[34:37], v[172:175], v[188:191], v[34:37]
	v_mfma_f32_16x16x32_bf16 v[34:37], v[176:179], v[192:195], v[34:37]
	v_mfma_f32_16x16x32_bf16 v[38:41], v[164:167], v[188:191], v[38:41]
	v_mfma_f32_16x16x32_bf16 v[38:41], v[168:171], v[192:195], v[38:41]
	v_mfma_f32_16x16x32_bf16 v[22:25], v[164:167], v[196:199], v[22:25]
	v_mfma_f32_16x16x32_bf16 v[22:25], v[168:171], v[200:203], v[22:25]
	v_mfma_f32_16x16x32_bf16 v[18:21], v[172:175], v[196:199], v[18:21]
	v_mfma_f32_16x16x32_bf16 v[18:21], v[176:179], v[200:203], v[18:21]
	s_setprio 2
	s_barrier
	v_mfma_f32_16x16x32_bf16 v[2:5], v[172:175], v[204:207], v[2:5]
	v_mfma_f32_16x16x32_bf16 v[2:5], v[176:179], v[208:211], v[2:5]
	v_mfma_f32_16x16x32_bf16 v[6:9], v[164:167], v[204:207], v[6:9]
	v_mfma_f32_16x16x32_bf16 v[6:9], v[168:171], v[208:211], v[6:9]
	s_setprio 0
	ds_read_b128 v[148:151], v146
	ds_read_b128 v[152:155], v146 offset:1024
	ds_read_b128 v[156:159], v146 offset:2048
	ds_read_b128 v[160:163], v146 offset:3072
	ds_read_b128 v[164:167], v147
	ds_read_b128 v[168:171], v147 offset:1024
	ds_read_b128 v[172:175], v147 offset:2048
	ds_read_b128 v[176:179], v147 offset:3072
	ds_read_b128 v[180:183], v145 offset:32768
	ds_read_b128 v[184:187], v145 offset:33792
	ds_read_b128 v[188:191], v145 offset:34816
	ds_read_b128 v[192:195], v145 offset:35840
	ds_read_b128 v[196:199], v145 offset:36864
	ds_read_b128 v[200:203], v145 offset:37888
	ds_read_b128 v[204:207], v145 offset:38912
	ds_read_b128 v[208:211], v145 offset:39936
	s_mov_b32 s78, m0
	s_mov_b32 m0, s31
	s_nop 0
	global_load_lds_dwordx4 v138, s[22:23]
	s_mov_b32 m0, s78
	s_nop 0
	s_mov_b32 s78, m0
	s_mov_b32 m0, s41
	s_nop 0
	global_load_lds_dwordx4 v140, s[22:23]
	s_mov_b32 m0, s78
	s_add_u32 s22, s22, 0x80000
	s_addc_u32 s23, s23, 0
	s_mov_b32 s78, m0
	s_mov_b32 m0, s42
	s_nop 0
	global_load_lds_dwordx4 v138, s[22:23]
	s_mov_b32 m0, s78
	s_nop 0
	s_mov_b32 s78, m0
	s_mov_b32 m0, s43
	s_nop 0
	global_load_lds_dwordx4 v140, s[22:23]
	s_mov_b32 m0, s78
	s_waitcnt vmcnt(8)
	s_waitcnt lgkmcnt(0)
	s_barrier
	s_setprio 1
	s_waitcnt lgkmcnt(7)
	v_mfma_f32_16x16x32_bf16 v[126:129], v[148:151], v[180:183], v[126:129]
	v_mfma_f32_16x16x32_bf16 v[126:129], v[152:155], v[184:187], v[126:129]
	s_waitcnt lgkmcnt(5)
	v_mfma_f32_16x16x32_bf16 v[122:125], v[156:159], v[180:183], v[122:125]
	v_mfma_f32_16x16x32_bf16 v[122:125], v[160:163], v[184:187], v[122:125]
	s_waitcnt lgkmcnt(3)
	v_mfma_f32_16x16x32_bf16 v[106:109], v[156:159], v[188:191], v[106:109]
	v_mfma_f32_16x16x32_bf16 v[106:109], v[160:163], v[192:195], v[106:109]
	s_waitcnt lgkmcnt(1)
	v_mfma_f32_16x16x32_bf16 v[110:113], v[148:151], v[188:191], v[110:113]
	v_mfma_f32_16x16x32_bf16 v[110:113], v[152:155], v[192:195], v[110:113]
	v_mfma_f32_16x16x32_bf16 v[94:97], v[148:151], v[196:199], v[94:97]
	v_mfma_f32_16x16x32_bf16 v[94:97], v[152:155], v[200:203], v[94:97]
	v_mfma_f32_16x16x32_bf16 v[90:93], v[156:159], v[196:199], v[90:93]
	v_mfma_f32_16x16x32_bf16 v[90:93], v[160:163], v[200:203], v[90:93]
	v_mfma_f32_16x16x32_bf16 v[74:77], v[156:159], v[204:207], v[74:77]
	v_mfma_f32_16x16x32_bf16 v[74:77], v[160:163], v[208:211], v[74:77]
	s_waitcnt lgkmcnt(0)
	v_mfma_f32_16x16x32_bf16 v[78:81], v[148:151], v[204:207], v[78:81]
	v_mfma_f32_16x16x32_bf16 v[78:81], v[152:155], v[208:211], v[78:81]
	s_setprio 0
	s_setprio 1
	v_mfma_f32_16x16x32_bf16 v[118:121], v[164:167], v[180:183], v[118:121]
	v_mfma_f32_16x16x32_bf16 v[118:121], v[168:171], v[184:187], v[118:121]
	v_mfma_f32_16x16x32_bf16 v[114:117], v[172:175], v[180:183], v[114:117]
	v_mfma_f32_16x16x32_bf16 v[114:117], v[176:179], v[184:187], v[114:117]
	v_mfma_f32_16x16x32_bf16 v[98:101], v[172:175], v[188:191], v[98:101]
	v_mfma_f32_16x16x32_bf16 v[98:101], v[176:179], v[192:195], v[98:101]
	v_mfma_f32_16x16x32_bf16 v[102:105], v[164:167], v[188:191], v[102:105]
	v_mfma_f32_16x16x32_bf16 v[102:105], v[168:171], v[192:195], v[102:105]
	v_mfma_f32_16x16x32_bf16 v[86:89], v[164:167], v[196:199], v[86:89]
	v_mfma_f32_16x16x32_bf16 v[86:89], v[168:171], v[200:203], v[86:89]
	v_mfma_f32_16x16x32_bf16 v[82:85], v[172:175], v[196:199], v[82:85]
	v_mfma_f32_16x16x32_bf16 v[82:85], v[176:179], v[200:203], v[82:85]
	s_setprio 2
	s_barrier
	v_mfma_f32_16x16x32_bf16 v[66:69], v[172:175], v[204:207], v[66:69]
	v_mfma_f32_16x16x32_bf16 v[66:69], v[176:179], v[208:211], v[66:69]
	v_mfma_f32_16x16x32_bf16 v[70:73], v[164:167], v[204:207], v[70:73]
	v_mfma_f32_16x16x32_bf16 v[70:73], v[168:171], v[208:211], v[70:73]
	s_setprio 0
	ds_read_b128 v[180:183], v145 offset:49152
	ds_read_b128 v[184:187], v145 offset:50176
	ds_read_b128 v[188:191], v145 offset:51200
	ds_read_b128 v[192:195], v145 offset:52224
	ds_read_b128 v[196:199], v145 offset:53248
	ds_read_b128 v[200:203], v145 offset:54272
	ds_read_b128 v[204:207], v145 offset:55296
	ds_read_b128 v[208:211], v145 offset:56320
	s_add_u32 s22, s20, 0x80
	s_addc_u32 s23, s21, 0
	s_mov_b32 s78, m0
	s_mov_b32 m0, s46
	s_nop 0
	global_load_lds_dwordx4 v139, s[22:23]
	s_mov_b32 m0, s78
	s_add_u32 s20, s20, 0x80080
	s_mov_b32 s78, m0
	s_mov_b32 m0, s47
	s_nop 0
	global_load_lds_dwordx4 v141, s[22:23]
	s_mov_b32 m0, s78
	s_addc_u32 s21, s21, 0
	s_mov_b32 s22, m0
	s_mov_b32 m0, s48
	s_nop 0
	global_load_lds_dwordx4 v139, s[20:21]
	s_mov_b32 m0, s22
	s_nop 0
	s_mov_b32 s22, m0
	s_mov_b32 m0, s49
	s_nop 0
	global_load_lds_dwordx4 v141, s[20:21]
	s_mov_b32 m0, s22
	s_waitcnt vmcnt(4)
	s_waitcnt lgkmcnt(0)
	s_barrier
	s_setprio 1
	s_waitcnt lgkmcnt(7)
	v_mfma_f32_16x16x32_bf16 v[62:65], v[148:151], v[180:183], v[62:65]
	v_mfma_f32_16x16x32_bf16 v[62:65], v[152:155], v[184:187], v[62:65]
	s_waitcnt lgkmcnt(5)
	v_mfma_f32_16x16x32_bf16 v[58:61], v[156:159], v[180:183], v[58:61]
	v_mfma_f32_16x16x32_bf16 v[58:61], v[160:163], v[184:187], v[58:61]
	s_waitcnt lgkmcnt(3)
	v_mfma_f32_16x16x32_bf16 v[42:45], v[156:159], v[188:191], v[42:45]
	v_mfma_f32_16x16x32_bf16 v[42:45], v[160:163], v[192:195], v[42:45]
	s_waitcnt lgkmcnt(1)
	v_mfma_f32_16x16x32_bf16 v[46:49], v[148:151], v[188:191], v[46:49]
	v_mfma_f32_16x16x32_bf16 v[46:49], v[152:155], v[192:195], v[46:49]
	v_mfma_f32_16x16x32_bf16 v[30:33], v[148:151], v[196:199], v[30:33]
	v_mfma_f32_16x16x32_bf16 v[30:33], v[152:155], v[200:203], v[30:33]
	v_mfma_f32_16x16x32_bf16 v[26:29], v[156:159], v[196:199], v[26:29]
	v_mfma_f32_16x16x32_bf16 v[26:29], v[160:163], v[200:203], v[26:29]
	v_mfma_f32_16x16x32_bf16 v[10:13], v[156:159], v[204:207], v[10:13]
	v_mfma_f32_16x16x32_bf16 v[10:13], v[160:163], v[208:211], v[10:13]
	s_waitcnt lgkmcnt(0)
	v_mfma_f32_16x16x32_bf16 v[14:17], v[148:151], v[204:207], v[14:17]
	v_mfma_f32_16x16x32_bf16 v[14:17], v[152:155], v[208:211], v[14:17]
	s_setprio 0
	s_setprio 1
	v_mfma_f32_16x16x32_bf16 v[54:57], v[164:167], v[180:183], v[54:57]
	v_mfma_f32_16x16x32_bf16 v[54:57], v[168:171], v[184:187], v[54:57]
	v_mfma_f32_16x16x32_bf16 v[50:53], v[172:175], v[180:183], v[50:53]
	v_mfma_f32_16x16x32_bf16 v[50:53], v[176:179], v[184:187], v[50:53]
	v_mfma_f32_16x16x32_bf16 v[34:37], v[172:175], v[188:191], v[34:37]
	v_mfma_f32_16x16x32_bf16 v[34:37], v[176:179], v[192:195], v[34:37]
	v_mfma_f32_16x16x32_bf16 v[38:41], v[164:167], v[188:191], v[38:41]
	v_mfma_f32_16x16x32_bf16 v[38:41], v[168:171], v[192:195], v[38:41]
	v_mfma_f32_16x16x32_bf16 v[22:25], v[164:167], v[196:199], v[22:25]
	v_mfma_f32_16x16x32_bf16 v[22:25], v[168:171], v[200:203], v[22:25]
	v_mfma_f32_16x16x32_bf16 v[18:21], v[172:175], v[196:199], v[18:21]
	v_mfma_f32_16x16x32_bf16 v[18:21], v[176:179], v[200:203], v[18:21]
	s_setprio 2
	s_barrier
	v_mfma_f32_16x16x32_bf16 v[2:5], v[172:175], v[204:207], v[2:5]
	v_mfma_f32_16x16x32_bf16 v[2:5], v[176:179], v[208:211], v[2:5]
	v_mfma_f32_16x16x32_bf16 v[6:9], v[164:167], v[204:207], v[6:9]
	v_mfma_f32_16x16x32_bf16 v[6:9], v[168:171], v[208:211], v[6:9]
	s_setprio 0
	s_add_i32 s77, s77, 2
	s_add_u32 s73, s73, 0x100
	s_addc_u32 s74, s74, 0
	s_add_u32 s18, s18, 0x100
	s_addc_u32 s19, s19, 0
	s_add_u32 s75, s75, 0x100
	s_addc_u32 s76, s76, 0
	s_cmp_gt_u32 s77, 29
	s_cbranch_scc0 .LBB0_1224
	s_and_b64 vcc, exec, s[6:7]
	s_cbranch_vccz .LBB0_1227
	s_barrier

.LBB0_1356:
	s_ashr_i32 s13, s12, 31
	s_lshl_b64 s[14:15], s[12:13], 15
	s_add_u32 s14, s28, s14
	s_addc_u32 s15, s29, s15
	s_and_b64 s[16:17], s[2:3], exec
	s_cselect_b32 s13, s15, s23
	s_cselect_b32 s67, s14, s22
	s_ashr_i32 s11, s10, 31
	s_lshl_b64 s[16:17], s[10:11], 15
	s_add_u32 s16, s30, s16
	s_addc_u32 s17, s31, s17
	s_and_b64 s[24:25], s[2:3], exec
	s_cselect_b32 s11, s17, s21
	s_cselect_b32 s73, s16, s20
	s_add_u32 s74, s20, 0x80000
	s_addc_u32 s75, s21, 0
	s_add_u32 s20, s22, 0x204000
	s_addc_u32 s21, s23, 0
	s_add_u32 s76, s22, 0x400000
	s_addc_u32 s77, s23, 0
	s_mov_b32 s78, -2
	s_waitcnt vmcnt(25)
	s_waitcnt vmcnt(24)
	s_waitcnt vmcnt(15)
	s_waitcnt vmcnt(14)
	s_waitcnt vmcnt(13)
	s_waitcnt vmcnt(12)
	s_waitcnt vmcnt(11)
	s_waitcnt vmcnt(10)
	s_waitcnt vmcnt(9)
	s_waitcnt vmcnt(8)
	s_waitcnt vmcnt(7)
	s_waitcnt vmcnt(6)
	s_waitcnt vmcnt(5)
	s_waitcnt vmcnt(4)
	s_waitcnt vmcnt(3)
	s_waitcnt vmcnt(2)
	s_waitcnt vmcnt(1)
	s_waitcnt vmcnt(0)
	ds_read_b128 v[130:133], v181
	ds_read_b128 v[134:137], v181 offset:1024
	ds_read_b128 v[138:141], v181 offset:2048
	ds_read_b128 v[142:145], v181 offset:3072
	ds_read_b128 v[150:153], v182
	ds_read_b128 v[154:157], v182 offset:1024
	ds_read_b128 v[158:161], v182 offset:2048
	ds_read_b128 v[162:165], v182 offset:3072
	s_cmpk_eq_i32 s78, 0x52
	s_cselect_b32 s23, s11, s75
	s_cselect_b32 s22, s73, s74
	s_cselect_b32 s25, s13, s77
	s_cselect_b32 s24, s67, s76
	ds_read_b128 v[166:169], v183
	ds_read_b128 v[170:173], v183 offset:1024
	ds_read_b128 v[186:189], v183 offset:2048
	ds_read_b128 v[190:193], v183 offset:3072
	ds_read_b128 v[194:197], v183 offset:4096
	ds_read_b128 v[198:201], v183 offset:5120
	ds_read_b128 v[202:205], v183 offset:6144
	ds_read_b128 v[206:209], v183 offset:7168
	s_add_u32 s80, s20, 0xffffc000
	s_addc_u32 s81, s21, -1
	s_mov_b32 s79, m0
	s_mov_b32 m0, s58
	s_nop 0
	global_load_lds_dwordx4 v1, s[80:81]
	s_mov_b32 m0, s79
	s_nop 0
	s_mov_b32 s79, m0
	s_mov_b32 m0, s64
	s_nop 0
	global_load_lds_dwordx4 v177, s[80:81]
	s_mov_b32 m0, s79
	s_nop 0
	s_mov_b32 s79, m0
	s_mov_b32 m0, s59
	s_nop 0
	global_load_lds_dwordx4 v1, s[20:21]
	s_mov_b32 m0, s79
	s_nop 0
	s_mov_b32 s79, m0
	s_mov_b32 m0, s65
	s_nop 0
	global_load_lds_dwordx4 v177, s[20:21]
	s_mov_b32 m0, s79
	s_waitcnt vmcnt(8)
	s_waitcnt lgkmcnt(0)
	s_barrier
	s_setprio 1
	s_waitcnt lgkmcnt(7)
	v_mfma_f32_16x16x32_bf16 v[126:129], v[130:133], v[166:169], 0
	v_mfma_f32_16x16x32_bf16 v[126:129], v[134:137], v[170:173], v[126:129]
	s_waitcnt lgkmcnt(5)
	v_mfma_f32_16x16x32_bf16 v[122:125], v[138:141], v[166:169], 0
	v_mfma_f32_16x16x32_bf16 v[122:125], v[142:145], v[170:173], v[122:125]
	s_waitcnt lgkmcnt(3)
	v_mfma_f32_16x16x32_bf16 v[110:113], v[138:141], v[186:189], 0
	v_mfma_f32_16x16x32_bf16 v[110:113], v[142:145], v[190:193], v[110:113]
	s_waitcnt lgkmcnt(1)
	v_mfma_f32_16x16x32_bf16 v[118:121], v[130:133], v[186:189], 0
	v_mfma_f32_16x16x32_bf16 v[118:121], v[134:137], v[190:193], v[118:121]
	v_mfma_f32_16x16x32_bf16 v[94:97], v[130:133], v[194:197], 0
	v_mfma_f32_16x16x32_bf16 v[94:97], v[134:137], v[198:201], v[94:97]
	v_mfma_f32_16x16x32_bf16 v[90:93], v[138:141], v[194:197], 0
	v_mfma_f32_16x16x32_bf16 v[90:93], v[142:145], v[198:201], v[90:93]
	v_mfma_f32_16x16x32_bf16 v[78:81], v[138:141], v[202:205], 0
	v_mfma_f32_16x16x32_bf16 v[78:81], v[142:145], v[206:209], v[78:81]
	s_waitcnt lgkmcnt(0)
	v_mfma_f32_16x16x32_bf16 v[86:89], v[130:133], v[202:205], 0
	v_mfma_f32_16x16x32_bf16 v[86:89], v[134:137], v[206:209], v[86:89]
	s_setprio 0
	s_setprio 1
	v_mfma_f32_16x16x32_bf16 v[114:117], v[150:153], v[166:169], 0
	v_mfma_f32_16x16x32_bf16 v[114:117], v[154:157], v[170:173], v[114:117]
	v_mfma_f32_16x16x32_bf16 v[106:109], v[158:161], v[166:169], 0
	v_mfma_f32_16x16x32_bf16 v[106:109], v[162:165], v[170:173], v[106:109]
	v_mfma_f32_16x16x32_bf16 v[98:101], v[158:161], v[186:189], 0
	v_mfma_f32_16x16x32_bf16 v[98:101], v[162:165], v[190:193], v[98:101]
	v_mfma_f32_16x16x32_bf16 v[102:105], v[150:153], v[186:189], 0
	v_mfma_f32_16x16x32_bf16 v[102:105], v[154:157], v[190:193], v[102:105]
	v_mfma_f32_16x16x32_bf16 v[82:85], v[150:153], v[194:197], 0
	v_mfma_f32_16x16x32_bf16 v[82:85], v[154:157], v[198:201], v[82:85]
	v_mfma_f32_16x16x32_bf16 v[74:77], v[158:161], v[194:197], 0
	v_mfma_f32_16x16x32_bf16 v[74:77], v[162:165], v[198:201], v[74:77]
	s_setprio 2
	s_barrier
	v_mfma_f32_16x16x32_bf16 v[66:69], v[158:161], v[202:205], 0
	v_mfma_f32_16x16x32_bf16 v[66:69], v[162:165], v[206:209], v[66:69]
	v_mfma_f32_16x16x32_bf16 v[70:73], v[150:153], v[202:205], 0
	v_mfma_f32_16x16x32_bf16 v[70:73], v[154:157], v[206:209], v[70:73]
	s_setprio 0
	ds_read_b128 v[166:169], v183 offset:16384
	ds_read_b128 v[170:173], v183 offset:17408
	ds_read_b128 v[186:189], v183 offset:18432
	ds_read_b128 v[190:193], v183 offset:19456
	ds_read_b128 v[194:197], v183 offset:20480
	ds_read_b128 v[198:201], v183 offset:21504
	ds_read_b128 v[202:205], v183 offset:22528
	ds_read_b128 v[206:209], v183 offset:23552
	s_mov_b32 s79, m0
	s_mov_b32 m0, s35
	s_nop 0
	global_load_lds_dwordx4 v176, s[22:23]
	s_mov_b32 m0, s79
	s_add_u32 s80, s22, 0x4000
	s_mov_b32 s79, m0
	s_mov_b32 m0, s36
	s_nop 0
	global_load_lds_dwordx4 v178, s[22:23]
	s_mov_b32 m0, s79
	s_addc_u32 s81, s23, 0
	s_mov_b32 s79, m0
	s_mov_b32 m0, s37
	s_nop 0
	global_load_lds_dwordx4 v176, s[80:81]
	s_mov_b32 m0, s79
	s_nop 0
	s_mov_b32 s79, m0
	s_mov_b32 m0, s40
	s_nop 0
	global_load_lds_dwordx4 v178, s[80:81]
	s_mov_b32 m0, s79
	s_waitcnt vmcnt(4)
	s_waitcnt lgkmcnt(0)
	s_barrier
	s_setprio 1
	s_waitcnt lgkmcnt(7)
	v_mfma_f32_16x16x32_bf16 v[62:65], v[130:133], v[166:169], 0
	v_mfma_f32_16x16x32_bf16 v[62:65], v[134:137], v[170:173], v[62:65]
	s_waitcnt lgkmcnt(5)
	v_mfma_f32_16x16x32_bf16 v[58:61], v[138:141], v[166:169], 0
	v_mfma_f32_16x16x32_bf16 v[58:61], v[142:145], v[170:173], v[58:61]
	s_waitcnt lgkmcnt(3)
	v_mfma_f32_16x16x32_bf16 v[42:45], v[138:141], v[186:189], 0
	v_mfma_f32_16x16x32_bf16 v[42:45], v[142:145], v[190:193], v[42:45]
	s_waitcnt lgkmcnt(1)
	v_mfma_f32_16x16x32_bf16 v[46:49], v[130:133], v[186:189], 0
	v_mfma_f32_16x16x32_bf16 v[46:49], v[134:137], v[190:193], v[46:49]
	v_mfma_f32_16x16x32_bf16 v[30:33], v[130:133], v[194:197], 0
	v_mfma_f32_16x16x32_bf16 v[30:33], v[134:137], v[198:201], v[30:33]
	v_mfma_f32_16x16x32_bf16 v[26:29], v[138:141], v[194:197], 0
	v_mfma_f32_16x16x32_bf16 v[26:29], v[142:145], v[198:201], v[26:29]
	v_mfma_f32_16x16x32_bf16 v[10:13], v[138:141], v[202:205], 0
	v_mfma_f32_16x16x32_bf16 v[10:13], v[142:145], v[206:209], v[10:13]
	s_waitcnt lgkmcnt(0)
	v_mfma_f32_16x16x32_bf16 v[14:17], v[130:133], v[202:205], 0
	v_mfma_f32_16x16x32_bf16 v[14:17], v[134:137], v[206:209], v[14:17]
	s_setprio 0
	s_setprio 1
	v_mfma_f32_16x16x32_bf16 v[54:57], v[150:153], v[166:169], 0
	v_mfma_f32_16x16x32_bf16 v[54:57], v[154:157], v[170:173], v[54:57]
	v_mfma_f32_16x16x32_bf16 v[50:53], v[158:161], v[166:169], 0
	v_mfma_f32_16x16x32_bf16 v[50:53], v[162:165], v[170:173], v[50:53]
	v_mfma_f32_16x16x32_bf16 v[34:37], v[158:161], v[186:189], 0
	v_mfma_f32_16x16x32_bf16 v[34:37], v[162:165], v[190:193], v[34:37]
	v_mfma_f32_16x16x32_bf16 v[38:41], v[150:153], v[186:189], 0
	v_mfma_f32_16x16x32_bf16 v[38:41], v[154:157], v[190:193], v[38:41]
	v_mfma_f32_16x16x32_bf16 v[22:25], v[150:153], v[194:197], 0
	v_mfma_f32_16x16x32_bf16 v[22:25], v[154:157], v[198:201], v[22:25]
	v_mfma_f32_16x16x32_bf16 v[18:21], v[158:161], v[194:197], 0
	v_mfma_f32_16x16x32_bf16 v[18:21], v[162:165], v[198:201], v[18:21]
	s_setprio 2
	s_barrier
	v_mfma_f32_16x16x32_bf16 v[2:5], v[158:161], v[202:205], 0
	v_mfma_f32_16x16x32_bf16 v[2:5], v[162:165], v[206:209], v[2:5]
	v_mfma_f32_16x16x32_bf16 v[6:9], v[150:153], v[202:205], 0
	v_mfma_f32_16x16x32_bf16 v[6:9], v[154:157], v[206:209], v[6:9]
	s_setprio 0
	ds_read_b128 v[130:133], v184
	ds_read_b128 v[134:137], v184 offset:1024
	ds_read_b128 v[138:141], v184 offset:2048
	ds_read_b128 v[142:145], v184 offset:3072
	ds_read_b128 v[150:153], v185
	ds_read_b128 v[154:157], v185 offset:1024
	ds_read_b128 v[158:161], v185 offset:2048
	ds_read_b128 v[162:165], v185 offset:3072
	ds_read_b128 v[166:169], v183 offset:32768
	ds_read_b128 v[170:173], v183 offset:33792
	ds_read_b128 v[186:189], v183 offset:34816
	ds_read_b128 v[190:193], v183 offset:35840
	ds_read_b128 v[194:197], v183 offset:36864
	ds_read_b128 v[198:201], v183 offset:37888
	ds_read_b128 v[202:205], v183 offset:38912
	ds_read_b128 v[206:209], v183 offset:39936
	s_mov_b32 s79, m0
	s_mov_b32 m0, s34
	s_nop 0
	global_load_lds_dwordx4 v1, s[24:25]
	s_mov_b32 m0, s79
	s_nop 0
	s_mov_b32 s79, m0
	s_mov_b32 m0, s41
	s_nop 0
	global_load_lds_dwordx4 v177, s[24:25]
	s_mov_b32 m0, s79
	s_add_u32 s24, s24, 0x4000
	s_addc_u32 s25, s25, 0
	s_mov_b32 s79, m0
	s_mov_b32 m0, s42
	s_nop 0
	global_load_lds_dwordx4 v1, s[24:25]
	s_mov_b32 m0, s79
	s_nop 0
	s_mov_b32 s79, m0
	s_mov_b32 m0, s43
	s_nop 0
	global_load_lds_dwordx4 v177, s[24:25]
	s_mov_b32 m0, s79
	s_waitcnt vmcnt(8)
	s_waitcnt lgkmcnt(0)
	s_barrier
	s_setprio 1
	s_waitcnt lgkmcnt(7)
	v_mfma_f32_16x16x32_bf16 v[126:129], v[130:133], v[166:169], v[126:129]
	v_mfma_f32_16x16x32_bf16 v[126:129], v[134:137], v[170:173], v[126:129]
	s_waitcnt lgkmcnt(5)
	v_mfma_f32_16x16x32_bf16 v[122:125], v[138:141], v[166:169], v[122:125]
	v_mfma_f32_16x16x32_bf16 v[122:125], v[142:145], v[170:173], v[122:125]
	s_waitcnt lgkmcnt(3)
	v_mfma_f32_16x16x32_bf16 v[110:113], v[138:141], v[186:189], v[110:113]
	v_mfma_f32_16x16x32_bf16 v[110:113], v[142:145], v[190:193], v[110:113]
	s_waitcnt lgkmcnt(1)
	v_mfma_f32_16x16x32_bf16 v[118:121], v[130:133], v[186:189], v[118:121]
	v_mfma_f32_16x16x32_bf16 v[118:121], v[134:137], v[190:193], v[118:121]
	v_mfma_f32_16x16x32_bf16 v[94:97], v[130:133], v[194:197], v[94:97]
	v_mfma_f32_16x16x32_bf16 v[94:97], v[134:137], v[198:201], v[94:97]
	v_mfma_f32_16x16x32_bf16 v[90:93], v[138:141], v[194:197], v[90:93]
	v_mfma_f32_16x16x32_bf16 v[90:93], v[142:145], v[198:201], v[90:93]
	v_mfma_f32_16x16x32_bf16 v[78:81], v[138:141], v[202:205], v[78:81]
	v_mfma_f32_16x16x32_bf16 v[78:81], v[142:145], v[206:209], v[78:81]
	s_waitcnt lgkmcnt(0)
	v_mfma_f32_16x16x32_bf16 v[86:89], v[130:133], v[202:205], v[86:89]
	v_mfma_f32_16x16x32_bf16 v[86:89], v[134:137], v[206:209], v[86:89]
	s_setprio 0
	s_setprio 1
	v_mfma_f32_16x16x32_bf16 v[114:117], v[150:153], v[166:169], v[114:117]
	v_mfma_f32_16x16x32_bf16 v[114:117], v[154:157], v[170:173], v[114:117]
	v_mfma_f32_16x16x32_bf16 v[106:109], v[158:161], v[166:169], v[106:109]
	v_mfma_f32_16x16x32_bf16 v[106:109], v[162:165], v[170:173], v[106:109]
	v_mfma_f32_16x16x32_bf16 v[98:101], v[158:161], v[186:189], v[98:101]
	v_mfma_f32_16x16x32_bf16 v[98:101], v[162:165], v[190:193], v[98:101]
	v_mfma_f32_16x16x32_bf16 v[102:105], v[150:153], v[186:189], v[102:105]
	v_mfma_f32_16x16x32_bf16 v[102:105], v[154:157], v[190:193], v[102:105]
	v_mfma_f32_16x16x32_bf16 v[82:85], v[150:153], v[194:197], v[82:85]
	v_mfma_f32_16x16x32_bf16 v[82:85], v[154:157], v[198:201], v[82:85]
	v_mfma_f32_16x16x32_bf16 v[74:77], v[158:161], v[194:197], v[74:77]
	v_mfma_f32_16x16x32_bf16 v[74:77], v[162:165], v[198:201], v[74:77]
	s_setprio 2
	s_barrier
	v_mfma_f32_16x16x32_bf16 v[66:69], v[158:161], v[202:205], v[66:69]
	v_mfma_f32_16x16x32_bf16 v[66:69], v[162:165], v[206:209], v[66:69]
	v_mfma_f32_16x16x32_bf16 v[70:73], v[150:153], v[202:205], v[70:73]
	v_mfma_f32_16x16x32_bf16 v[70:73], v[154:157], v[206:209], v[70:73]
	s_setprio 0
	ds_read_b128 v[166:169], v183 offset:49152
	ds_read_b128 v[170:173], v183 offset:50176
	ds_read_b128 v[186:189], v183 offset:51200
	ds_read_b128 v[190:193], v183 offset:52224
	ds_read_b128 v[194:197], v183 offset:53248
	ds_read_b128 v[198:201], v183 offset:54272
	ds_read_b128 v[202:205], v183 offset:55296
	ds_read_b128 v[206:209], v183 offset:56320
	s_add_u32 s24, s22, 0x40000
	s_addc_u32 s25, s23, 0
	s_mov_b32 s79, m0
	s_mov_b32 m0, s46
	s_nop 0
	global_load_lds_dwordx4 v176, s[24:25]
	s_mov_b32 m0, s79
	s_add_u32 s22, s22, 0x44000
	s_mov_b32 s79, m0
	s_mov_b32 m0, s47
	s_nop 0
	global_load_lds_dwordx4 v178, s[24:25]
	s_mov_b32 m0, s79
	s_addc_u32 s23, s23, 0
	s_mov_b32 s24, m0
	s_mov_b32 m0, s48
	s_nop 0
	global_load_lds_dwordx4 v176, s[22:23]
	s_mov_b32 m0, s24
	s_nop 0
	s_mov_b32 s24, m0
	s_mov_b32 m0, s49
	s_nop 0
	global_load_lds_dwordx4 v178, s[22:23]
	s_mov_b32 m0, s24
	s_waitcnt vmcnt(4)
	s_waitcnt lgkmcnt(0)
	s_barrier
	s_setprio 1
	s_waitcnt lgkmcnt(7)
	v_mfma_f32_16x16x32_bf16 v[62:65], v[130:133], v[166:169], v[62:65]
	v_mfma_f32_16x16x32_bf16 v[62:65], v[134:137], v[170:173], v[62:65]
	s_waitcnt lgkmcnt(5)
	v_mfma_f32_16x16x32_bf16 v[58:61], v[138:141], v[166:169], v[58:61]
	v_mfma_f32_16x16x32_bf16 v[58:61], v[142:145], v[170:173], v[58:61]
	s_waitcnt lgkmcnt(3)
	v_mfma_f32_16x16x32_bf16 v[42:45], v[138:141], v[186:189], v[42:45]
	v_mfma_f32_16x16x32_bf16 v[42:45], v[142:145], v[190:193], v[42:45]
	s_waitcnt lgkmcnt(1)
	v_mfma_f32_16x16x32_bf16 v[46:49], v[130:133], v[186:189], v[46:49]
	v_mfma_f32_16x16x32_bf16 v[46:49], v[134:137], v[190:193], v[46:49]
	v_mfma_f32_16x16x32_bf16 v[30:33], v[130:133], v[194:197], v[30:33]
	v_mfma_f32_16x16x32_bf16 v[30:33], v[134:137], v[198:201], v[30:33]
	v_mfma_f32_16x16x32_bf16 v[26:29], v[138:141], v[194:197], v[26:29]
	v_mfma_f32_16x16x32_bf16 v[26:29], v[142:145], v[198:201], v[26:29]
	v_mfma_f32_16x16x32_bf16 v[10:13], v[138:141], v[202:205], v[10:13]
	v_mfma_f32_16x16x32_bf16 v[10:13], v[142:145], v[206:209], v[10:13]
	s_waitcnt lgkmcnt(0)
	v_mfma_f32_16x16x32_bf16 v[14:17], v[130:133], v[202:205], v[14:17]
	v_mfma_f32_16x16x32_bf16 v[14:17], v[134:137], v[206:209], v[14:17]
	s_setprio 0
	s_setprio 1
	v_mfma_f32_16x16x32_bf16 v[54:57], v[150:153], v[166:169], v[54:57]
	v_mfma_f32_16x16x32_bf16 v[54:57], v[154:157], v[170:173], v[54:57]
	v_mfma_f32_16x16x32_bf16 v[50:53], v[158:161], v[166:169], v[50:53]
	v_mfma_f32_16x16x32_bf16 v[50:53], v[162:165], v[170:173], v[50:53]
	v_mfma_f32_16x16x32_bf16 v[34:37], v[158:161], v[186:189], v[34:37]
	v_mfma_f32_16x16x32_bf16 v[34:37], v[162:165], v[190:193], v[34:37]
	v_mfma_f32_16x16x32_bf16 v[38:41], v[150:153], v[186:189], v[38:41]
	v_mfma_f32_16x16x32_bf16 v[38:41], v[154:157], v[190:193], v[38:41]
	v_mfma_f32_16x16x32_bf16 v[22:25], v[150:153], v[194:197], v[22:25]
	v_mfma_f32_16x16x32_bf16 v[22:25], v[154:157], v[198:201], v[22:25]
	v_mfma_f32_16x16x32_bf16 v[18:21], v[158:161], v[194:197], v[18:21]
	v_mfma_f32_16x16x32_bf16 v[18:21], v[162:165], v[198:201], v[18:21]
	s_setprio 2
	s_barrier
	v_mfma_f32_16x16x32_bf16 v[2:5], v[158:161], v[202:205], v[2:5]
	v_mfma_f32_16x16x32_bf16 v[2:5], v[162:165], v[206:209], v[2:5]
	v_mfma_f32_16x16x32_bf16 v[6:9], v[150:153], v[202:205], v[6:9]
	v_mfma_f32_16x16x32_bf16 v[6:9], v[154:157], v[206:209], v[6:9]
	s_setprio 0
	s_add_i32 s78, s78, 2
	s_add_u32 s74, s74, 0x80000
	s_addc_u32 s75, s75, 0
	s_add_u32 s20, s20, 0x400000
	s_addc_u32 s21, s21, 0
	s_add_u32 s76, s76, 0x400000
	s_addc_u32 s77, s77, 0
	s_cmpk_gt_u32 s78, 0x53
	.p2align 6
.LBB0_1357:
	ds_read_b128 v[130:133], v181
	ds_read_b128 v[134:137], v181 offset:1024
	ds_read_b128 v[138:141], v181 offset:2048
	ds_read_b128 v[142:145], v181 offset:3072
	ds_read_b128 v[150:153], v182
	ds_read_b128 v[154:157], v182 offset:1024
	ds_read_b128 v[158:161], v182 offset:2048
	ds_read_b128 v[162:165], v182 offset:3072
	s_cmpk_eq_i32 s78, 0x52
	s_cselect_b32 s23, s11, s75
	s_cselect_b32 s22, s73, s74
	s_cselect_b32 s25, s13, s77
	s_cselect_b32 s24, s67, s76
	ds_read_b128 v[166:169], v183
	ds_read_b128 v[170:173], v183 offset:1024
	ds_read_b128 v[186:189], v183 offset:2048
	ds_read_b128 v[190:193], v183 offset:3072
	ds_read_b128 v[194:197], v183 offset:4096
	ds_read_b128 v[198:201], v183 offset:5120
	ds_read_b128 v[202:205], v183 offset:6144
	ds_read_b128 v[206:209], v183 offset:7168
	s_add_u32 s80, s20, 0xffffc000
	s_addc_u32 s81, s21, -1
	s_mov_b32 s79, m0
	s_mov_b32 m0, s58
	s_nop 0
	global_load_lds_dwordx4 v1, s[80:81]
	s_mov_b32 m0, s79
	s_nop 0
	s_mov_b32 s79, m0
	s_mov_b32 m0, s64
	s_nop 0
	global_load_lds_dwordx4 v177, s[80:81]
	s_mov_b32 m0, s79
	s_nop 0
	s_mov_b32 s79, m0
	s_mov_b32 m0, s59
	s_nop 0
	global_load_lds_dwordx4 v1, s[20:21]
	s_mov_b32 m0, s79
	s_nop 0
	s_mov_b32 s79, m0
	s_mov_b32 m0, s65
	s_nop 0
	global_load_lds_dwordx4 v177, s[20:21]
	s_mov_b32 m0, s79
	s_waitcnt vmcnt(8)
	s_waitcnt lgkmcnt(0)
	s_barrier
	s_setprio 1
	s_waitcnt lgkmcnt(7)
	v_mfma_f32_16x16x32_bf16 v[126:129], v[130:133], v[166:169], v[126:129]
	v_mfma_f32_16x16x32_bf16 v[126:129], v[134:137], v[170:173], v[126:129]
	s_waitcnt lgkmcnt(5)
	v_mfma_f32_16x16x32_bf16 v[122:125], v[138:141], v[166:169], v[122:125]
	v_mfma_f32_16x16x32_bf16 v[122:125], v[142:145], v[170:173], v[122:125]
	s_waitcnt lgkmcnt(3)
	v_mfma_f32_16x16x32_bf16 v[110:113], v[138:141], v[186:189], v[110:113]
	v_mfma_f32_16x16x32_bf16 v[110:113], v[142:145], v[190:193], v[110:113]
	s_waitcnt lgkmcnt(1)
	v_mfma_f32_16x16x32_bf16 v[118:121], v[130:133], v[186:189], v[118:121]
	v_mfma_f32_16x16x32_bf16 v[118:121], v[134:137], v[190:193], v[118:121]
	v_mfma_f32_16x16x32_bf16 v[94:97], v[130:133], v[194:197], v[94:97]
	v_mfma_f32_16x16x32_bf16 v[94:97], v[134:137], v[198:201], v[94:97]
	v_mfma_f32_16x16x32_bf16 v[90:93], v[138:141], v[194:197], v[90:93]
	v_mfma_f32_16x16x32_bf16 v[90:93], v[142:145], v[198:201], v[90:93]
	v_mfma_f32_16x16x32_bf16 v[78:81], v[138:141], v[202:205], v[78:81]
	v_mfma_f32_16x16x32_bf16 v[78:81], v[142:145], v[206:209], v[78:81]
	s_waitcnt lgkmcnt(0)
	v_mfma_f32_16x16x32_bf16 v[86:89], v[130:133], v[202:205], v[86:89]
	v_mfma_f32_16x16x32_bf16 v[86:89], v[134:137], v[206:209], v[86:89]
	s_setprio 0
	s_setprio 1
	v_mfma_f32_16x16x32_bf16 v[114:117], v[150:153], v[166:169], v[114:117]
	v_mfma_f32_16x16x32_bf16 v[114:117], v[154:157], v[170:173], v[114:117]
	v_mfma_f32_16x16x32_bf16 v[106:109], v[158:161], v[166:169], v[106:109]
	v_mfma_f32_16x16x32_bf16 v[106:109], v[162:165], v[170:173], v[106:109]
	v_mfma_f32_16x16x32_bf16 v[98:101], v[158:161], v[186:189], v[98:101]
	v_mfma_f32_16x16x32_bf16 v[98:101], v[162:165], v[190:193], v[98:101]
	v_mfma_f32_16x16x32_bf16 v[102:105], v[150:153], v[186:189], v[102:105]
	v_mfma_f32_16x16x32_bf16 v[102:105], v[154:157], v[190:193], v[102:105]
	v_mfma_f32_16x16x32_bf16 v[82:85], v[150:153], v[194:197], v[82:85]
	v_mfma_f32_16x16x32_bf16 v[82:85], v[154:157], v[198:201], v[82:85]
	v_mfma_f32_16x16x32_bf16 v[74:77], v[158:161], v[194:197], v[74:77]
	v_mfma_f32_16x16x32_bf16 v[74:77], v[162:165], v[198:201], v[74:77]
	s_setprio 2
	s_barrier
	v_mfma_f32_16x16x32_bf16 v[66:69], v[158:161], v[202:205], v[66:69]
	v_mfma_f32_16x16x32_bf16 v[66:69], v[162:165], v[206:209], v[66:69]
	v_mfma_f32_16x16x32_bf16 v[70:73], v[150:153], v[202:205], v[70:73]
	v_mfma_f32_16x16x32_bf16 v[70:73], v[154:157], v[206:209], v[70:73]
	s_setprio 0
	ds_read_b128 v[166:169], v183 offset:16384
	ds_read_b128 v[170:173], v183 offset:17408
	ds_read_b128 v[186:189], v183 offset:18432
	ds_read_b128 v[190:193], v183 offset:19456
	ds_read_b128 v[194:197], v183 offset:20480
	ds_read_b128 v[198:201], v183 offset:21504
	ds_read_b128 v[202:205], v183 offset:22528
	ds_read_b128 v[206:209], v183 offset:23552
	s_mov_b32 s79, m0
	s_mov_b32 m0, s35
	s_nop 0
	global_load_lds_dwordx4 v176, s[22:23]
	s_mov_b32 m0, s79
	s_add_u32 s80, s22, 0x4000
	s_mov_b32 s79, m0
	s_mov_b32 m0, s36
	s_nop 0
	global_load_lds_dwordx4 v178, s[22:23]
	s_mov_b32 m0, s79
	s_addc_u32 s81, s23, 0
	s_mov_b32 s79, m0
	s_mov_b32 m0, s37
	s_nop 0
	global_load_lds_dwordx4 v176, s[80:81]
	s_mov_b32 m0, s79
	s_nop 0
	s_mov_b32 s79, m0
	s_mov_b32 m0, s40
	s_nop 0
	global_load_lds_dwordx4 v178, s[80:81]
	s_mov_b32 m0, s79
	s_waitcnt vmcnt(4)
	s_waitcnt lgkmcnt(0)
	s_barrier
	s_setprio 1
	s_waitcnt lgkmcnt(7)
	v_mfma_f32_16x16x32_bf16 v[62:65], v[130:133], v[166:169], v[62:65]
	v_mfma_f32_16x16x32_bf16 v[62:65], v[134:137], v[170:173], v[62:65]
	s_waitcnt lgkmcnt(5)
	v_mfma_f32_16x16x32_bf16 v[58:61], v[138:141], v[166:169], v[58:61]
	v_mfma_f32_16x16x32_bf16 v[58:61], v[142:145], v[170:173], v[58:61]
	s_waitcnt lgkmcnt(3)
	v_mfma_f32_16x16x32_bf16 v[42:45], v[138:141], v[186:189], v[42:45]
	v_mfma_f32_16x16x32_bf16 v[42:45], v[142:145], v[190:193], v[42:45]
	s_waitcnt lgkmcnt(1)
	v_mfma_f32_16x16x32_bf16 v[46:49], v[130:133], v[186:189], v[46:49]
	v_mfma_f32_16x16x32_bf16 v[46:49], v[134:137], v[190:193], v[46:49]
	v_mfma_f32_16x16x32_bf16 v[30:33], v[130:133], v[194:197], v[30:33]
	v_mfma_f32_16x16x32_bf16 v[30:33], v[134:137], v[198:201], v[30:33]
	v_mfma_f32_16x16x32_bf16 v[26:29], v[138:141], v[194:197], v[26:29]
	v_mfma_f32_16x16x32_bf16 v[26:29], v[142:145], v[198:201], v[26:29]
	v_mfma_f32_16x16x32_bf16 v[10:13], v[138:141], v[202:205], v[10:13]
	v_mfma_f32_16x16x32_bf16 v[10:13], v[142:145], v[206:209], v[10:13]
	s_waitcnt lgkmcnt(0)
	v_mfma_f32_16x16x32_bf16 v[14:17], v[130:133], v[202:205], v[14:17]
	v_mfma_f32_16x16x32_bf16 v[14:17], v[134:137], v[206:209], v[14:17]
	s_setprio 0
	s_setprio 1
	v_mfma_f32_16x16x32_bf16 v[54:57], v[150:153], v[166:169], v[54:57]
	v_mfma_f32_16x16x32_bf16 v[54:57], v[154:157], v[170:173], v[54:57]
	v_mfma_f32_16x16x32_bf16 v[50:53], v[158:161], v[166:169], v[50:53]
	v_mfma_f32_16x16x32_bf16 v[50:53], v[162:165], v[170:173], v[50:53]
	v_mfma_f32_16x16x32_bf16 v[34:37], v[158:161], v[186:189], v[34:37]
	v_mfma_f32_16x16x32_bf16 v[34:37], v[162:165], v[190:193], v[34:37]
	v_mfma_f32_16x16x32_bf16 v[38:41], v[150:153], v[186:189], v[38:41]
	v_mfma_f32_16x16x32_bf16 v[38:41], v[154:157], v[190:193], v[38:41]
	v_mfma_f32_16x16x32_bf16 v[22:25], v[150:153], v[194:197], v[22:25]
	v_mfma_f32_16x16x32_bf16 v[22:25], v[154:157], v[198:201], v[22:25]
	v_mfma_f32_16x16x32_bf16 v[18:21], v[158:161], v[194:197], v[18:21]
	v_mfma_f32_16x16x32_bf16 v[18:21], v[162:165], v[198:201], v[18:21]
	s_setprio 2
	s_barrier
	v_mfma_f32_16x16x32_bf16 v[2:5], v[158:161], v[202:205], v[2:5]
	v_mfma_f32_16x16x32_bf16 v[2:5], v[162:165], v[206:209], v[2:5]
	v_mfma_f32_16x16x32_bf16 v[6:9], v[150:153], v[202:205], v[6:9]
	v_mfma_f32_16x16x32_bf16 v[6:9], v[154:157], v[206:209], v[6:9]
	s_setprio 0
	ds_read_b128 v[130:133], v184
	ds_read_b128 v[134:137], v184 offset:1024
	ds_read_b128 v[138:141], v184 offset:2048
	ds_read_b128 v[142:145], v184 offset:3072
	ds_read_b128 v[150:153], v185
	ds_read_b128 v[154:157], v185 offset:1024
	ds_read_b128 v[158:161], v185 offset:2048
	ds_read_b128 v[162:165], v185 offset:3072
	ds_read_b128 v[166:169], v183 offset:32768
	ds_read_b128 v[170:173], v183 offset:33792
	ds_read_b128 v[186:189], v183 offset:34816
	ds_read_b128 v[190:193], v183 offset:35840
	ds_read_b128 v[194:197], v183 offset:36864
	ds_read_b128 v[198:201], v183 offset:37888
	ds_read_b128 v[202:205], v183 offset:38912
	ds_read_b128 v[206:209], v183 offset:39936
	s_mov_b32 s79, m0
	s_mov_b32 m0, s34
	s_nop 0
	global_load_lds_dwordx4 v1, s[24:25]
	s_mov_b32 m0, s79
	s_nop 0
	s_mov_b32 s79, m0
	s_mov_b32 m0, s41
	s_nop 0
	global_load_lds_dwordx4 v177, s[24:25]
	s_mov_b32 m0, s79
	s_add_u32 s24, s24, 0x4000
	s_addc_u32 s25, s25, 0
	s_mov_b32 s79, m0
	s_mov_b32 m0, s42
	s_nop 0
	global_load_lds_dwordx4 v1, s[24:25]
	s_mov_b32 m0, s79
	s_nop 0
	s_mov_b32 s79, m0
	s_mov_b32 m0, s43
	s_nop 0
	global_load_lds_dwordx4 v177, s[24:25]
	s_mov_b32 m0, s79
	s_waitcnt vmcnt(8)
	s_waitcnt lgkmcnt(0)
	s_barrier
	s_setprio 1
	s_waitcnt lgkmcnt(7)
	v_mfma_f32_16x16x32_bf16 v[126:129], v[130:133], v[166:169], v[126:129]
	v_mfma_f32_16x16x32_bf16 v[126:129], v[134:137], v[170:173], v[126:129]
	s_waitcnt lgkmcnt(5)
	v_mfma_f32_16x16x32_bf16 v[122:125], v[138:141], v[166:169], v[122:125]
	v_mfma_f32_16x16x32_bf16 v[122:125], v[142:145], v[170:173], v[122:125]
	s_waitcnt lgkmcnt(3)
	v_mfma_f32_16x16x32_bf16 v[110:113], v[138:141], v[186:189], v[110:113]
	v_mfma_f32_16x16x32_bf16 v[110:113], v[142:145], v[190:193], v[110:113]
	s_waitcnt lgkmcnt(1)
	v_mfma_f32_16x16x32_bf16 v[118:121], v[130:133], v[186:189], v[118:121]
	v_mfma_f32_16x16x32_bf16 v[118:121], v[134:137], v[190:193], v[118:121]
	v_mfma_f32_16x16x32_bf16 v[94:97], v[130:133], v[194:197], v[94:97]
	v_mfma_f32_16x16x32_bf16 v[94:97], v[134:137], v[198:201], v[94:97]
	v_mfma_f32_16x16x32_bf16 v[90:93], v[138:141], v[194:197], v[90:93]
	v_mfma_f32_16x16x32_bf16 v[90:93], v[142:145], v[198:201], v[90:93]
	v_mfma_f32_16x16x32_bf16 v[78:81], v[138:141], v[202:205], v[78:81]
	v_mfma_f32_16x16x32_bf16 v[78:81], v[142:145], v[206:209], v[78:81]
	s_waitcnt lgkmcnt(0)
	v_mfma_f32_16x16x32_bf16 v[86:89], v[130:133], v[202:205], v[86:89]
	v_mfma_f32_16x16x32_bf16 v[86:89], v[134:137], v[206:209], v[86:89]
	s_setprio 0
	s_setprio 1
	v_mfma_f32_16x16x32_bf16 v[114:117], v[150:153], v[166:169], v[114:117]
	v_mfma_f32_16x16x32_bf16 v[114:117], v[154:157], v[170:173], v[114:117]
	v_mfma_f32_16x16x32_bf16 v[106:109], v[158:161], v[166:169], v[106:109]
	v_mfma_f32_16x16x32_bf16 v[106:109], v[162:165], v[170:173], v[106:109]
	v_mfma_f32_16x16x32_bf16 v[98:101], v[158:161], v[186:189], v[98:101]
	v_mfma_f32_16x16x32_bf16 v[98:101], v[162:165], v[190:193], v[98:101]
	v_mfma_f32_16x16x32_bf16 v[102:105], v[150:153], v[186:189], v[102:105]
	v_mfma_f32_16x16x32_bf16 v[102:105], v[154:157], v[190:193], v[102:105]
	v_mfma_f32_16x16x32_bf16 v[82:85], v[150:153], v[194:197], v[82:85]
	v_mfma_f32_16x16x32_bf16 v[82:85], v[154:157], v[198:201], v[82:85]
	v_mfma_f32_16x16x32_bf16 v[74:77], v[158:161], v[194:197], v[74:77]
	v_mfma_f32_16x16x32_bf16 v[74:77], v[162:165], v[198:201], v[74:77]
	s_setprio 2
	s_barrier
	v_mfma_f32_16x16x32_bf16 v[66:69], v[158:161], v[202:205], v[66:69]
	v_mfma_f32_16x16x32_bf16 v[66:69], v[162:165], v[206:209], v[66:69]
	v_mfma_f32_16x16x32_bf16 v[70:73], v[150:153], v[202:205], v[70:73]
	v_mfma_f32_16x16x32_bf16 v[70:73], v[154:157], v[206:209], v[70:73]
	s_setprio 0
	ds_read_b128 v[166:169], v183 offset:49152
	ds_read_b128 v[170:173], v183 offset:50176
	ds_read_b128 v[186:189], v183 offset:51200
	ds_read_b128 v[190:193], v183 offset:52224
	ds_read_b128 v[194:197], v183 offset:53248
	ds_read_b128 v[198:201], v183 offset:54272
	ds_read_b128 v[202:205], v183 offset:55296
	ds_read_b128 v[206:209], v183 offset:56320
	s_add_u32 s24, s22, 0x40000
	s_addc_u32 s25, s23, 0
	s_mov_b32 s79, m0
	s_mov_b32 m0, s46
	s_nop 0
	global_load_lds_dwordx4 v176, s[24:25]
	s_mov_b32 m0, s79
	s_add_u32 s22, s22, 0x44000
	s_mov_b32 s79, m0
	s_mov_b32 m0, s47
	s_nop 0
	global_load_lds_dwordx4 v178, s[24:25]
	s_mov_b32 m0, s79
	s_addc_u32 s23, s23, 0
	s_mov_b32 s24, m0
	s_mov_b32 m0, s48
	s_nop 0
	global_load_lds_dwordx4 v176, s[22:23]
	s_mov_b32 m0, s24
	s_nop 0
	s_mov_b32 s24, m0
	s_mov_b32 m0, s49
	s_nop 0
	global_load_lds_dwordx4 v178, s[22:23]
	s_mov_b32 m0, s24
	s_waitcnt vmcnt(4)
	s_waitcnt lgkmcnt(0)
	s_barrier
	s_setprio 1
	s_waitcnt lgkmcnt(7)
	v_mfma_f32_16x16x32_bf16 v[62:65], v[130:133], v[166:169], v[62:65]
	v_mfma_f32_16x16x32_bf16 v[62:65], v[134:137], v[170:173], v[62:65]
	s_waitcnt lgkmcnt(5)
	v_mfma_f32_16x16x32_bf16 v[58:61], v[138:141], v[166:169], v[58:61]
	v_mfma_f32_16x16x32_bf16 v[58:61], v[142:145], v[170:173], v[58:61]
	s_waitcnt lgkmcnt(3)
	v_mfma_f32_16x16x32_bf16 v[42:45], v[138:141], v[186:189], v[42:45]
	v_mfma_f32_16x16x32_bf16 v[42:45], v[142:145], v[190:193], v[42:45]
	s_waitcnt lgkmcnt(1)
	v_mfma_f32_16x16x32_bf16 v[46:49], v[130:133], v[186:189], v[46:49]
	v_mfma_f32_16x16x32_bf16 v[46:49], v[134:137], v[190:193], v[46:49]
	v_mfma_f32_16x16x32_bf16 v[30:33], v[130:133], v[194:197], v[30:33]
	v_mfma_f32_16x16x32_bf16 v[30:33], v[134:137], v[198:201], v[30:33]
	v_mfma_f32_16x16x32_bf16 v[26:29], v[138:141], v[194:197], v[26:29]
	v_mfma_f32_16x16x32_bf16 v[26:29], v[142:145], v[198:201], v[26:29]
	v_mfma_f32_16x16x32_bf16 v[10:13], v[138:141], v[202:205], v[10:13]
	v_mfma_f32_16x16x32_bf16 v[10:13], v[142:145], v[206:209], v[10:13]
	s_waitcnt lgkmcnt(0)
	v_mfma_f32_16x16x32_bf16 v[14:17], v[130:133], v[202:205], v[14:17]
	v_mfma_f32_16x16x32_bf16 v[14:17], v[134:137], v[206:209], v[14:17]
	s_setprio 0
	s_setprio 1
	v_mfma_f32_16x16x32_bf16 v[54:57], v[150:153], v[166:169], v[54:57]
	v_mfma_f32_16x16x32_bf16 v[54:57], v[154:157], v[170:173], v[54:57]
	v_mfma_f32_16x16x32_bf16 v[50:53], v[158:161], v[166:169], v[50:53]
	v_mfma_f32_16x16x32_bf16 v[50:53], v[162:165], v[170:173], v[50:53]
	v_mfma_f32_16x16x32_bf16 v[34:37], v[158:161], v[186:189], v[34:37]
	v_mfma_f32_16x16x32_bf16 v[34:37], v[162:165], v[190:193], v[34:37]
	v_mfma_f32_16x16x32_bf16 v[38:41], v[150:153], v[186:189], v[38:41]
	v_mfma_f32_16x16x32_bf16 v[38:41], v[154:157], v[190:193], v[38:41]
	v_mfma_f32_16x16x32_bf16 v[22:25], v[150:153], v[194:197], v[22:25]
	v_mfma_f32_16x16x32_bf16 v[22:25], v[154:157], v[198:201], v[22:25]
	v_mfma_f32_16x16x32_bf16 v[18:21], v[158:161], v[194:197], v[18:21]
	v_mfma_f32_16x16x32_bf16 v[18:21], v[162:165], v[198:201], v[18:21]
	s_setprio 2
	s_barrier
	v_mfma_f32_16x16x32_bf16 v[2:5], v[158:161], v[202:205], v[2:5]
	v_mfma_f32_16x16x32_bf16 v[2:5], v[162:165], v[206:209], v[2:5]
	v_mfma_f32_16x16x32_bf16 v[6:9], v[150:153], v[202:205], v[6:9]
	v_mfma_f32_16x16x32_bf16 v[6:9], v[154:157], v[206:209], v[6:9]
	s_setprio 0
	s_add_i32 s78, s78, 2
	s_add_u32 s74, s74, 0x80000
	s_addc_u32 s75, s75, 0
	s_add_u32 s20, s20, 0x400000
	s_addc_u32 s21, s21, 0
	s_add_u32 s76, s76, 0x400000
	s_addc_u32 s77, s77, 0
	s_cmpk_gt_u32 s78, 0x53
	s_cbranch_scc0 .LBB0_1357
	s_and_b64 vcc, exec, s[8:9]
	s_cbranch_vccz .LBB0_1360
	s_barrier

.LBB0_1537:
	s_ashr_i32 s23, s22, 31
	s_lshl_b64 s[24:25], s[22:23], 20
	s_add_u32 s24, s41, s24
	s_addc_u32 s25, s42, s25
	s_and_b64 s[26:27], s[4:5], exec
	s_cselect_b32 s7, s25, s35
	s_cselect_b32 s23, s24, s34
	s_ashr_i32 s21, s20, 31
	s_lshl_b64 s[26:27], s[20:21], 20
	s_add_u32 s26, s43, s26
	s_addc_u32 s27, s46, s27
	s_and_b64 s[36:37], s[4:5], exec
	s_cselect_b32 s21, s27, s31
	s_cselect_b32 s29, s26, s30
	s_add_u32 s79, s30, 0x100
	s_addc_u32 s80, s31, 0
	s_add_u32 s30, s34, 0x80080
	s_addc_u32 s31, s35, 0
	s_add_u32 s81, s34, 0x100
	s_addc_u32 s82, s35, 0
	s_mov_b32 s83, -2
	s_waitcnt vmcnt(25)
	s_waitcnt vmcnt(24)
	s_waitcnt vmcnt(4)
	s_waitcnt vmcnt(14)
	s_waitcnt vmcnt(13)
	s_waitcnt vmcnt(12)
	s_waitcnt vmcnt(2)
	s_waitcnt vmcnt(10)
	s_waitcnt vmcnt(9)
	s_waitcnt vmcnt(8)
	s_waitcnt vmcnt(7)
	s_waitcnt vmcnt(6)
	s_waitcnt vmcnt(5)
	s_waitcnt vmcnt(4)
	s_waitcnt vmcnt(3)
	s_waitcnt vmcnt(2)
	s_waitcnt vmcnt(1)
	s_waitcnt vmcnt(0)
	ds_read_b128 v[46:49], v182
	ds_read_b128 v[54:57], v182 offset:1024
	ds_read_b128 v[58:61], v182 offset:2048
	ds_read_b128 v[62:65], v182 offset:3072
	ds_read_b128 v[146:149], v183
	ds_read_b128 v[150:153], v183 offset:1024
	ds_read_b128 v[154:157], v183 offset:2048
	ds_read_b128 v[158:161], v183 offset:3072
	s_cmp_eq_u32 s83, 28
	s_cselect_b32 s35, s21, s80
	s_cselect_b32 s34, s29, s79
	s_cselect_b32 s37, s7, s82
	s_cselect_b32 s36, s23, s81
	ds_read_b128 v[170:173], v184
	ds_read_b128 v[188:191], v184 offset:1024
	ds_read_b128 v[192:195], v184 offset:2048
	ds_read_b128 v[196:199], v184 offset:3072
	ds_read_b128 v[200:203], v184 offset:4096
	ds_read_b128 v[204:207], v184 offset:5120
	ds_read_b128 v[208:211], v184 offset:6144
	ds_read_b128 v[212:215], v184 offset:7168
	s_add_u32 s86, s30, 0xfff80000
	s_addc_u32 s87, s31, -1
	s_mov_b32 s92, m0
	s_mov_b32 m0, s73
	s_nop 0
	global_load_lds_dwordx4 v176, s[86:87]
	s_mov_b32 m0, s92
	s_nop 0
	s_mov_b32 s92, m0
	s_mov_b32 m0, s75
	s_nop 0
	global_load_lds_dwordx4 v178, s[86:87]
	s_mov_b32 m0, s92
	s_mov_b32 s86, m0
	s_mov_b32 m0, s74
	s_nop 0
	global_load_lds_dwordx4 v176, s[30:31]
	s_mov_b32 m0, s86
	s_nop 0
	s_mov_b32 s86, m0
	s_mov_b32 m0, s76
	s_nop 0
	global_load_lds_dwordx4 v178, s[30:31]
	s_mov_b32 m0, s86
	s_waitcnt vmcnt(8)
	s_waitcnt lgkmcnt(0)
	s_barrier
	s_setprio 1
	s_waitcnt lgkmcnt(7)
	v_mfma_f32_16x16x32_bf16 v[142:145], v[46:49], v[170:173], 0
	v_mfma_f32_16x16x32_bf16 v[142:145], v[54:57], v[188:191], v[142:145]
	s_waitcnt lgkmcnt(5)
	v_mfma_f32_16x16x32_bf16 v[138:141], v[58:61], v[170:173], 0
	v_mfma_f32_16x16x32_bf16 v[138:141], v[62:65], v[188:191], v[138:141]
	s_waitcnt lgkmcnt(3)
	v_mfma_f32_16x16x32_bf16 v[126:129], v[46:49], v[192:195], 0
	v_mfma_f32_16x16x32_bf16 v[126:129], v[54:57], v[196:199], v[126:129]
	s_waitcnt lgkmcnt(1)
	v_mfma_f32_16x16x32_bf16 v[122:125], v[58:61], v[192:195], 0
	v_mfma_f32_16x16x32_bf16 v[122:125], v[62:65], v[196:199], v[122:125]
	v_mfma_f32_16x16x32_bf16 v[110:113], v[46:49], v[200:203], 0
	v_mfma_f32_16x16x32_bf16 v[110:113], v[54:57], v[204:207], v[110:113]
	v_mfma_f32_16x16x32_bf16 v[106:109], v[58:61], v[200:203], 0
	v_mfma_f32_16x16x32_bf16 v[106:109], v[62:65], v[204:207], v[106:109]
	v_mfma_f32_16x16x32_bf16 v[94:97], v[46:49], v[208:211], 0
	v_mfma_f32_16x16x32_bf16 v[94:97], v[54:57], v[212:215], v[94:97]
	s_waitcnt lgkmcnt(0)
	v_mfma_f32_16x16x32_bf16 v[90:93], v[58:61], v[208:211], 0
	v_mfma_f32_16x16x32_bf16 v[90:93], v[62:65], v[212:215], v[90:93]
	s_setprio 0
	s_setprio 1
	v_mfma_f32_16x16x32_bf16 v[134:137], v[146:149], v[170:173], 0
	v_mfma_f32_16x16x32_bf16 v[134:137], v[150:153], v[188:191], v[134:137]
	v_mfma_f32_16x16x32_bf16 v[130:133], v[154:157], v[170:173], 0
	v_mfma_f32_16x16x32_bf16 v[130:133], v[158:161], v[188:191], v[130:133]
	v_mfma_f32_16x16x32_bf16 v[118:121], v[146:149], v[192:195], 0
	v_mfma_f32_16x16x32_bf16 v[118:121], v[150:153], v[196:199], v[118:121]
	v_mfma_f32_16x16x32_bf16 v[114:117], v[154:157], v[192:195], 0
	v_mfma_f32_16x16x32_bf16 v[114:117], v[158:161], v[196:199], v[114:117]
	v_mfma_f32_16x16x32_bf16 v[102:105], v[146:149], v[200:203], 0
	v_mfma_f32_16x16x32_bf16 v[102:105], v[150:153], v[204:207], v[102:105]
	v_mfma_f32_16x16x32_bf16 v[98:101], v[154:157], v[200:203], 0
	v_mfma_f32_16x16x32_bf16 v[98:101], v[158:161], v[204:207], v[98:101]
	s_setprio 2
	s_barrier
	v_mfma_f32_16x16x32_bf16 v[86:89], v[146:149], v[208:211], 0
	v_mfma_f32_16x16x32_bf16 v[86:89], v[150:153], v[212:215], v[86:89]
	v_mfma_f32_16x16x32_bf16 v[82:85], v[154:157], v[208:211], 0
	v_mfma_f32_16x16x32_bf16 v[82:85], v[158:161], v[212:215], v[82:85]
	s_setprio 0
	ds_read_b128 v[170:173], v184 offset:16384
	ds_read_b128 v[188:191], v184 offset:17408
	ds_read_b128 v[192:195], v184 offset:18432
	ds_read_b128 v[196:199], v184 offset:19456
	ds_read_b128 v[200:203], v184 offset:20480
	ds_read_b128 v[204:207], v184 offset:21504
	ds_read_b128 v[208:211], v184 offset:22528
	ds_read_b128 v[212:215], v184 offset:23552
	s_mov_b32 s86, m0
	s_mov_b32 m0, s49
	s_nop 0
	global_load_lds_dwordx4 v177, s[34:35]
	s_mov_b32 m0, s86
	s_nop 0
	s_mov_b32 s86, m0
	s_mov_b32 m0, s56
	s_nop 0
	global_load_lds_dwordx4 v179, s[34:35]
	s_mov_b32 m0, s86
	s_add_u32 s86, s34, 0x80000
	s_addc_u32 s87, s35, 0
	s_mov_b32 s92, m0
	s_mov_b32 m0, s57
	s_nop 0
	global_load_lds_dwordx4 v177, s[86:87]
	s_mov_b32 m0, s92
	s_nop 0
	s_mov_b32 s92, m0
	s_mov_b32 m0, s58
	s_nop 0
	global_load_lds_dwordx4 v179, s[86:87]
	s_mov_b32 m0, s92
	s_waitcnt vmcnt(4)
	s_waitcnt lgkmcnt(0)
	s_barrier
	s_setprio 1
	s_waitcnt lgkmcnt(7)
	v_mfma_f32_16x16x32_bf16 v[78:81], v[46:49], v[170:173], 0
	v_mfma_f32_16x16x32_bf16 v[78:81], v[54:57], v[188:191], v[78:81]
	s_waitcnt lgkmcnt(5)
	v_mfma_f32_16x16x32_bf16 v[74:77], v[58:61], v[170:173], 0
	v_mfma_f32_16x16x32_bf16 v[74:77], v[62:65], v[188:191], v[74:77]
	s_waitcnt lgkmcnt(3)
	v_mfma_f32_16x16x32_bf16 v[50:53], v[46:49], v[192:195], 0
	v_mfma_f32_16x16x32_bf16 v[50:53], v[54:57], v[196:199], v[50:53]
	s_waitcnt lgkmcnt(1)
	v_mfma_f32_16x16x32_bf16 v[42:45], v[58:61], v[192:195], 0
	v_mfma_f32_16x16x32_bf16 v[42:45], v[62:65], v[196:199], v[42:45]
	v_mfma_f32_16x16x32_bf16 v[30:33], v[46:49], v[200:203], 0
	v_mfma_f32_16x16x32_bf16 v[30:33], v[54:57], v[204:207], v[30:33]
	v_mfma_f32_16x16x32_bf16 v[26:29], v[58:61], v[200:203], 0
	v_mfma_f32_16x16x32_bf16 v[26:29], v[62:65], v[204:207], v[26:29]
	v_mfma_f32_16x16x32_bf16 v[14:17], v[46:49], v[208:211], 0
	v_mfma_f32_16x16x32_bf16 v[14:17], v[54:57], v[212:215], v[14:17]
	s_waitcnt lgkmcnt(0)
	v_mfma_f32_16x16x32_bf16 v[10:13], v[58:61], v[208:211], 0
	v_mfma_f32_16x16x32_bf16 v[10:13], v[62:65], v[212:215], v[10:13]
	s_setprio 0
	s_setprio 1
	v_mfma_f32_16x16x32_bf16 v[38:41], v[146:149], v[192:195], 0
	v_mfma_f32_16x16x32_bf16 v[38:41], v[150:153], v[196:199], v[38:41]
	v_mfma_f32_16x16x32_bf16 v[34:37], v[154:157], v[192:195], 0
	v_mfma_f32_16x16x32_bf16 v[34:37], v[158:161], v[196:199], v[34:37]
	v_mfma_f32_16x16x32_bf16 v[22:25], v[146:149], v[200:203], 0
	v_mfma_f32_16x16x32_bf16 v[22:25], v[150:153], v[204:207], v[22:25]
	v_mfma_f32_16x16x32_bf16 v[18:21], v[154:157], v[200:203], 0
	v_mfma_f32_16x16x32_bf16 v[18:21], v[158:161], v[204:207], v[18:21]
	v_mfma_f32_16x16x32_bf16 v[6:9], v[146:149], v[208:211], 0
	v_mfma_f32_16x16x32_bf16 v[6:9], v[150:153], v[212:215], v[6:9]
	v_mfma_f32_16x16x32_bf16 v[2:5], v[154:157], v[208:211], 0
	v_mfma_f32_16x16x32_bf16 v[2:5], v[158:161], v[212:215], v[2:5]
	s_setprio 2
	s_barrier
	v_mfma_f32_16x16x32_bf16 v[46:49], v[146:149], v[170:173], 0
	v_mfma_f32_16x16x32_bf16 v[46:49], v[150:153], v[188:191], v[46:49]
	v_mfma_f32_16x16x32_bf16 v[54:57], v[154:157], v[170:173], 0
	v_mfma_f32_16x16x32_bf16 v[54:57], v[158:161], v[188:191], v[54:57]
	s_setprio 0
	ds_read_b128 v[58:61], v185
	ds_read_b128 v[62:65], v185 offset:1024
	ds_read_b128 v[66:69], v185 offset:2048
	ds_read_b128 v[70:73], v185 offset:3072
	ds_read_b128 v[146:149], v186
	ds_read_b128 v[150:153], v186 offset:1024
	ds_read_b128 v[154:157], v186 offset:2048
	ds_read_b128 v[158:161], v186 offset:3072
	ds_read_b128 v[170:173], v184 offset:32768
	ds_read_b128 v[188:191], v184 offset:33792
	ds_read_b128 v[192:195], v184 offset:34816
	ds_read_b128 v[196:199], v184 offset:35840
	ds_read_b128 v[200:203], v184 offset:36864
	ds_read_b128 v[204:207], v184 offset:37888
	ds_read_b128 v[208:211], v184 offset:38912
	ds_read_b128 v[212:215], v184 offset:39936
	s_mov_b32 s86, m0
	s_mov_b32 m0, s48
	s_nop 0
	global_load_lds_dwordx4 v176, s[36:37]
	s_mov_b32 m0, s86
	s_nop 0
	s_mov_b32 s86, m0
	s_mov_b32 m0, s59
	s_nop 0
	global_load_lds_dwordx4 v178, s[36:37]
	s_mov_b32 m0, s86
	s_add_u32 s36, s36, 0x80000
	s_addc_u32 s37, s37, 0
	s_mov_b32 s86, m0
	s_mov_b32 m0, s62
	s_nop 0
	global_load_lds_dwordx4 v176, s[36:37]
	s_mov_b32 m0, s86
	s_nop 0
	s_mov_b32 s86, m0
	s_mov_b32 m0, s63
	s_nop 0
	global_load_lds_dwordx4 v178, s[36:37]
	s_mov_b32 m0, s86
	s_waitcnt vmcnt(8)
	s_waitcnt lgkmcnt(0)
	s_barrier
	s_setprio 1
	s_waitcnt lgkmcnt(7)
	v_mfma_f32_16x16x32_bf16 v[142:145], v[58:61], v[170:173], v[142:145]
	v_mfma_f32_16x16x32_bf16 v[142:145], v[62:65], v[188:191], v[142:145]
	s_waitcnt lgkmcnt(5)
	v_mfma_f32_16x16x32_bf16 v[138:141], v[66:69], v[170:173], v[138:141]
	v_mfma_f32_16x16x32_bf16 v[138:141], v[70:73], v[188:191], v[138:141]
	s_waitcnt lgkmcnt(3)
	v_mfma_f32_16x16x32_bf16 v[126:129], v[58:61], v[192:195], v[126:129]
	v_mfma_f32_16x16x32_bf16 v[126:129], v[62:65], v[196:199], v[126:129]
	s_waitcnt lgkmcnt(1)
	v_mfma_f32_16x16x32_bf16 v[122:125], v[66:69], v[192:195], v[122:125]
	v_mfma_f32_16x16x32_bf16 v[122:125], v[70:73], v[196:199], v[122:125]
	v_mfma_f32_16x16x32_bf16 v[110:113], v[58:61], v[200:203], v[110:113]
	v_mfma_f32_16x16x32_bf16 v[110:113], v[62:65], v[204:207], v[110:113]
	v_mfma_f32_16x16x32_bf16 v[106:109], v[66:69], v[200:203], v[106:109]
	v_mfma_f32_16x16x32_bf16 v[106:109], v[70:73], v[204:207], v[106:109]
	v_mfma_f32_16x16x32_bf16 v[94:97], v[58:61], v[208:211], v[94:97]
	v_mfma_f32_16x16x32_bf16 v[94:97], v[62:65], v[212:215], v[94:97]
	s_waitcnt lgkmcnt(0)
	v_mfma_f32_16x16x32_bf16 v[90:93], v[66:69], v[208:211], v[90:93]
	v_mfma_f32_16x16x32_bf16 v[90:93], v[70:73], v[212:215], v[90:93]
	s_setprio 0
	s_setprio 1
	v_mfma_f32_16x16x32_bf16 v[134:137], v[146:149], v[170:173], v[134:137]
	v_mfma_f32_16x16x32_bf16 v[134:137], v[150:153], v[188:191], v[134:137]
	v_mfma_f32_16x16x32_bf16 v[130:133], v[154:157], v[170:173], v[130:133]
	v_mfma_f32_16x16x32_bf16 v[130:133], v[158:161], v[188:191], v[130:133]
	v_mfma_f32_16x16x32_bf16 v[118:121], v[146:149], v[192:195], v[118:121]
	v_mfma_f32_16x16x32_bf16 v[118:121], v[150:153], v[196:199], v[118:121]
	v_mfma_f32_16x16x32_bf16 v[114:117], v[154:157], v[192:195], v[114:117]
	v_mfma_f32_16x16x32_bf16 v[114:117], v[158:161], v[196:199], v[114:117]
	v_mfma_f32_16x16x32_bf16 v[102:105], v[146:149], v[200:203], v[102:105]
	v_mfma_f32_16x16x32_bf16 v[102:105], v[150:153], v[204:207], v[102:105]
	v_mfma_f32_16x16x32_bf16 v[98:101], v[154:157], v[200:203], v[98:101]
	v_mfma_f32_16x16x32_bf16 v[98:101], v[158:161], v[204:207], v[98:101]
	s_setprio 2
	s_barrier
	v_mfma_f32_16x16x32_bf16 v[86:89], v[146:149], v[208:211], v[86:89]
	v_mfma_f32_16x16x32_bf16 v[86:89], v[150:153], v[212:215], v[86:89]
	v_mfma_f32_16x16x32_bf16 v[82:85], v[154:157], v[208:211], v[82:85]
	v_mfma_f32_16x16x32_bf16 v[82:85], v[158:161], v[212:215], v[82:85]
	s_setprio 0
	ds_read_b128 v[170:173], v184 offset:49152
	ds_read_b128 v[188:191], v184 offset:50176
	ds_read_b128 v[192:195], v184 offset:51200
	ds_read_b128 v[196:199], v184 offset:52224
	ds_read_b128 v[200:203], v184 offset:53248
	ds_read_b128 v[204:207], v184 offset:54272
	ds_read_b128 v[208:211], v184 offset:55296
	ds_read_b128 v[212:215], v184 offset:56320
	s_add_u32 s36, s34, 0x80
	s_addc_u32 s37, s35, 0
	s_mov_b32 s86, m0
	s_mov_b32 m0, s64
	s_nop 0
	global_load_lds_dwordx4 v177, s[36:37]
	s_mov_b32 m0, s86
	s_add_u32 s34, s34, 0x80080
	s_mov_b32 s86, m0
	s_mov_b32 m0, s65
	s_nop 0
	global_load_lds_dwordx4 v179, s[36:37]
	s_mov_b32 m0, s86
	s_addc_u32 s35, s35, 0
	s_mov_b32 s36, m0
	s_mov_b32 m0, s66
	s_nop 0
	global_load_lds_dwordx4 v177, s[34:35]
	s_mov_b32 m0, s36
	s_nop 0
	s_mov_b32 s36, m0
	s_mov_b32 m0, s67
	s_nop 0
	global_load_lds_dwordx4 v179, s[34:35]
	s_mov_b32 m0, s36
	s_waitcnt vmcnt(4)
	s_waitcnt lgkmcnt(0)
	s_barrier
	s_setprio 1
	s_waitcnt lgkmcnt(7)
	v_mfma_f32_16x16x32_bf16 v[78:81], v[58:61], v[170:173], v[78:81]
	v_mfma_f32_16x16x32_bf16 v[78:81], v[62:65], v[188:191], v[78:81]
	s_waitcnt lgkmcnt(5)
	v_mfma_f32_16x16x32_bf16 v[74:77], v[66:69], v[170:173], v[74:77]
	v_mfma_f32_16x16x32_bf16 v[74:77], v[70:73], v[188:191], v[74:77]
	s_waitcnt lgkmcnt(3)
	v_mfma_f32_16x16x32_bf16 v[50:53], v[58:61], v[192:195], v[50:53]
	v_mfma_f32_16x16x32_bf16 v[50:53], v[62:65], v[196:199], v[50:53]
	s_waitcnt lgkmcnt(1)
	v_mfma_f32_16x16x32_bf16 v[42:45], v[66:69], v[192:195], v[42:45]
	v_mfma_f32_16x16x32_bf16 v[42:45], v[70:73], v[196:199], v[42:45]
	v_mfma_f32_16x16x32_bf16 v[30:33], v[58:61], v[200:203], v[30:33]
	v_mfma_f32_16x16x32_bf16 v[30:33], v[62:65], v[204:207], v[30:33]
	v_mfma_f32_16x16x32_bf16 v[26:29], v[66:69], v[200:203], v[26:29]
	v_mfma_f32_16x16x32_bf16 v[26:29], v[70:73], v[204:207], v[26:29]
	v_mfma_f32_16x16x32_bf16 v[14:17], v[58:61], v[208:211], v[14:17]
	v_mfma_f32_16x16x32_bf16 v[14:17], v[62:65], v[212:215], v[14:17]
	s_waitcnt lgkmcnt(0)
	v_mfma_f32_16x16x32_bf16 v[10:13], v[66:69], v[208:211], v[10:13]
	v_mfma_f32_16x16x32_bf16 v[10:13], v[70:73], v[212:215], v[10:13]
	s_setprio 0
	s_setprio 1
	v_mfma_f32_16x16x32_bf16 v[46:49], v[146:149], v[170:173], v[46:49]
	v_mfma_f32_16x16x32_bf16 v[70:73], v[150:153], v[188:191], v[46:49]
	v_mfma_f32_16x16x32_bf16 v[46:49], v[154:157], v[170:173], v[54:57]
	v_mfma_f32_16x16x32_bf16 v[66:69], v[158:161], v[188:191], v[46:49]
	v_mfma_f32_16x16x32_bf16 v[38:41], v[146:149], v[192:195], v[38:41]
	v_mfma_f32_16x16x32_bf16 v[38:41], v[150:153], v[196:199], v[38:41]
	v_mfma_f32_16x16x32_bf16 v[34:37], v[154:157], v[192:195], v[34:37]
	v_mfma_f32_16x16x32_bf16 v[34:37], v[158:161], v[196:199], v[34:37]
	v_mfma_f32_16x16x32_bf16 v[22:25], v[146:149], v[200:203], v[22:25]
	v_mfma_f32_16x16x32_bf16 v[22:25], v[150:153], v[204:207], v[22:25]
	v_mfma_f32_16x16x32_bf16 v[18:21], v[154:157], v[200:203], v[18:21]
	v_mfma_f32_16x16x32_bf16 v[18:21], v[158:161], v[204:207], v[18:21]
	s_setprio 2
	s_barrier
	v_mfma_f32_16x16x32_bf16 v[6:9], v[146:149], v[208:211], v[6:9]
	v_mfma_f32_16x16x32_bf16 v[6:9], v[150:153], v[212:215], v[6:9]
	v_mfma_f32_16x16x32_bf16 v[2:5], v[154:157], v[208:211], v[2:5]
	v_mfma_f32_16x16x32_bf16 v[2:5], v[158:161], v[212:215], v[2:5]
	s_setprio 0
	s_add_i32 s83, s83, 2
	s_add_u32 s79, s79, 0x100
	s_addc_u32 s80, s80, 0
	s_add_u32 s30, s30, 0x100
	s_addc_u32 s31, s31, 0
	s_add_u32 s81, s81, 0x100
	s_addc_u32 s82, s82, 0
	s_cmp_gt_u32 s83, 29
	.p2align 6
.LBB0_1538:
	ds_read_b128 v[46:49], v182
	ds_read_b128 v[54:57], v182 offset:1024
	ds_read_b128 v[58:61], v182 offset:2048
	ds_read_b128 v[62:65], v182 offset:3072
	ds_read_b128 v[146:149], v183
	ds_read_b128 v[150:153], v183 offset:1024
	ds_read_b128 v[154:157], v183 offset:2048
	ds_read_b128 v[158:161], v183 offset:3072
	s_cmp_eq_u32 s83, 28
	s_cselect_b32 s35, s21, s80
	s_cselect_b32 s34, s29, s79
	s_cselect_b32 s37, s7, s82
	s_cselect_b32 s36, s23, s81
	ds_read_b128 v[170:173], v184
	ds_read_b128 v[188:191], v184 offset:1024
	ds_read_b128 v[192:195], v184 offset:2048
	ds_read_b128 v[196:199], v184 offset:3072
	ds_read_b128 v[200:203], v184 offset:4096
	ds_read_b128 v[204:207], v184 offset:5120
	ds_read_b128 v[208:211], v184 offset:6144
	ds_read_b128 v[212:215], v184 offset:7168
	s_add_u32 s86, s30, 0xfff80000
	s_addc_u32 s87, s31, -1
	s_mov_b32 s92, m0
	s_mov_b32 m0, s73
	s_nop 0
	global_load_lds_dwordx4 v176, s[86:87]
	s_mov_b32 m0, s92
	s_nop 0
	s_mov_b32 s92, m0
	s_mov_b32 m0, s75
	s_nop 0
	global_load_lds_dwordx4 v178, s[86:87]
	s_mov_b32 m0, s92
	s_mov_b32 s86, m0
	s_mov_b32 m0, s74
	s_nop 0
	global_load_lds_dwordx4 v176, s[30:31]
	s_mov_b32 m0, s86
	s_nop 0
	s_mov_b32 s86, m0
	s_mov_b32 m0, s76
	s_nop 0
	global_load_lds_dwordx4 v178, s[30:31]
	s_mov_b32 m0, s86
	s_waitcnt vmcnt(8)
	s_waitcnt lgkmcnt(0)
	s_barrier
	s_setprio 1
	s_waitcnt lgkmcnt(7)
	v_mfma_f32_16x16x32_bf16 v[142:145], v[46:49], v[170:173], v[142:145]
	v_mfma_f32_16x16x32_bf16 v[142:145], v[54:57], v[188:191], v[142:145]
	s_waitcnt lgkmcnt(5)
	v_mfma_f32_16x16x32_bf16 v[138:141], v[58:61], v[170:173], v[138:141]
	v_mfma_f32_16x16x32_bf16 v[138:141], v[62:65], v[188:191], v[138:141]
	s_waitcnt lgkmcnt(3)
	v_mfma_f32_16x16x32_bf16 v[126:129], v[46:49], v[192:195], v[126:129]
	v_mfma_f32_16x16x32_bf16 v[126:129], v[54:57], v[196:199], v[126:129]
	s_waitcnt lgkmcnt(1)
	v_mfma_f32_16x16x32_bf16 v[122:125], v[58:61], v[192:195], v[122:125]
	v_mfma_f32_16x16x32_bf16 v[122:125], v[62:65], v[196:199], v[122:125]
	v_mfma_f32_16x16x32_bf16 v[110:113], v[46:49], v[200:203], v[110:113]
	v_mfma_f32_16x16x32_bf16 v[110:113], v[54:57], v[204:207], v[110:113]
	v_mfma_f32_16x16x32_bf16 v[106:109], v[58:61], v[200:203], v[106:109]
	v_mfma_f32_16x16x32_bf16 v[106:109], v[62:65], v[204:207], v[106:109]
	v_mfma_f32_16x16x32_bf16 v[94:97], v[46:49], v[208:211], v[94:97]
	v_mfma_f32_16x16x32_bf16 v[94:97], v[54:57], v[212:215], v[94:97]
	s_waitcnt lgkmcnt(0)
	v_mfma_f32_16x16x32_bf16 v[90:93], v[58:61], v[208:211], v[90:93]
	v_mfma_f32_16x16x32_bf16 v[90:93], v[62:65], v[212:215], v[90:93]
	s_setprio 0
	s_setprio 1
	v_mfma_f32_16x16x32_bf16 v[134:137], v[146:149], v[170:173], v[134:137]
	v_mfma_f32_16x16x32_bf16 v[134:137], v[150:153], v[188:191], v[134:137]
	v_mfma_f32_16x16x32_bf16 v[130:133], v[154:157], v[170:173], v[130:133]
	v_mfma_f32_16x16x32_bf16 v[130:133], v[158:161], v[188:191], v[130:133]
	v_mfma_f32_16x16x32_bf16 v[118:121], v[146:149], v[192:195], v[118:121]
	v_mfma_f32_16x16x32_bf16 v[118:121], v[150:153], v[196:199], v[118:121]
	v_mfma_f32_16x16x32_bf16 v[114:117], v[154:157], v[192:195], v[114:117]
	v_mfma_f32_16x16x32_bf16 v[114:117], v[158:161], v[196:199], v[114:117]
	v_mfma_f32_16x16x32_bf16 v[102:105], v[146:149], v[200:203], v[102:105]
	v_mfma_f32_16x16x32_bf16 v[102:105], v[150:153], v[204:207], v[102:105]
	v_mfma_f32_16x16x32_bf16 v[98:101], v[154:157], v[200:203], v[98:101]
	v_mfma_f32_16x16x32_bf16 v[98:101], v[158:161], v[204:207], v[98:101]
	s_setprio 2
	s_barrier
	v_mfma_f32_16x16x32_bf16 v[86:89], v[146:149], v[208:211], v[86:89]
	v_mfma_f32_16x16x32_bf16 v[86:89], v[150:153], v[212:215], v[86:89]
	v_mfma_f32_16x16x32_bf16 v[82:85], v[154:157], v[208:211], v[82:85]
	v_mfma_f32_16x16x32_bf16 v[82:85], v[158:161], v[212:215], v[82:85]
	s_setprio 0
	ds_read_b128 v[170:173], v184 offset:16384
	ds_read_b128 v[188:191], v184 offset:17408
	ds_read_b128 v[192:195], v184 offset:18432
	ds_read_b128 v[196:199], v184 offset:19456
	ds_read_b128 v[200:203], v184 offset:20480
	ds_read_b128 v[204:207], v184 offset:21504
	ds_read_b128 v[208:211], v184 offset:22528
	ds_read_b128 v[212:215], v184 offset:23552
	s_mov_b32 s86, m0
	s_mov_b32 m0, s49
	s_nop 0
	global_load_lds_dwordx4 v177, s[34:35]
	s_mov_b32 m0, s86
	s_nop 0
	s_mov_b32 s86, m0
	s_mov_b32 m0, s56
	s_nop 0
	global_load_lds_dwordx4 v179, s[34:35]
	s_mov_b32 m0, s86
	s_add_u32 s86, s34, 0x80000
	s_addc_u32 s87, s35, 0
	s_mov_b32 s92, m0
	s_mov_b32 m0, s57
	s_nop 0
	global_load_lds_dwordx4 v177, s[86:87]
	s_mov_b32 m0, s92
	s_nop 0
	s_mov_b32 s92, m0
	s_mov_b32 m0, s58
	s_nop 0
	global_load_lds_dwordx4 v179, s[86:87]
	s_mov_b32 m0, s92
	s_waitcnt vmcnt(4)
	s_waitcnt lgkmcnt(0)
	s_barrier
	s_setprio 1
	s_waitcnt lgkmcnt(7)
	v_mfma_f32_16x16x32_bf16 v[78:81], v[46:49], v[170:173], v[78:81]
	v_mfma_f32_16x16x32_bf16 v[78:81], v[54:57], v[188:191], v[78:81]
	s_waitcnt lgkmcnt(5)
	v_mfma_f32_16x16x32_bf16 v[74:77], v[58:61], v[170:173], v[74:77]
	v_mfma_f32_16x16x32_bf16 v[74:77], v[62:65], v[188:191], v[74:77]
	s_waitcnt lgkmcnt(3)
	v_mfma_f32_16x16x32_bf16 v[50:53], v[46:49], v[192:195], v[50:53]
	v_mfma_f32_16x16x32_bf16 v[50:53], v[54:57], v[196:199], v[50:53]
	s_waitcnt lgkmcnt(1)
	v_mfma_f32_16x16x32_bf16 v[42:45], v[58:61], v[192:195], v[42:45]
	v_mfma_f32_16x16x32_bf16 v[42:45], v[62:65], v[196:199], v[42:45]
	v_mfma_f32_16x16x32_bf16 v[30:33], v[46:49], v[200:203], v[30:33]
	v_mfma_f32_16x16x32_bf16 v[30:33], v[54:57], v[204:207], v[30:33]
	v_mfma_f32_16x16x32_bf16 v[26:29], v[58:61], v[200:203], v[26:29]
	v_mfma_f32_16x16x32_bf16 v[26:29], v[62:65], v[204:207], v[26:29]
	v_mfma_f32_16x16x32_bf16 v[14:17], v[46:49], v[208:211], v[14:17]
	v_mfma_f32_16x16x32_bf16 v[14:17], v[54:57], v[212:215], v[14:17]
	s_waitcnt lgkmcnt(0)
	v_mfma_f32_16x16x32_bf16 v[10:13], v[58:61], v[208:211], v[10:13]
	v_mfma_f32_16x16x32_bf16 v[10:13], v[62:65], v[212:215], v[10:13]
	s_setprio 0
	s_setprio 1
	v_mfma_f32_16x16x32_bf16 v[38:41], v[146:149], v[192:195], v[38:41]
	v_mfma_f32_16x16x32_bf16 v[38:41], v[150:153], v[196:199], v[38:41]
	v_mfma_f32_16x16x32_bf16 v[34:37], v[154:157], v[192:195], v[34:37]
	v_mfma_f32_16x16x32_bf16 v[34:37], v[158:161], v[196:199], v[34:37]
	v_mfma_f32_16x16x32_bf16 v[22:25], v[146:149], v[200:203], v[22:25]
	v_mfma_f32_16x16x32_bf16 v[22:25], v[150:153], v[204:207], v[22:25]
	v_mfma_f32_16x16x32_bf16 v[18:21], v[154:157], v[200:203], v[18:21]
	v_mfma_f32_16x16x32_bf16 v[18:21], v[158:161], v[204:207], v[18:21]
	v_mfma_f32_16x16x32_bf16 v[6:9], v[146:149], v[208:211], v[6:9]
	v_mfma_f32_16x16x32_bf16 v[6:9], v[150:153], v[212:215], v[6:9]
	v_mfma_f32_16x16x32_bf16 v[2:5], v[154:157], v[208:211], v[2:5]
	v_mfma_f32_16x16x32_bf16 v[2:5], v[158:161], v[212:215], v[2:5]
	s_setprio 2
	s_barrier
	v_mfma_f32_16x16x32_bf16 v[46:49], v[146:149], v[170:173], v[70:73]
	v_mfma_f32_16x16x32_bf16 v[46:49], v[150:153], v[188:191], v[46:49]
	v_mfma_f32_16x16x32_bf16 v[54:57], v[154:157], v[170:173], v[66:69]
	v_mfma_f32_16x16x32_bf16 v[54:57], v[158:161], v[188:191], v[54:57]
	s_setprio 0
	ds_read_b128 v[58:61], v185
	ds_read_b128 v[62:65], v185 offset:1024
	ds_read_b128 v[66:69], v185 offset:2048
	ds_read_b128 v[70:73], v185 offset:3072
	ds_read_b128 v[146:149], v186
	ds_read_b128 v[150:153], v186 offset:1024
	ds_read_b128 v[154:157], v186 offset:2048
	ds_read_b128 v[158:161], v186 offset:3072
	ds_read_b128 v[170:173], v184 offset:32768
	ds_read_b128 v[188:191], v184 offset:33792
	ds_read_b128 v[192:195], v184 offset:34816
	ds_read_b128 v[196:199], v184 offset:35840
	ds_read_b128 v[200:203], v184 offset:36864
	ds_read_b128 v[204:207], v184 offset:37888
	ds_read_b128 v[208:211], v184 offset:38912
	ds_read_b128 v[212:215], v184 offset:39936
	s_mov_b32 s86, m0
	s_mov_b32 m0, s48
	s_nop 0
	global_load_lds_dwordx4 v176, s[36:37]
	s_mov_b32 m0, s86
	s_nop 0
	s_mov_b32 s86, m0
	s_mov_b32 m0, s59
	s_nop 0
	global_load_lds_dwordx4 v178, s[36:37]
	s_mov_b32 m0, s86
	s_add_u32 s36, s36, 0x80000
	s_addc_u32 s37, s37, 0
	s_mov_b32 s86, m0
	s_mov_b32 m0, s62
	s_nop 0
	global_load_lds_dwordx4 v176, s[36:37]
	s_mov_b32 m0, s86
	s_nop 0
	s_mov_b32 s86, m0
	s_mov_b32 m0, s63
	s_nop 0
	global_load_lds_dwordx4 v178, s[36:37]
	s_mov_b32 m0, s86
	s_waitcnt vmcnt(8)
	s_waitcnt lgkmcnt(0)
	s_barrier
	s_setprio 1
	s_waitcnt lgkmcnt(7)
	v_mfma_f32_16x16x32_bf16 v[142:145], v[58:61], v[170:173], v[142:145]
	v_mfma_f32_16x16x32_bf16 v[142:145], v[62:65], v[188:191], v[142:145]
	s_waitcnt lgkmcnt(5)
	v_mfma_f32_16x16x32_bf16 v[138:141], v[66:69], v[170:173], v[138:141]
	v_mfma_f32_16x16x32_bf16 v[138:141], v[70:73], v[188:191], v[138:141]
	s_waitcnt lgkmcnt(3)
	v_mfma_f32_16x16x32_bf16 v[126:129], v[58:61], v[192:195], v[126:129]
	v_mfma_f32_16x16x32_bf16 v[126:129], v[62:65], v[196:199], v[126:129]
	s_waitcnt lgkmcnt(1)
	v_mfma_f32_16x16x32_bf16 v[122:125], v[66:69], v[192:195], v[122:125]
	v_mfma_f32_16x16x32_bf16 v[122:125], v[70:73], v[196:199], v[122:125]
	v_mfma_f32_16x16x32_bf16 v[110:113], v[58:61], v[200:203], v[110:113]
	v_mfma_f32_16x16x32_bf16 v[110:113], v[62:65], v[204:207], v[110:113]
	v_mfma_f32_16x16x32_bf16 v[106:109], v[66:69], v[200:203], v[106:109]
	v_mfma_f32_16x16x32_bf16 v[106:109], v[70:73], v[204:207], v[106:109]
	v_mfma_f32_16x16x32_bf16 v[94:97], v[58:61], v[208:211], v[94:97]
	v_mfma_f32_16x16x32_bf16 v[94:97], v[62:65], v[212:215], v[94:97]
	s_waitcnt lgkmcnt(0)
	v_mfma_f32_16x16x32_bf16 v[90:93], v[66:69], v[208:211], v[90:93]
	v_mfma_f32_16x16x32_bf16 v[90:93], v[70:73], v[212:215], v[90:93]
	s_setprio 0
	s_setprio 1
	v_mfma_f32_16x16x32_bf16 v[134:137], v[146:149], v[170:173], v[134:137]
	v_mfma_f32_16x16x32_bf16 v[134:137], v[150:153], v[188:191], v[134:137]
	v_mfma_f32_16x16x32_bf16 v[130:133], v[154:157], v[170:173], v[130:133]
	v_mfma_f32_16x16x32_bf16 v[130:133], v[158:161], v[188:191], v[130:133]
	v_mfma_f32_16x16x32_bf16 v[118:121], v[146:149], v[192:195], v[118:121]
	v_mfma_f32_16x16x32_bf16 v[118:121], v[150:153], v[196:199], v[118:121]
	v_mfma_f32_16x16x32_bf16 v[114:117], v[154:157], v[192:195], v[114:117]
	v_mfma_f32_16x16x32_bf16 v[114:117], v[158:161], v[196:199], v[114:117]
	v_mfma_f32_16x16x32_bf16 v[102:105], v[146:149], v[200:203], v[102:105]
	v_mfma_f32_16x16x32_bf16 v[102:105], v[150:153], v[204:207], v[102:105]
	v_mfma_f32_16x16x32_bf16 v[98:101], v[154:157], v[200:203], v[98:101]
	v_mfma_f32_16x16x32_bf16 v[98:101], v[158:161], v[204:207], v[98:101]
	s_setprio 2
	s_barrier
	v_mfma_f32_16x16x32_bf16 v[86:89], v[146:149], v[208:211], v[86:89]
	v_mfma_f32_16x16x32_bf16 v[86:89], v[150:153], v[212:215], v[86:89]
	v_mfma_f32_16x16x32_bf16 v[82:85], v[154:157], v[208:211], v[82:85]
	v_mfma_f32_16x16x32_bf16 v[82:85], v[158:161], v[212:215], v[82:85]
	s_setprio 0
	ds_read_b128 v[170:173], v184 offset:49152
	ds_read_b128 v[188:191], v184 offset:50176
	ds_read_b128 v[192:195], v184 offset:51200
	ds_read_b128 v[196:199], v184 offset:52224
	ds_read_b128 v[200:203], v184 offset:53248
	ds_read_b128 v[204:207], v184 offset:54272
	ds_read_b128 v[208:211], v184 offset:55296
	ds_read_b128 v[212:215], v184 offset:56320
	s_add_u32 s36, s34, 0x80
	s_addc_u32 s37, s35, 0
	s_mov_b32 s86, m0
	s_mov_b32 m0, s64
	s_nop 0
	global_load_lds_dwordx4 v177, s[36:37]
	s_mov_b32 m0, s86
	s_add_u32 s34, s34, 0x80080
	s_mov_b32 s86, m0
	s_mov_b32 m0, s65
	s_nop 0
	global_load_lds_dwordx4 v179, s[36:37]
	s_mov_b32 m0, s86
	s_addc_u32 s35, s35, 0
	s_mov_b32 s36, m0
	s_mov_b32 m0, s66
	s_nop 0
	global_load_lds_dwordx4 v177, s[34:35]
	s_mov_b32 m0, s36
	s_nop 0
	s_mov_b32 s36, m0
	s_mov_b32 m0, s67
	s_nop 0
	global_load_lds_dwordx4 v179, s[34:35]
	s_mov_b32 m0, s36
	s_waitcnt vmcnt(4)
	s_waitcnt lgkmcnt(0)
	s_barrier
	s_setprio 1
	s_waitcnt lgkmcnt(7)
	v_mfma_f32_16x16x32_bf16 v[78:81], v[58:61], v[170:173], v[78:81]
	v_mfma_f32_16x16x32_bf16 v[78:81], v[62:65], v[188:191], v[78:81]
	s_waitcnt lgkmcnt(5)
	v_mfma_f32_16x16x32_bf16 v[74:77], v[66:69], v[170:173], v[74:77]
	v_mfma_f32_16x16x32_bf16 v[74:77], v[70:73], v[188:191], v[74:77]
	s_waitcnt lgkmcnt(3)
	v_mfma_f32_16x16x32_bf16 v[50:53], v[58:61], v[192:195], v[50:53]
	v_mfma_f32_16x16x32_bf16 v[50:53], v[62:65], v[196:199], v[50:53]
	s_waitcnt lgkmcnt(1)
	v_mfma_f32_16x16x32_bf16 v[42:45], v[66:69], v[192:195], v[42:45]
	v_mfma_f32_16x16x32_bf16 v[42:45], v[70:73], v[196:199], v[42:45]
	v_mfma_f32_16x16x32_bf16 v[30:33], v[58:61], v[200:203], v[30:33]
	v_mfma_f32_16x16x32_bf16 v[30:33], v[62:65], v[204:207], v[30:33]
	v_mfma_f32_16x16x32_bf16 v[26:29], v[66:69], v[200:203], v[26:29]
	v_mfma_f32_16x16x32_bf16 v[26:29], v[70:73], v[204:207], v[26:29]
	v_mfma_f32_16x16x32_bf16 v[14:17], v[58:61], v[208:211], v[14:17]
	v_mfma_f32_16x16x32_bf16 v[14:17], v[62:65], v[212:215], v[14:17]
	s_waitcnt lgkmcnt(0)
	v_mfma_f32_16x16x32_bf16 v[10:13], v[66:69], v[208:211], v[10:13]
	v_mfma_f32_16x16x32_bf16 v[10:13], v[70:73], v[212:215], v[10:13]
	s_setprio 0
	s_setprio 1
	v_mfma_f32_16x16x32_bf16 v[46:49], v[146:149], v[170:173], v[46:49]
	v_mfma_f32_16x16x32_bf16 v[70:73], v[150:153], v[188:191], v[46:49]
	v_mfma_f32_16x16x32_bf16 v[46:49], v[154:157], v[170:173], v[54:57]
	v_mfma_f32_16x16x32_bf16 v[66:69], v[158:161], v[188:191], v[46:49]
	v_mfma_f32_16x16x32_bf16 v[38:41], v[146:149], v[192:195], v[38:41]
	v_mfma_f32_16x16x32_bf16 v[38:41], v[150:153], v[196:199], v[38:41]
	v_mfma_f32_16x16x32_bf16 v[34:37], v[154:157], v[192:195], v[34:37]
	v_mfma_f32_16x16x32_bf16 v[34:37], v[158:161], v[196:199], v[34:37]
	v_mfma_f32_16x16x32_bf16 v[22:25], v[146:149], v[200:203], v[22:25]
	v_mfma_f32_16x16x32_bf16 v[22:25], v[150:153], v[204:207], v[22:25]
	v_mfma_f32_16x16x32_bf16 v[18:21], v[154:157], v[200:203], v[18:21]
	v_mfma_f32_16x16x32_bf16 v[18:21], v[158:161], v[204:207], v[18:21]
	s_setprio 2
	s_barrier
	v_mfma_f32_16x16x32_bf16 v[6:9], v[146:149], v[208:211], v[6:9]
	v_mfma_f32_16x16x32_bf16 v[6:9], v[150:153], v[212:215], v[6:9]
	v_mfma_f32_16x16x32_bf16 v[2:5], v[154:157], v[208:211], v[2:5]
	v_mfma_f32_16x16x32_bf16 v[2:5], v[158:161], v[212:215], v[2:5]
	s_setprio 0
	s_add_i32 s83, s83, 2
	s_add_u32 s79, s79, 0x100
	s_addc_u32 s80, s80, 0
	s_add_u32 s30, s30, 0x100
	s_addc_u32 s31, s31, 0
	s_add_u32 s81, s81, 0x100
	s_addc_u32 s82, s82, 0
	s_cmp_gt_u32 s83, 29
	s_cbranch_scc0 .LBB0_1538
	s_and_b64 vcc, exec, s[16:17]
	s_cbranch_vccz .LBB0_1541
	s_barrier

.LBB0_1784:
	s_ashr_i32 s11, s10, 31
	s_lshl_b64 s[12:13], s[10:11], 20
	s_add_u32 s12, s26, s12
	s_addc_u32 s13, s27, s13
	s_and_b64 s[14:15], s[2:3], exec
	s_cselect_b32 s11, s13, s21
	s_cselect_b32 s64, s12, s20
	s_ashr_i32 s9, s8, 31
	s_lshl_b64 s[14:15], s[8:9], 20
	s_add_u32 s14, s28, s14
	s_addc_u32 s15, s29, s15
	s_and_b64 s[22:23], s[2:3], exec
	s_cselect_b32 s9, s15, s19
	s_cselect_b32 s65, s14, s18
	s_add_u32 s66, s18, 0x100
	s_addc_u32 s67, s19, 0
	s_add_u32 s18, s20, 0x80080
	s_addc_u32 s19, s21, 0
	s_add_u32 s70, s20, 0x100
	s_addc_u32 s71, s21, 0
	s_mov_b32 s73, -2
	ds_read_b128 v[148:151], v143
	ds_read_b128 v[152:155], v143 offset:1024
	ds_read_b128 v[156:159], v143 offset:2048
	ds_read_b128 v[160:163], v143 offset:3072
	ds_read_b128 v[164:167], v144
	ds_read_b128 v[168:171], v144 offset:1024
	ds_read_b128 v[172:175], v144 offset:2048
	ds_read_b128 v[176:179], v144 offset:3072
	s_cmp_eq_u32 s73, 28
	s_cselect_b32 s21, s9, s67
	s_cselect_b32 s20, s65, s66
	s_cselect_b32 s23, s11, s71
	s_cselect_b32 s22, s64, s70
	ds_read_b128 v[180:183], v145
	ds_read_b128 v[184:187], v145 offset:1024
	ds_read_b128 v[188:191], v145 offset:2048
	ds_read_b128 v[192:195], v145 offset:3072
	ds_read_b128 v[196:199], v145 offset:4096
	ds_read_b128 v[200:203], v145 offset:5120
	ds_read_b128 v[204:207], v145 offset:6144
	ds_read_b128 v[208:211], v145 offset:7168
	s_add_u32 s74, s18, 0xfff80000
	s_addc_u32 s75, s19, -1
	s_mov_b32 s76, m0
	s_mov_b32 m0, s56
	s_nop 0
	global_load_lds_dwordx4 v138, s[74:75]
	s_mov_b32 m0, s76
	s_nop 0
	s_mov_b32 s76, m0
	s_mov_b32 m0, s59
	s_nop 0
	global_load_lds_dwordx4 v140, s[74:75]
	s_mov_b32 m0, s76
	s_mov_b32 s74, m0
	s_mov_b32 m0, s57
	s_nop 0
	global_load_lds_dwordx4 v138, s[18:19]
	s_mov_b32 m0, s74
	s_nop 0
	s_mov_b32 s74, m0
	s_mov_b32 m0, s62
	s_nop 0
	global_load_lds_dwordx4 v140, s[18:19]
	s_mov_b32 m0, s74
	s_waitcnt vmcnt(8)
	s_waitcnt lgkmcnt(0)
	s_barrier
	s_setprio 1
	s_waitcnt lgkmcnt(7)
	v_mfma_f32_16x16x32_bf16 v[126:129], v[148:151], v[180:183], 0
	v_mfma_f32_16x16x32_bf16 v[126:129], v[152:155], v[184:187], v[126:129]
	s_waitcnt lgkmcnt(5)
	v_mfma_f32_16x16x32_bf16 v[122:125], v[156:159], v[180:183], 0
	v_mfma_f32_16x16x32_bf16 v[122:125], v[160:163], v[184:187], v[122:125]
	s_waitcnt lgkmcnt(3)
	v_mfma_f32_16x16x32_bf16 v[106:109], v[156:159], v[188:191], 0
	v_mfma_f32_16x16x32_bf16 v[106:109], v[160:163], v[192:195], v[106:109]
	s_waitcnt lgkmcnt(1)
	v_mfma_f32_16x16x32_bf16 v[110:113], v[148:151], v[188:191], 0
	v_mfma_f32_16x16x32_bf16 v[110:113], v[152:155], v[192:195], v[110:113]
	v_mfma_f32_16x16x32_bf16 v[94:97], v[148:151], v[196:199], 0
	v_mfma_f32_16x16x32_bf16 v[94:97], v[152:155], v[200:203], v[94:97]
	v_mfma_f32_16x16x32_bf16 v[90:93], v[156:159], v[196:199], 0
	v_mfma_f32_16x16x32_bf16 v[90:93], v[160:163], v[200:203], v[90:93]
	v_mfma_f32_16x16x32_bf16 v[74:77], v[156:159], v[204:207], 0
	v_mfma_f32_16x16x32_bf16 v[74:77], v[160:163], v[208:211], v[74:77]
	s_waitcnt lgkmcnt(0)
	v_mfma_f32_16x16x32_bf16 v[78:81], v[148:151], v[204:207], 0
	v_mfma_f32_16x16x32_bf16 v[78:81], v[152:155], v[208:211], v[78:81]
	s_setprio 0
	s_setprio 1
	v_mfma_f32_16x16x32_bf16 v[118:121], v[164:167], v[180:183], 0
	v_mfma_f32_16x16x32_bf16 v[118:121], v[168:171], v[184:187], v[118:121]
	v_mfma_f32_16x16x32_bf16 v[114:117], v[172:175], v[180:183], 0
	v_mfma_f32_16x16x32_bf16 v[114:117], v[176:179], v[184:187], v[114:117]
	v_mfma_f32_16x16x32_bf16 v[98:101], v[172:175], v[188:191], 0
	v_mfma_f32_16x16x32_bf16 v[98:101], v[176:179], v[192:195], v[98:101]
	v_mfma_f32_16x16x32_bf16 v[102:105], v[164:167], v[188:191], 0
	v_mfma_f32_16x16x32_bf16 v[102:105], v[168:171], v[192:195], v[102:105]
	v_mfma_f32_16x16x32_bf16 v[86:89], v[164:167], v[196:199], 0
	v_mfma_f32_16x16x32_bf16 v[86:89], v[168:171], v[200:203], v[86:89]
	v_mfma_f32_16x16x32_bf16 v[82:85], v[172:175], v[196:199], 0
	v_mfma_f32_16x16x32_bf16 v[82:85], v[176:179], v[200:203], v[82:85]
	s_setprio 2
	s_barrier
	v_mfma_f32_16x16x32_bf16 v[66:69], v[172:175], v[204:207], 0
	v_mfma_f32_16x16x32_bf16 v[66:69], v[176:179], v[208:211], v[66:69]
	v_mfma_f32_16x16x32_bf16 v[70:73], v[164:167], v[204:207], 0
	v_mfma_f32_16x16x32_bf16 v[70:73], v[168:171], v[208:211], v[70:73]
	s_setprio 0
	ds_read_b128 v[180:183], v145 offset:16384
	ds_read_b128 v[184:187], v145 offset:17408
	ds_read_b128 v[188:191], v145 offset:18432
	ds_read_b128 v[192:195], v145 offset:19456
	ds_read_b128 v[196:199], v145 offset:20480
	ds_read_b128 v[200:203], v145 offset:21504
	ds_read_b128 v[204:207], v145 offset:22528
	ds_read_b128 v[208:211], v145 offset:23552
	s_mov_b32 s74, m0
	s_mov_b32 m0, s35
	s_nop 0
	global_load_lds_dwordx4 v139, s[20:21]
	s_mov_b32 m0, s74
	s_nop 0
	s_mov_b32 s74, m0
	s_mov_b32 m0, s36
	s_nop 0
	global_load_lds_dwordx4 v141, s[20:21]
	s_mov_b32 m0, s74
	s_add_u32 s74, s20, 0x80000
	s_addc_u32 s75, s21, 0
	s_mov_b32 s76, m0
	s_mov_b32 m0, s37
	s_nop 0
	global_load_lds_dwordx4 v139, s[74:75]
	s_mov_b32 m0, s76
	s_nop 0
	s_mov_b32 s76, m0
	s_mov_b32 m0, s40
	s_nop 0
	global_load_lds_dwordx4 v141, s[74:75]
	s_mov_b32 m0, s76
	s_waitcnt vmcnt(4)
	s_waitcnt lgkmcnt(0)
	s_barrier
	s_setprio 1
	s_waitcnt lgkmcnt(7)
	v_mfma_f32_16x16x32_bf16 v[62:65], v[148:151], v[180:183], 0
	v_mfma_f32_16x16x32_bf16 v[62:65], v[152:155], v[184:187], v[62:65]
	s_waitcnt lgkmcnt(5)
	v_mfma_f32_16x16x32_bf16 v[58:61], v[156:159], v[180:183], 0
	v_mfma_f32_16x16x32_bf16 v[58:61], v[160:163], v[184:187], v[58:61]
	s_waitcnt lgkmcnt(3)
	v_mfma_f32_16x16x32_bf16 v[42:45], v[156:159], v[188:191], 0
	v_mfma_f32_16x16x32_bf16 v[42:45], v[160:163], v[192:195], v[42:45]
	s_waitcnt lgkmcnt(1)
	v_mfma_f32_16x16x32_bf16 v[46:49], v[148:151], v[188:191], 0
	v_mfma_f32_16x16x32_bf16 v[46:49], v[152:155], v[192:195], v[46:49]
	v_mfma_f32_16x16x32_bf16 v[30:33], v[148:151], v[196:199], 0
	v_mfma_f32_16x16x32_bf16 v[30:33], v[152:155], v[200:203], v[30:33]
	v_mfma_f32_16x16x32_bf16 v[26:29], v[156:159], v[196:199], 0
	v_mfma_f32_16x16x32_bf16 v[26:29], v[160:163], v[200:203], v[26:29]
	v_mfma_f32_16x16x32_bf16 v[10:13], v[156:159], v[204:207], 0
	v_mfma_f32_16x16x32_bf16 v[10:13], v[160:163], v[208:211], v[10:13]
	s_waitcnt lgkmcnt(0)
	v_mfma_f32_16x16x32_bf16 v[14:17], v[148:151], v[204:207], 0
	v_mfma_f32_16x16x32_bf16 v[14:17], v[152:155], v[208:211], v[14:17]
	s_setprio 0
	s_setprio 1
	v_mfma_f32_16x16x32_bf16 v[54:57], v[164:167], v[180:183], 0
	v_mfma_f32_16x16x32_bf16 v[54:57], v[168:171], v[184:187], v[54:57]
	v_mfma_f32_16x16x32_bf16 v[50:53], v[172:175], v[180:183], 0
	v_mfma_f32_16x16x32_bf16 v[50:53], v[176:179], v[184:187], v[50:53]
	v_mfma_f32_16x16x32_bf16 v[34:37], v[172:175], v[188:191], 0
	v_mfma_f32_16x16x32_bf16 v[34:37], v[176:179], v[192:195], v[34:37]
	v_mfma_f32_16x16x32_bf16 v[38:41], v[164:167], v[188:191], 0
	v_mfma_f32_16x16x32_bf16 v[38:41], v[168:171], v[192:195], v[38:41]
	v_mfma_f32_16x16x32_bf16 v[22:25], v[164:167], v[196:199], 0
	v_mfma_f32_16x16x32_bf16 v[22:25], v[168:171], v[200:203], v[22:25]
	v_mfma_f32_16x16x32_bf16 v[18:21], v[172:175], v[196:199], 0
	v_mfma_f32_16x16x32_bf16 v[18:21], v[176:179], v[200:203], v[18:21]
	s_setprio 2
	s_barrier
	v_mfma_f32_16x16x32_bf16 v[2:5], v[172:175], v[204:207], 0
	v_mfma_f32_16x16x32_bf16 v[2:5], v[176:179], v[208:211], v[2:5]
	v_mfma_f32_16x16x32_bf16 v[6:9], v[164:167], v[204:207], 0
	v_mfma_f32_16x16x32_bf16 v[6:9], v[168:171], v[208:211], v[6:9]
	s_setprio 0
	ds_read_b128 v[148:151], v146
	ds_read_b128 v[152:155], v146 offset:1024
	ds_read_b128 v[156:159], v146 offset:2048
	ds_read_b128 v[160:163], v146 offset:3072
	ds_read_b128 v[164:167], v147
	ds_read_b128 v[168:171], v147 offset:1024
	ds_read_b128 v[172:175], v147 offset:2048
	ds_read_b128 v[176:179], v147 offset:3072
	ds_read_b128 v[180:183], v145 offset:32768
	ds_read_b128 v[184:187], v145 offset:33792
	ds_read_b128 v[188:191], v145 offset:34816
	ds_read_b128 v[192:195], v145 offset:35840
	ds_read_b128 v[196:199], v145 offset:36864
	ds_read_b128 v[200:203], v145 offset:37888
	ds_read_b128 v[204:207], v145 offset:38912
	ds_read_b128 v[208:211], v145 offset:39936
	s_mov_b32 s74, m0
	s_mov_b32 m0, s31
	s_nop 0
	global_load_lds_dwordx4 v138, s[22:23]
	s_mov_b32 m0, s74
	s_nop 0
	s_mov_b32 s74, m0
	s_mov_b32 m0, s41
	s_nop 0
	global_load_lds_dwordx4 v140, s[22:23]
	s_mov_b32 m0, s74
	s_add_u32 s22, s22, 0x80000
	s_addc_u32 s23, s23, 0
	s_mov_b32 s74, m0
	s_mov_b32 m0, s42
	s_nop 0
	global_load_lds_dwordx4 v138, s[22:23]
	s_mov_b32 m0, s74
	s_nop 0
	s_mov_b32 s74, m0
	s_mov_b32 m0, s43
	s_nop 0
	global_load_lds_dwordx4 v140, s[22:23]
	s_mov_b32 m0, s74
	s_waitcnt vmcnt(8)
	s_waitcnt lgkmcnt(0)
	s_barrier
	s_setprio 1
	s_waitcnt lgkmcnt(7)
	v_mfma_f32_16x16x32_bf16 v[126:129], v[148:151], v[180:183], v[126:129]
	v_mfma_f32_16x16x32_bf16 v[126:129], v[152:155], v[184:187], v[126:129]
	s_waitcnt lgkmcnt(5)
	v_mfma_f32_16x16x32_bf16 v[122:125], v[156:159], v[180:183], v[122:125]
	v_mfma_f32_16x16x32_bf16 v[122:125], v[160:163], v[184:187], v[122:125]
	s_waitcnt lgkmcnt(3)
	v_mfma_f32_16x16x32_bf16 v[106:109], v[156:159], v[188:191], v[106:109]
	v_mfma_f32_16x16x32_bf16 v[106:109], v[160:163], v[192:195], v[106:109]
	s_waitcnt lgkmcnt(1)
	v_mfma_f32_16x16x32_bf16 v[110:113], v[148:151], v[188:191], v[110:113]
	v_mfma_f32_16x16x32_bf16 v[110:113], v[152:155], v[192:195], v[110:113]
	v_mfma_f32_16x16x32_bf16 v[94:97], v[148:151], v[196:199], v[94:97]
	v_mfma_f32_16x16x32_bf16 v[94:97], v[152:155], v[200:203], v[94:97]
	v_mfma_f32_16x16x32_bf16 v[90:93], v[156:159], v[196:199], v[90:93]
	v_mfma_f32_16x16x32_bf16 v[90:93], v[160:163], v[200:203], v[90:93]
	v_mfma_f32_16x16x32_bf16 v[74:77], v[156:159], v[204:207], v[74:77]
	v_mfma_f32_16x16x32_bf16 v[74:77], v[160:163], v[208:211], v[74:77]
	s_waitcnt lgkmcnt(0)
	v_mfma_f32_16x16x32_bf16 v[78:81], v[148:151], v[204:207], v[78:81]
	v_mfma_f32_16x16x32_bf16 v[78:81], v[152:155], v[208:211], v[78:81]
	s_setprio 0
	s_setprio 1
	v_mfma_f32_16x16x32_bf16 v[118:121], v[164:167], v[180:183], v[118:121]
	v_mfma_f32_16x16x32_bf16 v[118:121], v[168:171], v[184:187], v[118:121]
	v_mfma_f32_16x16x32_bf16 v[114:117], v[172:175], v[180:183], v[114:117]
	v_mfma_f32_16x16x32_bf16 v[114:117], v[176:179], v[184:187], v[114:117]
	v_mfma_f32_16x16x32_bf16 v[98:101], v[172:175], v[188:191], v[98:101]
	v_mfma_f32_16x16x32_bf16 v[98:101], v[176:179], v[192:195], v[98:101]
	v_mfma_f32_16x16x32_bf16 v[102:105], v[164:167], v[188:191], v[102:105]
	v_mfma_f32_16x16x32_bf16 v[102:105], v[168:171], v[192:195], v[102:105]
	v_mfma_f32_16x16x32_bf16 v[86:89], v[164:167], v[196:199], v[86:89]
	v_mfma_f32_16x16x32_bf16 v[86:89], v[168:171], v[200:203], v[86:89]
	v_mfma_f32_16x16x32_bf16 v[82:85], v[172:175], v[196:199], v[82:85]
	v_mfma_f32_16x16x32_bf16 v[82:85], v[176:179], v[200:203], v[82:85]
	s_setprio 2
	s_barrier
	v_mfma_f32_16x16x32_bf16 v[66:69], v[172:175], v[204:207], v[66:69]
	v_mfma_f32_16x16x32_bf16 v[66:69], v[176:179], v[208:211], v[66:69]
	v_mfma_f32_16x16x32_bf16 v[70:73], v[164:167], v[204:207], v[70:73]
	v_mfma_f32_16x16x32_bf16 v[70:73], v[168:171], v[208:211], v[70:73]
	s_setprio 0
	ds_read_b128 v[180:183], v145 offset:49152
	ds_read_b128 v[184:187], v145 offset:50176
	ds_read_b128 v[188:191], v145 offset:51200
	ds_read_b128 v[192:195], v145 offset:52224
	ds_read_b128 v[196:199], v145 offset:53248
	ds_read_b128 v[200:203], v145 offset:54272
	ds_read_b128 v[204:207], v145 offset:55296
	ds_read_b128 v[208:211], v145 offset:56320
	s_add_u32 s22, s20, 0x80
	s_addc_u32 s23, s21, 0
	s_mov_b32 s74, m0
	s_mov_b32 m0, s46
	s_nop 0
	global_load_lds_dwordx4 v139, s[22:23]
	s_mov_b32 m0, s74
	s_add_u32 s20, s20, 0x80080
	s_mov_b32 s74, m0
	s_mov_b32 m0, s47
	s_nop 0
	global_load_lds_dwordx4 v141, s[22:23]
	s_mov_b32 m0, s74
	s_addc_u32 s21, s21, 0
	s_mov_b32 s22, m0
	s_mov_b32 m0, s48
	s_nop 0
	global_load_lds_dwordx4 v139, s[20:21]
	s_mov_b32 m0, s22
	s_nop 0
	s_mov_b32 s22, m0
	s_mov_b32 m0, s49
	s_nop 0
	global_load_lds_dwordx4 v141, s[20:21]
	s_mov_b32 m0, s22
	s_waitcnt vmcnt(4)
	s_waitcnt lgkmcnt(0)
	s_barrier
	s_setprio 1
	s_waitcnt lgkmcnt(7)
	v_mfma_f32_16x16x32_bf16 v[62:65], v[148:151], v[180:183], v[62:65]
	v_mfma_f32_16x16x32_bf16 v[62:65], v[152:155], v[184:187], v[62:65]
	s_waitcnt lgkmcnt(5)
	v_mfma_f32_16x16x32_bf16 v[58:61], v[156:159], v[180:183], v[58:61]
	v_mfma_f32_16x16x32_bf16 v[58:61], v[160:163], v[184:187], v[58:61]
	s_waitcnt lgkmcnt(3)
	v_mfma_f32_16x16x32_bf16 v[42:45], v[156:159], v[188:191], v[42:45]
	v_mfma_f32_16x16x32_bf16 v[42:45], v[160:163], v[192:195], v[42:45]
	s_waitcnt lgkmcnt(1)
	v_mfma_f32_16x16x32_bf16 v[46:49], v[148:151], v[188:191], v[46:49]
	v_mfma_f32_16x16x32_bf16 v[46:49], v[152:155], v[192:195], v[46:49]
	v_mfma_f32_16x16x32_bf16 v[30:33], v[148:151], v[196:199], v[30:33]
	v_mfma_f32_16x16x32_bf16 v[30:33], v[152:155], v[200:203], v[30:33]
	v_mfma_f32_16x16x32_bf16 v[26:29], v[156:159], v[196:199], v[26:29]
	v_mfma_f32_16x16x32_bf16 v[26:29], v[160:163], v[200:203], v[26:29]
	v_mfma_f32_16x16x32_bf16 v[10:13], v[156:159], v[204:207], v[10:13]
	v_mfma_f32_16x16x32_bf16 v[10:13], v[160:163], v[208:211], v[10:13]
	s_waitcnt lgkmcnt(0)
	v_mfma_f32_16x16x32_bf16 v[14:17], v[148:151], v[204:207], v[14:17]
	v_mfma_f32_16x16x32_bf16 v[14:17], v[152:155], v[208:211], v[14:17]
	s_setprio 0
	s_setprio 1
	v_mfma_f32_16x16x32_bf16 v[54:57], v[164:167], v[180:183], v[54:57]
	v_mfma_f32_16x16x32_bf16 v[54:57], v[168:171], v[184:187], v[54:57]
	v_mfma_f32_16x16x32_bf16 v[50:53], v[172:175], v[180:183], v[50:53]
	v_mfma_f32_16x16x32_bf16 v[50:53], v[176:179], v[184:187], v[50:53]
	v_mfma_f32_16x16x32_bf16 v[34:37], v[172:175], v[188:191], v[34:37]
	v_mfma_f32_16x16x32_bf16 v[34:37], v[176:179], v[192:195], v[34:37]
	v_mfma_f32_16x16x32_bf16 v[38:41], v[164:167], v[188:191], v[38:41]
	v_mfma_f32_16x16x32_bf16 v[38:41], v[168:171], v[192:195], v[38:41]
	v_mfma_f32_16x16x32_bf16 v[22:25], v[164:167], v[196:199], v[22:25]
	v_mfma_f32_16x16x32_bf16 v[22:25], v[168:171], v[200:203], v[22:25]
	v_mfma_f32_16x16x32_bf16 v[18:21], v[172:175], v[196:199], v[18:21]
	v_mfma_f32_16x16x32_bf16 v[18:21], v[176:179], v[200:203], v[18:21]
	s_setprio 2
	s_barrier
	v_mfma_f32_16x16x32_bf16 v[2:5], v[172:175], v[204:207], v[2:5]
	v_mfma_f32_16x16x32_bf16 v[2:5], v[176:179], v[208:211], v[2:5]
	v_mfma_f32_16x16x32_bf16 v[6:9], v[164:167], v[204:207], v[6:9]
	v_mfma_f32_16x16x32_bf16 v[6:9], v[168:171], v[208:211], v[6:9]
	s_setprio 0
	s_add_i32 s73, s73, 2
	s_add_u32 s66, s66, 0x100
	s_addc_u32 s67, s67, 0
	s_add_u32 s18, s18, 0x100
	s_addc_u32 s19, s19, 0
	s_add_u32 s70, s70, 0x100
	s_addc_u32 s71, s71, 0
	s_cmp_gt_u32 s73, 29
	.p2align 6
.LBB0_1785:
	ds_read_b128 v[148:151], v143
	ds_read_b128 v[152:155], v143 offset:1024
	ds_read_b128 v[156:159], v143 offset:2048
	ds_read_b128 v[160:163], v143 offset:3072
	ds_read_b128 v[164:167], v144
	ds_read_b128 v[168:171], v144 offset:1024
	ds_read_b128 v[172:175], v144 offset:2048
	ds_read_b128 v[176:179], v144 offset:3072
	s_cmp_eq_u32 s73, 28
	s_cselect_b32 s21, s9, s67
	s_cselect_b32 s20, s65, s66
	s_cselect_b32 s23, s11, s71
	s_cselect_b32 s22, s64, s70
	ds_read_b128 v[180:183], v145
	ds_read_b128 v[184:187], v145 offset:1024
	ds_read_b128 v[188:191], v145 offset:2048
	ds_read_b128 v[192:195], v145 offset:3072
	ds_read_b128 v[196:199], v145 offset:4096
	ds_read_b128 v[200:203], v145 offset:5120
	ds_read_b128 v[204:207], v145 offset:6144
	ds_read_b128 v[208:211], v145 offset:7168
	s_add_u32 s74, s18, 0xfff80000
	s_addc_u32 s75, s19, -1
	s_mov_b32 s76, m0
	s_mov_b32 m0, s56
	s_nop 0
	global_load_lds_dwordx4 v138, s[74:75]
	s_mov_b32 m0, s76
	s_nop 0
	s_mov_b32 s76, m0
	s_mov_b32 m0, s59
	s_nop 0
	global_load_lds_dwordx4 v140, s[74:75]
	s_mov_b32 m0, s76
	s_mov_b32 s74, m0
	s_mov_b32 m0, s57
	s_nop 0
	global_load_lds_dwordx4 v138, s[18:19]
	s_mov_b32 m0, s74
	s_nop 0
	s_mov_b32 s74, m0
	s_mov_b32 m0, s62
	s_nop 0
	global_load_lds_dwordx4 v140, s[18:19]
	s_mov_b32 m0, s74
	s_waitcnt vmcnt(8)
	s_waitcnt lgkmcnt(0)
	s_barrier
	s_setprio 1
	s_waitcnt lgkmcnt(7)
	v_mfma_f32_16x16x32_bf16 v[126:129], v[148:151], v[180:183], v[126:129]
	v_mfma_f32_16x16x32_bf16 v[126:129], v[152:155], v[184:187], v[126:129]
	s_waitcnt lgkmcnt(5)
	v_mfma_f32_16x16x32_bf16 v[122:125], v[156:159], v[180:183], v[122:125]
	v_mfma_f32_16x16x32_bf16 v[122:125], v[160:163], v[184:187], v[122:125]
	s_waitcnt lgkmcnt(3)
	v_mfma_f32_16x16x32_bf16 v[106:109], v[156:159], v[188:191], v[106:109]
	v_mfma_f32_16x16x32_bf16 v[106:109], v[160:163], v[192:195], v[106:109]
	s_waitcnt lgkmcnt(1)
	v_mfma_f32_16x16x32_bf16 v[110:113], v[148:151], v[188:191], v[110:113]
	v_mfma_f32_16x16x32_bf16 v[110:113], v[152:155], v[192:195], v[110:113]
	v_mfma_f32_16x16x32_bf16 v[94:97], v[148:151], v[196:199], v[94:97]
	v_mfma_f32_16x16x32_bf16 v[94:97], v[152:155], v[200:203], v[94:97]
	v_mfma_f32_16x16x32_bf16 v[90:93], v[156:159], v[196:199], v[90:93]
	v_mfma_f32_16x16x32_bf16 v[90:93], v[160:163], v[200:203], v[90:93]
	v_mfma_f32_16x16x32_bf16 v[74:77], v[156:159], v[204:207], v[74:77]
	v_mfma_f32_16x16x32_bf16 v[74:77], v[160:163], v[208:211], v[74:77]
	s_waitcnt lgkmcnt(0)
	v_mfma_f32_16x16x32_bf16 v[78:81], v[148:151], v[204:207], v[78:81]
	v_mfma_f32_16x16x32_bf16 v[78:81], v[152:155], v[208:211], v[78:81]
	s_setprio 0
	s_setprio 1
	v_mfma_f32_16x16x32_bf16 v[118:121], v[164:167], v[180:183], v[118:121]
	v_mfma_f32_16x16x32_bf16 v[118:121], v[168:171], v[184:187], v[118:121]
	v_mfma_f32_16x16x32_bf16 v[114:117], v[172:175], v[180:183], v[114:117]
	v_mfma_f32_16x16x32_bf16 v[114:117], v[176:179], v[184:187], v[114:117]
	v_mfma_f32_16x16x32_bf16 v[98:101], v[172:175], v[188:191], v[98:101]
	v_mfma_f32_16x16x32_bf16 v[98:101], v[176:179], v[192:195], v[98:101]
	v_mfma_f32_16x16x32_bf16 v[102:105], v[164:167], v[188:191], v[102:105]
	v_mfma_f32_16x16x32_bf16 v[102:105], v[168:171], v[192:195], v[102:105]
	v_mfma_f32_16x16x32_bf16 v[86:89], v[164:167], v[196:199], v[86:89]
	v_mfma_f32_16x16x32_bf16 v[86:89], v[168:171], v[200:203], v[86:89]
	v_mfma_f32_16x16x32_bf16 v[82:85], v[172:175], v[196:199], v[82:85]
	v_mfma_f32_16x16x32_bf16 v[82:85], v[176:179], v[200:203], v[82:85]
	s_setprio 2
	s_barrier
	v_mfma_f32_16x16x32_bf16 v[66:69], v[172:175], v[204:207], v[66:69]
	v_mfma_f32_16x16x32_bf16 v[66:69], v[176:179], v[208:211], v[66:69]
	v_mfma_f32_16x16x32_bf16 v[70:73], v[164:167], v[204:207], v[70:73]
	v_mfma_f32_16x16x32_bf16 v[70:73], v[168:171], v[208:211], v[70:73]
	s_setprio 0
	ds_read_b128 v[180:183], v145 offset:16384
	ds_read_b128 v[184:187], v145 offset:17408
	ds_read_b128 v[188:191], v145 offset:18432
	ds_read_b128 v[192:195], v145 offset:19456
	ds_read_b128 v[196:199], v145 offset:20480
	ds_read_b128 v[200:203], v145 offset:21504
	ds_read_b128 v[204:207], v145 offset:22528
	ds_read_b128 v[208:211], v145 offset:23552
	s_mov_b32 s74, m0
	s_mov_b32 m0, s35
	s_nop 0
	global_load_lds_dwordx4 v139, s[20:21]
	s_mov_b32 m0, s74
	s_nop 0
	s_mov_b32 s74, m0
	s_mov_b32 m0, s36
	s_nop 0
	global_load_lds_dwordx4 v141, s[20:21]
	s_mov_b32 m0, s74
	s_add_u32 s74, s20, 0x80000
	s_addc_u32 s75, s21, 0
	s_mov_b32 s76, m0
	s_mov_b32 m0, s37
	s_nop 0
	global_load_lds_dwordx4 v139, s[74:75]
	s_mov_b32 m0, s76
	s_nop 0
	s_mov_b32 s76, m0
	s_mov_b32 m0, s40
	s_nop 0
	global_load_lds_dwordx4 v141, s[74:75]
	s_mov_b32 m0, s76
	s_waitcnt vmcnt(4)
	s_waitcnt lgkmcnt(0)
	s_barrier
	s_setprio 1
	s_waitcnt lgkmcnt(7)
	v_mfma_f32_16x16x32_bf16 v[62:65], v[148:151], v[180:183], v[62:65]
	v_mfma_f32_16x16x32_bf16 v[62:65], v[152:155], v[184:187], v[62:65]
	s_waitcnt lgkmcnt(5)
	v_mfma_f32_16x16x32_bf16 v[58:61], v[156:159], v[180:183], v[58:61]
	v_mfma_f32_16x16x32_bf16 v[58:61], v[160:163], v[184:187], v[58:61]
	s_waitcnt lgkmcnt(3)
	v_mfma_f32_16x16x32_bf16 v[42:45], v[156:159], v[188:191], v[42:45]
	v_mfma_f32_16x16x32_bf16 v[42:45], v[160:163], v[192:195], v[42:45]
	s_waitcnt lgkmcnt(1)
	v_mfma_f32_16x16x32_bf16 v[46:49], v[148:151], v[188:191], v[46:49]
	v_mfma_f32_16x16x32_bf16 v[46:49], v[152:155], v[192:195], v[46:49]
	v_mfma_f32_16x16x32_bf16 v[30:33], v[148:151], v[196:199], v[30:33]
	v_mfma_f32_16x16x32_bf16 v[30:33], v[152:155], v[200:203], v[30:33]
	v_mfma_f32_16x16x32_bf16 v[26:29], v[156:159], v[196:199], v[26:29]
	v_mfma_f32_16x16x32_bf16 v[26:29], v[160:163], v[200:203], v[26:29]
	v_mfma_f32_16x16x32_bf16 v[10:13], v[156:159], v[204:207], v[10:13]
	v_mfma_f32_16x16x32_bf16 v[10:13], v[160:163], v[208:211], v[10:13]
	s_waitcnt lgkmcnt(0)
	v_mfma_f32_16x16x32_bf16 v[14:17], v[148:151], v[204:207], v[14:17]
	v_mfma_f32_16x16x32_bf16 v[14:17], v[152:155], v[208:211], v[14:17]
	s_setprio 0
	s_setprio 1
	v_mfma_f32_16x16x32_bf16 v[54:57], v[164:167], v[180:183], v[54:57]
	v_mfma_f32_16x16x32_bf16 v[54:57], v[168:171], v[184:187], v[54:57]
	v_mfma_f32_16x16x32_bf16 v[50:53], v[172:175], v[180:183], v[50:53]
	v_mfma_f32_16x16x32_bf16 v[50:53], v[176:179], v[184:187], v[50:53]
	v_mfma_f32_16x16x32_bf16 v[34:37], v[172:175], v[188:191], v[34:37]
	v_mfma_f32_16x16x32_bf16 v[34:37], v[176:179], v[192:195], v[34:37]
	v_mfma_f32_16x16x32_bf16 v[38:41], v[164:167], v[188:191], v[38:41]
	v_mfma_f32_16x16x32_bf16 v[38:41], v[168:171], v[192:195], v[38:41]
	v_mfma_f32_16x16x32_bf16 v[22:25], v[164:167], v[196:199], v[22:25]
	v_mfma_f32_16x16x32_bf16 v[22:25], v[168:171], v[200:203], v[22:25]
	v_mfma_f32_16x16x32_bf16 v[18:21], v[172:175], v[196:199], v[18:21]
	v_mfma_f32_16x16x32_bf16 v[18:21], v[176:179], v[200:203], v[18:21]
	s_setprio 2
	s_barrier
	v_mfma_f32_16x16x32_bf16 v[2:5], v[172:175], v[204:207], v[2:5]
	v_mfma_f32_16x16x32_bf16 v[2:5], v[176:179], v[208:211], v[2:5]
	v_mfma_f32_16x16x32_bf16 v[6:9], v[164:167], v[204:207], v[6:9]
	v_mfma_f32_16x16x32_bf16 v[6:9], v[168:171], v[208:211], v[6:9]
	s_setprio 0
	ds_read_b128 v[148:151], v146
	ds_read_b128 v[152:155], v146 offset:1024
	ds_read_b128 v[156:159], v146 offset:2048
	ds_read_b128 v[160:163], v146 offset:3072
	ds_read_b128 v[164:167], v147
	ds_read_b128 v[168:171], v147 offset:1024
	ds_read_b128 v[172:175], v147 offset:2048
	ds_read_b128 v[176:179], v147 offset:3072
	ds_read_b128 v[180:183], v145 offset:32768
	ds_read_b128 v[184:187], v145 offset:33792
	ds_read_b128 v[188:191], v145 offset:34816
	ds_read_b128 v[192:195], v145 offset:35840
	ds_read_b128 v[196:199], v145 offset:36864
	ds_read_b128 v[200:203], v145 offset:37888
	ds_read_b128 v[204:207], v145 offset:38912
	ds_read_b128 v[208:211], v145 offset:39936
	s_mov_b32 s74, m0
	s_mov_b32 m0, s31
	s_nop 0
	global_load_lds_dwordx4 v138, s[22:23]
	s_mov_b32 m0, s74
	s_nop 0
	s_mov_b32 s74, m0
	s_mov_b32 m0, s41
	s_nop 0
	global_load_lds_dwordx4 v140, s[22:23]
	s_mov_b32 m0, s74
	s_add_u32 s22, s22, 0x80000
	s_addc_u32 s23, s23, 0
	s_mov_b32 s74, m0
	s_mov_b32 m0, s42
	s_nop 0
	global_load_lds_dwordx4 v138, s[22:23]
	s_mov_b32 m0, s74
	s_nop 0
	s_mov_b32 s74, m0
	s_mov_b32 m0, s43
	s_nop 0
	global_load_lds_dwordx4 v140, s[22:23]
	s_mov_b32 m0, s74
	s_waitcnt vmcnt(8)
	s_waitcnt lgkmcnt(0)
	s_barrier
	s_setprio 1
	s_waitcnt lgkmcnt(7)
	v_mfma_f32_16x16x32_bf16 v[126:129], v[148:151], v[180:183], v[126:129]
	v_mfma_f32_16x16x32_bf16 v[126:129], v[152:155], v[184:187], v[126:129]
	s_waitcnt lgkmcnt(5)
	v_mfma_f32_16x16x32_bf16 v[122:125], v[156:159], v[180:183], v[122:125]
	v_mfma_f32_16x16x32_bf16 v[122:125], v[160:163], v[184:187], v[122:125]
	s_waitcnt lgkmcnt(3)
	v_mfma_f32_16x16x32_bf16 v[106:109], v[156:159], v[188:191], v[106:109]
	v_mfma_f32_16x16x32_bf16 v[106:109], v[160:163], v[192:195], v[106:109]
	s_waitcnt lgkmcnt(1)
	v_mfma_f32_16x16x32_bf16 v[110:113], v[148:151], v[188:191], v[110:113]
	v_mfma_f32_16x16x32_bf16 v[110:113], v[152:155], v[192:195], v[110:113]
	v_mfma_f32_16x16x32_bf16 v[94:97], v[148:151], v[196:199], v[94:97]
	v_mfma_f32_16x16x32_bf16 v[94:97], v[152:155], v[200:203], v[94:97]
	v_mfma_f32_16x16x32_bf16 v[90:93], v[156:159], v[196:199], v[90:93]
	v_mfma_f32_16x16x32_bf16 v[90:93], v[160:163], v[200:203], v[90:93]
	v_mfma_f32_16x16x32_bf16 v[74:77], v[156:159], v[204:207], v[74:77]
	v_mfma_f32_16x16x32_bf16 v[74:77], v[160:163], v[208:211], v[74:77]
	s_waitcnt lgkmcnt(0)
	v_mfma_f32_16x16x32_bf16 v[78:81], v[148:151], v[204:207], v[78:81]
	v_mfma_f32_16x16x32_bf16 v[78:81], v[152:155], v[208:211], v[78:81]
	s_setprio 0
	s_setprio 1
	v_mfma_f32_16x16x32_bf16 v[118:121], v[164:167], v[180:183], v[118:121]
	v_mfma_f32_16x16x32_bf16 v[118:121], v[168:171], v[184:187], v[118:121]
	v_mfma_f32_16x16x32_bf16 v[114:117], v[172:175], v[180:183], v[114:117]
	v_mfma_f32_16x16x32_bf16 v[114:117], v[176:179], v[184:187], v[114:117]
	v_mfma_f32_16x16x32_bf16 v[98:101], v[172:175], v[188:191], v[98:101]
	v_mfma_f32_16x16x32_bf16 v[98:101], v[176:179], v[192:195], v[98:101]
	v_mfma_f32_16x16x32_bf16 v[102:105], v[164:167], v[188:191], v[102:105]
	v_mfma_f32_16x16x32_bf16 v[102:105], v[168:171], v[192:195], v[102:105]
	v_mfma_f32_16x16x32_bf16 v[86:89], v[164:167], v[196:199], v[86:89]
	v_mfma_f32_16x16x32_bf16 v[86:89], v[168:171], v[200:203], v[86:89]
	v_mfma_f32_16x16x32_bf16 v[82:85], v[172:175], v[196:199], v[82:85]
	v_mfma_f32_16x16x32_bf16 v[82:85], v[176:179], v[200:203], v[82:85]
	s_setprio 2
	s_barrier
	v_mfma_f32_16x16x32_bf16 v[66:69], v[172:175], v[204:207], v[66:69]
	v_mfma_f32_16x16x32_bf16 v[66:69], v[176:179], v[208:211], v[66:69]
	v_mfma_f32_16x16x32_bf16 v[70:73], v[164:167], v[204:207], v[70:73]
	v_mfma_f32_16x16x32_bf16 v[70:73], v[168:171], v[208:211], v[70:73]
	s_setprio 0
	ds_read_b128 v[180:183], v145 offset:49152
	ds_read_b128 v[184:187], v145 offset:50176
	ds_read_b128 v[188:191], v145 offset:51200
	ds_read_b128 v[192:195], v145 offset:52224
	ds_read_b128 v[196:199], v145 offset:53248
	ds_read_b128 v[200:203], v145 offset:54272
	ds_read_b128 v[204:207], v145 offset:55296
	ds_read_b128 v[208:211], v145 offset:56320
	s_add_u32 s22, s20, 0x80
	s_addc_u32 s23, s21, 0
	s_mov_b32 s74, m0
	s_mov_b32 m0, s46
	s_nop 0
	global_load_lds_dwordx4 v139, s[22:23]
	s_mov_b32 m0, s74
	s_add_u32 s20, s20, 0x80080
	s_mov_b32 s74, m0
	s_mov_b32 m0, s47
	s_nop 0
	global_load_lds_dwordx4 v141, s[22:23]
	s_mov_b32 m0, s74
	s_addc_u32 s21, s21, 0
	s_mov_b32 s22, m0
	s_mov_b32 m0, s48
	s_nop 0
	global_load_lds_dwordx4 v139, s[20:21]
	s_mov_b32 m0, s22
	s_nop 0
	s_mov_b32 s22, m0
	s_mov_b32 m0, s49
	s_nop 0
	global_load_lds_dwordx4 v141, s[20:21]
	s_mov_b32 m0, s22
	s_waitcnt vmcnt(4)
	s_waitcnt lgkmcnt(0)
	s_barrier
	s_setprio 1
	s_waitcnt lgkmcnt(7)
	v_mfma_f32_16x16x32_bf16 v[62:65], v[148:151], v[180:183], v[62:65]
	v_mfma_f32_16x16x32_bf16 v[62:65], v[152:155], v[184:187], v[62:65]
	s_waitcnt lgkmcnt(5)
	v_mfma_f32_16x16x32_bf16 v[58:61], v[156:159], v[180:183], v[58:61]
	v_mfma_f32_16x16x32_bf16 v[58:61], v[160:163], v[184:187], v[58:61]
	s_waitcnt lgkmcnt(3)
	v_mfma_f32_16x16x32_bf16 v[42:45], v[156:159], v[188:191], v[42:45]
	v_mfma_f32_16x16x32_bf16 v[42:45], v[160:163], v[192:195], v[42:45]
	s_waitcnt lgkmcnt(1)
	v_mfma_f32_16x16x32_bf16 v[46:49], v[148:151], v[188:191], v[46:49]
	v_mfma_f32_16x16x32_bf16 v[46:49], v[152:155], v[192:195], v[46:49]
	v_mfma_f32_16x16x32_bf16 v[30:33], v[148:151], v[196:199], v[30:33]
	v_mfma_f32_16x16x32_bf16 v[30:33], v[152:155], v[200:203], v[30:33]
	v_mfma_f32_16x16x32_bf16 v[26:29], v[156:159], v[196:199], v[26:29]
	v_mfma_f32_16x16x32_bf16 v[26:29], v[160:163], v[200:203], v[26:29]
	v_mfma_f32_16x16x32_bf16 v[10:13], v[156:159], v[204:207], v[10:13]
	v_mfma_f32_16x16x32_bf16 v[10:13], v[160:163], v[208:211], v[10:13]
	s_waitcnt lgkmcnt(0)
	v_mfma_f32_16x16x32_bf16 v[14:17], v[148:151], v[204:207], v[14:17]
	v_mfma_f32_16x16x32_bf16 v[14:17], v[152:155], v[208:211], v[14:17]
	s_setprio 0
	s_setprio 1
	v_mfma_f32_16x16x32_bf16 v[54:57], v[164:167], v[180:183], v[54:57]
	v_mfma_f32_16x16x32_bf16 v[54:57], v[168:171], v[184:187], v[54:57]
	v_mfma_f32_16x16x32_bf16 v[50:53], v[172:175], v[180:183], v[50:53]
	v_mfma_f32_16x16x32_bf16 v[50:53], v[176:179], v[184:187], v[50:53]
	v_mfma_f32_16x16x32_bf16 v[34:37], v[172:175], v[188:191], v[34:37]
	v_mfma_f32_16x16x32_bf16 v[34:37], v[176:179], v[192:195], v[34:37]
	v_mfma_f32_16x16x32_bf16 v[38:41], v[164:167], v[188:191], v[38:41]
	v_mfma_f32_16x16x32_bf16 v[38:41], v[168:171], v[192:195], v[38:41]
	v_mfma_f32_16x16x32_bf16 v[22:25], v[164:167], v[196:199], v[22:25]
	v_mfma_f32_16x16x32_bf16 v[22:25], v[168:171], v[200:203], v[22:25]
	v_mfma_f32_16x16x32_bf16 v[18:21], v[172:175], v[196:199], v[18:21]
	v_mfma_f32_16x16x32_bf16 v[18:21], v[176:179], v[200:203], v[18:21]
	s_setprio 2
	s_barrier
	v_mfma_f32_16x16x32_bf16 v[2:5], v[172:175], v[204:207], v[2:5]
	v_mfma_f32_16x16x32_bf16 v[2:5], v[176:179], v[208:211], v[2:5]
	v_mfma_f32_16x16x32_bf16 v[6:9], v[164:167], v[204:207], v[6:9]
	v_mfma_f32_16x16x32_bf16 v[6:9], v[168:171], v[208:211], v[6:9]
	s_setprio 0
	s_add_i32 s73, s73, 2
	s_add_u32 s66, s66, 0x100
	s_addc_u32 s67, s67, 0
	s_add_u32 s18, s18, 0x100
	s_addc_u32 s19, s19, 0
	s_add_u32 s70, s70, 0x100
	s_addc_u32 s71, s71, 0
	s_cmp_gt_u32 s73, 29
	s_cbranch_scc0 .LBB0_1785
	s_and_b64 vcc, exec, s[6:7]
	s_cbranch_vccz .LBB0_1788
	s_barrier

.LBB0_1951:
	s_ashr_i32 s13, s12, 31
	s_lshl_b64 s[14:15], s[12:13], 15
	s_add_u32 s14, s28, s14
	s_addc_u32 s15, s29, s15
	s_and_b64 s[16:17], s[2:3], exec
	s_cselect_b32 s13, s15, s23
	s_cselect_b32 s65, s14, s22
	s_ashr_i32 s11, s10, 31
	s_lshl_b64 s[16:17], s[10:11], 15
	s_add_u32 s16, s30, s16
	s_addc_u32 s17, s31, s17
	s_and_b64 s[24:25], s[2:3], exec
	s_cselect_b32 s11, s17, s21
	s_cselect_b32 s66, s16, s20
	s_add_u32 s67, s20, 0x80000
	s_addc_u32 s70, s21, 0
	s_add_u32 s20, s22, 0x204000
	s_addc_u32 s21, s23, 0
	s_add_u32 s71, s22, 0x400000
	s_addc_u32 s73, s23, 0
	s_mov_b32 s74, -2
	s_waitcnt vmcnt(25)
	s_waitcnt vmcnt(24)
	s_waitcnt vmcnt(4)
	s_waitcnt vmcnt(2)
	s_waitcnt vmcnt(1)
	s_waitcnt vmcnt(0)
	ds_read_b128 v[130:133], v181
	ds_read_b128 v[134:137], v181 offset:1024
	ds_read_b128 v[138:141], v181 offset:2048
	ds_read_b128 v[142:145], v181 offset:3072
	ds_read_b128 v[150:153], v182
	ds_read_b128 v[154:157], v182 offset:1024
	ds_read_b128 v[158:161], v182 offset:2048
	ds_read_b128 v[162:165], v182 offset:3072
	s_cmpk_eq_i32 s74, 0x52
	s_cselect_b32 s23, s11, s70
	s_cselect_b32 s22, s66, s67
	s_cselect_b32 s25, s13, s73
	s_cselect_b32 s24, s65, s71
	ds_read_b128 v[166:169], v183
	ds_read_b128 v[170:173], v183 offset:1024
	ds_read_b128 v[186:189], v183 offset:2048
	ds_read_b128 v[190:193], v183 offset:3072
	ds_read_b128 v[194:197], v183 offset:4096
	ds_read_b128 v[198:201], v183 offset:5120
	ds_read_b128 v[202:205], v183 offset:6144
	ds_read_b128 v[206:209], v183 offset:7168
	s_add_u32 s76, s20, 0xffffc000
	s_addc_u32 s77, s21, -1
	s_mov_b32 s75, m0
	s_mov_b32 m0, s58
	s_nop 0
	global_load_lds_dwordx4 v1, s[76:77]
	s_mov_b32 m0, s75
	s_nop 0
	s_mov_b32 s75, m0
	s_mov_b32 m0, s62
	s_nop 0
	global_load_lds_dwordx4 v177, s[76:77]
	s_mov_b32 m0, s75
	s_nop 0
	s_mov_b32 s75, m0
	s_mov_b32 m0, s59
	s_nop 0
	global_load_lds_dwordx4 v1, s[20:21]
	s_mov_b32 m0, s75
	s_nop 0
	s_mov_b32 s75, m0
	s_mov_b32 m0, s63
	s_nop 0
	global_load_lds_dwordx4 v177, s[20:21]
	s_mov_b32 m0, s75
	s_waitcnt vmcnt(8)
	s_waitcnt lgkmcnt(0)
	s_barrier
	s_setprio 1
	s_waitcnt lgkmcnt(7)
	v_mfma_f32_16x16x32_bf16 v[126:129], v[130:133], v[166:169], 0
	v_mfma_f32_16x16x32_bf16 v[126:129], v[134:137], v[170:173], v[126:129]
	s_waitcnt lgkmcnt(5)
	v_mfma_f32_16x16x32_bf16 v[122:125], v[138:141], v[166:169], 0
	v_mfma_f32_16x16x32_bf16 v[122:125], v[142:145], v[170:173], v[122:125]
	s_waitcnt lgkmcnt(3)
	v_mfma_f32_16x16x32_bf16 v[110:113], v[138:141], v[186:189], 0
	v_mfma_f32_16x16x32_bf16 v[110:113], v[142:145], v[190:193], v[110:113]
	s_waitcnt lgkmcnt(1)
	v_mfma_f32_16x16x32_bf16 v[118:121], v[130:133], v[186:189], 0
	v_mfma_f32_16x16x32_bf16 v[118:121], v[134:137], v[190:193], v[118:121]
	v_mfma_f32_16x16x32_bf16 v[94:97], v[130:133], v[194:197], 0
	v_mfma_f32_16x16x32_bf16 v[94:97], v[134:137], v[198:201], v[94:97]
	v_mfma_f32_16x16x32_bf16 v[90:93], v[138:141], v[194:197], 0
	v_mfma_f32_16x16x32_bf16 v[90:93], v[142:145], v[198:201], v[90:93]
	v_mfma_f32_16x16x32_bf16 v[78:81], v[138:141], v[202:205], 0
	v_mfma_f32_16x16x32_bf16 v[78:81], v[142:145], v[206:209], v[78:81]
	s_waitcnt lgkmcnt(0)
	v_mfma_f32_16x16x32_bf16 v[86:89], v[130:133], v[202:205], 0
	v_mfma_f32_16x16x32_bf16 v[86:89], v[134:137], v[206:209], v[86:89]
	s_setprio 0
	s_setprio 1
	v_mfma_f32_16x16x32_bf16 v[114:117], v[150:153], v[166:169], 0
	v_mfma_f32_16x16x32_bf16 v[114:117], v[154:157], v[170:173], v[114:117]
	v_mfma_f32_16x16x32_bf16 v[106:109], v[158:161], v[166:169], 0
	v_mfma_f32_16x16x32_bf16 v[106:109], v[162:165], v[170:173], v[106:109]
	v_mfma_f32_16x16x32_bf16 v[98:101], v[158:161], v[186:189], 0
	v_mfma_f32_16x16x32_bf16 v[98:101], v[162:165], v[190:193], v[98:101]
	v_mfma_f32_16x16x32_bf16 v[102:105], v[150:153], v[186:189], 0
	v_mfma_f32_16x16x32_bf16 v[102:105], v[154:157], v[190:193], v[102:105]
	v_mfma_f32_16x16x32_bf16 v[82:85], v[150:153], v[194:197], 0
	v_mfma_f32_16x16x32_bf16 v[82:85], v[154:157], v[198:201], v[82:85]
	v_mfma_f32_16x16x32_bf16 v[74:77], v[158:161], v[194:197], 0
	v_mfma_f32_16x16x32_bf16 v[74:77], v[162:165], v[198:201], v[74:77]
	s_setprio 2
	s_barrier
	v_mfma_f32_16x16x32_bf16 v[66:69], v[158:161], v[202:205], 0
	v_mfma_f32_16x16x32_bf16 v[66:69], v[162:165], v[206:209], v[66:69]
	v_mfma_f32_16x16x32_bf16 v[70:73], v[150:153], v[202:205], 0
	v_mfma_f32_16x16x32_bf16 v[70:73], v[154:157], v[206:209], v[70:73]
	s_setprio 0
	ds_read_b128 v[166:169], v183 offset:16384
	ds_read_b128 v[170:173], v183 offset:17408
	ds_read_b128 v[186:189], v183 offset:18432
	ds_read_b128 v[190:193], v183 offset:19456
	ds_read_b128 v[194:197], v183 offset:20480
	ds_read_b128 v[198:201], v183 offset:21504
	ds_read_b128 v[202:205], v183 offset:22528
	ds_read_b128 v[206:209], v183 offset:23552
	s_mov_b32 s75, m0
	s_mov_b32 m0, s35
	s_nop 0
	global_load_lds_dwordx4 v176, s[22:23]
	s_mov_b32 m0, s75
	s_add_u32 s76, s22, 0x4000
	s_mov_b32 s75, m0
	s_mov_b32 m0, s36
	s_nop 0
	global_load_lds_dwordx4 v178, s[22:23]
	s_mov_b32 m0, s75
	s_addc_u32 s77, s23, 0
	s_mov_b32 s75, m0
	s_mov_b32 m0, s37
	s_nop 0
	global_load_lds_dwordx4 v176, s[76:77]
	s_mov_b32 m0, s75
	s_nop 0
	s_mov_b32 s75, m0
	s_mov_b32 m0, s40
	s_nop 0
	global_load_lds_dwordx4 v178, s[76:77]
	s_mov_b32 m0, s75
	s_waitcnt vmcnt(4)
	s_waitcnt lgkmcnt(0)
	s_barrier
	s_setprio 1
	s_waitcnt lgkmcnt(7)
	v_mfma_f32_16x16x32_bf16 v[62:65], v[130:133], v[166:169], 0
	v_mfma_f32_16x16x32_bf16 v[62:65], v[134:137], v[170:173], v[62:65]
	s_waitcnt lgkmcnt(5)
	v_mfma_f32_16x16x32_bf16 v[58:61], v[138:141], v[166:169], 0
	v_mfma_f32_16x16x32_bf16 v[58:61], v[142:145], v[170:173], v[58:61]
	s_waitcnt lgkmcnt(3)
	v_mfma_f32_16x16x32_bf16 v[42:45], v[138:141], v[186:189], 0
	v_mfma_f32_16x16x32_bf16 v[42:45], v[142:145], v[190:193], v[42:45]
	s_waitcnt lgkmcnt(1)
	v_mfma_f32_16x16x32_bf16 v[46:49], v[130:133], v[186:189], 0
	v_mfma_f32_16x16x32_bf16 v[46:49], v[134:137], v[190:193], v[46:49]
	v_mfma_f32_16x16x32_bf16 v[30:33], v[130:133], v[194:197], 0
	v_mfma_f32_16x16x32_bf16 v[30:33], v[134:137], v[198:201], v[30:33]
	v_mfma_f32_16x16x32_bf16 v[26:29], v[138:141], v[194:197], 0
	v_mfma_f32_16x16x32_bf16 v[26:29], v[142:145], v[198:201], v[26:29]
	v_mfma_f32_16x16x32_bf16 v[10:13], v[138:141], v[202:205], 0
	v_mfma_f32_16x16x32_bf16 v[10:13], v[142:145], v[206:209], v[10:13]
	s_waitcnt lgkmcnt(0)
	v_mfma_f32_16x16x32_bf16 v[14:17], v[130:133], v[202:205], 0
	v_mfma_f32_16x16x32_bf16 v[14:17], v[134:137], v[206:209], v[14:17]
	s_setprio 0
	s_setprio 1
	v_mfma_f32_16x16x32_bf16 v[54:57], v[150:153], v[166:169], 0
	v_mfma_f32_16x16x32_bf16 v[54:57], v[154:157], v[170:173], v[54:57]
	v_mfma_f32_16x16x32_bf16 v[50:53], v[158:161], v[166:169], 0
	v_mfma_f32_16x16x32_bf16 v[50:53], v[162:165], v[170:173], v[50:53]
	v_mfma_f32_16x16x32_bf16 v[34:37], v[158:161], v[186:189], 0
	v_mfma_f32_16x16x32_bf16 v[34:37], v[162:165], v[190:193], v[34:37]
	v_mfma_f32_16x16x32_bf16 v[38:41], v[150:153], v[186:189], 0
	v_mfma_f32_16x16x32_bf16 v[38:41], v[154:157], v[190:193], v[38:41]
	v_mfma_f32_16x16x32_bf16 v[22:25], v[150:153], v[194:197], 0
	v_mfma_f32_16x16x32_bf16 v[22:25], v[154:157], v[198:201], v[22:25]
	v_mfma_f32_16x16x32_bf16 v[18:21], v[158:161], v[194:197], 0
	v_mfma_f32_16x16x32_bf16 v[18:21], v[162:165], v[198:201], v[18:21]
	s_setprio 2
	s_barrier
	v_mfma_f32_16x16x32_bf16 v[2:5], v[158:161], v[202:205], 0
	v_mfma_f32_16x16x32_bf16 v[2:5], v[162:165], v[206:209], v[2:5]
	v_mfma_f32_16x16x32_bf16 v[6:9], v[150:153], v[202:205], 0
	v_mfma_f32_16x16x32_bf16 v[6:9], v[154:157], v[206:209], v[6:9]
	s_setprio 0
	ds_read_b128 v[130:133], v184
	ds_read_b128 v[134:137], v184 offset:1024
	ds_read_b128 v[138:141], v184 offset:2048
	ds_read_b128 v[142:145], v184 offset:3072
	ds_read_b128 v[150:153], v185
	ds_read_b128 v[154:157], v185 offset:1024
	ds_read_b128 v[158:161], v185 offset:2048
	ds_read_b128 v[162:165], v185 offset:3072
	ds_read_b128 v[166:169], v183 offset:32768
	ds_read_b128 v[170:173], v183 offset:33792
	ds_read_b128 v[186:189], v183 offset:34816
	ds_read_b128 v[190:193], v183 offset:35840
	ds_read_b128 v[194:197], v183 offset:36864
	ds_read_b128 v[198:201], v183 offset:37888
	ds_read_b128 v[202:205], v183 offset:38912
	ds_read_b128 v[206:209], v183 offset:39936
	s_mov_b32 s75, m0
	s_mov_b32 m0, s34
	s_nop 0
	global_load_lds_dwordx4 v1, s[24:25]
	s_mov_b32 m0, s75
	s_nop 0
	s_mov_b32 s75, m0
	s_mov_b32 m0, s41
	s_nop 0
	global_load_lds_dwordx4 v177, s[24:25]
	s_mov_b32 m0, s75
	s_add_u32 s24, s24, 0x4000
	s_addc_u32 s25, s25, 0
	s_mov_b32 s75, m0
	s_mov_b32 m0, s42
	s_nop 0
	global_load_lds_dwordx4 v1, s[24:25]
	s_mov_b32 m0, s75
	s_nop 0
	s_mov_b32 s75, m0
	s_mov_b32 m0, s43
	s_nop 0
	global_load_lds_dwordx4 v177, s[24:25]
	s_mov_b32 m0, s75
	s_waitcnt vmcnt(8)
	s_waitcnt lgkmcnt(0)
	s_barrier
	s_setprio 1
	s_waitcnt lgkmcnt(7)
	v_mfma_f32_16x16x32_bf16 v[126:129], v[130:133], v[166:169], v[126:129]
	v_mfma_f32_16x16x32_bf16 v[126:129], v[134:137], v[170:173], v[126:129]
	s_waitcnt lgkmcnt(5)
	v_mfma_f32_16x16x32_bf16 v[122:125], v[138:141], v[166:169], v[122:125]
	v_mfma_f32_16x16x32_bf16 v[122:125], v[142:145], v[170:173], v[122:125]
	s_waitcnt lgkmcnt(3)
	v_mfma_f32_16x16x32_bf16 v[110:113], v[138:141], v[186:189], v[110:113]
	v_mfma_f32_16x16x32_bf16 v[110:113], v[142:145], v[190:193], v[110:113]
	s_waitcnt lgkmcnt(1)
	v_mfma_f32_16x16x32_bf16 v[118:121], v[130:133], v[186:189], v[118:121]
	v_mfma_f32_16x16x32_bf16 v[118:121], v[134:137], v[190:193], v[118:121]
	v_mfma_f32_16x16x32_bf16 v[94:97], v[130:133], v[194:197], v[94:97]
	v_mfma_f32_16x16x32_bf16 v[94:97], v[134:137], v[198:201], v[94:97]
	v_mfma_f32_16x16x32_bf16 v[90:93], v[138:141], v[194:197], v[90:93]
	v_mfma_f32_16x16x32_bf16 v[90:93], v[142:145], v[198:201], v[90:93]
	v_mfma_f32_16x16x32_bf16 v[78:81], v[138:141], v[202:205], v[78:81]
	v_mfma_f32_16x16x32_bf16 v[78:81], v[142:145], v[206:209], v[78:81]
	s_waitcnt lgkmcnt(0)
	v_mfma_f32_16x16x32_bf16 v[86:89], v[130:133], v[202:205], v[86:89]
	v_mfma_f32_16x16x32_bf16 v[86:89], v[134:137], v[206:209], v[86:89]
	s_setprio 0
	s_setprio 1
	v_mfma_f32_16x16x32_bf16 v[114:117], v[150:153], v[166:169], v[114:117]
	v_mfma_f32_16x16x32_bf16 v[114:117], v[154:157], v[170:173], v[114:117]
	v_mfma_f32_16x16x32_bf16 v[106:109], v[158:161], v[166:169], v[106:109]
	v_mfma_f32_16x16x32_bf16 v[106:109], v[162:165], v[170:173], v[106:109]
	v_mfma_f32_16x16x32_bf16 v[98:101], v[158:161], v[186:189], v[98:101]
	v_mfma_f32_16x16x32_bf16 v[98:101], v[162:165], v[190:193], v[98:101]
	v_mfma_f32_16x16x32_bf16 v[102:105], v[150:153], v[186:189], v[102:105]
	v_mfma_f32_16x16x32_bf16 v[102:105], v[154:157], v[190:193], v[102:105]
	v_mfma_f32_16x16x32_bf16 v[82:85], v[150:153], v[194:197], v[82:85]
	v_mfma_f32_16x16x32_bf16 v[82:85], v[154:157], v[198:201], v[82:85]
	v_mfma_f32_16x16x32_bf16 v[74:77], v[158:161], v[194:197], v[74:77]
	v_mfma_f32_16x16x32_bf16 v[74:77], v[162:165], v[198:201], v[74:77]
	s_setprio 2
	s_barrier
	v_mfma_f32_16x16x32_bf16 v[66:69], v[158:161], v[202:205], v[66:69]
	v_mfma_f32_16x16x32_bf16 v[66:69], v[162:165], v[206:209], v[66:69]
	v_mfma_f32_16x16x32_bf16 v[70:73], v[150:153], v[202:205], v[70:73]
	v_mfma_f32_16x16x32_bf16 v[70:73], v[154:157], v[206:209], v[70:73]
	s_setprio 0
	ds_read_b128 v[166:169], v183 offset:49152
	ds_read_b128 v[170:173], v183 offset:50176
	ds_read_b128 v[186:189], v183 offset:51200
	ds_read_b128 v[190:193], v183 offset:52224
	ds_read_b128 v[194:197], v183 offset:53248
	ds_read_b128 v[198:201], v183 offset:54272
	ds_read_b128 v[202:205], v183 offset:55296
	ds_read_b128 v[206:209], v183 offset:56320
	s_add_u32 s24, s22, 0x40000
	s_addc_u32 s25, s23, 0
	s_mov_b32 s75, m0
	s_mov_b32 m0, s46
	s_nop 0
	global_load_lds_dwordx4 v176, s[24:25]
	s_mov_b32 m0, s75
	s_add_u32 s22, s22, 0x44000
	s_mov_b32 s75, m0
	s_mov_b32 m0, s47
	s_nop 0
	global_load_lds_dwordx4 v178, s[24:25]
	s_mov_b32 m0, s75
	s_addc_u32 s23, s23, 0
	s_mov_b32 s24, m0
	s_mov_b32 m0, s48
	s_nop 0
	global_load_lds_dwordx4 v176, s[22:23]
	s_mov_b32 m0, s24
	s_nop 0
	s_mov_b32 s24, m0
	s_mov_b32 m0, s49
	s_nop 0
	global_load_lds_dwordx4 v178, s[22:23]
	s_mov_b32 m0, s24
	s_waitcnt vmcnt(4)
	s_waitcnt lgkmcnt(0)
	s_barrier
	s_setprio 1
	s_waitcnt lgkmcnt(7)
	v_mfma_f32_16x16x32_bf16 v[62:65], v[130:133], v[166:169], v[62:65]
	v_mfma_f32_16x16x32_bf16 v[62:65], v[134:137], v[170:173], v[62:65]
	s_waitcnt lgkmcnt(5)
	v_mfma_f32_16x16x32_bf16 v[58:61], v[138:141], v[166:169], v[58:61]
	v_mfma_f32_16x16x32_bf16 v[58:61], v[142:145], v[170:173], v[58:61]
	s_waitcnt lgkmcnt(3)
	v_mfma_f32_16x16x32_bf16 v[42:45], v[138:141], v[186:189], v[42:45]
	v_mfma_f32_16x16x32_bf16 v[42:45], v[142:145], v[190:193], v[42:45]
	s_waitcnt lgkmcnt(1)
	v_mfma_f32_16x16x32_bf16 v[46:49], v[130:133], v[186:189], v[46:49]
	v_mfma_f32_16x16x32_bf16 v[46:49], v[134:137], v[190:193], v[46:49]
	v_mfma_f32_16x16x32_bf16 v[30:33], v[130:133], v[194:197], v[30:33]
	v_mfma_f32_16x16x32_bf16 v[30:33], v[134:137], v[198:201], v[30:33]
	v_mfma_f32_16x16x32_bf16 v[26:29], v[138:141], v[194:197], v[26:29]
	v_mfma_f32_16x16x32_bf16 v[26:29], v[142:145], v[198:201], v[26:29]
	v_mfma_f32_16x16x32_bf16 v[10:13], v[138:141], v[202:205], v[10:13]
	v_mfma_f32_16x16x32_bf16 v[10:13], v[142:145], v[206:209], v[10:13]
	s_waitcnt lgkmcnt(0)
	v_mfma_f32_16x16x32_bf16 v[14:17], v[130:133], v[202:205], v[14:17]
	v_mfma_f32_16x16x32_bf16 v[14:17], v[134:137], v[206:209], v[14:17]
	s_setprio 0
	s_setprio 1
	v_mfma_f32_16x16x32_bf16 v[54:57], v[150:153], v[166:169], v[54:57]
	v_mfma_f32_16x16x32_bf16 v[54:57], v[154:157], v[170:173], v[54:57]
	v_mfma_f32_16x16x32_bf16 v[50:53], v[158:161], v[166:169], v[50:53]
	v_mfma_f32_16x16x32_bf16 v[50:53], v[162:165], v[170:173], v[50:53]
	v_mfma_f32_16x16x32_bf16 v[34:37], v[158:161], v[186:189], v[34:37]
	v_mfma_f32_16x16x32_bf16 v[34:37], v[162:165], v[190:193], v[34:37]
	v_mfma_f32_16x16x32_bf16 v[38:41], v[150:153], v[186:189], v[38:41]
	v_mfma_f32_16x16x32_bf16 v[38:41], v[154:157], v[190:193], v[38:41]
	v_mfma_f32_16x16x32_bf16 v[22:25], v[150:153], v[194:197], v[22:25]
	v_mfma_f32_16x16x32_bf16 v[22:25], v[154:157], v[198:201], v[22:25]
	v_mfma_f32_16x16x32_bf16 v[18:21], v[158:161], v[194:197], v[18:21]
	v_mfma_f32_16x16x32_bf16 v[18:21], v[162:165], v[198:201], v[18:21]
	s_setprio 2
	s_barrier
	v_mfma_f32_16x16x32_bf16 v[2:5], v[158:161], v[202:205], v[2:5]
	v_mfma_f32_16x16x32_bf16 v[2:5], v[162:165], v[206:209], v[2:5]
	v_mfma_f32_16x16x32_bf16 v[6:9], v[150:153], v[202:205], v[6:9]
	v_mfma_f32_16x16x32_bf16 v[6:9], v[154:157], v[206:209], v[6:9]
	s_setprio 0
	s_add_i32 s74, s74, 2
	s_add_u32 s67, s67, 0x80000
	s_addc_u32 s70, s70, 0
	s_add_u32 s20, s20, 0x400000
	s_addc_u32 s21, s21, 0
	s_add_u32 s71, s71, 0x400000
	s_addc_u32 s73, s73, 0
	s_cmpk_gt_u32 s74, 0x53
	.p2align 6
.LBB0_1952:
	ds_read_b128 v[130:133], v181
	ds_read_b128 v[134:137], v181 offset:1024
	ds_read_b128 v[138:141], v181 offset:2048
	ds_read_b128 v[142:145], v181 offset:3072
	ds_read_b128 v[150:153], v182
	ds_read_b128 v[154:157], v182 offset:1024
	ds_read_b128 v[158:161], v182 offset:2048
	ds_read_b128 v[162:165], v182 offset:3072
	s_cmpk_eq_i32 s74, 0x52
	s_cselect_b32 s23, s11, s70
	s_cselect_b32 s22, s66, s67
	s_cselect_b32 s25, s13, s73
	s_cselect_b32 s24, s65, s71
	ds_read_b128 v[166:169], v183
	ds_read_b128 v[170:173], v183 offset:1024
	ds_read_b128 v[186:189], v183 offset:2048
	ds_read_b128 v[190:193], v183 offset:3072
	ds_read_b128 v[194:197], v183 offset:4096
	ds_read_b128 v[198:201], v183 offset:5120
	ds_read_b128 v[202:205], v183 offset:6144
	ds_read_b128 v[206:209], v183 offset:7168
	s_add_u32 s76, s20, 0xffffc000
	s_addc_u32 s77, s21, -1
	s_mov_b32 s75, m0
	s_mov_b32 m0, s58
	s_nop 0
	global_load_lds_dwordx4 v1, s[76:77]
	s_mov_b32 m0, s75
	s_nop 0
	s_mov_b32 s75, m0
	s_mov_b32 m0, s62
	s_nop 0
	global_load_lds_dwordx4 v177, s[76:77]
	s_mov_b32 m0, s75
	s_nop 0
	s_mov_b32 s75, m0
	s_mov_b32 m0, s59
	s_nop 0
	global_load_lds_dwordx4 v1, s[20:21]
	s_mov_b32 m0, s75
	s_nop 0
	s_mov_b32 s75, m0
	s_mov_b32 m0, s63
	s_nop 0
	global_load_lds_dwordx4 v177, s[20:21]
	s_mov_b32 m0, s75
	s_waitcnt vmcnt(8)
	s_waitcnt lgkmcnt(0)
	s_barrier
	s_setprio 1
	s_waitcnt lgkmcnt(7)
	v_mfma_f32_16x16x32_bf16 v[126:129], v[130:133], v[166:169], v[126:129]
	v_mfma_f32_16x16x32_bf16 v[126:129], v[134:137], v[170:173], v[126:129]
	s_waitcnt lgkmcnt(5)
	v_mfma_f32_16x16x32_bf16 v[122:125], v[138:141], v[166:169], v[122:125]
	v_mfma_f32_16x16x32_bf16 v[122:125], v[142:145], v[170:173], v[122:125]
	s_waitcnt lgkmcnt(3)
	v_mfma_f32_16x16x32_bf16 v[110:113], v[138:141], v[186:189], v[110:113]
	v_mfma_f32_16x16x32_bf16 v[110:113], v[142:145], v[190:193], v[110:113]
	s_waitcnt lgkmcnt(1)
	v_mfma_f32_16x16x32_bf16 v[118:121], v[130:133], v[186:189], v[118:121]
	v_mfma_f32_16x16x32_bf16 v[118:121], v[134:137], v[190:193], v[118:121]
	v_mfma_f32_16x16x32_bf16 v[94:97], v[130:133], v[194:197], v[94:97]
	v_mfma_f32_16x16x32_bf16 v[94:97], v[134:137], v[198:201], v[94:97]
	v_mfma_f32_16x16x32_bf16 v[90:93], v[138:141], v[194:197], v[90:93]
	v_mfma_f32_16x16x32_bf16 v[90:93], v[142:145], v[198:201], v[90:93]
	v_mfma_f32_16x16x32_bf16 v[78:81], v[138:141], v[202:205], v[78:81]
	v_mfma_f32_16x16x32_bf16 v[78:81], v[142:145], v[206:209], v[78:81]
	s_waitcnt lgkmcnt(0)
	v_mfma_f32_16x16x32_bf16 v[86:89], v[130:133], v[202:205], v[86:89]
	v_mfma_f32_16x16x32_bf16 v[86:89], v[134:137], v[206:209], v[86:89]
	s_setprio 0
	s_setprio 1
	v_mfma_f32_16x16x32_bf16 v[114:117], v[150:153], v[166:169], v[114:117]
	v_mfma_f32_16x16x32_bf16 v[114:117], v[154:157], v[170:173], v[114:117]
	v_mfma_f32_16x16x32_bf16 v[106:109], v[158:161], v[166:169], v[106:109]
	v_mfma_f32_16x16x32_bf16 v[106:109], v[162:165], v[170:173], v[106:109]
	v_mfma_f32_16x16x32_bf16 v[98:101], v[158:161], v[186:189], v[98:101]
	v_mfma_f32_16x16x32_bf16 v[98:101], v[162:165], v[190:193], v[98:101]
	v_mfma_f32_16x16x32_bf16 v[102:105], v[150:153], v[186:189], v[102:105]
	v_mfma_f32_16x16x32_bf16 v[102:105], v[154:157], v[190:193], v[102:105]
	v_mfma_f32_16x16x32_bf16 v[82:85], v[150:153], v[194:197], v[82:85]
	v_mfma_f32_16x16x32_bf16 v[82:85], v[154:157], v[198:201], v[82:85]
	v_mfma_f32_16x16x32_bf16 v[74:77], v[158:161], v[194:197], v[74:77]
	v_mfma_f32_16x16x32_bf16 v[74:77], v[162:165], v[198:201], v[74:77]
	s_setprio 2
	s_barrier
	v_mfma_f32_16x16x32_bf16 v[66:69], v[158:161], v[202:205], v[66:69]
	v_mfma_f32_16x16x32_bf16 v[66:69], v[162:165], v[206:209], v[66:69]
	v_mfma_f32_16x16x32_bf16 v[70:73], v[150:153], v[202:205], v[70:73]
	v_mfma_f32_16x16x32_bf16 v[70:73], v[154:157], v[206:209], v[70:73]
	s_setprio 0
	ds_read_b128 v[166:169], v183 offset:16384
	ds_read_b128 v[170:173], v183 offset:17408
	ds_read_b128 v[186:189], v183 offset:18432
	ds_read_b128 v[190:193], v183 offset:19456
	ds_read_b128 v[194:197], v183 offset:20480
	ds_read_b128 v[198:201], v183 offset:21504
	ds_read_b128 v[202:205], v183 offset:22528
	ds_read_b128 v[206:209], v183 offset:23552
	s_mov_b32 s75, m0
	s_mov_b32 m0, s35
	s_nop 0
	global_load_lds_dwordx4 v176, s[22:23]
	s_mov_b32 m0, s75
	s_add_u32 s76, s22, 0x4000
	s_mov_b32 s75, m0
	s_mov_b32 m0, s36
	s_nop 0
	global_load_lds_dwordx4 v178, s[22:23]
	s_mov_b32 m0, s75
	s_addc_u32 s77, s23, 0
	s_mov_b32 s75, m0
	s_mov_b32 m0, s37
	s_nop 0
	global_load_lds_dwordx4 v176, s[76:77]
	s_mov_b32 m0, s75
	s_nop 0
	s_mov_b32 s75, m0
	s_mov_b32 m0, s40
	s_nop 0
	global_load_lds_dwordx4 v178, s[76:77]
	s_mov_b32 m0, s75
	s_waitcnt vmcnt(4)
	s_waitcnt lgkmcnt(0)
	s_barrier
	s_setprio 1
	s_waitcnt lgkmcnt(7)
	v_mfma_f32_16x16x32_bf16 v[62:65], v[130:133], v[166:169], v[62:65]
	v_mfma_f32_16x16x32_bf16 v[62:65], v[134:137], v[170:173], v[62:65]
	s_waitcnt lgkmcnt(5)
	v_mfma_f32_16x16x32_bf16 v[58:61], v[138:141], v[166:169], v[58:61]
	v_mfma_f32_16x16x32_bf16 v[58:61], v[142:145], v[170:173], v[58:61]
	s_waitcnt lgkmcnt(3)
	v_mfma_f32_16x16x32_bf16 v[42:45], v[138:141], v[186:189], v[42:45]
	v_mfma_f32_16x16x32_bf16 v[42:45], v[142:145], v[190:193], v[42:45]
	s_waitcnt lgkmcnt(1)
	v_mfma_f32_16x16x32_bf16 v[46:49], v[130:133], v[186:189], v[46:49]
	v_mfma_f32_16x16x32_bf16 v[46:49], v[134:137], v[190:193], v[46:49]
	v_mfma_f32_16x16x32_bf16 v[30:33], v[130:133], v[194:197], v[30:33]
	v_mfma_f32_16x16x32_bf16 v[30:33], v[134:137], v[198:201], v[30:33]
	v_mfma_f32_16x16x32_bf16 v[26:29], v[138:141], v[194:197], v[26:29]
	v_mfma_f32_16x16x32_bf16 v[26:29], v[142:145], v[198:201], v[26:29]
	v_mfma_f32_16x16x32_bf16 v[10:13], v[138:141], v[202:205], v[10:13]
	v_mfma_f32_16x16x32_bf16 v[10:13], v[142:145], v[206:209], v[10:13]
	s_waitcnt lgkmcnt(0)
	v_mfma_f32_16x16x32_bf16 v[14:17], v[130:133], v[202:205], v[14:17]
	v_mfma_f32_16x16x32_bf16 v[14:17], v[134:137], v[206:209], v[14:17]
	s_setprio 0
	s_setprio 1
	v_mfma_f32_16x16x32_bf16 v[54:57], v[150:153], v[166:169], v[54:57]
	v_mfma_f32_16x16x32_bf16 v[54:57], v[154:157], v[170:173], v[54:57]
	v_mfma_f32_16x16x32_bf16 v[50:53], v[158:161], v[166:169], v[50:53]
	v_mfma_f32_16x16x32_bf16 v[50:53], v[162:165], v[170:173], v[50:53]
	v_mfma_f32_16x16x32_bf16 v[34:37], v[158:161], v[186:189], v[34:37]
	v_mfma_f32_16x16x32_bf16 v[34:37], v[162:165], v[190:193], v[34:37]
	v_mfma_f32_16x16x32_bf16 v[38:41], v[150:153], v[186:189], v[38:41]
	v_mfma_f32_16x16x32_bf16 v[38:41], v[154:157], v[190:193], v[38:41]
	v_mfma_f32_16x16x32_bf16 v[22:25], v[150:153], v[194:197], v[22:25]
	v_mfma_f32_16x16x32_bf16 v[22:25], v[154:157], v[198:201], v[22:25]
	v_mfma_f32_16x16x32_bf16 v[18:21], v[158:161], v[194:197], v[18:21]
	v_mfma_f32_16x16x32_bf16 v[18:21], v[162:165], v[198:201], v[18:21]
	s_setprio 2
	s_barrier
	v_mfma_f32_16x16x32_bf16 v[2:5], v[158:161], v[202:205], v[2:5]
	v_mfma_f32_16x16x32_bf16 v[2:5], v[162:165], v[206:209], v[2:5]
	v_mfma_f32_16x16x32_bf16 v[6:9], v[150:153], v[202:205], v[6:9]
	v_mfma_f32_16x16x32_bf16 v[6:9], v[154:157], v[206:209], v[6:9]
	s_setprio 0
	ds_read_b128 v[130:133], v184
	ds_read_b128 v[134:137], v184 offset:1024
	ds_read_b128 v[138:141], v184 offset:2048
	ds_read_b128 v[142:145], v184 offset:3072
	ds_read_b128 v[150:153], v185
	ds_read_b128 v[154:157], v185 offset:1024
	ds_read_b128 v[158:161], v185 offset:2048
	ds_read_b128 v[162:165], v185 offset:3072
	ds_read_b128 v[166:169], v183 offset:32768
	ds_read_b128 v[170:173], v183 offset:33792
	ds_read_b128 v[186:189], v183 offset:34816
	ds_read_b128 v[190:193], v183 offset:35840
	ds_read_b128 v[194:197], v183 offset:36864
	ds_read_b128 v[198:201], v183 offset:37888
	ds_read_b128 v[202:205], v183 offset:38912
	ds_read_b128 v[206:209], v183 offset:39936
	s_mov_b32 s75, m0
	s_mov_b32 m0, s34
	s_nop 0
	global_load_lds_dwordx4 v1, s[24:25]
	s_mov_b32 m0, s75
	s_nop 0
	s_mov_b32 s75, m0
	s_mov_b32 m0, s41
	s_nop 0
	global_load_lds_dwordx4 v177, s[24:25]
	s_mov_b32 m0, s75
	s_add_u32 s24, s24, 0x4000
	s_addc_u32 s25, s25, 0
	s_mov_b32 s75, m0
	s_mov_b32 m0, s42
	s_nop 0
	global_load_lds_dwordx4 v1, s[24:25]
	s_mov_b32 m0, s75
	s_nop 0
	s_mov_b32 s75, m0
	s_mov_b32 m0, s43
	s_nop 0
	global_load_lds_dwordx4 v177, s[24:25]
	s_mov_b32 m0, s75
	s_waitcnt vmcnt(8)
	s_waitcnt lgkmcnt(0)
	s_barrier
	s_setprio 1
	s_waitcnt lgkmcnt(7)
	v_mfma_f32_16x16x32_bf16 v[126:129], v[130:133], v[166:169], v[126:129]
	v_mfma_f32_16x16x32_bf16 v[126:129], v[134:137], v[170:173], v[126:129]
	s_waitcnt lgkmcnt(5)
	v_mfma_f32_16x16x32_bf16 v[122:125], v[138:141], v[166:169], v[122:125]
	v_mfma_f32_16x16x32_bf16 v[122:125], v[142:145], v[170:173], v[122:125]
	s_waitcnt lgkmcnt(3)
	v_mfma_f32_16x16x32_bf16 v[110:113], v[138:141], v[186:189], v[110:113]
	v_mfma_f32_16x16x32_bf16 v[110:113], v[142:145], v[190:193], v[110:113]
	s_waitcnt lgkmcnt(1)
	v_mfma_f32_16x16x32_bf16 v[118:121], v[130:133], v[186:189], v[118:121]
	v_mfma_f32_16x16x32_bf16 v[118:121], v[134:137], v[190:193], v[118:121]
	v_mfma_f32_16x16x32_bf16 v[94:97], v[130:133], v[194:197], v[94:97]
	v_mfma_f32_16x16x32_bf16 v[94:97], v[134:137], v[198:201], v[94:97]
	v_mfma_f32_16x16x32_bf16 v[90:93], v[138:141], v[194:197], v[90:93]
	v_mfma_f32_16x16x32_bf16 v[90:93], v[142:145], v[198:201], v[90:93]
	v_mfma_f32_16x16x32_bf16 v[78:81], v[138:141], v[202:205], v[78:81]
	v_mfma_f32_16x16x32_bf16 v[78:81], v[142:145], v[206:209], v[78:81]
	s_waitcnt lgkmcnt(0)
	v_mfma_f32_16x16x32_bf16 v[86:89], v[130:133], v[202:205], v[86:89]
	v_mfma_f32_16x16x32_bf16 v[86:89], v[134:137], v[206:209], v[86:89]
	s_setprio 0
	s_setprio 1
	v_mfma_f32_16x16x32_bf16 v[114:117], v[150:153], v[166:169], v[114:117]
	v_mfma_f32_16x16x32_bf16 v[114:117], v[154:157], v[170:173], v[114:117]
	v_mfma_f32_16x16x32_bf16 v[106:109], v[158:161], v[166:169], v[106:109]
	v_mfma_f32_16x16x32_bf16 v[106:109], v[162:165], v[170:173], v[106:109]
	v_mfma_f32_16x16x32_bf16 v[98:101], v[158:161], v[186:189], v[98:101]
	v_mfma_f32_16x16x32_bf16 v[98:101], v[162:165], v[190:193], v[98:101]
	v_mfma_f32_16x16x32_bf16 v[102:105], v[150:153], v[186:189], v[102:105]
	v_mfma_f32_16x16x32_bf16 v[102:105], v[154:157], v[190:193], v[102:105]
	v_mfma_f32_16x16x32_bf16 v[82:85], v[150:153], v[194:197], v[82:85]
	v_mfma_f32_16x16x32_bf16 v[82:85], v[154:157], v[198:201], v[82:85]
	v_mfma_f32_16x16x32_bf16 v[74:77], v[158:161], v[194:197], v[74:77]
	v_mfma_f32_16x16x32_bf16 v[74:77], v[162:165], v[198:201], v[74:77]
	s_setprio 2
	s_barrier
	v_mfma_f32_16x16x32_bf16 v[66:69], v[158:161], v[202:205], v[66:69]
	v_mfma_f32_16x16x32_bf16 v[66:69], v[162:165], v[206:209], v[66:69]
	v_mfma_f32_16x16x32_bf16 v[70:73], v[150:153], v[202:205], v[70:73]
	v_mfma_f32_16x16x32_bf16 v[70:73], v[154:157], v[206:209], v[70:73]
	s_setprio 0
	ds_read_b128 v[166:169], v183 offset:49152
	ds_read_b128 v[170:173], v183 offset:50176
	ds_read_b128 v[186:189], v183 offset:51200
	ds_read_b128 v[190:193], v183 offset:52224
	ds_read_b128 v[194:197], v183 offset:53248
	ds_read_b128 v[198:201], v183 offset:54272
	ds_read_b128 v[202:205], v183 offset:55296
	ds_read_b128 v[206:209], v183 offset:56320
	s_add_u32 s24, s22, 0x40000
	s_addc_u32 s25, s23, 0
	s_mov_b32 s75, m0
	s_mov_b32 m0, s46
	s_nop 0
	global_load_lds_dwordx4 v176, s[24:25]
	s_mov_b32 m0, s75
	s_add_u32 s22, s22, 0x44000
	s_mov_b32 s75, m0
	s_mov_b32 m0, s47
	s_nop 0
	global_load_lds_dwordx4 v178, s[24:25]
	s_mov_b32 m0, s75
	s_addc_u32 s23, s23, 0
	s_mov_b32 s24, m0
	s_mov_b32 m0, s48
	s_nop 0
	global_load_lds_dwordx4 v176, s[22:23]
	s_mov_b32 m0, s24
	s_nop 0
	s_mov_b32 s24, m0
	s_mov_b32 m0, s49
	s_nop 0
	global_load_lds_dwordx4 v178, s[22:23]
	s_mov_b32 m0, s24
	s_waitcnt vmcnt(4)
	s_waitcnt lgkmcnt(0)
	s_barrier
	s_setprio 1
	s_waitcnt lgkmcnt(7)
	v_mfma_f32_16x16x32_bf16 v[62:65], v[130:133], v[166:169], v[62:65]
	v_mfma_f32_16x16x32_bf16 v[62:65], v[134:137], v[170:173], v[62:65]
	s_waitcnt lgkmcnt(5)
	v_mfma_f32_16x16x32_bf16 v[58:61], v[138:141], v[166:169], v[58:61]
	v_mfma_f32_16x16x32_bf16 v[58:61], v[142:145], v[170:173], v[58:61]
	s_waitcnt lgkmcnt(3)
	v_mfma_f32_16x16x32_bf16 v[42:45], v[138:141], v[186:189], v[42:45]
	v_mfma_f32_16x16x32_bf16 v[42:45], v[142:145], v[190:193], v[42:45]
	s_waitcnt lgkmcnt(1)
	v_mfma_f32_16x16x32_bf16 v[46:49], v[130:133], v[186:189], v[46:49]
	v_mfma_f32_16x16x32_bf16 v[46:49], v[134:137], v[190:193], v[46:49]
	v_mfma_f32_16x16x32_bf16 v[30:33], v[130:133], v[194:197], v[30:33]
	v_mfma_f32_16x16x32_bf16 v[30:33], v[134:137], v[198:201], v[30:33]
	v_mfma_f32_16x16x32_bf16 v[26:29], v[138:141], v[194:197], v[26:29]
	v_mfma_f32_16x16x32_bf16 v[26:29], v[142:145], v[198:201], v[26:29]
	v_mfma_f32_16x16x32_bf16 v[10:13], v[138:141], v[202:205], v[10:13]
	v_mfma_f32_16x16x32_bf16 v[10:13], v[142:145], v[206:209], v[10:13]
	s_waitcnt lgkmcnt(0)
	v_mfma_f32_16x16x32_bf16 v[14:17], v[130:133], v[202:205], v[14:17]
	v_mfma_f32_16x16x32_bf16 v[14:17], v[134:137], v[206:209], v[14:17]
	s_setprio 0
	s_setprio 1
	v_mfma_f32_16x16x32_bf16 v[54:57], v[150:153], v[166:169], v[54:57]
	v_mfma_f32_16x16x32_bf16 v[54:57], v[154:157], v[170:173], v[54:57]
	v_mfma_f32_16x16x32_bf16 v[50:53], v[158:161], v[166:169], v[50:53]
	v_mfma_f32_16x16x32_bf16 v[50:53], v[162:165], v[170:173], v[50:53]
	v_mfma_f32_16x16x32_bf16 v[34:37], v[158:161], v[186:189], v[34:37]
	v_mfma_f32_16x16x32_bf16 v[34:37], v[162:165], v[190:193], v[34:37]
	v_mfma_f32_16x16x32_bf16 v[38:41], v[150:153], v[186:189], v[38:41]
	v_mfma_f32_16x16x32_bf16 v[38:41], v[154:157], v[190:193], v[38:41]
	v_mfma_f32_16x16x32_bf16 v[22:25], v[150:153], v[194:197], v[22:25]
	v_mfma_f32_16x16x32_bf16 v[22:25], v[154:157], v[198:201], v[22:25]
	v_mfma_f32_16x16x32_bf16 v[18:21], v[158:161], v[194:197], v[18:21]
	v_mfma_f32_16x16x32_bf16 v[18:21], v[162:165], v[198:201], v[18:21]
	s_setprio 2
	s_barrier
	v_mfma_f32_16x16x32_bf16 v[2:5], v[158:161], v[202:205], v[2:5]
	v_mfma_f32_16x16x32_bf16 v[2:5], v[162:165], v[206:209], v[2:5]
	v_mfma_f32_16x16x32_bf16 v[6:9], v[150:153], v[202:205], v[6:9]
	v_mfma_f32_16x16x32_bf16 v[6:9], v[154:157], v[206:209], v[6:9]
	s_setprio 0
	s_add_i32 s74, s74, 2
	s_add_u32 s67, s67, 0x80000
	s_addc_u32 s70, s70, 0
	s_add_u32 s20, s20, 0x400000
	s_addc_u32 s21, s21, 0
	s_add_u32 s71, s71, 0x400000
	s_addc_u32 s73, s73, 0
	s_cmpk_gt_u32 s74, 0x53
	s_cbranch_scc0 .LBB0_1952
	s_and_b64 vcc, exec, s[8:9]
	s_cbranch_vccz .LBB0_1955
	s_barrier

.LBB0_2145:
	s_ashr_i32 s25, s24, 31
	s_lshl_b64 s[26:27], s[24:25], 20
	s_add_u32 s26, s33, s26
	s_addc_u32 s27, s42, s27
	s_and_b64 s[28:29], s[2:3], exec
	s_cselect_b32 s5, s27, s37
	s_cselect_b32 s25, s26, s36
	s_ashr_i32 s23, s22, 31
	s_lshl_b64 s[28:29], s[22:23], 20
	s_add_u32 s28, s43, s28
	s_addc_u32 s29, s46, s29
	s_and_b64 s[40:41], s[2:3], exec
	s_cselect_b32 s23, s29, s35
	s_cselect_b32 s31, s28, s34
	s_add_u32 s77, s34, 0x100
	s_addc_u32 s78, s35, 0
	s_add_u32 s34, s36, 0x80080
	s_addc_u32 s35, s37, 0
	s_add_u32 s79, s36, 0x100
	s_addc_u32 s80, s37, 0
	s_mov_b32 s81, -2
	s_waitcnt vmcnt(25)
	s_waitcnt vmcnt(24)
	s_waitcnt vmcnt(4)
	s_waitcnt vmcnt(2)
	s_waitcnt vmcnt(1)
	s_waitcnt vmcnt(0)
	ds_read_b128 v[42:45], v181
	ds_read_b128 v[46:49], v181 offset:1024
	ds_read_b128 v[58:61], v181 offset:2048
	ds_read_b128 v[62:65], v181 offset:3072
	ds_read_b128 v[146:149], v182
	ds_read_b128 v[150:153], v182 offset:1024
	ds_read_b128 v[154:157], v182 offset:2048
	ds_read_b128 v[158:161], v182 offset:3072
	s_cmp_eq_u32 s81, 28
	s_cselect_b32 s37, s23, s78
	s_cselect_b32 s36, s31, s77
	s_cselect_b32 s41, s5, s80
	s_cselect_b32 s40, s25, s79
	ds_read_b128 v[170:173], v183
	ds_read_b128 v[188:191], v183 offset:1024
	ds_read_b128 v[192:195], v183 offset:2048
	ds_read_b128 v[196:199], v183 offset:3072
	ds_read_b128 v[200:203], v183 offset:4096
	ds_read_b128 v[204:207], v183 offset:5120
	ds_read_b128 v[208:211], v183 offset:6144
	ds_read_b128 v[212:215], v183 offset:7168
	s_add_u32 s82, s34, 0xfff80000
	s_addc_u32 s83, s35, -1
	s_mov_b32 s86, m0
	s_mov_b32 m0, s70
	s_nop 0
	global_load_lds_dwordx4 v1, s[82:83]
	s_mov_b32 m0, s86
	s_nop 0
	s_mov_b32 s86, m0
	s_mov_b32 m0, s73
	s_nop 0
	global_load_lds_dwordx4 v177, s[82:83]
	s_mov_b32 m0, s86
	s_mov_b32 s82, m0
	s_mov_b32 m0, s71
	s_nop 0
	global_load_lds_dwordx4 v1, s[34:35]
	s_mov_b32 m0, s82
	s_nop 0
	s_mov_b32 s82, m0
	s_mov_b32 m0, s74
	s_nop 0
	global_load_lds_dwordx4 v177, s[34:35]
	s_mov_b32 m0, s82
	s_waitcnt vmcnt(8)
	s_waitcnt lgkmcnt(0)
	s_barrier
	s_setprio 1
	s_waitcnt lgkmcnt(7)
	v_mfma_f32_16x16x32_bf16 v[142:145], v[42:45], v[170:173], 0
	v_mfma_f32_16x16x32_bf16 v[142:145], v[46:49], v[188:191], v[142:145]
	s_waitcnt lgkmcnt(5)
	v_mfma_f32_16x16x32_bf16 v[138:141], v[58:61], v[170:173], 0
	v_mfma_f32_16x16x32_bf16 v[138:141], v[62:65], v[188:191], v[138:141]
	s_waitcnt lgkmcnt(3)
	v_mfma_f32_16x16x32_bf16 v[126:129], v[42:45], v[192:195], 0
	v_mfma_f32_16x16x32_bf16 v[126:129], v[46:49], v[196:199], v[126:129]
	s_waitcnt lgkmcnt(1)
	v_mfma_f32_16x16x32_bf16 v[122:125], v[58:61], v[192:195], 0
	v_mfma_f32_16x16x32_bf16 v[122:125], v[62:65], v[196:199], v[122:125]
	v_mfma_f32_16x16x32_bf16 v[110:113], v[42:45], v[200:203], 0
	v_mfma_f32_16x16x32_bf16 v[110:113], v[46:49], v[204:207], v[110:113]
	v_mfma_f32_16x16x32_bf16 v[106:109], v[58:61], v[200:203], 0
	v_mfma_f32_16x16x32_bf16 v[106:109], v[62:65], v[204:207], v[106:109]
	v_mfma_f32_16x16x32_bf16 v[94:97], v[42:45], v[208:211], 0
	v_mfma_f32_16x16x32_bf16 v[94:97], v[46:49], v[212:215], v[94:97]
	s_waitcnt lgkmcnt(0)
	v_mfma_f32_16x16x32_bf16 v[90:93], v[58:61], v[208:211], 0
	v_mfma_f32_16x16x32_bf16 v[90:93], v[62:65], v[212:215], v[90:93]
	s_setprio 0
	s_setprio 1
	v_mfma_f32_16x16x32_bf16 v[134:137], v[146:149], v[170:173], 0
	v_mfma_f32_16x16x32_bf16 v[134:137], v[150:153], v[188:191], v[134:137]
	v_mfma_f32_16x16x32_bf16 v[130:133], v[154:157], v[170:173], 0
	v_mfma_f32_16x16x32_bf16 v[130:133], v[158:161], v[188:191], v[130:133]
	v_mfma_f32_16x16x32_bf16 v[118:121], v[146:149], v[192:195], 0
	v_mfma_f32_16x16x32_bf16 v[118:121], v[150:153], v[196:199], v[118:121]
	v_mfma_f32_16x16x32_bf16 v[114:117], v[154:157], v[192:195], 0
	v_mfma_f32_16x16x32_bf16 v[114:117], v[158:161], v[196:199], v[114:117]
	v_mfma_f32_16x16x32_bf16 v[102:105], v[146:149], v[200:203], 0
	v_mfma_f32_16x16x32_bf16 v[102:105], v[150:153], v[204:207], v[102:105]
	v_mfma_f32_16x16x32_bf16 v[98:101], v[154:157], v[200:203], 0
	v_mfma_f32_16x16x32_bf16 v[98:101], v[158:161], v[204:207], v[98:101]
	s_setprio 2
	s_barrier
	v_mfma_f32_16x16x32_bf16 v[86:89], v[146:149], v[208:211], 0
	v_mfma_f32_16x16x32_bf16 v[86:89], v[150:153], v[212:215], v[86:89]
	v_mfma_f32_16x16x32_bf16 v[82:85], v[154:157], v[208:211], 0
	v_mfma_f32_16x16x32_bf16 v[82:85], v[158:161], v[212:215], v[82:85]
	s_setprio 0
	ds_read_b128 v[170:173], v183 offset:16384
	ds_read_b128 v[188:191], v183 offset:17408
	ds_read_b128 v[192:195], v183 offset:18432
	ds_read_b128 v[196:199], v183 offset:19456
	ds_read_b128 v[200:203], v183 offset:20480
	ds_read_b128 v[204:207], v183 offset:21504
	ds_read_b128 v[208:211], v183 offset:22528
	ds_read_b128 v[212:215], v183 offset:23552
	s_mov_b32 s82, m0
	s_mov_b32 m0, s49
	s_nop 0
	global_load_lds_dwordx4 v176, s[36:37]
	s_mov_b32 m0, s82
	s_nop 0
	s_mov_b32 s82, m0
	s_mov_b32 m0, s56
	s_nop 0
	global_load_lds_dwordx4 v178, s[36:37]
	s_mov_b32 m0, s82
	s_add_u32 s82, s36, 0x80000
	s_addc_u32 s83, s37, 0
	s_mov_b32 s86, m0
	s_mov_b32 m0, s57
	s_nop 0
	global_load_lds_dwordx4 v176, s[82:83]
	s_mov_b32 m0, s86
	s_nop 0
	s_mov_b32 s86, m0
	s_mov_b32 m0, s58
	s_nop 0
	global_load_lds_dwordx4 v178, s[82:83]
	s_mov_b32 m0, s86
	s_waitcnt vmcnt(4)
	s_waitcnt lgkmcnt(0)
	s_barrier
	s_setprio 1
	s_waitcnt lgkmcnt(7)
	v_mfma_f32_16x16x32_bf16 v[78:81], v[42:45], v[170:173], 0
	v_mfma_f32_16x16x32_bf16 v[78:81], v[46:49], v[188:191], v[78:81]
	s_waitcnt lgkmcnt(5)
	v_mfma_f32_16x16x32_bf16 v[74:77], v[58:61], v[170:173], 0
	v_mfma_f32_16x16x32_bf16 v[74:77], v[62:65], v[188:191], v[74:77]
	s_waitcnt lgkmcnt(3)
	v_mfma_f32_16x16x32_bf16 v[54:57], v[42:45], v[192:195], 0
	v_mfma_f32_16x16x32_bf16 v[54:57], v[46:49], v[196:199], v[54:57]
	s_waitcnt lgkmcnt(1)
	v_mfma_f32_16x16x32_bf16 v[50:53], v[58:61], v[192:195], 0
	v_mfma_f32_16x16x32_bf16 v[50:53], v[62:65], v[196:199], v[50:53]
	v_mfma_f32_16x16x32_bf16 v[30:33], v[42:45], v[200:203], 0
	v_mfma_f32_16x16x32_bf16 v[30:33], v[46:49], v[204:207], v[30:33]
	v_mfma_f32_16x16x32_bf16 v[26:29], v[58:61], v[200:203], 0
	v_mfma_f32_16x16x32_bf16 v[26:29], v[62:65], v[204:207], v[26:29]
	v_mfma_f32_16x16x32_bf16 v[14:17], v[42:45], v[208:211], 0
	v_mfma_f32_16x16x32_bf16 v[14:17], v[46:49], v[212:215], v[14:17]
	s_waitcnt lgkmcnt(0)
	v_mfma_f32_16x16x32_bf16 v[10:13], v[58:61], v[208:211], 0
	v_mfma_f32_16x16x32_bf16 v[10:13], v[62:65], v[212:215], v[10:13]
	s_setprio 0
	s_setprio 1
	v_mfma_f32_16x16x32_bf16 v[38:41], v[146:149], v[192:195], 0
	v_mfma_f32_16x16x32_bf16 v[38:41], v[150:153], v[196:199], v[38:41]
	v_mfma_f32_16x16x32_bf16 v[34:37], v[154:157], v[192:195], 0
	v_mfma_f32_16x16x32_bf16 v[34:37], v[158:161], v[196:199], v[34:37]
	v_mfma_f32_16x16x32_bf16 v[22:25], v[146:149], v[200:203], 0
	v_mfma_f32_16x16x32_bf16 v[22:25], v[150:153], v[204:207], v[22:25]
	v_mfma_f32_16x16x32_bf16 v[18:21], v[154:157], v[200:203], 0
	v_mfma_f32_16x16x32_bf16 v[18:21], v[158:161], v[204:207], v[18:21]
	v_mfma_f32_16x16x32_bf16 v[6:9], v[146:149], v[208:211], 0
	v_mfma_f32_16x16x32_bf16 v[6:9], v[150:153], v[212:215], v[6:9]
	v_mfma_f32_16x16x32_bf16 v[2:5], v[154:157], v[208:211], 0
	v_mfma_f32_16x16x32_bf16 v[2:5], v[158:161], v[212:215], v[2:5]
	s_setprio 2
	s_barrier
	v_mfma_f32_16x16x32_bf16 v[42:45], v[146:149], v[170:173], 0
	v_mfma_f32_16x16x32_bf16 v[42:45], v[150:153], v[188:191], v[42:45]
	v_mfma_f32_16x16x32_bf16 v[46:49], v[154:157], v[170:173], 0
	v_mfma_f32_16x16x32_bf16 v[46:49], v[158:161], v[188:191], v[46:49]
	s_setprio 0
	ds_read_b128 v[58:61], v184
	ds_read_b128 v[62:65], v184 offset:1024
	ds_read_b128 v[66:69], v184 offset:2048
	ds_read_b128 v[70:73], v184 offset:3072
	ds_read_b128 v[146:149], v185
	ds_read_b128 v[150:153], v185 offset:1024
	ds_read_b128 v[154:157], v185 offset:2048
	ds_read_b128 v[158:161], v185 offset:3072
	ds_read_b128 v[170:173], v183 offset:32768
	ds_read_b128 v[188:191], v183 offset:33792
	ds_read_b128 v[192:195], v183 offset:34816
	ds_read_b128 v[196:199], v183 offset:35840
	ds_read_b128 v[200:203], v183 offset:36864
	ds_read_b128 v[204:207], v183 offset:37888
	ds_read_b128 v[208:211], v183 offset:38912
	ds_read_b128 v[212:215], v183 offset:39936
	s_mov_b32 s82, m0
	s_mov_b32 m0, s48
	s_nop 0
	global_load_lds_dwordx4 v1, s[40:41]
	s_mov_b32 m0, s82
	s_nop 0
	s_mov_b32 s82, m0
	s_mov_b32 m0, s59
	s_nop 0
	global_load_lds_dwordx4 v177, s[40:41]
	s_mov_b32 m0, s82
	s_add_u32 s40, s40, 0x80000
	s_addc_u32 s41, s41, 0
	s_mov_b32 s82, m0
	s_mov_b32 m0, s62
	s_nop 0
	global_load_lds_dwordx4 v1, s[40:41]
	s_mov_b32 m0, s82
	s_nop 0
	s_mov_b32 s82, m0
	s_mov_b32 m0, s63
	s_nop 0
	global_load_lds_dwordx4 v177, s[40:41]
	s_mov_b32 m0, s82
	s_waitcnt vmcnt(8)
	s_waitcnt lgkmcnt(0)
	s_barrier
	s_setprio 1
	s_waitcnt lgkmcnt(7)
	v_mfma_f32_16x16x32_bf16 v[142:145], v[58:61], v[170:173], v[142:145]
	v_mfma_f32_16x16x32_bf16 v[142:145], v[62:65], v[188:191], v[142:145]
	s_waitcnt lgkmcnt(5)
	v_mfma_f32_16x16x32_bf16 v[138:141], v[66:69], v[170:173], v[138:141]
	v_mfma_f32_16x16x32_bf16 v[138:141], v[70:73], v[188:191], v[138:141]
	s_waitcnt lgkmcnt(3)
	v_mfma_f32_16x16x32_bf16 v[126:129], v[58:61], v[192:195], v[126:129]
	v_mfma_f32_16x16x32_bf16 v[126:129], v[62:65], v[196:199], v[126:129]
	s_waitcnt lgkmcnt(1)
	v_mfma_f32_16x16x32_bf16 v[122:125], v[66:69], v[192:195], v[122:125]
	v_mfma_f32_16x16x32_bf16 v[122:125], v[70:73], v[196:199], v[122:125]
	v_mfma_f32_16x16x32_bf16 v[110:113], v[58:61], v[200:203], v[110:113]
	v_mfma_f32_16x16x32_bf16 v[110:113], v[62:65], v[204:207], v[110:113]
	v_mfma_f32_16x16x32_bf16 v[106:109], v[66:69], v[200:203], v[106:109]
	v_mfma_f32_16x16x32_bf16 v[106:109], v[70:73], v[204:207], v[106:109]
	v_mfma_f32_16x16x32_bf16 v[94:97], v[58:61], v[208:211], v[94:97]
	v_mfma_f32_16x16x32_bf16 v[94:97], v[62:65], v[212:215], v[94:97]
	s_waitcnt lgkmcnt(0)
	v_mfma_f32_16x16x32_bf16 v[90:93], v[66:69], v[208:211], v[90:93]
	v_mfma_f32_16x16x32_bf16 v[90:93], v[70:73], v[212:215], v[90:93]
	s_setprio 0
	s_setprio 1
	v_mfma_f32_16x16x32_bf16 v[134:137], v[146:149], v[170:173], v[134:137]
	v_mfma_f32_16x16x32_bf16 v[134:137], v[150:153], v[188:191], v[134:137]
	v_mfma_f32_16x16x32_bf16 v[130:133], v[154:157], v[170:173], v[130:133]
	v_mfma_f32_16x16x32_bf16 v[130:133], v[158:161], v[188:191], v[130:133]
	v_mfma_f32_16x16x32_bf16 v[118:121], v[146:149], v[192:195], v[118:121]
	v_mfma_f32_16x16x32_bf16 v[118:121], v[150:153], v[196:199], v[118:121]
	v_mfma_f32_16x16x32_bf16 v[114:117], v[154:157], v[192:195], v[114:117]
	v_mfma_f32_16x16x32_bf16 v[114:117], v[158:161], v[196:199], v[114:117]
	v_mfma_f32_16x16x32_bf16 v[102:105], v[146:149], v[200:203], v[102:105]
	v_mfma_f32_16x16x32_bf16 v[102:105], v[150:153], v[204:207], v[102:105]
	v_mfma_f32_16x16x32_bf16 v[98:101], v[154:157], v[200:203], v[98:101]
	v_mfma_f32_16x16x32_bf16 v[98:101], v[158:161], v[204:207], v[98:101]
	s_setprio 2
	s_barrier
	v_mfma_f32_16x16x32_bf16 v[86:89], v[146:149], v[208:211], v[86:89]
	v_mfma_f32_16x16x32_bf16 v[86:89], v[150:153], v[212:215], v[86:89]
	v_mfma_f32_16x16x32_bf16 v[82:85], v[154:157], v[208:211], v[82:85]
	v_mfma_f32_16x16x32_bf16 v[82:85], v[158:161], v[212:215], v[82:85]
	s_setprio 0
	ds_read_b128 v[170:173], v183 offset:49152
	ds_read_b128 v[188:191], v183 offset:50176
	ds_read_b128 v[192:195], v183 offset:51200
	ds_read_b128 v[196:199], v183 offset:52224
	ds_read_b128 v[200:203], v183 offset:53248
	ds_read_b128 v[204:207], v183 offset:54272
	ds_read_b128 v[208:211], v183 offset:55296
	ds_read_b128 v[212:215], v183 offset:56320
	s_add_u32 s40, s36, 0x80
	s_addc_u32 s41, s37, 0
	s_mov_b32 s82, m0
	s_mov_b32 m0, s64
	s_nop 0
	global_load_lds_dwordx4 v176, s[40:41]
	s_mov_b32 m0, s82
	s_add_u32 s36, s36, 0x80080
	s_mov_b32 s82, m0
	s_mov_b32 m0, s65
	s_nop 0
	global_load_lds_dwordx4 v178, s[40:41]
	s_mov_b32 m0, s82
	s_addc_u32 s37, s37, 0
	s_mov_b32 s40, m0
	s_mov_b32 m0, s66
	s_nop 0
	global_load_lds_dwordx4 v176, s[36:37]
	s_mov_b32 m0, s40
	s_nop 0
	s_mov_b32 s40, m0
	s_mov_b32 m0, s67
	s_nop 0
	global_load_lds_dwordx4 v178, s[36:37]
	s_mov_b32 m0, s40
	s_waitcnt vmcnt(4)
	s_waitcnt lgkmcnt(0)
	s_barrier
	s_setprio 1
	s_waitcnt lgkmcnt(7)
	v_mfma_f32_16x16x32_bf16 v[78:81], v[58:61], v[170:173], v[78:81]
	v_mfma_f32_16x16x32_bf16 v[78:81], v[62:65], v[188:191], v[78:81]
	s_waitcnt lgkmcnt(5)
	v_mfma_f32_16x16x32_bf16 v[74:77], v[66:69], v[170:173], v[74:77]
	v_mfma_f32_16x16x32_bf16 v[74:77], v[70:73], v[188:191], v[74:77]
	s_waitcnt lgkmcnt(3)
	v_mfma_f32_16x16x32_bf16 v[54:57], v[58:61], v[192:195], v[54:57]
	v_mfma_f32_16x16x32_bf16 v[54:57], v[62:65], v[196:199], v[54:57]
	s_waitcnt lgkmcnt(1)
	v_mfma_f32_16x16x32_bf16 v[50:53], v[66:69], v[192:195], v[50:53]
	v_mfma_f32_16x16x32_bf16 v[50:53], v[70:73], v[196:199], v[50:53]
	v_mfma_f32_16x16x32_bf16 v[30:33], v[58:61], v[200:203], v[30:33]
	v_mfma_f32_16x16x32_bf16 v[30:33], v[62:65], v[204:207], v[30:33]
	v_mfma_f32_16x16x32_bf16 v[26:29], v[66:69], v[200:203], v[26:29]
	v_mfma_f32_16x16x32_bf16 v[26:29], v[70:73], v[204:207], v[26:29]
	v_mfma_f32_16x16x32_bf16 v[14:17], v[58:61], v[208:211], v[14:17]
	v_mfma_f32_16x16x32_bf16 v[14:17], v[62:65], v[212:215], v[14:17]
	s_waitcnt lgkmcnt(0)
	v_mfma_f32_16x16x32_bf16 v[10:13], v[66:69], v[208:211], v[10:13]
	v_mfma_f32_16x16x32_bf16 v[10:13], v[70:73], v[212:215], v[10:13]
	s_setprio 0
	s_setprio 1
	v_mfma_f32_16x16x32_bf16 v[42:45], v[146:149], v[170:173], v[42:45]
	v_mfma_f32_16x16x32_bf16 v[70:73], v[150:153], v[188:191], v[42:45]
	v_mfma_f32_16x16x32_bf16 v[42:45], v[154:157], v[170:173], v[46:49]
	v_mfma_f32_16x16x32_bf16 v[66:69], v[158:161], v[188:191], v[42:45]
	v_mfma_f32_16x16x32_bf16 v[38:41], v[146:149], v[192:195], v[38:41]
	v_mfma_f32_16x16x32_bf16 v[38:41], v[150:153], v[196:199], v[38:41]
	v_mfma_f32_16x16x32_bf16 v[34:37], v[154:157], v[192:195], v[34:37]
	v_mfma_f32_16x16x32_bf16 v[34:37], v[158:161], v[196:199], v[34:37]
	v_mfma_f32_16x16x32_bf16 v[22:25], v[146:149], v[200:203], v[22:25]
	v_mfma_f32_16x16x32_bf16 v[22:25], v[150:153], v[204:207], v[22:25]
	v_mfma_f32_16x16x32_bf16 v[18:21], v[154:157], v[200:203], v[18:21]
	v_mfma_f32_16x16x32_bf16 v[18:21], v[158:161], v[204:207], v[18:21]
	s_setprio 2
	s_barrier
	v_mfma_f32_16x16x32_bf16 v[6:9], v[146:149], v[208:211], v[6:9]
	v_mfma_f32_16x16x32_bf16 v[6:9], v[150:153], v[212:215], v[6:9]
	v_mfma_f32_16x16x32_bf16 v[2:5], v[154:157], v[208:211], v[2:5]
	v_mfma_f32_16x16x32_bf16 v[2:5], v[158:161], v[212:215], v[2:5]
	s_setprio 0
	s_add_i32 s81, s81, 2
	s_add_u32 s77, s77, 0x100
	s_addc_u32 s78, s78, 0
	s_add_u32 s34, s34, 0x100
	s_addc_u32 s35, s35, 0
	s_add_u32 s79, s79, 0x100
	s_addc_u32 s80, s80, 0
	s_cmp_gt_u32 s81, 29
	.p2align 6
.LBB0_2146:
	ds_read_b128 v[42:45], v181
	ds_read_b128 v[46:49], v181 offset:1024
	ds_read_b128 v[58:61], v181 offset:2048
	ds_read_b128 v[62:65], v181 offset:3072
	ds_read_b128 v[146:149], v182
	ds_read_b128 v[150:153], v182 offset:1024
	ds_read_b128 v[154:157], v182 offset:2048
	ds_read_b128 v[158:161], v182 offset:3072
	s_cmp_eq_u32 s81, 28
	s_cselect_b32 s37, s23, s78
	s_cselect_b32 s36, s31, s77
	s_cselect_b32 s41, s5, s80
	s_cselect_b32 s40, s25, s79
	ds_read_b128 v[170:173], v183
	ds_read_b128 v[188:191], v183 offset:1024
	ds_read_b128 v[192:195], v183 offset:2048
	ds_read_b128 v[196:199], v183 offset:3072
	ds_read_b128 v[200:203], v183 offset:4096
	ds_read_b128 v[204:207], v183 offset:5120
	ds_read_b128 v[208:211], v183 offset:6144
	ds_read_b128 v[212:215], v183 offset:7168
	s_add_u32 s82, s34, 0xfff80000
	s_addc_u32 s83, s35, -1
	s_mov_b32 s86, m0
	s_mov_b32 m0, s70
	s_nop 0
	global_load_lds_dwordx4 v1, s[82:83]
	s_mov_b32 m0, s86
	s_nop 0
	s_mov_b32 s86, m0
	s_mov_b32 m0, s73
	s_nop 0
	global_load_lds_dwordx4 v177, s[82:83]
	s_mov_b32 m0, s86
	s_mov_b32 s82, m0
	s_mov_b32 m0, s71
	s_nop 0
	global_load_lds_dwordx4 v1, s[34:35]
	s_mov_b32 m0, s82
	s_nop 0
	s_mov_b32 s82, m0
	s_mov_b32 m0, s74
	s_nop 0
	global_load_lds_dwordx4 v177, s[34:35]
	s_mov_b32 m0, s82
	s_waitcnt vmcnt(8)
	s_waitcnt lgkmcnt(0)
	s_barrier
	s_setprio 1
	s_waitcnt lgkmcnt(7)
	v_mfma_f32_16x16x32_bf16 v[142:145], v[42:45], v[170:173], v[142:145]
	v_mfma_f32_16x16x32_bf16 v[142:145], v[46:49], v[188:191], v[142:145]
	s_waitcnt lgkmcnt(5)
	v_mfma_f32_16x16x32_bf16 v[138:141], v[58:61], v[170:173], v[138:141]
	v_mfma_f32_16x16x32_bf16 v[138:141], v[62:65], v[188:191], v[138:141]
	s_waitcnt lgkmcnt(3)
	v_mfma_f32_16x16x32_bf16 v[126:129], v[42:45], v[192:195], v[126:129]
	v_mfma_f32_16x16x32_bf16 v[126:129], v[46:49], v[196:199], v[126:129]
	s_waitcnt lgkmcnt(1)
	v_mfma_f32_16x16x32_bf16 v[122:125], v[58:61], v[192:195], v[122:125]
	v_mfma_f32_16x16x32_bf16 v[122:125], v[62:65], v[196:199], v[122:125]
	v_mfma_f32_16x16x32_bf16 v[110:113], v[42:45], v[200:203], v[110:113]
	v_mfma_f32_16x16x32_bf16 v[110:113], v[46:49], v[204:207], v[110:113]
	v_mfma_f32_16x16x32_bf16 v[106:109], v[58:61], v[200:203], v[106:109]
	v_mfma_f32_16x16x32_bf16 v[106:109], v[62:65], v[204:207], v[106:109]
	v_mfma_f32_16x16x32_bf16 v[94:97], v[42:45], v[208:211], v[94:97]
	v_mfma_f32_16x16x32_bf16 v[94:97], v[46:49], v[212:215], v[94:97]
	s_waitcnt lgkmcnt(0)
	v_mfma_f32_16x16x32_bf16 v[90:93], v[58:61], v[208:211], v[90:93]
	v_mfma_f32_16x16x32_bf16 v[90:93], v[62:65], v[212:215], v[90:93]
	s_setprio 0
	s_setprio 1
	v_mfma_f32_16x16x32_bf16 v[134:137], v[146:149], v[170:173], v[134:137]
	v_mfma_f32_16x16x32_bf16 v[134:137], v[150:153], v[188:191], v[134:137]
	v_mfma_f32_16x16x32_bf16 v[130:133], v[154:157], v[170:173], v[130:133]
	v_mfma_f32_16x16x32_bf16 v[130:133], v[158:161], v[188:191], v[130:133]
	v_mfma_f32_16x16x32_bf16 v[118:121], v[146:149], v[192:195], v[118:121]
	v_mfma_f32_16x16x32_bf16 v[118:121], v[150:153], v[196:199], v[118:121]
	v_mfma_f32_16x16x32_bf16 v[114:117], v[154:157], v[192:195], v[114:117]
	v_mfma_f32_16x16x32_bf16 v[114:117], v[158:161], v[196:199], v[114:117]
	v_mfma_f32_16x16x32_bf16 v[102:105], v[146:149], v[200:203], v[102:105]
	v_mfma_f32_16x16x32_bf16 v[102:105], v[150:153], v[204:207], v[102:105]
	v_mfma_f32_16x16x32_bf16 v[98:101], v[154:157], v[200:203], v[98:101]
	v_mfma_f32_16x16x32_bf16 v[98:101], v[158:161], v[204:207], v[98:101]
	s_setprio 2
	s_barrier
	v_mfma_f32_16x16x32_bf16 v[86:89], v[146:149], v[208:211], v[86:89]
	v_mfma_f32_16x16x32_bf16 v[86:89], v[150:153], v[212:215], v[86:89]
	v_mfma_f32_16x16x32_bf16 v[82:85], v[154:157], v[208:211], v[82:85]
	v_mfma_f32_16x16x32_bf16 v[82:85], v[158:161], v[212:215], v[82:85]
	s_setprio 0
	ds_read_b128 v[170:173], v183 offset:16384
	ds_read_b128 v[188:191], v183 offset:17408
	ds_read_b128 v[192:195], v183 offset:18432
	ds_read_b128 v[196:199], v183 offset:19456
	ds_read_b128 v[200:203], v183 offset:20480
	ds_read_b128 v[204:207], v183 offset:21504
	ds_read_b128 v[208:211], v183 offset:22528
	ds_read_b128 v[212:215], v183 offset:23552
	s_mov_b32 s82, m0
	s_mov_b32 m0, s49
	s_nop 0
	global_load_lds_dwordx4 v176, s[36:37]
	s_mov_b32 m0, s82
	s_nop 0
	s_mov_b32 s82, m0
	s_mov_b32 m0, s56
	s_nop 0
	global_load_lds_dwordx4 v178, s[36:37]
	s_mov_b32 m0, s82
	s_add_u32 s82, s36, 0x80000
	s_addc_u32 s83, s37, 0
	s_mov_b32 s86, m0
	s_mov_b32 m0, s57
	s_nop 0
	global_load_lds_dwordx4 v176, s[82:83]
	s_mov_b32 m0, s86
	s_nop 0
	s_mov_b32 s86, m0
	s_mov_b32 m0, s58
	s_nop 0
	global_load_lds_dwordx4 v178, s[82:83]
	s_mov_b32 m0, s86
	s_waitcnt vmcnt(4)
	s_waitcnt lgkmcnt(0)
	s_barrier
	s_setprio 1
	s_waitcnt lgkmcnt(7)
	v_mfma_f32_16x16x32_bf16 v[78:81], v[42:45], v[170:173], v[78:81]
	v_mfma_f32_16x16x32_bf16 v[78:81], v[46:49], v[188:191], v[78:81]
	s_waitcnt lgkmcnt(5)
	v_mfma_f32_16x16x32_bf16 v[74:77], v[58:61], v[170:173], v[74:77]
	v_mfma_f32_16x16x32_bf16 v[74:77], v[62:65], v[188:191], v[74:77]
	s_waitcnt lgkmcnt(3)
	v_mfma_f32_16x16x32_bf16 v[54:57], v[42:45], v[192:195], v[54:57]
	v_mfma_f32_16x16x32_bf16 v[54:57], v[46:49], v[196:199], v[54:57]
	s_waitcnt lgkmcnt(1)
	v_mfma_f32_16x16x32_bf16 v[50:53], v[58:61], v[192:195], v[50:53]
	v_mfma_f32_16x16x32_bf16 v[50:53], v[62:65], v[196:199], v[50:53]
	v_mfma_f32_16x16x32_bf16 v[30:33], v[42:45], v[200:203], v[30:33]
	v_mfma_f32_16x16x32_bf16 v[30:33], v[46:49], v[204:207], v[30:33]
	v_mfma_f32_16x16x32_bf16 v[26:29], v[58:61], v[200:203], v[26:29]
	v_mfma_f32_16x16x32_bf16 v[26:29], v[62:65], v[204:207], v[26:29]
	v_mfma_f32_16x16x32_bf16 v[14:17], v[42:45], v[208:211], v[14:17]
	v_mfma_f32_16x16x32_bf16 v[14:17], v[46:49], v[212:215], v[14:17]
	s_waitcnt lgkmcnt(0)
	v_mfma_f32_16x16x32_bf16 v[10:13], v[58:61], v[208:211], v[10:13]
	v_mfma_f32_16x16x32_bf16 v[10:13], v[62:65], v[212:215], v[10:13]
	s_setprio 0
	s_setprio 1
	v_mfma_f32_16x16x32_bf16 v[38:41], v[146:149], v[192:195], v[38:41]
	v_mfma_f32_16x16x32_bf16 v[38:41], v[150:153], v[196:199], v[38:41]
	v_mfma_f32_16x16x32_bf16 v[34:37], v[154:157], v[192:195], v[34:37]
	v_mfma_f32_16x16x32_bf16 v[34:37], v[158:161], v[196:199], v[34:37]
	v_mfma_f32_16x16x32_bf16 v[22:25], v[146:149], v[200:203], v[22:25]
	v_mfma_f32_16x16x32_bf16 v[22:25], v[150:153], v[204:207], v[22:25]
	v_mfma_f32_16x16x32_bf16 v[18:21], v[154:157], v[200:203], v[18:21]
	v_mfma_f32_16x16x32_bf16 v[18:21], v[158:161], v[204:207], v[18:21]
	v_mfma_f32_16x16x32_bf16 v[6:9], v[146:149], v[208:211], v[6:9]
	v_mfma_f32_16x16x32_bf16 v[6:9], v[150:153], v[212:215], v[6:9]
	v_mfma_f32_16x16x32_bf16 v[2:5], v[154:157], v[208:211], v[2:5]
	v_mfma_f32_16x16x32_bf16 v[2:5], v[158:161], v[212:215], v[2:5]
	s_setprio 2
	s_barrier
	v_mfma_f32_16x16x32_bf16 v[42:45], v[146:149], v[170:173], v[70:73]
	v_mfma_f32_16x16x32_bf16 v[42:45], v[150:153], v[188:191], v[42:45]
	v_mfma_f32_16x16x32_bf16 v[46:49], v[154:157], v[170:173], v[66:69]
	v_mfma_f32_16x16x32_bf16 v[46:49], v[158:161], v[188:191], v[46:49]
	s_setprio 0
	ds_read_b128 v[58:61], v184
	ds_read_b128 v[62:65], v184 offset:1024
	ds_read_b128 v[66:69], v184 offset:2048
	ds_read_b128 v[70:73], v184 offset:3072
	ds_read_b128 v[146:149], v185
	ds_read_b128 v[150:153], v185 offset:1024
	ds_read_b128 v[154:157], v185 offset:2048
	ds_read_b128 v[158:161], v185 offset:3072
	ds_read_b128 v[170:173], v183 offset:32768
	ds_read_b128 v[188:191], v183 offset:33792
	ds_read_b128 v[192:195], v183 offset:34816
	ds_read_b128 v[196:199], v183 offset:35840
	ds_read_b128 v[200:203], v183 offset:36864
	ds_read_b128 v[204:207], v183 offset:37888
	ds_read_b128 v[208:211], v183 offset:38912
	ds_read_b128 v[212:215], v183 offset:39936
	s_mov_b32 s82, m0
	s_mov_b32 m0, s48
	s_nop 0
	global_load_lds_dwordx4 v1, s[40:41]
	s_mov_b32 m0, s82
	s_nop 0
	s_mov_b32 s82, m0
	s_mov_b32 m0, s59
	s_nop 0
	global_load_lds_dwordx4 v177, s[40:41]
	s_mov_b32 m0, s82
	s_add_u32 s40, s40, 0x80000
	s_addc_u32 s41, s41, 0
	s_mov_b32 s82, m0
	s_mov_b32 m0, s62
	s_nop 0
	global_load_lds_dwordx4 v1, s[40:41]
	s_mov_b32 m0, s82
	s_nop 0
	s_mov_b32 s82, m0
	s_mov_b32 m0, s63
	s_nop 0
	global_load_lds_dwordx4 v177, s[40:41]
	s_mov_b32 m0, s82
	s_waitcnt vmcnt(8)
	s_waitcnt lgkmcnt(0)
	s_barrier
	s_setprio 1
	s_waitcnt lgkmcnt(7)
	v_mfma_f32_16x16x32_bf16 v[142:145], v[58:61], v[170:173], v[142:145]
	v_mfma_f32_16x16x32_bf16 v[142:145], v[62:65], v[188:191], v[142:145]
	s_waitcnt lgkmcnt(5)
	v_mfma_f32_16x16x32_bf16 v[138:141], v[66:69], v[170:173], v[138:141]
	v_mfma_f32_16x16x32_bf16 v[138:141], v[70:73], v[188:191], v[138:141]
	s_waitcnt lgkmcnt(3)
	v_mfma_f32_16x16x32_bf16 v[126:129], v[58:61], v[192:195], v[126:129]
	v_mfma_f32_16x16x32_bf16 v[126:129], v[62:65], v[196:199], v[126:129]
	s_waitcnt lgkmcnt(1)
	v_mfma_f32_16x16x32_bf16 v[122:125], v[66:69], v[192:195], v[122:125]
	v_mfma_f32_16x16x32_bf16 v[122:125], v[70:73], v[196:199], v[122:125]
	v_mfma_f32_16x16x32_bf16 v[110:113], v[58:61], v[200:203], v[110:113]
	v_mfma_f32_16x16x32_bf16 v[110:113], v[62:65], v[204:207], v[110:113]
	v_mfma_f32_16x16x32_bf16 v[106:109], v[66:69], v[200:203], v[106:109]
	v_mfma_f32_16x16x32_bf16 v[106:109], v[70:73], v[204:207], v[106:109]
	v_mfma_f32_16x16x32_bf16 v[94:97], v[58:61], v[208:211], v[94:97]
	v_mfma_f32_16x16x32_bf16 v[94:97], v[62:65], v[212:215], v[94:97]
	s_waitcnt lgkmcnt(0)
	v_mfma_f32_16x16x32_bf16 v[90:93], v[66:69], v[208:211], v[90:93]
	v_mfma_f32_16x16x32_bf16 v[90:93], v[70:73], v[212:215], v[90:93]
	s_setprio 0
	s_setprio 1
	v_mfma_f32_16x16x32_bf16 v[134:137], v[146:149], v[170:173], v[134:137]
	v_mfma_f32_16x16x32_bf16 v[134:137], v[150:153], v[188:191], v[134:137]
	v_mfma_f32_16x16x32_bf16 v[130:133], v[154:157], v[170:173], v[130:133]
	v_mfma_f32_16x16x32_bf16 v[130:133], v[158:161], v[188:191], v[130:133]
	v_mfma_f32_16x16x32_bf16 v[118:121], v[146:149], v[192:195], v[118:121]
	v_mfma_f32_16x16x32_bf16 v[118:121], v[150:153], v[196:199], v[118:121]
	v_mfma_f32_16x16x32_bf16 v[114:117], v[154:157], v[192:195], v[114:117]
	v_mfma_f32_16x16x32_bf16 v[114:117], v[158:161], v[196:199], v[114:117]
	v_mfma_f32_16x16x32_bf16 v[102:105], v[146:149], v[200:203], v[102:105]
	v_mfma_f32_16x16x32_bf16 v[102:105], v[150:153], v[204:207], v[102:105]
	v_mfma_f32_16x16x32_bf16 v[98:101], v[154:157], v[200:203], v[98:101]
	v_mfma_f32_16x16x32_bf16 v[98:101], v[158:161], v[204:207], v[98:101]
	s_setprio 2
	s_barrier
	v_mfma_f32_16x16x32_bf16 v[86:89], v[146:149], v[208:211], v[86:89]
	v_mfma_f32_16x16x32_bf16 v[86:89], v[150:153], v[212:215], v[86:89]
	v_mfma_f32_16x16x32_bf16 v[82:85], v[154:157], v[208:211], v[82:85]
	v_mfma_f32_16x16x32_bf16 v[82:85], v[158:161], v[212:215], v[82:85]
	s_setprio 0
	ds_read_b128 v[170:173], v183 offset:49152
	ds_read_b128 v[188:191], v183 offset:50176
	ds_read_b128 v[192:195], v183 offset:51200
	ds_read_b128 v[196:199], v183 offset:52224
	ds_read_b128 v[200:203], v183 offset:53248
	ds_read_b128 v[204:207], v183 offset:54272
	ds_read_b128 v[208:211], v183 offset:55296
	ds_read_b128 v[212:215], v183 offset:56320
	s_add_u32 s40, s36, 0x80
	s_addc_u32 s41, s37, 0
	s_mov_b32 s82, m0
	s_mov_b32 m0, s64
	s_nop 0
	global_load_lds_dwordx4 v176, s[40:41]
	s_mov_b32 m0, s82
	s_add_u32 s36, s36, 0x80080
	s_mov_b32 s82, m0
	s_mov_b32 m0, s65
	s_nop 0
	global_load_lds_dwordx4 v178, s[40:41]
	s_mov_b32 m0, s82
	s_addc_u32 s37, s37, 0
	s_mov_b32 s40, m0
	s_mov_b32 m0, s66
	s_nop 0
	global_load_lds_dwordx4 v176, s[36:37]
	s_mov_b32 m0, s40
	s_nop 0
	s_mov_b32 s40, m0
	s_mov_b32 m0, s67
	s_nop 0
	global_load_lds_dwordx4 v178, s[36:37]
	s_mov_b32 m0, s40
	s_waitcnt vmcnt(4)
	s_waitcnt lgkmcnt(0)
	s_barrier
	s_setprio 1
	s_waitcnt lgkmcnt(7)
	v_mfma_f32_16x16x32_bf16 v[78:81], v[58:61], v[170:173], v[78:81]
	v_mfma_f32_16x16x32_bf16 v[78:81], v[62:65], v[188:191], v[78:81]
	s_waitcnt lgkmcnt(5)
	v_mfma_f32_16x16x32_bf16 v[74:77], v[66:69], v[170:173], v[74:77]
	v_mfma_f32_16x16x32_bf16 v[74:77], v[70:73], v[188:191], v[74:77]
	s_waitcnt lgkmcnt(3)
	v_mfma_f32_16x16x32_bf16 v[54:57], v[58:61], v[192:195], v[54:57]
	v_mfma_f32_16x16x32_bf16 v[54:57], v[62:65], v[196:199], v[54:57]
	s_waitcnt lgkmcnt(1)
	v_mfma_f32_16x16x32_bf16 v[50:53], v[66:69], v[192:195], v[50:53]
	v_mfma_f32_16x16x32_bf16 v[50:53], v[70:73], v[196:199], v[50:53]
	v_mfma_f32_16x16x32_bf16 v[30:33], v[58:61], v[200:203], v[30:33]
	v_mfma_f32_16x16x32_bf16 v[30:33], v[62:65], v[204:207], v[30:33]
	v_mfma_f32_16x16x32_bf16 v[26:29], v[66:69], v[200:203], v[26:29]
	v_mfma_f32_16x16x32_bf16 v[26:29], v[70:73], v[204:207], v[26:29]
	v_mfma_f32_16x16x32_bf16 v[14:17], v[58:61], v[208:211], v[14:17]
	v_mfma_f32_16x16x32_bf16 v[14:17], v[62:65], v[212:215], v[14:17]
	s_waitcnt lgkmcnt(0)
	v_mfma_f32_16x16x32_bf16 v[10:13], v[66:69], v[208:211], v[10:13]
	v_mfma_f32_16x16x32_bf16 v[10:13], v[70:73], v[212:215], v[10:13]
	s_setprio 0
	s_setprio 1
	v_mfma_f32_16x16x32_bf16 v[42:45], v[146:149], v[170:173], v[42:45]
	v_mfma_f32_16x16x32_bf16 v[70:73], v[150:153], v[188:191], v[42:45]
	v_mfma_f32_16x16x32_bf16 v[42:45], v[154:157], v[170:173], v[46:49]
	v_mfma_f32_16x16x32_bf16 v[66:69], v[158:161], v[188:191], v[42:45]
	v_mfma_f32_16x16x32_bf16 v[38:41], v[146:149], v[192:195], v[38:41]
	v_mfma_f32_16x16x32_bf16 v[38:41], v[150:153], v[196:199], v[38:41]
	v_mfma_f32_16x16x32_bf16 v[34:37], v[154:157], v[192:195], v[34:37]
	v_mfma_f32_16x16x32_bf16 v[34:37], v[158:161], v[196:199], v[34:37]
	v_mfma_f32_16x16x32_bf16 v[22:25], v[146:149], v[200:203], v[22:25]
	v_mfma_f32_16x16x32_bf16 v[22:25], v[150:153], v[204:207], v[22:25]
	v_mfma_f32_16x16x32_bf16 v[18:21], v[154:157], v[200:203], v[18:21]
	v_mfma_f32_16x16x32_bf16 v[18:21], v[158:161], v[204:207], v[18:21]
	s_setprio 2
	s_barrier
	v_mfma_f32_16x16x32_bf16 v[6:9], v[146:149], v[208:211], v[6:9]
	v_mfma_f32_16x16x32_bf16 v[6:9], v[150:153], v[212:215], v[6:9]
	v_mfma_f32_16x16x32_bf16 v[2:5], v[154:157], v[208:211], v[2:5]
	v_mfma_f32_16x16x32_bf16 v[2:5], v[158:161], v[212:215], v[2:5]
	s_setprio 0
	s_add_i32 s81, s81, 2
	s_add_u32 s77, s77, 0x100
	s_addc_u32 s78, s78, 0
	s_add_u32 s34, s34, 0x100
	s_addc_u32 s35, s35, 0
	s_add_u32 s79, s79, 0x100
	s_addc_u32 s80, s80, 0
	s_cmp_gt_u32 s81, 29
	s_cbranch_scc0 .LBB0_2146
	s_and_b64 vcc, exec, s[14:15]
	s_cbranch_vccz .LBB0_2149
	s_barrier

.LBB0_2409:
	s_ashr_i32 s17, s16, 31
	s_lshl_b64 s[18:19], s[16:17], 20
	s_add_u32 s18, s33, s18
	s_addc_u32 s19, s34, s19
	s_and_b64 s[20:21], s[2:3], exec
	s_cselect_b32 s17, s19, s27
	s_cselect_b32 s71, s18, s26
	s_ashr_i32 s15, s14, 31
	s_lshl_b64 s[20:21], s[14:15], 20
	s_add_u32 s20, s35, s20
	s_addc_u32 s21, s36, s21
	s_and_b64 s[28:29], s[2:3], exec
	s_cselect_b32 s15, s21, s25
	s_cselect_b32 s73, s20, s24
	s_add_u32 s74, s24, 0x100
	s_addc_u32 s75, s25, 0
	s_add_u32 s24, s26, 0x80080
	s_addc_u32 s25, s27, 0
	s_add_u32 s76, s26, 0x100
	s_addc_u32 s77, s27, 0
	s_mov_b32 s78, -2
	s_waitcnt vmcnt(25)
	s_waitcnt vmcnt(24)
	s_waitcnt vmcnt(4)
	s_waitcnt vmcnt(2)
	s_waitcnt vmcnt(1)
	s_waitcnt vmcnt(0)
	ds_read_b128 v[130:133], v181
	ds_read_b128 v[134:137], v181 offset:1024
	ds_read_b128 v[138:141], v181 offset:2048
	ds_read_b128 v[142:145], v181 offset:3072
	ds_read_b128 v[146:149], v182
	ds_read_b128 v[150:153], v182 offset:1024
	ds_read_b128 v[154:157], v182 offset:2048
	ds_read_b128 v[158:161], v182 offset:3072
	s_cmp_eq_u32 s78, 28
	s_cselect_b32 s27, s15, s75
	s_cselect_b32 s26, s73, s74
	s_cselect_b32 s29, s17, s77
	s_cselect_b32 s28, s71, s76
	ds_read_b128 v[166:169], v183
	ds_read_b128 v[170:173], v183 offset:1024
	ds_read_b128 v[186:189], v183 offset:2048
	ds_read_b128 v[190:193], v183 offset:3072
	ds_read_b128 v[194:197], v183 offset:4096
	ds_read_b128 v[198:201], v183 offset:5120
	ds_read_b128 v[202:205], v183 offset:6144
	ds_read_b128 v[206:209], v183 offset:7168
	s_add_u32 s80, s24, 0xfff80000
	s_addc_u32 s81, s25, -1
	s_mov_b32 s79, m0
	s_mov_b32 m0, s64
	s_nop 0
	global_load_lds_dwordx4 v1, s[80:81]
	s_mov_b32 m0, s79
	s_nop 0
	s_mov_b32 s79, m0
	s_mov_b32 m0, s66
	s_nop 0
	global_load_lds_dwordx4 v177, s[80:81]
	s_mov_b32 m0, s79
	s_nop 0
	s_mov_b32 s79, m0
	s_mov_b32 m0, s65
	s_nop 0
	global_load_lds_dwordx4 v1, s[24:25]
	s_mov_b32 m0, s79
	s_nop 0
	s_mov_b32 s79, m0
	s_mov_b32 m0, s67
	s_nop 0
	global_load_lds_dwordx4 v177, s[24:25]
	s_mov_b32 m0, s79
	s_waitcnt vmcnt(8)
	s_waitcnt lgkmcnt(0)
	s_barrier
	s_setprio 1
	s_waitcnt lgkmcnt(7)
	v_mfma_f32_16x16x32_bf16 v[126:129], v[130:133], v[166:169], 0
	v_mfma_f32_16x16x32_bf16 v[126:129], v[134:137], v[170:173], v[126:129]
	s_waitcnt lgkmcnt(5)
	v_mfma_f32_16x16x32_bf16 v[122:125], v[138:141], v[166:169], 0
	v_mfma_f32_16x16x32_bf16 v[122:125], v[142:145], v[170:173], v[122:125]
	s_waitcnt lgkmcnt(3)
	v_mfma_f32_16x16x32_bf16 v[114:117], v[138:141], v[186:189], 0
	v_mfma_f32_16x16x32_bf16 v[114:117], v[142:145], v[190:193], v[114:117]
	s_waitcnt lgkmcnt(1)
	v_mfma_f32_16x16x32_bf16 v[118:121], v[130:133], v[186:189], 0
	v_mfma_f32_16x16x32_bf16 v[118:121], v[134:137], v[190:193], v[118:121]
	v_mfma_f32_16x16x32_bf16 v[94:97], v[130:133], v[194:197], 0
	v_mfma_f32_16x16x32_bf16 v[94:97], v[134:137], v[198:201], v[94:97]
	v_mfma_f32_16x16x32_bf16 v[90:93], v[138:141], v[194:197], 0
	v_mfma_f32_16x16x32_bf16 v[90:93], v[142:145], v[198:201], v[90:93]
	v_mfma_f32_16x16x32_bf16 v[78:81], v[138:141], v[202:205], 0
	v_mfma_f32_16x16x32_bf16 v[78:81], v[142:145], v[206:209], v[78:81]
	s_waitcnt lgkmcnt(0)
	v_mfma_f32_16x16x32_bf16 v[86:89], v[130:133], v[202:205], 0
	v_mfma_f32_16x16x32_bf16 v[86:89], v[134:137], v[206:209], v[86:89]
	s_setprio 0
	s_setprio 1
	v_mfma_f32_16x16x32_bf16 v[110:113], v[146:149], v[166:169], 0
	v_mfma_f32_16x16x32_bf16 v[110:113], v[150:153], v[170:173], v[110:113]
	v_mfma_f32_16x16x32_bf16 v[106:109], v[154:157], v[166:169], 0
	v_mfma_f32_16x16x32_bf16 v[106:109], v[158:161], v[170:173], v[106:109]
	v_mfma_f32_16x16x32_bf16 v[98:101], v[154:157], v[186:189], 0
	v_mfma_f32_16x16x32_bf16 v[98:101], v[158:161], v[190:193], v[98:101]
	v_mfma_f32_16x16x32_bf16 v[102:105], v[146:149], v[186:189], 0
	v_mfma_f32_16x16x32_bf16 v[102:105], v[150:153], v[190:193], v[102:105]
	v_mfma_f32_16x16x32_bf16 v[82:85], v[146:149], v[194:197], 0
	v_mfma_f32_16x16x32_bf16 v[82:85], v[150:153], v[198:201], v[82:85]
	v_mfma_f32_16x16x32_bf16 v[74:77], v[154:157], v[194:197], 0
	v_mfma_f32_16x16x32_bf16 v[74:77], v[158:161], v[198:201], v[74:77]
	s_setprio 2
	s_barrier
	v_mfma_f32_16x16x32_bf16 v[66:69], v[154:157], v[202:205], 0
	v_mfma_f32_16x16x32_bf16 v[66:69], v[158:161], v[206:209], v[66:69]
	v_mfma_f32_16x16x32_bf16 v[70:73], v[146:149], v[202:205], 0
	v_mfma_f32_16x16x32_bf16 v[70:73], v[150:153], v[206:209], v[70:73]
	s_setprio 0
	ds_read_b128 v[166:169], v183 offset:16384
	ds_read_b128 v[170:173], v183 offset:17408
	ds_read_b128 v[186:189], v183 offset:18432
	ds_read_b128 v[190:193], v183 offset:19456
	ds_read_b128 v[194:197], v183 offset:20480
	ds_read_b128 v[198:201], v183 offset:21504
	ds_read_b128 v[202:205], v183 offset:22528
	ds_read_b128 v[206:209], v183 offset:23552
	s_mov_b32 s79, m0
	s_mov_b32 m0, s41
	s_nop 0
	global_load_lds_dwordx4 v176, s[26:27]
	s_mov_b32 m0, s79
	s_add_u32 s80, s26, 0x80000
	s_mov_b32 s79, m0
	s_mov_b32 m0, s42
	s_nop 0
	global_load_lds_dwordx4 v178, s[26:27]
	s_mov_b32 m0, s79
	s_addc_u32 s81, s27, 0
	s_mov_b32 s79, m0
	s_mov_b32 m0, s43
	s_nop 0
	global_load_lds_dwordx4 v176, s[80:81]
	s_mov_b32 m0, s79
	s_nop 0
	s_mov_b32 s79, m0
	s_mov_b32 m0, s46
	s_nop 0
	global_load_lds_dwordx4 v178, s[80:81]
	s_mov_b32 m0, s79
	s_waitcnt vmcnt(4)
	s_waitcnt lgkmcnt(0)
	s_barrier
	s_setprio 1
	s_waitcnt lgkmcnt(7)
	v_mfma_f32_16x16x32_bf16 v[62:65], v[130:133], v[166:169], 0
	v_mfma_f32_16x16x32_bf16 v[62:65], v[134:137], v[170:173], v[62:65]
	s_waitcnt lgkmcnt(5)
	v_mfma_f32_16x16x32_bf16 v[58:61], v[138:141], v[166:169], 0
	v_mfma_f32_16x16x32_bf16 v[58:61], v[142:145], v[170:173], v[58:61]
	s_waitcnt lgkmcnt(3)
	v_mfma_f32_16x16x32_bf16 v[42:45], v[138:141], v[186:189], 0
	v_mfma_f32_16x16x32_bf16 v[42:45], v[142:145], v[190:193], v[42:45]
	s_waitcnt lgkmcnt(1)
	v_mfma_f32_16x16x32_bf16 v[46:49], v[130:133], v[186:189], 0
	v_mfma_f32_16x16x32_bf16 v[46:49], v[134:137], v[190:193], v[46:49]
	v_mfma_f32_16x16x32_bf16 v[30:33], v[130:133], v[194:197], 0
	v_mfma_f32_16x16x32_bf16 v[30:33], v[134:137], v[198:201], v[30:33]
	v_mfma_f32_16x16x32_bf16 v[26:29], v[138:141], v[194:197], 0
	v_mfma_f32_16x16x32_bf16 v[26:29], v[142:145], v[198:201], v[26:29]
	v_mfma_f32_16x16x32_bf16 v[10:13], v[138:141], v[202:205], 0
	v_mfma_f32_16x16x32_bf16 v[10:13], v[142:145], v[206:209], v[10:13]
	s_waitcnt lgkmcnt(0)
	v_mfma_f32_16x16x32_bf16 v[14:17], v[130:133], v[202:205], 0
	v_mfma_f32_16x16x32_bf16 v[14:17], v[134:137], v[206:209], v[14:17]
	s_setprio 0
	s_setprio 1
	v_mfma_f32_16x16x32_bf16 v[54:57], v[146:149], v[166:169], 0
	v_mfma_f32_16x16x32_bf16 v[54:57], v[150:153], v[170:173], v[54:57]
	v_mfma_f32_16x16x32_bf16 v[50:53], v[154:157], v[166:169], 0
	v_mfma_f32_16x16x32_bf16 v[50:53], v[158:161], v[170:173], v[50:53]
	v_mfma_f32_16x16x32_bf16 v[34:37], v[154:157], v[186:189], 0
	v_mfma_f32_16x16x32_bf16 v[34:37], v[158:161], v[190:193], v[34:37]
	v_mfma_f32_16x16x32_bf16 v[38:41], v[146:149], v[186:189], 0
	v_mfma_f32_16x16x32_bf16 v[38:41], v[150:153], v[190:193], v[38:41]
	v_mfma_f32_16x16x32_bf16 v[22:25], v[146:149], v[194:197], 0
	v_mfma_f32_16x16x32_bf16 v[22:25], v[150:153], v[198:201], v[22:25]
	v_mfma_f32_16x16x32_bf16 v[18:21], v[154:157], v[194:197], 0
	v_mfma_f32_16x16x32_bf16 v[18:21], v[158:161], v[198:201], v[18:21]
	s_setprio 2
	s_barrier
	v_mfma_f32_16x16x32_bf16 v[2:5], v[154:157], v[202:205], 0
	v_mfma_f32_16x16x32_bf16 v[2:5], v[158:161], v[206:209], v[2:5]
	v_mfma_f32_16x16x32_bf16 v[6:9], v[146:149], v[202:205], 0
	v_mfma_f32_16x16x32_bf16 v[6:9], v[150:153], v[206:209], v[6:9]
	s_setprio 0
	ds_read_b128 v[130:133], v184
	ds_read_b128 v[134:137], v184 offset:1024
	ds_read_b128 v[138:141], v184 offset:2048
	ds_read_b128 v[142:145], v184 offset:3072
	ds_read_b128 v[146:149], v185
	ds_read_b128 v[150:153], v185 offset:1024
	ds_read_b128 v[154:157], v185 offset:2048
	ds_read_b128 v[158:161], v185 offset:3072
	ds_read_b128 v[166:169], v183 offset:32768
	ds_read_b128 v[170:173], v183 offset:33792
	ds_read_b128 v[186:189], v183 offset:34816
	ds_read_b128 v[190:193], v183 offset:35840
	ds_read_b128 v[194:197], v183 offset:36864
	ds_read_b128 v[198:201], v183 offset:37888
	ds_read_b128 v[202:205], v183 offset:38912
	ds_read_b128 v[206:209], v183 offset:39936
	s_mov_b32 s79, m0
	s_mov_b32 m0, s40
	s_nop 0
	global_load_lds_dwordx4 v1, s[28:29]
	s_mov_b32 m0, s79
	s_nop 0
	s_mov_b32 s79, m0
	s_mov_b32 m0, s47
	s_nop 0
	global_load_lds_dwordx4 v177, s[28:29]
	s_mov_b32 m0, s79
	s_add_u32 s28, s28, 0x80000
	s_addc_u32 s29, s29, 0
	s_mov_b32 s79, m0
	s_mov_b32 m0, s48
	s_nop 0
	global_load_lds_dwordx4 v1, s[28:29]
	s_mov_b32 m0, s79
	s_nop 0
	s_mov_b32 s79, m0
	s_mov_b32 m0, s49
	s_nop 0
	global_load_lds_dwordx4 v177, s[28:29]
	s_mov_b32 m0, s79
	s_waitcnt vmcnt(8)
	s_waitcnt lgkmcnt(0)
	s_barrier
	s_setprio 1
	s_waitcnt lgkmcnt(7)
	v_mfma_f32_16x16x32_bf16 v[126:129], v[130:133], v[166:169], v[126:129]
	v_mfma_f32_16x16x32_bf16 v[126:129], v[134:137], v[170:173], v[126:129]
	s_waitcnt lgkmcnt(5)
	v_mfma_f32_16x16x32_bf16 v[122:125], v[138:141], v[166:169], v[122:125]
	v_mfma_f32_16x16x32_bf16 v[122:125], v[142:145], v[170:173], v[122:125]
	s_waitcnt lgkmcnt(3)
	v_mfma_f32_16x16x32_bf16 v[114:117], v[138:141], v[186:189], v[114:117]
	v_mfma_f32_16x16x32_bf16 v[114:117], v[142:145], v[190:193], v[114:117]
	s_waitcnt lgkmcnt(1)
	v_mfma_f32_16x16x32_bf16 v[118:121], v[130:133], v[186:189], v[118:121]
	v_mfma_f32_16x16x32_bf16 v[118:121], v[134:137], v[190:193], v[118:121]
	v_mfma_f32_16x16x32_bf16 v[94:97], v[130:133], v[194:197], v[94:97]
	v_mfma_f32_16x16x32_bf16 v[94:97], v[134:137], v[198:201], v[94:97]
	v_mfma_f32_16x16x32_bf16 v[90:93], v[138:141], v[194:197], v[90:93]
	v_mfma_f32_16x16x32_bf16 v[90:93], v[142:145], v[198:201], v[90:93]
	v_mfma_f32_16x16x32_bf16 v[78:81], v[138:141], v[202:205], v[78:81]
	v_mfma_f32_16x16x32_bf16 v[78:81], v[142:145], v[206:209], v[78:81]
	s_waitcnt lgkmcnt(0)
	v_mfma_f32_16x16x32_bf16 v[86:89], v[130:133], v[202:205], v[86:89]
	v_mfma_f32_16x16x32_bf16 v[86:89], v[134:137], v[206:209], v[86:89]
	s_setprio 0
	s_setprio 1
	v_mfma_f32_16x16x32_bf16 v[110:113], v[146:149], v[166:169], v[110:113]
	v_mfma_f32_16x16x32_bf16 v[110:113], v[150:153], v[170:173], v[110:113]
	v_mfma_f32_16x16x32_bf16 v[106:109], v[154:157], v[166:169], v[106:109]
	v_mfma_f32_16x16x32_bf16 v[106:109], v[158:161], v[170:173], v[106:109]
	v_mfma_f32_16x16x32_bf16 v[98:101], v[154:157], v[186:189], v[98:101]
	v_mfma_f32_16x16x32_bf16 v[98:101], v[158:161], v[190:193], v[98:101]
	v_mfma_f32_16x16x32_bf16 v[102:105], v[146:149], v[186:189], v[102:105]
	v_mfma_f32_16x16x32_bf16 v[102:105], v[150:153], v[190:193], v[102:105]
	v_mfma_f32_16x16x32_bf16 v[82:85], v[146:149], v[194:197], v[82:85]
	v_mfma_f32_16x16x32_bf16 v[82:85], v[150:153], v[198:201], v[82:85]
	v_mfma_f32_16x16x32_bf16 v[74:77], v[154:157], v[194:197], v[74:77]
	v_mfma_f32_16x16x32_bf16 v[74:77], v[158:161], v[198:201], v[74:77]
	s_setprio 2
	s_barrier
	v_mfma_f32_16x16x32_bf16 v[66:69], v[154:157], v[202:205], v[66:69]
	v_mfma_f32_16x16x32_bf16 v[66:69], v[158:161], v[206:209], v[66:69]
	v_mfma_f32_16x16x32_bf16 v[70:73], v[146:149], v[202:205], v[70:73]
	v_mfma_f32_16x16x32_bf16 v[70:73], v[150:153], v[206:209], v[70:73]
	s_setprio 0
	ds_read_b128 v[166:169], v183 offset:49152
	ds_read_b128 v[170:173], v183 offset:50176
	ds_read_b128 v[186:189], v183 offset:51200
	ds_read_b128 v[190:193], v183 offset:52224
	ds_read_b128 v[194:197], v183 offset:53248
	ds_read_b128 v[198:201], v183 offset:54272
	ds_read_b128 v[202:205], v183 offset:55296
	ds_read_b128 v[206:209], v183 offset:56320
	s_add_u32 s28, s26, 0x80
	s_addc_u32 s29, s27, 0
	s_mov_b32 s79, m0
	s_mov_b32 m0, s56
	s_nop 0
	global_load_lds_dwordx4 v176, s[28:29]
	s_mov_b32 m0, s79
	s_add_u32 s26, s26, 0x80080
	s_mov_b32 s79, m0
	s_mov_b32 m0, s57
	s_nop 0
	global_load_lds_dwordx4 v178, s[28:29]
	s_mov_b32 m0, s79
	s_addc_u32 s27, s27, 0
	s_mov_b32 s28, m0
	s_mov_b32 m0, s58
	s_nop 0
	global_load_lds_dwordx4 v176, s[26:27]
	s_mov_b32 m0, s28
	s_nop 0
	s_mov_b32 s28, m0
	s_mov_b32 m0, s59
	s_nop 0
	global_load_lds_dwordx4 v178, s[26:27]
	s_mov_b32 m0, s28
	s_waitcnt vmcnt(4)
	s_waitcnt lgkmcnt(0)
	s_barrier
	s_setprio 1
	s_waitcnt lgkmcnt(7)
	v_mfma_f32_16x16x32_bf16 v[62:65], v[130:133], v[166:169], v[62:65]
	v_mfma_f32_16x16x32_bf16 v[62:65], v[134:137], v[170:173], v[62:65]
	s_waitcnt lgkmcnt(5)
	v_mfma_f32_16x16x32_bf16 v[58:61], v[138:141], v[166:169], v[58:61]
	v_mfma_f32_16x16x32_bf16 v[58:61], v[142:145], v[170:173], v[58:61]
	s_waitcnt lgkmcnt(3)
	v_mfma_f32_16x16x32_bf16 v[42:45], v[138:141], v[186:189], v[42:45]
	v_mfma_f32_16x16x32_bf16 v[42:45], v[142:145], v[190:193], v[42:45]
	s_waitcnt lgkmcnt(1)
	v_mfma_f32_16x16x32_bf16 v[46:49], v[130:133], v[186:189], v[46:49]
	v_mfma_f32_16x16x32_bf16 v[46:49], v[134:137], v[190:193], v[46:49]
	v_mfma_f32_16x16x32_bf16 v[30:33], v[130:133], v[194:197], v[30:33]
	v_mfma_f32_16x16x32_bf16 v[30:33], v[134:137], v[198:201], v[30:33]
	v_mfma_f32_16x16x32_bf16 v[26:29], v[138:141], v[194:197], v[26:29]
	v_mfma_f32_16x16x32_bf16 v[26:29], v[142:145], v[198:201], v[26:29]
	v_mfma_f32_16x16x32_bf16 v[10:13], v[138:141], v[202:205], v[10:13]
	v_mfma_f32_16x16x32_bf16 v[10:13], v[142:145], v[206:209], v[10:13]
	s_waitcnt lgkmcnt(0)
	v_mfma_f32_16x16x32_bf16 v[14:17], v[130:133], v[202:205], v[14:17]
	v_mfma_f32_16x16x32_bf16 v[14:17], v[134:137], v[206:209], v[14:17]
	s_setprio 0
	s_setprio 1
	v_mfma_f32_16x16x32_bf16 v[54:57], v[146:149], v[166:169], v[54:57]
	v_mfma_f32_16x16x32_bf16 v[54:57], v[150:153], v[170:173], v[54:57]
	v_mfma_f32_16x16x32_bf16 v[50:53], v[154:157], v[166:169], v[50:53]
	v_mfma_f32_16x16x32_bf16 v[50:53], v[158:161], v[170:173], v[50:53]
	v_mfma_f32_16x16x32_bf16 v[34:37], v[154:157], v[186:189], v[34:37]
	v_mfma_f32_16x16x32_bf16 v[34:37], v[158:161], v[190:193], v[34:37]
	v_mfma_f32_16x16x32_bf16 v[38:41], v[146:149], v[186:189], v[38:41]
	v_mfma_f32_16x16x32_bf16 v[38:41], v[150:153], v[190:193], v[38:41]
	v_mfma_f32_16x16x32_bf16 v[22:25], v[146:149], v[194:197], v[22:25]
	v_mfma_f32_16x16x32_bf16 v[22:25], v[150:153], v[198:201], v[22:25]
	v_mfma_f32_16x16x32_bf16 v[18:21], v[154:157], v[194:197], v[18:21]
	v_mfma_f32_16x16x32_bf16 v[18:21], v[158:161], v[198:201], v[18:21]
	s_setprio 2
	s_barrier
	v_mfma_f32_16x16x32_bf16 v[2:5], v[154:157], v[202:205], v[2:5]
	v_mfma_f32_16x16x32_bf16 v[2:5], v[158:161], v[206:209], v[2:5]
	v_mfma_f32_16x16x32_bf16 v[6:9], v[146:149], v[202:205], v[6:9]
	v_mfma_f32_16x16x32_bf16 v[6:9], v[150:153], v[206:209], v[6:9]
	s_setprio 0
	s_add_i32 s78, s78, 2
	s_add_u32 s74, s74, 0x100
	s_addc_u32 s75, s75, 0
	s_add_u32 s24, s24, 0x100
	s_addc_u32 s25, s25, 0
	s_add_u32 s76, s76, 0x100
	s_addc_u32 s77, s77, 0
	s_cmp_gt_u32 s78, 29
	.p2align 6
.LBB0_2410:
	ds_read_b128 v[130:133], v181
	ds_read_b128 v[134:137], v181 offset:1024
	ds_read_b128 v[138:141], v181 offset:2048
	ds_read_b128 v[142:145], v181 offset:3072
	ds_read_b128 v[146:149], v182
	ds_read_b128 v[150:153], v182 offset:1024
	ds_read_b128 v[154:157], v182 offset:2048
	ds_read_b128 v[158:161], v182 offset:3072
	s_cmp_eq_u32 s78, 28
	s_cselect_b32 s27, s15, s75
	s_cselect_b32 s26, s73, s74
	s_cselect_b32 s29, s17, s77
	s_cselect_b32 s28, s71, s76
	ds_read_b128 v[166:169], v183
	ds_read_b128 v[170:173], v183 offset:1024
	ds_read_b128 v[186:189], v183 offset:2048
	ds_read_b128 v[190:193], v183 offset:3072
	ds_read_b128 v[194:197], v183 offset:4096
	ds_read_b128 v[198:201], v183 offset:5120
	ds_read_b128 v[202:205], v183 offset:6144
	ds_read_b128 v[206:209], v183 offset:7168
	s_add_u32 s80, s24, 0xfff80000
	s_addc_u32 s81, s25, -1
	s_mov_b32 s79, m0
	s_mov_b32 m0, s64
	s_nop 0
	global_load_lds_dwordx4 v1, s[80:81]
	s_mov_b32 m0, s79
	s_nop 0
	s_mov_b32 s79, m0
	s_mov_b32 m0, s66
	s_nop 0
	global_load_lds_dwordx4 v177, s[80:81]
	s_mov_b32 m0, s79
	s_nop 0
	s_mov_b32 s79, m0
	s_mov_b32 m0, s65
	s_nop 0
	global_load_lds_dwordx4 v1, s[24:25]
	s_mov_b32 m0, s79
	s_nop 0
	s_mov_b32 s79, m0
	s_mov_b32 m0, s67
	s_nop 0
	global_load_lds_dwordx4 v177, s[24:25]
	s_mov_b32 m0, s79
	s_waitcnt vmcnt(8)
	s_waitcnt lgkmcnt(0)
	s_barrier
	s_setprio 1
	s_waitcnt lgkmcnt(7)
	v_mfma_f32_16x16x32_bf16 v[126:129], v[130:133], v[166:169], v[126:129]
	v_mfma_f32_16x16x32_bf16 v[126:129], v[134:137], v[170:173], v[126:129]
	s_waitcnt lgkmcnt(5)
	v_mfma_f32_16x16x32_bf16 v[122:125], v[138:141], v[166:169], v[122:125]
	v_mfma_f32_16x16x32_bf16 v[122:125], v[142:145], v[170:173], v[122:125]
	s_waitcnt lgkmcnt(3)
	v_mfma_f32_16x16x32_bf16 v[114:117], v[138:141], v[186:189], v[114:117]
	v_mfma_f32_16x16x32_bf16 v[114:117], v[142:145], v[190:193], v[114:117]
	s_waitcnt lgkmcnt(1)
	v_mfma_f32_16x16x32_bf16 v[118:121], v[130:133], v[186:189], v[118:121]
	v_mfma_f32_16x16x32_bf16 v[118:121], v[134:137], v[190:193], v[118:121]
	v_mfma_f32_16x16x32_bf16 v[94:97], v[130:133], v[194:197], v[94:97]
	v_mfma_f32_16x16x32_bf16 v[94:97], v[134:137], v[198:201], v[94:97]
	v_mfma_f32_16x16x32_bf16 v[90:93], v[138:141], v[194:197], v[90:93]
	v_mfma_f32_16x16x32_bf16 v[90:93], v[142:145], v[198:201], v[90:93]
	v_mfma_f32_16x16x32_bf16 v[78:81], v[138:141], v[202:205], v[78:81]
	v_mfma_f32_16x16x32_bf16 v[78:81], v[142:145], v[206:209], v[78:81]
	s_waitcnt lgkmcnt(0)
	v_mfma_f32_16x16x32_bf16 v[86:89], v[130:133], v[202:205], v[86:89]
	v_mfma_f32_16x16x32_bf16 v[86:89], v[134:137], v[206:209], v[86:89]
	s_setprio 0
	s_setprio 1
	v_mfma_f32_16x16x32_bf16 v[110:113], v[146:149], v[166:169], v[110:113]
	v_mfma_f32_16x16x32_bf16 v[110:113], v[150:153], v[170:173], v[110:113]
	v_mfma_f32_16x16x32_bf16 v[106:109], v[154:157], v[166:169], v[106:109]
	v_mfma_f32_16x16x32_bf16 v[106:109], v[158:161], v[170:173], v[106:109]
	v_mfma_f32_16x16x32_bf16 v[98:101], v[154:157], v[186:189], v[98:101]
	v_mfma_f32_16x16x32_bf16 v[98:101], v[158:161], v[190:193], v[98:101]
	v_mfma_f32_16x16x32_bf16 v[102:105], v[146:149], v[186:189], v[102:105]
	v_mfma_f32_16x16x32_bf16 v[102:105], v[150:153], v[190:193], v[102:105]
	v_mfma_f32_16x16x32_bf16 v[82:85], v[146:149], v[194:197], v[82:85]
	v_mfma_f32_16x16x32_bf16 v[82:85], v[150:153], v[198:201], v[82:85]
	v_mfma_f32_16x16x32_bf16 v[74:77], v[154:157], v[194:197], v[74:77]
	v_mfma_f32_16x16x32_bf16 v[74:77], v[158:161], v[198:201], v[74:77]
	s_setprio 2
	s_barrier
	v_mfma_f32_16x16x32_bf16 v[66:69], v[154:157], v[202:205], v[66:69]
	v_mfma_f32_16x16x32_bf16 v[66:69], v[158:161], v[206:209], v[66:69]
	v_mfma_f32_16x16x32_bf16 v[70:73], v[146:149], v[202:205], v[70:73]
	v_mfma_f32_16x16x32_bf16 v[70:73], v[150:153], v[206:209], v[70:73]
	s_setprio 0
	ds_read_b128 v[166:169], v183 offset:16384
	ds_read_b128 v[170:173], v183 offset:17408
	ds_read_b128 v[186:189], v183 offset:18432
	ds_read_b128 v[190:193], v183 offset:19456
	ds_read_b128 v[194:197], v183 offset:20480
	ds_read_b128 v[198:201], v183 offset:21504
	ds_read_b128 v[202:205], v183 offset:22528
	ds_read_b128 v[206:209], v183 offset:23552
	s_mov_b32 s79, m0
	s_mov_b32 m0, s41
	s_nop 0
	global_load_lds_dwordx4 v176, s[26:27]
	s_mov_b32 m0, s79
	s_add_u32 s80, s26, 0x80000
	s_mov_b32 s79, m0
	s_mov_b32 m0, s42
	s_nop 0
	global_load_lds_dwordx4 v178, s[26:27]
	s_mov_b32 m0, s79
	s_addc_u32 s81, s27, 0
	s_mov_b32 s79, m0
	s_mov_b32 m0, s43
	s_nop 0
	global_load_lds_dwordx4 v176, s[80:81]
	s_mov_b32 m0, s79
	s_nop 0
	s_mov_b32 s79, m0
	s_mov_b32 m0, s46
	s_nop 0
	global_load_lds_dwordx4 v178, s[80:81]
	s_mov_b32 m0, s79
	s_waitcnt vmcnt(4)
	s_waitcnt lgkmcnt(0)
	s_barrier
	s_setprio 1
	s_waitcnt lgkmcnt(7)
	v_mfma_f32_16x16x32_bf16 v[62:65], v[130:133], v[166:169], v[62:65]
	v_mfma_f32_16x16x32_bf16 v[62:65], v[134:137], v[170:173], v[62:65]
	s_waitcnt lgkmcnt(5)
	v_mfma_f32_16x16x32_bf16 v[58:61], v[138:141], v[166:169], v[58:61]
	v_mfma_f32_16x16x32_bf16 v[58:61], v[142:145], v[170:173], v[58:61]
	s_waitcnt lgkmcnt(3)
	v_mfma_f32_16x16x32_bf16 v[42:45], v[138:141], v[186:189], v[42:45]
	v_mfma_f32_16x16x32_bf16 v[42:45], v[142:145], v[190:193], v[42:45]
	s_waitcnt lgkmcnt(1)
	v_mfma_f32_16x16x32_bf16 v[46:49], v[130:133], v[186:189], v[46:49]
	v_mfma_f32_16x16x32_bf16 v[46:49], v[134:137], v[190:193], v[46:49]
	v_mfma_f32_16x16x32_bf16 v[30:33], v[130:133], v[194:197], v[30:33]
	v_mfma_f32_16x16x32_bf16 v[30:33], v[134:137], v[198:201], v[30:33]
	v_mfma_f32_16x16x32_bf16 v[26:29], v[138:141], v[194:197], v[26:29]
	v_mfma_f32_16x16x32_bf16 v[26:29], v[142:145], v[198:201], v[26:29]
	v_mfma_f32_16x16x32_bf16 v[10:13], v[138:141], v[202:205], v[10:13]
	v_mfma_f32_16x16x32_bf16 v[10:13], v[142:145], v[206:209], v[10:13]
	s_waitcnt lgkmcnt(0)
	v_mfma_f32_16x16x32_bf16 v[14:17], v[130:133], v[202:205], v[14:17]
	v_mfma_f32_16x16x32_bf16 v[14:17], v[134:137], v[206:209], v[14:17]
	s_setprio 0
	s_setprio 1
	v_mfma_f32_16x16x32_bf16 v[54:57], v[146:149], v[166:169], v[54:57]
	v_mfma_f32_16x16x32_bf16 v[54:57], v[150:153], v[170:173], v[54:57]
	v_mfma_f32_16x16x32_bf16 v[50:53], v[154:157], v[166:169], v[50:53]
	v_mfma_f32_16x16x32_bf16 v[50:53], v[158:161], v[170:173], v[50:53]
	v_mfma_f32_16x16x32_bf16 v[34:37], v[154:157], v[186:189], v[34:37]
	v_mfma_f32_16x16x32_bf16 v[34:37], v[158:161], v[190:193], v[34:37]
	v_mfma_f32_16x16x32_bf16 v[38:41], v[146:149], v[186:189], v[38:41]
	v_mfma_f32_16x16x32_bf16 v[38:41], v[150:153], v[190:193], v[38:41]
	v_mfma_f32_16x16x32_bf16 v[22:25], v[146:149], v[194:197], v[22:25]
	v_mfma_f32_16x16x32_bf16 v[22:25], v[150:153], v[198:201], v[22:25]
	v_mfma_f32_16x16x32_bf16 v[18:21], v[154:157], v[194:197], v[18:21]
	v_mfma_f32_16x16x32_bf16 v[18:21], v[158:161], v[198:201], v[18:21]
	s_setprio 2
	s_barrier
	v_mfma_f32_16x16x32_bf16 v[2:5], v[154:157], v[202:205], v[2:5]
	v_mfma_f32_16x16x32_bf16 v[2:5], v[158:161], v[206:209], v[2:5]
	v_mfma_f32_16x16x32_bf16 v[6:9], v[146:149], v[202:205], v[6:9]
	v_mfma_f32_16x16x32_bf16 v[6:9], v[150:153], v[206:209], v[6:9]
	s_setprio 0
	ds_read_b128 v[130:133], v184
	ds_read_b128 v[134:137], v184 offset:1024
	ds_read_b128 v[138:141], v184 offset:2048
	ds_read_b128 v[142:145], v184 offset:3072
	ds_read_b128 v[146:149], v185
	ds_read_b128 v[150:153], v185 offset:1024
	ds_read_b128 v[154:157], v185 offset:2048
	ds_read_b128 v[158:161], v185 offset:3072
	ds_read_b128 v[166:169], v183 offset:32768
	ds_read_b128 v[170:173], v183 offset:33792
	ds_read_b128 v[186:189], v183 offset:34816
	ds_read_b128 v[190:193], v183 offset:35840
	ds_read_b128 v[194:197], v183 offset:36864
	ds_read_b128 v[198:201], v183 offset:37888
	ds_read_b128 v[202:205], v183 offset:38912
	ds_read_b128 v[206:209], v183 offset:39936
	s_mov_b32 s79, m0
	s_mov_b32 m0, s40
	s_nop 0
	global_load_lds_dwordx4 v1, s[28:29]
	s_mov_b32 m0, s79
	s_nop 0
	s_mov_b32 s79, m0
	s_mov_b32 m0, s47
	s_nop 0
	global_load_lds_dwordx4 v177, s[28:29]
	s_mov_b32 m0, s79
	s_add_u32 s28, s28, 0x80000
	s_addc_u32 s29, s29, 0
	s_mov_b32 s79, m0
	s_mov_b32 m0, s48
	s_nop 0
	global_load_lds_dwordx4 v1, s[28:29]
	s_mov_b32 m0, s79
	s_nop 0
	s_mov_b32 s79, m0
	s_mov_b32 m0, s49
	s_nop 0
	global_load_lds_dwordx4 v177, s[28:29]
	s_mov_b32 m0, s79
	s_waitcnt vmcnt(8)
	s_waitcnt lgkmcnt(0)
	s_barrier
	s_setprio 1
	s_waitcnt lgkmcnt(7)
	v_mfma_f32_16x16x32_bf16 v[126:129], v[130:133], v[166:169], v[126:129]
	v_mfma_f32_16x16x32_bf16 v[126:129], v[134:137], v[170:173], v[126:129]
	s_waitcnt lgkmcnt(5)
	v_mfma_f32_16x16x32_bf16 v[122:125], v[138:141], v[166:169], v[122:125]
	v_mfma_f32_16x16x32_bf16 v[122:125], v[142:145], v[170:173], v[122:125]
	s_waitcnt lgkmcnt(3)
	v_mfma_f32_16x16x32_bf16 v[114:117], v[138:141], v[186:189], v[114:117]
	v_mfma_f32_16x16x32_bf16 v[114:117], v[142:145], v[190:193], v[114:117]
	s_waitcnt lgkmcnt(1)
	v_mfma_f32_16x16x32_bf16 v[118:121], v[130:133], v[186:189], v[118:121]
	v_mfma_f32_16x16x32_bf16 v[118:121], v[134:137], v[190:193], v[118:121]
	v_mfma_f32_16x16x32_bf16 v[94:97], v[130:133], v[194:197], v[94:97]
	v_mfma_f32_16x16x32_bf16 v[94:97], v[134:137], v[198:201], v[94:97]
	v_mfma_f32_16x16x32_bf16 v[90:93], v[138:141], v[194:197], v[90:93]
	v_mfma_f32_16x16x32_bf16 v[90:93], v[142:145], v[198:201], v[90:93]
	v_mfma_f32_16x16x32_bf16 v[78:81], v[138:141], v[202:205], v[78:81]
	v_mfma_f32_16x16x32_bf16 v[78:81], v[142:145], v[206:209], v[78:81]
	s_waitcnt lgkmcnt(0)
	v_mfma_f32_16x16x32_bf16 v[86:89], v[130:133], v[202:205], v[86:89]
	v_mfma_f32_16x16x32_bf16 v[86:89], v[134:137], v[206:209], v[86:89]
	s_setprio 0
	s_setprio 1
	v_mfma_f32_16x16x32_bf16 v[110:113], v[146:149], v[166:169], v[110:113]
	v_mfma_f32_16x16x32_bf16 v[110:113], v[150:153], v[170:173], v[110:113]
	v_mfma_f32_16x16x32_bf16 v[106:109], v[154:157], v[166:169], v[106:109]
	v_mfma_f32_16x16x32_bf16 v[106:109], v[158:161], v[170:173], v[106:109]
	v_mfma_f32_16x16x32_bf16 v[98:101], v[154:157], v[186:189], v[98:101]
	v_mfma_f32_16x16x32_bf16 v[98:101], v[158:161], v[190:193], v[98:101]
	v_mfma_f32_16x16x32_bf16 v[102:105], v[146:149], v[186:189], v[102:105]
	v_mfma_f32_16x16x32_bf16 v[102:105], v[150:153], v[190:193], v[102:105]
	v_mfma_f32_16x16x32_bf16 v[82:85], v[146:149], v[194:197], v[82:85]
	v_mfma_f32_16x16x32_bf16 v[82:85], v[150:153], v[198:201], v[82:85]
	v_mfma_f32_16x16x32_bf16 v[74:77], v[154:157], v[194:197], v[74:77]
	v_mfma_f32_16x16x32_bf16 v[74:77], v[158:161], v[198:201], v[74:77]
	s_setprio 2
	s_barrier
	v_mfma_f32_16x16x32_bf16 v[66:69], v[154:157], v[202:205], v[66:69]
	v_mfma_f32_16x16x32_bf16 v[66:69], v[158:161], v[206:209], v[66:69]
	v_mfma_f32_16x16x32_bf16 v[70:73], v[146:149], v[202:205], v[70:73]
	v_mfma_f32_16x16x32_bf16 v[70:73], v[150:153], v[206:209], v[70:73]
	s_setprio 0
	ds_read_b128 v[166:169], v183 offset:49152
	ds_read_b128 v[170:173], v183 offset:50176
	ds_read_b128 v[186:189], v183 offset:51200
	ds_read_b128 v[190:193], v183 offset:52224
	ds_read_b128 v[194:197], v183 offset:53248
	ds_read_b128 v[198:201], v183 offset:54272
	ds_read_b128 v[202:205], v183 offset:55296
	ds_read_b128 v[206:209], v183 offset:56320
	s_add_u32 s28, s26, 0x80
	s_addc_u32 s29, s27, 0
	s_mov_b32 s79, m0
	s_mov_b32 m0, s56
	s_nop 0
	global_load_lds_dwordx4 v176, s[28:29]
	s_mov_b32 m0, s79
	s_add_u32 s26, s26, 0x80080
	s_mov_b32 s79, m0
	s_mov_b32 m0, s57
	s_nop 0
	global_load_lds_dwordx4 v178, s[28:29]
	s_mov_b32 m0, s79
	s_addc_u32 s27, s27, 0
	s_mov_b32 s28, m0
	s_mov_b32 m0, s58
	s_nop 0
	global_load_lds_dwordx4 v176, s[26:27]
	s_mov_b32 m0, s28
	s_nop 0
	s_mov_b32 s28, m0
	s_mov_b32 m0, s59
	s_nop 0
	global_load_lds_dwordx4 v178, s[26:27]
	s_mov_b32 m0, s28
	s_waitcnt vmcnt(4)
	s_waitcnt lgkmcnt(0)
	s_barrier
	s_setprio 1
	s_waitcnt lgkmcnt(7)
	v_mfma_f32_16x16x32_bf16 v[62:65], v[130:133], v[166:169], v[62:65]
	v_mfma_f32_16x16x32_bf16 v[62:65], v[134:137], v[170:173], v[62:65]
	s_waitcnt lgkmcnt(5)
	v_mfma_f32_16x16x32_bf16 v[58:61], v[138:141], v[166:169], v[58:61]
	v_mfma_f32_16x16x32_bf16 v[58:61], v[142:145], v[170:173], v[58:61]
	s_waitcnt lgkmcnt(3)
	v_mfma_f32_16x16x32_bf16 v[42:45], v[138:141], v[186:189], v[42:45]
	v_mfma_f32_16x16x32_bf16 v[42:45], v[142:145], v[190:193], v[42:45]
	s_waitcnt lgkmcnt(1)
	v_mfma_f32_16x16x32_bf16 v[46:49], v[130:133], v[186:189], v[46:49]
	v_mfma_f32_16x16x32_bf16 v[46:49], v[134:137], v[190:193], v[46:49]
	v_mfma_f32_16x16x32_bf16 v[30:33], v[130:133], v[194:197], v[30:33]
	v_mfma_f32_16x16x32_bf16 v[30:33], v[134:137], v[198:201], v[30:33]
	v_mfma_f32_16x16x32_bf16 v[26:29], v[138:141], v[194:197], v[26:29]
	v_mfma_f32_16x16x32_bf16 v[26:29], v[142:145], v[198:201], v[26:29]
	v_mfma_f32_16x16x32_bf16 v[10:13], v[138:141], v[202:205], v[10:13]
	v_mfma_f32_16x16x32_bf16 v[10:13], v[142:145], v[206:209], v[10:13]
	s_waitcnt lgkmcnt(0)
	v_mfma_f32_16x16x32_bf16 v[14:17], v[130:133], v[202:205], v[14:17]
	v_mfma_f32_16x16x32_bf16 v[14:17], v[134:137], v[206:209], v[14:17]
	s_setprio 0
	s_setprio 1
	v_mfma_f32_16x16x32_bf16 v[54:57], v[146:149], v[166:169], v[54:57]
	v_mfma_f32_16x16x32_bf16 v[54:57], v[150:153], v[170:173], v[54:57]
	v_mfma_f32_16x16x32_bf16 v[50:53], v[154:157], v[166:169], v[50:53]
	v_mfma_f32_16x16x32_bf16 v[50:53], v[158:161], v[170:173], v[50:53]
	v_mfma_f32_16x16x32_bf16 v[34:37], v[154:157], v[186:189], v[34:37]
	v_mfma_f32_16x16x32_bf16 v[34:37], v[158:161], v[190:193], v[34:37]
	v_mfma_f32_16x16x32_bf16 v[38:41], v[146:149], v[186:189], v[38:41]
	v_mfma_f32_16x16x32_bf16 v[38:41], v[150:153], v[190:193], v[38:41]
	v_mfma_f32_16x16x32_bf16 v[22:25], v[146:149], v[194:197], v[22:25]
	v_mfma_f32_16x16x32_bf16 v[22:25], v[150:153], v[198:201], v[22:25]
	v_mfma_f32_16x16x32_bf16 v[18:21], v[154:157], v[194:197], v[18:21]
	v_mfma_f32_16x16x32_bf16 v[18:21], v[158:161], v[198:201], v[18:21]
	s_setprio 2
	s_barrier
	v_mfma_f32_16x16x32_bf16 v[2:5], v[154:157], v[202:205], v[2:5]
	v_mfma_f32_16x16x32_bf16 v[2:5], v[158:161], v[206:209], v[2:5]
	v_mfma_f32_16x16x32_bf16 v[6:9], v[146:149], v[202:205], v[6:9]
	v_mfma_f32_16x16x32_bf16 v[6:9], v[150:153], v[206:209], v[6:9]
	s_setprio 0
	s_add_i32 s78, s78, 2
	s_add_u32 s74, s74, 0x100
	s_addc_u32 s75, s75, 0
	s_add_u32 s24, s24, 0x100
	s_addc_u32 s25, s25, 0
	s_add_u32 s76, s76, 0x100
	s_addc_u32 s77, s77, 0
	s_cmp_gt_u32 s78, 29
	s_cbranch_scc0 .LBB0_2410
	s_and_b64 vcc, exec, s[8:9]
	s_cbranch_vccz .LBB0_2413
	s_barrier

.LBB0_2593:
	s_ashr_i32 s11, s10, 31
	s_lshl_b64 s[12:13], s[10:11], 20
	s_add_u32 s12, s26, s12
	s_addc_u32 s13, s27, s13
	s_and_b64 s[14:15], s[2:3], exec
	s_cselect_b32 s11, s13, s21
	s_cselect_b32 s62, s12, s20
	s_ashr_i32 s9, s8, 31
	s_lshl_b64 s[14:15], s[8:9], 20
	s_add_u32 s14, s28, s14
	s_addc_u32 s15, s29, s15
	s_and_b64 s[22:23], s[2:3], exec
	s_cselect_b32 s9, s15, s19
	s_cselect_b32 s63, s14, s18
	s_add_u32 s64, s18, 0x100
	s_addc_u32 s65, s19, 0
	s_add_u32 s18, s20, 0x80080
	s_addc_u32 s19, s21, 0
	s_add_u32 s66, s20, 0x100
	s_addc_u32 s67, s21, 0
	s_mov_b32 s70, -2
	ds_read_b128 v[148:151], v143
	ds_read_b128 v[152:155], v143 offset:1024
	ds_read_b128 v[156:159], v143 offset:2048
	ds_read_b128 v[160:163], v143 offset:3072
	ds_read_b128 v[164:167], v144
	ds_read_b128 v[168:171], v144 offset:1024
	ds_read_b128 v[172:175], v144 offset:2048
	ds_read_b128 v[176:179], v144 offset:3072
	s_cmp_eq_u32 s70, 28
	s_cselect_b32 s21, s9, s65
	s_cselect_b32 s20, s63, s64
	s_cselect_b32 s23, s11, s67
	s_cselect_b32 s22, s62, s66
	ds_read_b128 v[180:183], v145
	ds_read_b128 v[184:187], v145 offset:1024
	ds_read_b128 v[188:191], v145 offset:2048
	ds_read_b128 v[192:195], v145 offset:3072
	ds_read_b128 v[196:199], v145 offset:4096
	ds_read_b128 v[200:203], v145 offset:5120
	ds_read_b128 v[204:207], v145 offset:6144
	ds_read_b128 v[208:211], v145 offset:7168
	s_add_u32 s74, s18, 0xfff80000
	s_addc_u32 s75, s19, -1
	s_mov_b32 s71, m0
	s_mov_b32 m0, s48
	s_nop 0
	global_load_lds_dwordx4 v138, s[74:75]
	s_mov_b32 m0, s71
	s_nop 0
	s_mov_b32 s71, m0
	s_mov_b32 m0, s57
	s_nop 0
	global_load_lds_dwordx4 v140, s[74:75]
	s_mov_b32 m0, s71
	s_nop 0
	s_mov_b32 s71, m0
	s_mov_b32 m0, s49
	s_nop 0
	global_load_lds_dwordx4 v138, s[18:19]
	s_mov_b32 m0, s71
	s_nop 0
	s_mov_b32 s71, m0
	s_mov_b32 m0, s58
	s_nop 0
	global_load_lds_dwordx4 v140, s[18:19]
	s_mov_b32 m0, s71
	s_waitcnt vmcnt(8)
	s_waitcnt lgkmcnt(0)
	s_barrier
	s_setprio 1
	s_waitcnt lgkmcnt(7)
	v_mfma_f32_16x16x32_bf16 v[126:129], v[148:151], v[180:183], 0
	v_mfma_f32_16x16x32_bf16 v[126:129], v[152:155], v[184:187], v[126:129]
	s_waitcnt lgkmcnt(5)
	v_mfma_f32_16x16x32_bf16 v[122:125], v[156:159], v[180:183], 0
	v_mfma_f32_16x16x32_bf16 v[122:125], v[160:163], v[184:187], v[122:125]
	s_waitcnt lgkmcnt(3)
	v_mfma_f32_16x16x32_bf16 v[106:109], v[156:159], v[188:191], 0
	v_mfma_f32_16x16x32_bf16 v[106:109], v[160:163], v[192:195], v[106:109]
	s_waitcnt lgkmcnt(1)
	v_mfma_f32_16x16x32_bf16 v[110:113], v[148:151], v[188:191], 0
	v_mfma_f32_16x16x32_bf16 v[110:113], v[152:155], v[192:195], v[110:113]
	v_mfma_f32_16x16x32_bf16 v[94:97], v[148:151], v[196:199], 0
	v_mfma_f32_16x16x32_bf16 v[94:97], v[152:155], v[200:203], v[94:97]
	v_mfma_f32_16x16x32_bf16 v[90:93], v[156:159], v[196:199], 0
	v_mfma_f32_16x16x32_bf16 v[90:93], v[160:163], v[200:203], v[90:93]
	v_mfma_f32_16x16x32_bf16 v[74:77], v[156:159], v[204:207], 0
	v_mfma_f32_16x16x32_bf16 v[74:77], v[160:163], v[208:211], v[74:77]
	s_waitcnt lgkmcnt(0)
	v_mfma_f32_16x16x32_bf16 v[78:81], v[148:151], v[204:207], 0
	v_mfma_f32_16x16x32_bf16 v[78:81], v[152:155], v[208:211], v[78:81]
	s_setprio 0
	s_setprio 1
	v_mfma_f32_16x16x32_bf16 v[118:121], v[164:167], v[180:183], 0
	v_mfma_f32_16x16x32_bf16 v[118:121], v[168:171], v[184:187], v[118:121]
	v_mfma_f32_16x16x32_bf16 v[114:117], v[172:175], v[180:183], 0
	v_mfma_f32_16x16x32_bf16 v[114:117], v[176:179], v[184:187], v[114:117]
	v_mfma_f32_16x16x32_bf16 v[98:101], v[172:175], v[188:191], 0
	v_mfma_f32_16x16x32_bf16 v[98:101], v[176:179], v[192:195], v[98:101]
	v_mfma_f32_16x16x32_bf16 v[102:105], v[164:167], v[188:191], 0
	v_mfma_f32_16x16x32_bf16 v[102:105], v[168:171], v[192:195], v[102:105]
	v_mfma_f32_16x16x32_bf16 v[86:89], v[164:167], v[196:199], 0
	v_mfma_f32_16x16x32_bf16 v[86:89], v[168:171], v[200:203], v[86:89]
	v_mfma_f32_16x16x32_bf16 v[82:85], v[172:175], v[196:199], 0
	v_mfma_f32_16x16x32_bf16 v[82:85], v[176:179], v[200:203], v[82:85]
	s_setprio 2
	s_barrier
	v_mfma_f32_16x16x32_bf16 v[66:69], v[172:175], v[204:207], 0
	v_mfma_f32_16x16x32_bf16 v[66:69], v[176:179], v[208:211], v[66:69]
	v_mfma_f32_16x16x32_bf16 v[70:73], v[164:167], v[204:207], 0
	v_mfma_f32_16x16x32_bf16 v[70:73], v[168:171], v[208:211], v[70:73]
	s_setprio 0
	ds_read_b128 v[180:183], v145 offset:16384
	ds_read_b128 v[184:187], v145 offset:17408
	ds_read_b128 v[188:191], v145 offset:18432
	ds_read_b128 v[192:195], v145 offset:19456
	ds_read_b128 v[196:199], v145 offset:20480
	ds_read_b128 v[200:203], v145 offset:21504
	ds_read_b128 v[204:207], v145 offset:22528
	ds_read_b128 v[208:211], v145 offset:23552
	s_mov_b32 s71, m0
	s_mov_b32 m0, s35
	s_nop 0
	global_load_lds_dwordx4 v139, s[20:21]
	s_mov_b32 m0, s71
	s_add_u32 s74, s20, 0x80000
	s_mov_b32 s71, m0
	s_mov_b32 m0, s36
	s_nop 0
	global_load_lds_dwordx4 v141, s[20:21]
	s_mov_b32 m0, s71
	s_addc_u32 s75, s21, 0
	s_mov_b32 s71, m0
	s_mov_b32 m0, s37
	s_nop 0
	global_load_lds_dwordx4 v139, s[74:75]
	s_mov_b32 m0, s71
	s_nop 0
	s_mov_b32 s71, m0
	s_mov_b32 m0, s40
	s_nop 0
	global_load_lds_dwordx4 v141, s[74:75]
	s_mov_b32 m0, s71
	s_waitcnt vmcnt(4)
	s_waitcnt lgkmcnt(0)
	s_barrier
	s_setprio 1
	s_waitcnt lgkmcnt(7)
	v_mfma_f32_16x16x32_bf16 v[62:65], v[148:151], v[180:183], 0
	v_mfma_f32_16x16x32_bf16 v[62:65], v[152:155], v[184:187], v[62:65]
	s_waitcnt lgkmcnt(5)
	v_mfma_f32_16x16x32_bf16 v[58:61], v[156:159], v[180:183], 0
	v_mfma_f32_16x16x32_bf16 v[58:61], v[160:163], v[184:187], v[58:61]
	s_waitcnt lgkmcnt(3)
	v_mfma_f32_16x16x32_bf16 v[42:45], v[156:159], v[188:191], 0
	v_mfma_f32_16x16x32_bf16 v[42:45], v[160:163], v[192:195], v[42:45]
	s_waitcnt lgkmcnt(1)
	v_mfma_f32_16x16x32_bf16 v[46:49], v[148:151], v[188:191], 0
	v_mfma_f32_16x16x32_bf16 v[46:49], v[152:155], v[192:195], v[46:49]
	v_mfma_f32_16x16x32_bf16 v[30:33], v[148:151], v[196:199], 0
	v_mfma_f32_16x16x32_bf16 v[30:33], v[152:155], v[200:203], v[30:33]
	v_mfma_f32_16x16x32_bf16 v[26:29], v[156:159], v[196:199], 0
	v_mfma_f32_16x16x32_bf16 v[26:29], v[160:163], v[200:203], v[26:29]
	v_mfma_f32_16x16x32_bf16 v[10:13], v[156:159], v[204:207], 0
	v_mfma_f32_16x16x32_bf16 v[10:13], v[160:163], v[208:211], v[10:13]
	s_waitcnt lgkmcnt(0)
	v_mfma_f32_16x16x32_bf16 v[14:17], v[148:151], v[204:207], 0
	v_mfma_f32_16x16x32_bf16 v[14:17], v[152:155], v[208:211], v[14:17]
	s_setprio 0
	s_setprio 1
	v_mfma_f32_16x16x32_bf16 v[54:57], v[164:167], v[180:183], 0
	v_mfma_f32_16x16x32_bf16 v[54:57], v[168:171], v[184:187], v[54:57]
	v_mfma_f32_16x16x32_bf16 v[50:53], v[172:175], v[180:183], 0
	v_mfma_f32_16x16x32_bf16 v[50:53], v[176:179], v[184:187], v[50:53]
	v_mfma_f32_16x16x32_bf16 v[34:37], v[172:175], v[188:191], 0
	v_mfma_f32_16x16x32_bf16 v[34:37], v[176:179], v[192:195], v[34:37]
	v_mfma_f32_16x16x32_bf16 v[38:41], v[164:167], v[188:191], 0
	v_mfma_f32_16x16x32_bf16 v[38:41], v[168:171], v[192:195], v[38:41]
	v_mfma_f32_16x16x32_bf16 v[22:25], v[164:167], v[196:199], 0
	v_mfma_f32_16x16x32_bf16 v[22:25], v[168:171], v[200:203], v[22:25]
	v_mfma_f32_16x16x32_bf16 v[18:21], v[172:175], v[196:199], 0
	v_mfma_f32_16x16x32_bf16 v[18:21], v[176:179], v[200:203], v[18:21]
	s_setprio 2
	s_barrier
	v_mfma_f32_16x16x32_bf16 v[2:5], v[172:175], v[204:207], 0
	v_mfma_f32_16x16x32_bf16 v[2:5], v[176:179], v[208:211], v[2:5]
	v_mfma_f32_16x16x32_bf16 v[6:9], v[164:167], v[204:207], 0
	v_mfma_f32_16x16x32_bf16 v[6:9], v[168:171], v[208:211], v[6:9]
	s_setprio 0
	ds_read_b128 v[148:151], v146
	ds_read_b128 v[152:155], v146 offset:1024
	ds_read_b128 v[156:159], v146 offset:2048
	ds_read_b128 v[160:163], v146 offset:3072
	ds_read_b128 v[164:167], v147
	ds_read_b128 v[168:171], v147 offset:1024
	ds_read_b128 v[172:175], v147 offset:2048
	ds_read_b128 v[176:179], v147 offset:3072
	ds_read_b128 v[180:183], v145 offset:32768
	ds_read_b128 v[184:187], v145 offset:33792
	ds_read_b128 v[188:191], v145 offset:34816
	ds_read_b128 v[192:195], v145 offset:35840
	ds_read_b128 v[196:199], v145 offset:36864
	ds_read_b128 v[200:203], v145 offset:37888
	ds_read_b128 v[204:207], v145 offset:38912
	ds_read_b128 v[208:211], v145 offset:39936
	s_mov_b32 s71, m0
	s_mov_b32 m0, s31
	s_nop 0
	global_load_lds_dwordx4 v138, s[22:23]
	s_mov_b32 m0, s71
	s_nop 0
	s_mov_b32 s71, m0
	s_mov_b32 m0, s41
	s_nop 0
	global_load_lds_dwordx4 v140, s[22:23]
	s_mov_b32 m0, s71
	s_add_u32 s22, s22, 0x80000
	s_addc_u32 s23, s23, 0
	s_mov_b32 s71, m0
	s_mov_b32 m0, s42
	s_nop 0
	global_load_lds_dwordx4 v138, s[22:23]
	s_mov_b32 m0, s71
	s_nop 0
	s_mov_b32 s71, m0
	s_mov_b32 m0, s43
	s_nop 0
	global_load_lds_dwordx4 v140, s[22:23]
	s_mov_b32 m0, s71
	s_waitcnt vmcnt(8)
	s_waitcnt lgkmcnt(0)
	s_barrier
	s_setprio 1
	s_waitcnt lgkmcnt(7)
	v_mfma_f32_16x16x32_bf16 v[126:129], v[148:151], v[180:183], v[126:129]
	v_mfma_f32_16x16x32_bf16 v[126:129], v[152:155], v[184:187], v[126:129]
	s_waitcnt lgkmcnt(5)
	v_mfma_f32_16x16x32_bf16 v[122:125], v[156:159], v[180:183], v[122:125]
	v_mfma_f32_16x16x32_bf16 v[122:125], v[160:163], v[184:187], v[122:125]
	s_waitcnt lgkmcnt(3)
	v_mfma_f32_16x16x32_bf16 v[106:109], v[156:159], v[188:191], v[106:109]
	v_mfma_f32_16x16x32_bf16 v[106:109], v[160:163], v[192:195], v[106:109]
	s_waitcnt lgkmcnt(1)
	v_mfma_f32_16x16x32_bf16 v[110:113], v[148:151], v[188:191], v[110:113]
	v_mfma_f32_16x16x32_bf16 v[110:113], v[152:155], v[192:195], v[110:113]
	v_mfma_f32_16x16x32_bf16 v[94:97], v[148:151], v[196:199], v[94:97]
	v_mfma_f32_16x16x32_bf16 v[94:97], v[152:155], v[200:203], v[94:97]
	v_mfma_f32_16x16x32_bf16 v[90:93], v[156:159], v[196:199], v[90:93]
	v_mfma_f32_16x16x32_bf16 v[90:93], v[160:163], v[200:203], v[90:93]
	v_mfma_f32_16x16x32_bf16 v[74:77], v[156:159], v[204:207], v[74:77]
	v_mfma_f32_16x16x32_bf16 v[74:77], v[160:163], v[208:211], v[74:77]
	s_waitcnt lgkmcnt(0)
	v_mfma_f32_16x16x32_bf16 v[78:81], v[148:151], v[204:207], v[78:81]
	v_mfma_f32_16x16x32_bf16 v[78:81], v[152:155], v[208:211], v[78:81]
	s_setprio 0
	s_setprio 1
	v_mfma_f32_16x16x32_bf16 v[118:121], v[164:167], v[180:183], v[118:121]
	v_mfma_f32_16x16x32_bf16 v[118:121], v[168:171], v[184:187], v[118:121]
	v_mfma_f32_16x16x32_bf16 v[114:117], v[172:175], v[180:183], v[114:117]
	v_mfma_f32_16x16x32_bf16 v[114:117], v[176:179], v[184:187], v[114:117]
	v_mfma_f32_16x16x32_bf16 v[98:101], v[172:175], v[188:191], v[98:101]
	v_mfma_f32_16x16x32_bf16 v[98:101], v[176:179], v[192:195], v[98:101]
	v_mfma_f32_16x16x32_bf16 v[102:105], v[164:167], v[188:191], v[102:105]
	v_mfma_f32_16x16x32_bf16 v[102:105], v[168:171], v[192:195], v[102:105]
	v_mfma_f32_16x16x32_bf16 v[86:89], v[164:167], v[196:199], v[86:89]
	v_mfma_f32_16x16x32_bf16 v[86:89], v[168:171], v[200:203], v[86:89]
	v_mfma_f32_16x16x32_bf16 v[82:85], v[172:175], v[196:199], v[82:85]
	v_mfma_f32_16x16x32_bf16 v[82:85], v[176:179], v[200:203], v[82:85]
	s_setprio 2
	s_barrier
	v_mfma_f32_16x16x32_bf16 v[66:69], v[172:175], v[204:207], v[66:69]
	v_mfma_f32_16x16x32_bf16 v[66:69], v[176:179], v[208:211], v[66:69]
	v_mfma_f32_16x16x32_bf16 v[70:73], v[164:167], v[204:207], v[70:73]
	v_mfma_f32_16x16x32_bf16 v[70:73], v[168:171], v[208:211], v[70:73]
	s_setprio 0
	ds_read_b128 v[180:183], v145 offset:49152
	ds_read_b128 v[184:187], v145 offset:50176
	ds_read_b128 v[188:191], v145 offset:51200
	ds_read_b128 v[192:195], v145 offset:52224
	ds_read_b128 v[196:199], v145 offset:53248
	ds_read_b128 v[200:203], v145 offset:54272
	ds_read_b128 v[204:207], v145 offset:55296
	ds_read_b128 v[208:211], v145 offset:56320
	s_add_u32 s22, s20, 0x80
	s_addc_u32 s23, s21, 0
	s_mov_b32 s71, m0
	s_mov_b32 m0, s44
	s_nop 0
	global_load_lds_dwordx4 v139, s[22:23]
	s_mov_b32 m0, s71
	s_add_u32 s20, s20, 0x80080
	s_mov_b32 s71, m0
	s_mov_b32 m0, s45
	s_nop 0
	global_load_lds_dwordx4 v141, s[22:23]
	s_mov_b32 m0, s71
	s_addc_u32 s21, s21, 0
	s_mov_b32 s22, m0
	s_mov_b32 m0, s46
	s_nop 0
	global_load_lds_dwordx4 v139, s[20:21]
	s_mov_b32 m0, s22
	s_nop 0
	s_mov_b32 s22, m0
	s_mov_b32 m0, s47
	s_nop 0
	global_load_lds_dwordx4 v141, s[20:21]
	s_mov_b32 m0, s22
	s_waitcnt vmcnt(4)
	s_waitcnt lgkmcnt(0)
	s_barrier
	s_setprio 1
	s_waitcnt lgkmcnt(7)
	v_mfma_f32_16x16x32_bf16 v[62:65], v[148:151], v[180:183], v[62:65]
	v_mfma_f32_16x16x32_bf16 v[62:65], v[152:155], v[184:187], v[62:65]
	s_waitcnt lgkmcnt(5)
	v_mfma_f32_16x16x32_bf16 v[58:61], v[156:159], v[180:183], v[58:61]
	v_mfma_f32_16x16x32_bf16 v[58:61], v[160:163], v[184:187], v[58:61]
	s_waitcnt lgkmcnt(3)
	v_mfma_f32_16x16x32_bf16 v[42:45], v[156:159], v[188:191], v[42:45]
	v_mfma_f32_16x16x32_bf16 v[42:45], v[160:163], v[192:195], v[42:45]
	s_waitcnt lgkmcnt(1)
	v_mfma_f32_16x16x32_bf16 v[46:49], v[148:151], v[188:191], v[46:49]
	v_mfma_f32_16x16x32_bf16 v[46:49], v[152:155], v[192:195], v[46:49]
	v_mfma_f32_16x16x32_bf16 v[30:33], v[148:151], v[196:199], v[30:33]
	v_mfma_f32_16x16x32_bf16 v[30:33], v[152:155], v[200:203], v[30:33]
	v_mfma_f32_16x16x32_bf16 v[26:29], v[156:159], v[196:199], v[26:29]
	v_mfma_f32_16x16x32_bf16 v[26:29], v[160:163], v[200:203], v[26:29]
	v_mfma_f32_16x16x32_bf16 v[10:13], v[156:159], v[204:207], v[10:13]
	v_mfma_f32_16x16x32_bf16 v[10:13], v[160:163], v[208:211], v[10:13]
	s_waitcnt lgkmcnt(0)
	v_mfma_f32_16x16x32_bf16 v[14:17], v[148:151], v[204:207], v[14:17]
	v_mfma_f32_16x16x32_bf16 v[14:17], v[152:155], v[208:211], v[14:17]
	s_setprio 0
	s_setprio 1
	v_mfma_f32_16x16x32_bf16 v[54:57], v[164:167], v[180:183], v[54:57]
	v_mfma_f32_16x16x32_bf16 v[54:57], v[168:171], v[184:187], v[54:57]
	v_mfma_f32_16x16x32_bf16 v[50:53], v[172:175], v[180:183], v[50:53]
	v_mfma_f32_16x16x32_bf16 v[50:53], v[176:179], v[184:187], v[50:53]
	v_mfma_f32_16x16x32_bf16 v[34:37], v[172:175], v[188:191], v[34:37]
	v_mfma_f32_16x16x32_bf16 v[34:37], v[176:179], v[192:195], v[34:37]
	v_mfma_f32_16x16x32_bf16 v[38:41], v[164:167], v[188:191], v[38:41]
	v_mfma_f32_16x16x32_bf16 v[38:41], v[168:171], v[192:195], v[38:41]
	v_mfma_f32_16x16x32_bf16 v[22:25], v[164:167], v[196:199], v[22:25]
	v_mfma_f32_16x16x32_bf16 v[22:25], v[168:171], v[200:203], v[22:25]
	v_mfma_f32_16x16x32_bf16 v[18:21], v[172:175], v[196:199], v[18:21]
	v_mfma_f32_16x16x32_bf16 v[18:21], v[176:179], v[200:203], v[18:21]
	s_setprio 2
	s_barrier
	v_mfma_f32_16x16x32_bf16 v[2:5], v[172:175], v[204:207], v[2:5]
	v_mfma_f32_16x16x32_bf16 v[2:5], v[176:179], v[208:211], v[2:5]
	v_mfma_f32_16x16x32_bf16 v[6:9], v[164:167], v[204:207], v[6:9]
	v_mfma_f32_16x16x32_bf16 v[6:9], v[168:171], v[208:211], v[6:9]
	s_setprio 0
	s_add_i32 s70, s70, 2
	s_add_u32 s64, s64, 0x100
	s_addc_u32 s65, s65, 0
	s_add_u32 s18, s18, 0x100
	s_addc_u32 s19, s19, 0
	s_add_u32 s66, s66, 0x100
	s_addc_u32 s67, s67, 0
	s_cmp_gt_u32 s70, 29
	.p2align 6
.LBB0_2594:
	ds_read_b128 v[148:151], v143
	ds_read_b128 v[152:155], v143 offset:1024
	ds_read_b128 v[156:159], v143 offset:2048
	ds_read_b128 v[160:163], v143 offset:3072
	ds_read_b128 v[164:167], v144
	ds_read_b128 v[168:171], v144 offset:1024
	ds_read_b128 v[172:175], v144 offset:2048
	ds_read_b128 v[176:179], v144 offset:3072
	s_cmp_eq_u32 s70, 28
	s_cselect_b32 s21, s9, s65
	s_cselect_b32 s20, s63, s64
	s_cselect_b32 s23, s11, s67
	s_cselect_b32 s22, s62, s66
	ds_read_b128 v[180:183], v145
	ds_read_b128 v[184:187], v145 offset:1024
	ds_read_b128 v[188:191], v145 offset:2048
	ds_read_b128 v[192:195], v145 offset:3072
	ds_read_b128 v[196:199], v145 offset:4096
	ds_read_b128 v[200:203], v145 offset:5120
	ds_read_b128 v[204:207], v145 offset:6144
	ds_read_b128 v[208:211], v145 offset:7168
	s_add_u32 s74, s18, 0xfff80000
	s_addc_u32 s75, s19, -1
	s_mov_b32 s71, m0
	s_mov_b32 m0, s48
	s_nop 0
	global_load_lds_dwordx4 v138, s[74:75]
	s_mov_b32 m0, s71
	s_nop 0
	s_mov_b32 s71, m0
	s_mov_b32 m0, s57
	s_nop 0
	global_load_lds_dwordx4 v140, s[74:75]
	s_mov_b32 m0, s71
	s_nop 0
	s_mov_b32 s71, m0
	s_mov_b32 m0, s49
	s_nop 0
	global_load_lds_dwordx4 v138, s[18:19]
	s_mov_b32 m0, s71
	s_nop 0
	s_mov_b32 s71, m0
	s_mov_b32 m0, s58
	s_nop 0
	global_load_lds_dwordx4 v140, s[18:19]
	s_mov_b32 m0, s71
	s_waitcnt vmcnt(8)
	s_waitcnt lgkmcnt(0)
	s_barrier
	s_setprio 1
	s_waitcnt lgkmcnt(7)
	v_mfma_f32_16x16x32_bf16 v[126:129], v[148:151], v[180:183], v[126:129]
	v_mfma_f32_16x16x32_bf16 v[126:129], v[152:155], v[184:187], v[126:129]
	s_waitcnt lgkmcnt(5)
	v_mfma_f32_16x16x32_bf16 v[122:125], v[156:159], v[180:183], v[122:125]
	v_mfma_f32_16x16x32_bf16 v[122:125], v[160:163], v[184:187], v[122:125]
	s_waitcnt lgkmcnt(3)
	v_mfma_f32_16x16x32_bf16 v[106:109], v[156:159], v[188:191], v[106:109]
	v_mfma_f32_16x16x32_bf16 v[106:109], v[160:163], v[192:195], v[106:109]
	s_waitcnt lgkmcnt(1)
	v_mfma_f32_16x16x32_bf16 v[110:113], v[148:151], v[188:191], v[110:113]
	v_mfma_f32_16x16x32_bf16 v[110:113], v[152:155], v[192:195], v[110:113]
	v_mfma_f32_16x16x32_bf16 v[94:97], v[148:151], v[196:199], v[94:97]
	v_mfma_f32_16x16x32_bf16 v[94:97], v[152:155], v[200:203], v[94:97]
	v_mfma_f32_16x16x32_bf16 v[90:93], v[156:159], v[196:199], v[90:93]
	v_mfma_f32_16x16x32_bf16 v[90:93], v[160:163], v[200:203], v[90:93]
	v_mfma_f32_16x16x32_bf16 v[74:77], v[156:159], v[204:207], v[74:77]
	v_mfma_f32_16x16x32_bf16 v[74:77], v[160:163], v[208:211], v[74:77]
	s_waitcnt lgkmcnt(0)
	v_mfma_f32_16x16x32_bf16 v[78:81], v[148:151], v[204:207], v[78:81]
	v_mfma_f32_16x16x32_bf16 v[78:81], v[152:155], v[208:211], v[78:81]
	s_setprio 0
	s_setprio 1
	v_mfma_f32_16x16x32_bf16 v[118:121], v[164:167], v[180:183], v[118:121]
	v_mfma_f32_16x16x32_bf16 v[118:121], v[168:171], v[184:187], v[118:121]
	v_mfma_f32_16x16x32_bf16 v[114:117], v[172:175], v[180:183], v[114:117]
	v_mfma_f32_16x16x32_bf16 v[114:117], v[176:179], v[184:187], v[114:117]
	v_mfma_f32_16x16x32_bf16 v[98:101], v[172:175], v[188:191], v[98:101]
	v_mfma_f32_16x16x32_bf16 v[98:101], v[176:179], v[192:195], v[98:101]
	v_mfma_f32_16x16x32_bf16 v[102:105], v[164:167], v[188:191], v[102:105]
	v_mfma_f32_16x16x32_bf16 v[102:105], v[168:171], v[192:195], v[102:105]
	v_mfma_f32_16x16x32_bf16 v[86:89], v[164:167], v[196:199], v[86:89]
	v_mfma_f32_16x16x32_bf16 v[86:89], v[168:171], v[200:203], v[86:89]
	v_mfma_f32_16x16x32_bf16 v[82:85], v[172:175], v[196:199], v[82:85]
	v_mfma_f32_16x16x32_bf16 v[82:85], v[176:179], v[200:203], v[82:85]
	s_setprio 2
	s_barrier
	v_mfma_f32_16x16x32_bf16 v[66:69], v[172:175], v[204:207], v[66:69]
	v_mfma_f32_16x16x32_bf16 v[66:69], v[176:179], v[208:211], v[66:69]
	v_mfma_f32_16x16x32_bf16 v[70:73], v[164:167], v[204:207], v[70:73]
	v_mfma_f32_16x16x32_bf16 v[70:73], v[168:171], v[208:211], v[70:73]
	s_setprio 0
	ds_read_b128 v[180:183], v145 offset:16384
	ds_read_b128 v[184:187], v145 offset:17408
	ds_read_b128 v[188:191], v145 offset:18432
	ds_read_b128 v[192:195], v145 offset:19456
	ds_read_b128 v[196:199], v145 offset:20480
	ds_read_b128 v[200:203], v145 offset:21504
	ds_read_b128 v[204:207], v145 offset:22528
	ds_read_b128 v[208:211], v145 offset:23552
	s_mov_b32 s71, m0
	s_mov_b32 m0, s35
	s_nop 0
	global_load_lds_dwordx4 v139, s[20:21]
	s_mov_b32 m0, s71
	s_add_u32 s74, s20, 0x80000
	s_mov_b32 s71, m0
	s_mov_b32 m0, s36
	s_nop 0
	global_load_lds_dwordx4 v141, s[20:21]
	s_mov_b32 m0, s71
	s_addc_u32 s75, s21, 0
	s_mov_b32 s71, m0
	s_mov_b32 m0, s37
	s_nop 0
	global_load_lds_dwordx4 v139, s[74:75]
	s_mov_b32 m0, s71
	s_nop 0
	s_mov_b32 s71, m0
	s_mov_b32 m0, s40
	s_nop 0
	global_load_lds_dwordx4 v141, s[74:75]
	s_mov_b32 m0, s71
	s_waitcnt vmcnt(4)
	s_waitcnt lgkmcnt(0)
	s_barrier
	s_setprio 1
	s_waitcnt lgkmcnt(7)
	v_mfma_f32_16x16x32_bf16 v[62:65], v[148:151], v[180:183], v[62:65]
	v_mfma_f32_16x16x32_bf16 v[62:65], v[152:155], v[184:187], v[62:65]
	s_waitcnt lgkmcnt(5)
	v_mfma_f32_16x16x32_bf16 v[58:61], v[156:159], v[180:183], v[58:61]
	v_mfma_f32_16x16x32_bf16 v[58:61], v[160:163], v[184:187], v[58:61]
	s_waitcnt lgkmcnt(3)
	v_mfma_f32_16x16x32_bf16 v[42:45], v[156:159], v[188:191], v[42:45]
	v_mfma_f32_16x16x32_bf16 v[42:45], v[160:163], v[192:195], v[42:45]
	s_waitcnt lgkmcnt(1)
	v_mfma_f32_16x16x32_bf16 v[46:49], v[148:151], v[188:191], v[46:49]
	v_mfma_f32_16x16x32_bf16 v[46:49], v[152:155], v[192:195], v[46:49]
	v_mfma_f32_16x16x32_bf16 v[30:33], v[148:151], v[196:199], v[30:33]
	v_mfma_f32_16x16x32_bf16 v[30:33], v[152:155], v[200:203], v[30:33]
	v_mfma_f32_16x16x32_bf16 v[26:29], v[156:159], v[196:199], v[26:29]
	v_mfma_f32_16x16x32_bf16 v[26:29], v[160:163], v[200:203], v[26:29]
	v_mfma_f32_16x16x32_bf16 v[10:13], v[156:159], v[204:207], v[10:13]
	v_mfma_f32_16x16x32_bf16 v[10:13], v[160:163], v[208:211], v[10:13]
	s_waitcnt lgkmcnt(0)
	v_mfma_f32_16x16x32_bf16 v[14:17], v[148:151], v[204:207], v[14:17]
	v_mfma_f32_16x16x32_bf16 v[14:17], v[152:155], v[208:211], v[14:17]
	s_setprio 0
	s_setprio 1
	v_mfma_f32_16x16x32_bf16 v[54:57], v[164:167], v[180:183], v[54:57]
	v_mfma_f32_16x16x32_bf16 v[54:57], v[168:171], v[184:187], v[54:57]
	v_mfma_f32_16x16x32_bf16 v[50:53], v[172:175], v[180:183], v[50:53]
	v_mfma_f32_16x16x32_bf16 v[50:53], v[176:179], v[184:187], v[50:53]
	v_mfma_f32_16x16x32_bf16 v[34:37], v[172:175], v[188:191], v[34:37]
	v_mfma_f32_16x16x32_bf16 v[34:37], v[176:179], v[192:195], v[34:37]
	v_mfma_f32_16x16x32_bf16 v[38:41], v[164:167], v[188:191], v[38:41]
	v_mfma_f32_16x16x32_bf16 v[38:41], v[168:171], v[192:195], v[38:41]
	v_mfma_f32_16x16x32_bf16 v[22:25], v[164:167], v[196:199], v[22:25]
	v_mfma_f32_16x16x32_bf16 v[22:25], v[168:171], v[200:203], v[22:25]
	v_mfma_f32_16x16x32_bf16 v[18:21], v[172:175], v[196:199], v[18:21]
	v_mfma_f32_16x16x32_bf16 v[18:21], v[176:179], v[200:203], v[18:21]
	s_setprio 2
	s_barrier
	v_mfma_f32_16x16x32_bf16 v[2:5], v[172:175], v[204:207], v[2:5]
	v_mfma_f32_16x16x32_bf16 v[2:5], v[176:179], v[208:211], v[2:5]
	v_mfma_f32_16x16x32_bf16 v[6:9], v[164:167], v[204:207], v[6:9]
	v_mfma_f32_16x16x32_bf16 v[6:9], v[168:171], v[208:211], v[6:9]
	s_setprio 0
	ds_read_b128 v[148:151], v146
	ds_read_b128 v[152:155], v146 offset:1024
	ds_read_b128 v[156:159], v146 offset:2048
	ds_read_b128 v[160:163], v146 offset:3072
	ds_read_b128 v[164:167], v147
	ds_read_b128 v[168:171], v147 offset:1024
	ds_read_b128 v[172:175], v147 offset:2048
	ds_read_b128 v[176:179], v147 offset:3072
	ds_read_b128 v[180:183], v145 offset:32768
	ds_read_b128 v[184:187], v145 offset:33792
	ds_read_b128 v[188:191], v145 offset:34816
	ds_read_b128 v[192:195], v145 offset:35840
	ds_read_b128 v[196:199], v145 offset:36864
	ds_read_b128 v[200:203], v145 offset:37888
	ds_read_b128 v[204:207], v145 offset:38912
	ds_read_b128 v[208:211], v145 offset:39936
	s_mov_b32 s71, m0
	s_mov_b32 m0, s31
	s_nop 0
	global_load_lds_dwordx4 v138, s[22:23]
	s_mov_b32 m0, s71
	s_nop 0
	s_mov_b32 s71, m0
	s_mov_b32 m0, s41
	s_nop 0
	global_load_lds_dwordx4 v140, s[22:23]
	s_mov_b32 m0, s71
	s_add_u32 s22, s22, 0x80000
	s_addc_u32 s23, s23, 0
	s_mov_b32 s71, m0
	s_mov_b32 m0, s42
	s_nop 0
	global_load_lds_dwordx4 v138, s[22:23]
	s_mov_b32 m0, s71
	s_nop 0
	s_mov_b32 s71, m0
	s_mov_b32 m0, s43
	s_nop 0
	global_load_lds_dwordx4 v140, s[22:23]
	s_mov_b32 m0, s71
	s_waitcnt vmcnt(8)
	s_waitcnt lgkmcnt(0)
	s_barrier
	s_setprio 1
	s_waitcnt lgkmcnt(7)
	v_mfma_f32_16x16x32_bf16 v[126:129], v[148:151], v[180:183], v[126:129]
	v_mfma_f32_16x16x32_bf16 v[126:129], v[152:155], v[184:187], v[126:129]
	s_waitcnt lgkmcnt(5)
	v_mfma_f32_16x16x32_bf16 v[122:125], v[156:159], v[180:183], v[122:125]
	v_mfma_f32_16x16x32_bf16 v[122:125], v[160:163], v[184:187], v[122:125]
	s_waitcnt lgkmcnt(3)
	v_mfma_f32_16x16x32_bf16 v[106:109], v[156:159], v[188:191], v[106:109]
	v_mfma_f32_16x16x32_bf16 v[106:109], v[160:163], v[192:195], v[106:109]
	s_waitcnt lgkmcnt(1)
	v_mfma_f32_16x16x32_bf16 v[110:113], v[148:151], v[188:191], v[110:113]
	v_mfma_f32_16x16x32_bf16 v[110:113], v[152:155], v[192:195], v[110:113]
	v_mfma_f32_16x16x32_bf16 v[94:97], v[148:151], v[196:199], v[94:97]
	v_mfma_f32_16x16x32_bf16 v[94:97], v[152:155], v[200:203], v[94:97]
	v_mfma_f32_16x16x32_bf16 v[90:93], v[156:159], v[196:199], v[90:93]
	v_mfma_f32_16x16x32_bf16 v[90:93], v[160:163], v[200:203], v[90:93]
	v_mfma_f32_16x16x32_bf16 v[74:77], v[156:159], v[204:207], v[74:77]
	v_mfma_f32_16x16x32_bf16 v[74:77], v[160:163], v[208:211], v[74:77]
	s_waitcnt lgkmcnt(0)
	v_mfma_f32_16x16x32_bf16 v[78:81], v[148:151], v[204:207], v[78:81]
	v_mfma_f32_16x16x32_bf16 v[78:81], v[152:155], v[208:211], v[78:81]
	s_setprio 0
	s_setprio 1
	v_mfma_f32_16x16x32_bf16 v[118:121], v[164:167], v[180:183], v[118:121]
	v_mfma_f32_16x16x32_bf16 v[118:121], v[168:171], v[184:187], v[118:121]
	v_mfma_f32_16x16x32_bf16 v[114:117], v[172:175], v[180:183], v[114:117]
	v_mfma_f32_16x16x32_bf16 v[114:117], v[176:179], v[184:187], v[114:117]
	v_mfma_f32_16x16x32_bf16 v[98:101], v[172:175], v[188:191], v[98:101]
	v_mfma_f32_16x16x32_bf16 v[98:101], v[176:179], v[192:195], v[98:101]
	v_mfma_f32_16x16x32_bf16 v[102:105], v[164:167], v[188:191], v[102:105]
	v_mfma_f32_16x16x32_bf16 v[102:105], v[168:171], v[192:195], v[102:105]
	v_mfma_f32_16x16x32_bf16 v[86:89], v[164:167], v[196:199], v[86:89]
	v_mfma_f32_16x16x32_bf16 v[86:89], v[168:171], v[200:203], v[86:89]
	v_mfma_f32_16x16x32_bf16 v[82:85], v[172:175], v[196:199], v[82:85]
	v_mfma_f32_16x16x32_bf16 v[82:85], v[176:179], v[200:203], v[82:85]
	s_setprio 2
	s_barrier
	v_mfma_f32_16x16x32_bf16 v[66:69], v[172:175], v[204:207], v[66:69]
	v_mfma_f32_16x16x32_bf16 v[66:69], v[176:179], v[208:211], v[66:69]
	v_mfma_f32_16x16x32_bf16 v[70:73], v[164:167], v[204:207], v[70:73]
	v_mfma_f32_16x16x32_bf16 v[70:73], v[168:171], v[208:211], v[70:73]
	s_setprio 0
	ds_read_b128 v[180:183], v145 offset:49152
	ds_read_b128 v[184:187], v145 offset:50176
	ds_read_b128 v[188:191], v145 offset:51200
	ds_read_b128 v[192:195], v145 offset:52224
	ds_read_b128 v[196:199], v145 offset:53248
	ds_read_b128 v[200:203], v145 offset:54272
	ds_read_b128 v[204:207], v145 offset:55296
	ds_read_b128 v[208:211], v145 offset:56320
	s_add_u32 s22, s20, 0x80
	s_addc_u32 s23, s21, 0
	s_mov_b32 s71, m0
	s_mov_b32 m0, s44
	s_nop 0
	global_load_lds_dwordx4 v139, s[22:23]
	s_mov_b32 m0, s71
	s_add_u32 s20, s20, 0x80080
	s_mov_b32 s71, m0
	s_mov_b32 m0, s45
	s_nop 0
	global_load_lds_dwordx4 v141, s[22:23]
	s_mov_b32 m0, s71
	s_addc_u32 s21, s21, 0
	s_mov_b32 s22, m0
	s_mov_b32 m0, s46
	s_nop 0
	global_load_lds_dwordx4 v139, s[20:21]
	s_mov_b32 m0, s22
	s_nop 0
	s_mov_b32 s22, m0
	s_mov_b32 m0, s47
	s_nop 0
	global_load_lds_dwordx4 v141, s[20:21]
	s_mov_b32 m0, s22
	s_waitcnt vmcnt(4)
	s_waitcnt lgkmcnt(0)
	s_barrier
	s_setprio 1
	s_waitcnt lgkmcnt(7)
	v_mfma_f32_16x16x32_bf16 v[62:65], v[148:151], v[180:183], v[62:65]
	v_mfma_f32_16x16x32_bf16 v[62:65], v[152:155], v[184:187], v[62:65]
	s_waitcnt lgkmcnt(5)
	v_mfma_f32_16x16x32_bf16 v[58:61], v[156:159], v[180:183], v[58:61]
	v_mfma_f32_16x16x32_bf16 v[58:61], v[160:163], v[184:187], v[58:61]
	s_waitcnt lgkmcnt(3)
	v_mfma_f32_16x16x32_bf16 v[42:45], v[156:159], v[188:191], v[42:45]
	v_mfma_f32_16x16x32_bf16 v[42:45], v[160:163], v[192:195], v[42:45]
	s_waitcnt lgkmcnt(1)
	v_mfma_f32_16x16x32_bf16 v[46:49], v[148:151], v[188:191], v[46:49]
	v_mfma_f32_16x16x32_bf16 v[46:49], v[152:155], v[192:195], v[46:49]
	v_mfma_f32_16x16x32_bf16 v[30:33], v[148:151], v[196:199], v[30:33]
	v_mfma_f32_16x16x32_bf16 v[30:33], v[152:155], v[200:203], v[30:33]
	v_mfma_f32_16x16x32_bf16 v[26:29], v[156:159], v[196:199], v[26:29]
	v_mfma_f32_16x16x32_bf16 v[26:29], v[160:163], v[200:203], v[26:29]
	v_mfma_f32_16x16x32_bf16 v[10:13], v[156:159], v[204:207], v[10:13]
	v_mfma_f32_16x16x32_bf16 v[10:13], v[160:163], v[208:211], v[10:13]
	s_waitcnt lgkmcnt(0)
	v_mfma_f32_16x16x32_bf16 v[14:17], v[148:151], v[204:207], v[14:17]
	v_mfma_f32_16x16x32_bf16 v[14:17], v[152:155], v[208:211], v[14:17]
	s_setprio 0
	s_setprio 1
	v_mfma_f32_16x16x32_bf16 v[54:57], v[164:167], v[180:183], v[54:57]
	v_mfma_f32_16x16x32_bf16 v[54:57], v[168:171], v[184:187], v[54:57]
	v_mfma_f32_16x16x32_bf16 v[50:53], v[172:175], v[180:183], v[50:53]
	v_mfma_f32_16x16x32_bf16 v[50:53], v[176:179], v[184:187], v[50:53]
	v_mfma_f32_16x16x32_bf16 v[34:37], v[172:175], v[188:191], v[34:37]
	v_mfma_f32_16x16x32_bf16 v[34:37], v[176:179], v[192:195], v[34:37]
	v_mfma_f32_16x16x32_bf16 v[38:41], v[164:167], v[188:191], v[38:41]
	v_mfma_f32_16x16x32_bf16 v[38:41], v[168:171], v[192:195], v[38:41]
	v_mfma_f32_16x16x32_bf16 v[22:25], v[164:167], v[196:199], v[22:25]
	v_mfma_f32_16x16x32_bf16 v[22:25], v[168:171], v[200:203], v[22:25]
	v_mfma_f32_16x16x32_bf16 v[18:21], v[172:175], v[196:199], v[18:21]
	v_mfma_f32_16x16x32_bf16 v[18:21], v[176:179], v[200:203], v[18:21]
	s_setprio 2
	s_barrier
	v_mfma_f32_16x16x32_bf16 v[2:5], v[172:175], v[204:207], v[2:5]
	v_mfma_f32_16x16x32_bf16 v[2:5], v[176:179], v[208:211], v[2:5]
	v_mfma_f32_16x16x32_bf16 v[6:9], v[164:167], v[204:207], v[6:9]
	v_mfma_f32_16x16x32_bf16 v[6:9], v[168:171], v[208:211], v[6:9]
	s_setprio 0
	s_add_i32 s70, s70, 2
	s_add_u32 s64, s64, 0x100
	s_addc_u32 s65, s65, 0
	s_add_u32 s18, s18, 0x100
	s_addc_u32 s19, s19, 0
	s_add_u32 s66, s66, 0x100
	s_addc_u32 s67, s67, 0
	s_cmp_gt_u32 s70, 29
	s_cbranch_scc0 .LBB0_2594
	s_and_b64 vcc, exec, s[6:7]
	s_cbranch_vccz .LBB0_2597
	s_barrier

.LBB0_2791:
	s_ashr_i32 s21, s20, 31
	s_lshl_b64 s[22:23], s[20:21], 15
	s_add_u32 s22, s37, s22
	s_addc_u32 s23, s40, s23
	s_and_b64 s[24:25], s[2:3], exec
	s_cselect_b32 s21, s23, s31
	s_cselect_b32 s63, s22, s30
	s_ashr_i32 s19, s18, 31
	s_lshl_b64 s[24:25], s[18:19], 15
	s_add_u32 s24, s41, s24
	s_addc_u32 s25, s42, s25
	s_and_b64 s[34:35], s[2:3], exec
	s_cselect_b32 s19, s25, s29
	s_cselect_b32 s64, s24, s28
	s_add_u32 s65, s28, 0x80000
	s_addc_u32 s66, s29, 0
	s_add_u32 s28, s30, 0x204000
	s_addc_u32 s29, s31, 0
	s_add_u32 s67, s30, 0x400000
	s_addc_u32 s68, s31, 0
	s_mov_b32 s69, -2
	s_waitcnt vmcnt(25)
	s_waitcnt vmcnt(24)
	s_waitcnt vmcnt(4)
	s_waitcnt vmcnt(2)
	s_waitcnt vmcnt(1)
	s_waitcnt vmcnt(0)
	ds_read_b128 v[130:133], v181
	ds_read_b128 v[134:137], v181 offset:1024
	ds_read_b128 v[138:141], v181 offset:2048
	ds_read_b128 v[142:145], v181 offset:3072
	ds_read_b128 v[150:153], v182
	ds_read_b128 v[154:157], v182 offset:1024
	ds_read_b128 v[158:161], v182 offset:2048
	ds_read_b128 v[162:165], v182 offset:3072
	s_cmpk_eq_i32 s69, 0x52
	s_cselect_b32 s31, s19, s66
	s_cselect_b32 s30, s64, s65
	s_cselect_b32 s35, s21, s68
	s_cselect_b32 s34, s63, s67
	ds_read_b128 v[166:169], v183
	ds_read_b128 v[170:173], v183 offset:1024
	ds_read_b128 v[186:189], v183 offset:2048
	ds_read_b128 v[190:193], v183 offset:3072
	ds_read_b128 v[194:197], v183 offset:4096
	ds_read_b128 v[198:201], v183 offset:5120
	ds_read_b128 v[202:205], v183 offset:6144
	ds_read_b128 v[206:209], v183 offset:7168
	s_add_u32 s70, s28, 0xffffc000
	s_addc_u32 s71, s29, -1
	s_mov_b32 s73, m0
	s_mov_b32 m0, s57
	s_nop 0
	global_load_lds_dwordx4 v1, s[70:71]
	s_mov_b32 m0, s73
	s_nop 0
	s_mov_b32 s73, m0
	s_mov_b32 m0, s59
	s_nop 0
	global_load_lds_dwordx4 v177, s[70:71]
	s_mov_b32 m0, s73
	s_mov_b32 s70, m0
	s_mov_b32 m0, s58
	s_nop 0
	global_load_lds_dwordx4 v1, s[28:29]
	s_mov_b32 m0, s70
	s_nop 0
	s_mov_b32 s70, m0
	s_mov_b32 m0, s60
	s_nop 0
	global_load_lds_dwordx4 v177, s[28:29]
	s_mov_b32 m0, s70
	s_waitcnt vmcnt(8)
	s_waitcnt lgkmcnt(0)
	s_barrier
	s_setprio 1
	s_waitcnt lgkmcnt(7)
	v_mfma_f32_16x16x32_bf16 v[126:129], v[130:133], v[166:169], 0
	v_mfma_f32_16x16x32_bf16 v[126:129], v[134:137], v[170:173], v[126:129]
	s_waitcnt lgkmcnt(5)
	v_mfma_f32_16x16x32_bf16 v[122:125], v[138:141], v[166:169], 0
	v_mfma_f32_16x16x32_bf16 v[122:125], v[142:145], v[170:173], v[122:125]
	s_waitcnt lgkmcnt(3)
	v_mfma_f32_16x16x32_bf16 v[110:113], v[138:141], v[186:189], 0
	v_mfma_f32_16x16x32_bf16 v[110:113], v[142:145], v[190:193], v[110:113]
	s_waitcnt lgkmcnt(1)
	v_mfma_f32_16x16x32_bf16 v[118:121], v[130:133], v[186:189], 0
	v_mfma_f32_16x16x32_bf16 v[118:121], v[134:137], v[190:193], v[118:121]
	v_mfma_f32_16x16x32_bf16 v[94:97], v[130:133], v[194:197], 0
	v_mfma_f32_16x16x32_bf16 v[94:97], v[134:137], v[198:201], v[94:97]
	v_mfma_f32_16x16x32_bf16 v[90:93], v[138:141], v[194:197], 0
	v_mfma_f32_16x16x32_bf16 v[90:93], v[142:145], v[198:201], v[90:93]
	v_mfma_f32_16x16x32_bf16 v[78:81], v[138:141], v[202:205], 0
	v_mfma_f32_16x16x32_bf16 v[78:81], v[142:145], v[206:209], v[78:81]
	s_waitcnt lgkmcnt(0)
	v_mfma_f32_16x16x32_bf16 v[86:89], v[130:133], v[202:205], 0
	v_mfma_f32_16x16x32_bf16 v[86:89], v[134:137], v[206:209], v[86:89]
	s_setprio 0
	s_setprio 1
	v_mfma_f32_16x16x32_bf16 v[114:117], v[150:153], v[166:169], 0
	v_mfma_f32_16x16x32_bf16 v[114:117], v[154:157], v[170:173], v[114:117]
	v_mfma_f32_16x16x32_bf16 v[106:109], v[158:161], v[166:169], 0
	v_mfma_f32_16x16x32_bf16 v[106:109], v[162:165], v[170:173], v[106:109]
	v_mfma_f32_16x16x32_bf16 v[98:101], v[158:161], v[186:189], 0
	v_mfma_f32_16x16x32_bf16 v[98:101], v[162:165], v[190:193], v[98:101]
	v_mfma_f32_16x16x32_bf16 v[102:105], v[150:153], v[186:189], 0
	v_mfma_f32_16x16x32_bf16 v[102:105], v[154:157], v[190:193], v[102:105]
	v_mfma_f32_16x16x32_bf16 v[82:85], v[150:153], v[194:197], 0
	v_mfma_f32_16x16x32_bf16 v[82:85], v[154:157], v[198:201], v[82:85]
	v_mfma_f32_16x16x32_bf16 v[74:77], v[158:161], v[194:197], 0
	v_mfma_f32_16x16x32_bf16 v[74:77], v[162:165], v[198:201], v[74:77]
	s_setprio 2
	s_barrier
	v_mfma_f32_16x16x32_bf16 v[66:69], v[158:161], v[202:205], 0
	v_mfma_f32_16x16x32_bf16 v[66:69], v[162:165], v[206:209], v[66:69]
	v_mfma_f32_16x16x32_bf16 v[70:73], v[150:153], v[202:205], 0
	v_mfma_f32_16x16x32_bf16 v[70:73], v[154:157], v[206:209], v[70:73]
	s_setprio 0
	ds_read_b128 v[166:169], v183 offset:16384
	ds_read_b128 v[170:173], v183 offset:17408
	ds_read_b128 v[186:189], v183 offset:18432
	ds_read_b128 v[190:193], v183 offset:19456
	ds_read_b128 v[194:197], v183 offset:20480
	ds_read_b128 v[198:201], v183 offset:21504
	ds_read_b128 v[202:205], v183 offset:22528
	ds_read_b128 v[206:209], v183 offset:23552
	s_mov_b32 s70, m0
	s_mov_b32 m0, s27
	s_nop 0
	global_load_lds_dwordx4 v176, s[30:31]
	s_mov_b32 m0, s70
	s_nop 0
	s_mov_b32 s70, m0
	s_mov_b32 m0, s45
	s_nop 0
	global_load_lds_dwordx4 v178, s[30:31]
	s_mov_b32 m0, s70
	s_add_u32 s70, s30, 0x4000
	s_addc_u32 s71, s31, 0
	s_mov_b32 s73, m0
	s_mov_b32 m0, s46
	s_nop 0
	global_load_lds_dwordx4 v176, s[70:71]
	s_mov_b32 m0, s73
	s_nop 0
	s_mov_b32 s73, m0
	s_mov_b32 m0, s47
	s_nop 0
	global_load_lds_dwordx4 v178, s[70:71]
	s_mov_b32 m0, s73
	s_waitcnt vmcnt(4)
	s_waitcnt lgkmcnt(0)
	s_barrier
	s_setprio 1
	s_waitcnt lgkmcnt(7)
	v_mfma_f32_16x16x32_bf16 v[62:65], v[130:133], v[166:169], 0
	v_mfma_f32_16x16x32_bf16 v[62:65], v[134:137], v[170:173], v[62:65]
	s_waitcnt lgkmcnt(5)
	v_mfma_f32_16x16x32_bf16 v[58:61], v[138:141], v[166:169], 0
	v_mfma_f32_16x16x32_bf16 v[58:61], v[142:145], v[170:173], v[58:61]
	s_waitcnt lgkmcnt(3)
	v_mfma_f32_16x16x32_bf16 v[42:45], v[138:141], v[186:189], 0
	v_mfma_f32_16x16x32_bf16 v[42:45], v[142:145], v[190:193], v[42:45]
	s_waitcnt lgkmcnt(1)
	v_mfma_f32_16x16x32_bf16 v[46:49], v[130:133], v[186:189], 0
	v_mfma_f32_16x16x32_bf16 v[46:49], v[134:137], v[190:193], v[46:49]
	v_mfma_f32_16x16x32_bf16 v[30:33], v[130:133], v[194:197], 0
	v_mfma_f32_16x16x32_bf16 v[30:33], v[134:137], v[198:201], v[30:33]
	v_mfma_f32_16x16x32_bf16 v[26:29], v[138:141], v[194:197], 0
	v_mfma_f32_16x16x32_bf16 v[26:29], v[142:145], v[198:201], v[26:29]
	v_mfma_f32_16x16x32_bf16 v[10:13], v[138:141], v[202:205], 0
	v_mfma_f32_16x16x32_bf16 v[10:13], v[142:145], v[206:209], v[10:13]
	s_waitcnt lgkmcnt(0)
	v_mfma_f32_16x16x32_bf16 v[14:17], v[130:133], v[202:205], 0
	v_mfma_f32_16x16x32_bf16 v[14:17], v[134:137], v[206:209], v[14:17]
	s_setprio 0
	s_setprio 1
	v_mfma_f32_16x16x32_bf16 v[54:57], v[150:153], v[166:169], 0
	v_mfma_f32_16x16x32_bf16 v[54:57], v[154:157], v[170:173], v[54:57]
	v_mfma_f32_16x16x32_bf16 v[50:53], v[158:161], v[166:169], 0
	v_mfma_f32_16x16x32_bf16 v[50:53], v[162:165], v[170:173], v[50:53]
	v_mfma_f32_16x16x32_bf16 v[34:37], v[158:161], v[186:189], 0
	v_mfma_f32_16x16x32_bf16 v[34:37], v[162:165], v[190:193], v[34:37]
	v_mfma_f32_16x16x32_bf16 v[38:41], v[150:153], v[186:189], 0
	v_mfma_f32_16x16x32_bf16 v[38:41], v[154:157], v[190:193], v[38:41]
	v_mfma_f32_16x16x32_bf16 v[22:25], v[150:153], v[194:197], 0
	v_mfma_f32_16x16x32_bf16 v[22:25], v[154:157], v[198:201], v[22:25]
	v_mfma_f32_16x16x32_bf16 v[18:21], v[158:161], v[194:197], 0
	v_mfma_f32_16x16x32_bf16 v[18:21], v[162:165], v[198:201], v[18:21]
	s_setprio 2
	s_barrier
	v_mfma_f32_16x16x32_bf16 v[2:5], v[158:161], v[202:205], 0
	v_mfma_f32_16x16x32_bf16 v[2:5], v[162:165], v[206:209], v[2:5]
	v_mfma_f32_16x16x32_bf16 v[6:9], v[150:153], v[202:205], 0
	v_mfma_f32_16x16x32_bf16 v[6:9], v[154:157], v[206:209], v[6:9]
	s_setprio 0
	ds_read_b128 v[130:133], v184
	ds_read_b128 v[134:137], v184 offset:1024
	ds_read_b128 v[138:141], v184 offset:2048
	ds_read_b128 v[142:145], v184 offset:3072
	ds_read_b128 v[150:153], v185
	ds_read_b128 v[154:157], v185 offset:1024
	ds_read_b128 v[158:161], v185 offset:2048
	ds_read_b128 v[162:165], v185 offset:3072
	ds_read_b128 v[166:169], v183 offset:32768
	ds_read_b128 v[170:173], v183 offset:33792
	ds_read_b128 v[186:189], v183 offset:34816
	ds_read_b128 v[190:193], v183 offset:35840
	ds_read_b128 v[194:197], v183 offset:36864
	ds_read_b128 v[198:201], v183 offset:37888
	ds_read_b128 v[202:205], v183 offset:38912
	ds_read_b128 v[206:209], v183 offset:39936
	s_mov_b32 s70, m0
	s_mov_b32 m0, s44
	s_nop 0
	global_load_lds_dwordx4 v1, s[34:35]
	s_mov_b32 m0, s70
	s_nop 0
	s_mov_b32 s70, m0
	s_mov_b32 m0, s48
	s_nop 0
	global_load_lds_dwordx4 v177, s[34:35]
	s_mov_b32 m0, s70
	s_add_u32 s34, s34, 0x4000
	s_addc_u32 s35, s35, 0
	s_mov_b32 s70, m0
	s_mov_b32 m0, s49
	s_nop 0
	global_load_lds_dwordx4 v1, s[34:35]
	s_mov_b32 m0, s70
	s_nop 0
	s_mov_b32 s70, m0
	s_mov_b32 m0, s50
	s_nop 0
	global_load_lds_dwordx4 v177, s[34:35]
	s_mov_b32 m0, s70
	s_waitcnt vmcnt(8)
	s_waitcnt lgkmcnt(0)
	s_barrier
	s_setprio 1
	s_waitcnt lgkmcnt(7)
	v_mfma_f32_16x16x32_bf16 v[126:129], v[130:133], v[166:169], v[126:129]
	v_mfma_f32_16x16x32_bf16 v[126:129], v[134:137], v[170:173], v[126:129]
	s_waitcnt lgkmcnt(5)
	v_mfma_f32_16x16x32_bf16 v[122:125], v[138:141], v[166:169], v[122:125]
	v_mfma_f32_16x16x32_bf16 v[122:125], v[142:145], v[170:173], v[122:125]
	s_waitcnt lgkmcnt(3)
	v_mfma_f32_16x16x32_bf16 v[110:113], v[138:141], v[186:189], v[110:113]
	v_mfma_f32_16x16x32_bf16 v[110:113], v[142:145], v[190:193], v[110:113]
	s_waitcnt lgkmcnt(1)
	v_mfma_f32_16x16x32_bf16 v[118:121], v[130:133], v[186:189], v[118:121]
	v_mfma_f32_16x16x32_bf16 v[118:121], v[134:137], v[190:193], v[118:121]
	v_mfma_f32_16x16x32_bf16 v[94:97], v[130:133], v[194:197], v[94:97]
	v_mfma_f32_16x16x32_bf16 v[94:97], v[134:137], v[198:201], v[94:97]
	v_mfma_f32_16x16x32_bf16 v[90:93], v[138:141], v[194:197], v[90:93]
	v_mfma_f32_16x16x32_bf16 v[90:93], v[142:145], v[198:201], v[90:93]
	v_mfma_f32_16x16x32_bf16 v[78:81], v[138:141], v[202:205], v[78:81]
	v_mfma_f32_16x16x32_bf16 v[78:81], v[142:145], v[206:209], v[78:81]
	s_waitcnt lgkmcnt(0)
	v_mfma_f32_16x16x32_bf16 v[86:89], v[130:133], v[202:205], v[86:89]
	v_mfma_f32_16x16x32_bf16 v[86:89], v[134:137], v[206:209], v[86:89]
	s_setprio 0
	s_setprio 1
	v_mfma_f32_16x16x32_bf16 v[114:117], v[150:153], v[166:169], v[114:117]
	v_mfma_f32_16x16x32_bf16 v[114:117], v[154:157], v[170:173], v[114:117]
	v_mfma_f32_16x16x32_bf16 v[106:109], v[158:161], v[166:169], v[106:109]
	v_mfma_f32_16x16x32_bf16 v[106:109], v[162:165], v[170:173], v[106:109]
	v_mfma_f32_16x16x32_bf16 v[98:101], v[158:161], v[186:189], v[98:101]
	v_mfma_f32_16x16x32_bf16 v[98:101], v[162:165], v[190:193], v[98:101]
	v_mfma_f32_16x16x32_bf16 v[102:105], v[150:153], v[186:189], v[102:105]
	v_mfma_f32_16x16x32_bf16 v[102:105], v[154:157], v[190:193], v[102:105]
	v_mfma_f32_16x16x32_bf16 v[82:85], v[150:153], v[194:197], v[82:85]
	v_mfma_f32_16x16x32_bf16 v[82:85], v[154:157], v[198:201], v[82:85]
	v_mfma_f32_16x16x32_bf16 v[74:77], v[158:161], v[194:197], v[74:77]
	v_mfma_f32_16x16x32_bf16 v[74:77], v[162:165], v[198:201], v[74:77]
	s_setprio 2
	s_barrier
	v_mfma_f32_16x16x32_bf16 v[66:69], v[158:161], v[202:205], v[66:69]
	v_mfma_f32_16x16x32_bf16 v[66:69], v[162:165], v[206:209], v[66:69]
	v_mfma_f32_16x16x32_bf16 v[70:73], v[150:153], v[202:205], v[70:73]
	v_mfma_f32_16x16x32_bf16 v[70:73], v[154:157], v[206:209], v[70:73]
	s_setprio 0
	ds_read_b128 v[166:169], v183 offset:49152
	ds_read_b128 v[170:173], v183 offset:50176
	ds_read_b128 v[186:189], v183 offset:51200
	ds_read_b128 v[190:193], v183 offset:52224
	ds_read_b128 v[194:197], v183 offset:53248
	ds_read_b128 v[198:201], v183 offset:54272
	ds_read_b128 v[202:205], v183 offset:55296
	ds_read_b128 v[206:209], v183 offset:56320
	s_add_u32 s34, s30, 0x40000
	s_addc_u32 s35, s31, 0
	s_mov_b32 s70, m0
	s_mov_b32 m0, s51
	s_nop 0
	global_load_lds_dwordx4 v176, s[34:35]
	s_mov_b32 m0, s70
	s_add_u32 s30, s30, 0x44000
	s_mov_b32 s70, m0
	s_mov_b32 m0, s52
	s_nop 0
	global_load_lds_dwordx4 v178, s[34:35]
	s_mov_b32 m0, s70
	s_addc_u32 s31, s31, 0
	s_mov_b32 s34, m0
	s_mov_b32 m0, s53
	s_nop 0
	global_load_lds_dwordx4 v176, s[30:31]
	s_mov_b32 m0, s34
	s_nop 0
	s_mov_b32 s34, m0
	s_mov_b32 m0, s54
	s_nop 0
	global_load_lds_dwordx4 v178, s[30:31]
	s_mov_b32 m0, s34
	s_waitcnt vmcnt(4)
	s_waitcnt lgkmcnt(0)
	s_barrier
	s_setprio 1
	s_waitcnt lgkmcnt(7)
	v_mfma_f32_16x16x32_bf16 v[62:65], v[130:133], v[166:169], v[62:65]
	v_mfma_f32_16x16x32_bf16 v[62:65], v[134:137], v[170:173], v[62:65]
	s_waitcnt lgkmcnt(5)
	v_mfma_f32_16x16x32_bf16 v[58:61], v[138:141], v[166:169], v[58:61]
	v_mfma_f32_16x16x32_bf16 v[58:61], v[142:145], v[170:173], v[58:61]
	s_waitcnt lgkmcnt(3)
	v_mfma_f32_16x16x32_bf16 v[42:45], v[138:141], v[186:189], v[42:45]
	v_mfma_f32_16x16x32_bf16 v[42:45], v[142:145], v[190:193], v[42:45]
	s_waitcnt lgkmcnt(1)
	v_mfma_f32_16x16x32_bf16 v[46:49], v[130:133], v[186:189], v[46:49]
	v_mfma_f32_16x16x32_bf16 v[46:49], v[134:137], v[190:193], v[46:49]
	v_mfma_f32_16x16x32_bf16 v[30:33], v[130:133], v[194:197], v[30:33]
	v_mfma_f32_16x16x32_bf16 v[30:33], v[134:137], v[198:201], v[30:33]
	v_mfma_f32_16x16x32_bf16 v[26:29], v[138:141], v[194:197], v[26:29]
	v_mfma_f32_16x16x32_bf16 v[26:29], v[142:145], v[198:201], v[26:29]
	v_mfma_f32_16x16x32_bf16 v[10:13], v[138:141], v[202:205], v[10:13]
	v_mfma_f32_16x16x32_bf16 v[10:13], v[142:145], v[206:209], v[10:13]
	s_waitcnt lgkmcnt(0)
	v_mfma_f32_16x16x32_bf16 v[14:17], v[130:133], v[202:205], v[14:17]
	v_mfma_f32_16x16x32_bf16 v[14:17], v[134:137], v[206:209], v[14:17]
	s_setprio 0
	s_setprio 1
	v_mfma_f32_16x16x32_bf16 v[54:57], v[150:153], v[166:169], v[54:57]
	v_mfma_f32_16x16x32_bf16 v[54:57], v[154:157], v[170:173], v[54:57]
	v_mfma_f32_16x16x32_bf16 v[50:53], v[158:161], v[166:169], v[50:53]
	v_mfma_f32_16x16x32_bf16 v[50:53], v[162:165], v[170:173], v[50:53]
	v_mfma_f32_16x16x32_bf16 v[34:37], v[158:161], v[186:189], v[34:37]
	v_mfma_f32_16x16x32_bf16 v[34:37], v[162:165], v[190:193], v[34:37]
	v_mfma_f32_16x16x32_bf16 v[38:41], v[150:153], v[186:189], v[38:41]
	v_mfma_f32_16x16x32_bf16 v[38:41], v[154:157], v[190:193], v[38:41]
	v_mfma_f32_16x16x32_bf16 v[22:25], v[150:153], v[194:197], v[22:25]
	v_mfma_f32_16x16x32_bf16 v[22:25], v[154:157], v[198:201], v[22:25]
	v_mfma_f32_16x16x32_bf16 v[18:21], v[158:161], v[194:197], v[18:21]
	v_mfma_f32_16x16x32_bf16 v[18:21], v[162:165], v[198:201], v[18:21]
	s_setprio 2
	s_barrier
	v_mfma_f32_16x16x32_bf16 v[2:5], v[158:161], v[202:205], v[2:5]
	v_mfma_f32_16x16x32_bf16 v[2:5], v[162:165], v[206:209], v[2:5]
	v_mfma_f32_16x16x32_bf16 v[6:9], v[150:153], v[202:205], v[6:9]
	v_mfma_f32_16x16x32_bf16 v[6:9], v[154:157], v[206:209], v[6:9]
	s_setprio 0
	s_add_i32 s69, s69, 2
	s_add_u32 s65, s65, 0x80000
	s_addc_u32 s66, s66, 0
	s_add_u32 s28, s28, 0x400000
	s_addc_u32 s29, s29, 0
	s_add_u32 s67, s67, 0x400000
	s_addc_u32 s68, s68, 0
	s_cmpk_gt_u32 s69, 0x53
	.p2align 6
.LBB0_2792:
	ds_read_b128 v[130:133], v181
	ds_read_b128 v[134:137], v181 offset:1024
	ds_read_b128 v[138:141], v181 offset:2048
	ds_read_b128 v[142:145], v181 offset:3072
	ds_read_b128 v[150:153], v182
	ds_read_b128 v[154:157], v182 offset:1024
	ds_read_b128 v[158:161], v182 offset:2048
	ds_read_b128 v[162:165], v182 offset:3072
	s_cmpk_eq_i32 s69, 0x52
	s_cselect_b32 s31, s19, s66
	s_cselect_b32 s30, s64, s65
	s_cselect_b32 s35, s21, s68
	s_cselect_b32 s34, s63, s67
	ds_read_b128 v[166:169], v183
	ds_read_b128 v[170:173], v183 offset:1024
	ds_read_b128 v[186:189], v183 offset:2048
	ds_read_b128 v[190:193], v183 offset:3072
	ds_read_b128 v[194:197], v183 offset:4096
	ds_read_b128 v[198:201], v183 offset:5120
	ds_read_b128 v[202:205], v183 offset:6144
	ds_read_b128 v[206:209], v183 offset:7168
	s_add_u32 s70, s28, 0xffffc000
	s_addc_u32 s71, s29, -1
	s_mov_b32 s73, m0
	s_mov_b32 m0, s57
	s_nop 0
	global_load_lds_dwordx4 v1, s[70:71]
	s_mov_b32 m0, s73
	s_nop 0
	s_mov_b32 s73, m0
	s_mov_b32 m0, s59
	s_nop 0
	global_load_lds_dwordx4 v177, s[70:71]
	s_mov_b32 m0, s73
	s_mov_b32 s70, m0
	s_mov_b32 m0, s58
	s_nop 0
	global_load_lds_dwordx4 v1, s[28:29]
	s_mov_b32 m0, s70
	s_nop 0
	s_mov_b32 s70, m0
	s_mov_b32 m0, s60
	s_nop 0
	global_load_lds_dwordx4 v177, s[28:29]
	s_mov_b32 m0, s70
	s_waitcnt vmcnt(8)
	s_waitcnt lgkmcnt(0)
	s_barrier
	s_setprio 1
	s_waitcnt lgkmcnt(7)
	v_mfma_f32_16x16x32_bf16 v[126:129], v[130:133], v[166:169], v[126:129]
	v_mfma_f32_16x16x32_bf16 v[126:129], v[134:137], v[170:173], v[126:129]
	s_waitcnt lgkmcnt(5)
	v_mfma_f32_16x16x32_bf16 v[122:125], v[138:141], v[166:169], v[122:125]
	v_mfma_f32_16x16x32_bf16 v[122:125], v[142:145], v[170:173], v[122:125]
	s_waitcnt lgkmcnt(3)
	v_mfma_f32_16x16x32_bf16 v[110:113], v[138:141], v[186:189], v[110:113]
	v_mfma_f32_16x16x32_bf16 v[110:113], v[142:145], v[190:193], v[110:113]
	s_waitcnt lgkmcnt(1)
	v_mfma_f32_16x16x32_bf16 v[118:121], v[130:133], v[186:189], v[118:121]
	v_mfma_f32_16x16x32_bf16 v[118:121], v[134:137], v[190:193], v[118:121]
	v_mfma_f32_16x16x32_bf16 v[94:97], v[130:133], v[194:197], v[94:97]
	v_mfma_f32_16x16x32_bf16 v[94:97], v[134:137], v[198:201], v[94:97]
	v_mfma_f32_16x16x32_bf16 v[90:93], v[138:141], v[194:197], v[90:93]
	v_mfma_f32_16x16x32_bf16 v[90:93], v[142:145], v[198:201], v[90:93]
	v_mfma_f32_16x16x32_bf16 v[78:81], v[138:141], v[202:205], v[78:81]
	v_mfma_f32_16x16x32_bf16 v[78:81], v[142:145], v[206:209], v[78:81]
	s_waitcnt lgkmcnt(0)
	v_mfma_f32_16x16x32_bf16 v[86:89], v[130:133], v[202:205], v[86:89]
	v_mfma_f32_16x16x32_bf16 v[86:89], v[134:137], v[206:209], v[86:89]
	s_setprio 0
	s_setprio 1
	v_mfma_f32_16x16x32_bf16 v[114:117], v[150:153], v[166:169], v[114:117]
	v_mfma_f32_16x16x32_bf16 v[114:117], v[154:157], v[170:173], v[114:117]
	v_mfma_f32_16x16x32_bf16 v[106:109], v[158:161], v[166:169], v[106:109]
	v_mfma_f32_16x16x32_bf16 v[106:109], v[162:165], v[170:173], v[106:109]
	v_mfma_f32_16x16x32_bf16 v[98:101], v[158:161], v[186:189], v[98:101]
	v_mfma_f32_16x16x32_bf16 v[98:101], v[162:165], v[190:193], v[98:101]
	v_mfma_f32_16x16x32_bf16 v[102:105], v[150:153], v[186:189], v[102:105]
	v_mfma_f32_16x16x32_bf16 v[102:105], v[154:157], v[190:193], v[102:105]
	v_mfma_f32_16x16x32_bf16 v[82:85], v[150:153], v[194:197], v[82:85]
	v_mfma_f32_16x16x32_bf16 v[82:85], v[154:157], v[198:201], v[82:85]
	v_mfma_f32_16x16x32_bf16 v[74:77], v[158:161], v[194:197], v[74:77]
	v_mfma_f32_16x16x32_bf16 v[74:77], v[162:165], v[198:201], v[74:77]
	s_setprio 2
	s_barrier
	v_mfma_f32_16x16x32_bf16 v[66:69], v[158:161], v[202:205], v[66:69]
	v_mfma_f32_16x16x32_bf16 v[66:69], v[162:165], v[206:209], v[66:69]
	v_mfma_f32_16x16x32_bf16 v[70:73], v[150:153], v[202:205], v[70:73]
	v_mfma_f32_16x16x32_bf16 v[70:73], v[154:157], v[206:209], v[70:73]
	s_setprio 0
	ds_read_b128 v[166:169], v183 offset:16384
	ds_read_b128 v[170:173], v183 offset:17408
	ds_read_b128 v[186:189], v183 offset:18432
	ds_read_b128 v[190:193], v183 offset:19456
	ds_read_b128 v[194:197], v183 offset:20480
	ds_read_b128 v[198:201], v183 offset:21504
	ds_read_b128 v[202:205], v183 offset:22528
	ds_read_b128 v[206:209], v183 offset:23552
	s_mov_b32 s70, m0
	s_mov_b32 m0, s27
	s_nop 0
	global_load_lds_dwordx4 v176, s[30:31]
	s_mov_b32 m0, s70
	s_nop 0
	s_mov_b32 s70, m0
	s_mov_b32 m0, s45
	s_nop 0
	global_load_lds_dwordx4 v178, s[30:31]
	s_mov_b32 m0, s70
	s_add_u32 s70, s30, 0x4000
	s_addc_u32 s71, s31, 0
	s_mov_b32 s73, m0
	s_mov_b32 m0, s46
	s_nop 0
	global_load_lds_dwordx4 v176, s[70:71]
	s_mov_b32 m0, s73
	s_nop 0
	s_mov_b32 s73, m0
	s_mov_b32 m0, s47
	s_nop 0
	global_load_lds_dwordx4 v178, s[70:71]
	s_mov_b32 m0, s73
	s_waitcnt vmcnt(4)
	s_waitcnt lgkmcnt(0)
	s_barrier
	s_setprio 1
	s_waitcnt lgkmcnt(7)
	v_mfma_f32_16x16x32_bf16 v[62:65], v[130:133], v[166:169], v[62:65]
	v_mfma_f32_16x16x32_bf16 v[62:65], v[134:137], v[170:173], v[62:65]
	s_waitcnt lgkmcnt(5)
	v_mfma_f32_16x16x32_bf16 v[58:61], v[138:141], v[166:169], v[58:61]
	v_mfma_f32_16x16x32_bf16 v[58:61], v[142:145], v[170:173], v[58:61]
	s_waitcnt lgkmcnt(3)
	v_mfma_f32_16x16x32_bf16 v[42:45], v[138:141], v[186:189], v[42:45]
	v_mfma_f32_16x16x32_bf16 v[42:45], v[142:145], v[190:193], v[42:45]
	s_waitcnt lgkmcnt(1)
	v_mfma_f32_16x16x32_bf16 v[46:49], v[130:133], v[186:189], v[46:49]
	v_mfma_f32_16x16x32_bf16 v[46:49], v[134:137], v[190:193], v[46:49]
	v_mfma_f32_16x16x32_bf16 v[30:33], v[130:133], v[194:197], v[30:33]
	v_mfma_f32_16x16x32_bf16 v[30:33], v[134:137], v[198:201], v[30:33]
	v_mfma_f32_16x16x32_bf16 v[26:29], v[138:141], v[194:197], v[26:29]
	v_mfma_f32_16x16x32_bf16 v[26:29], v[142:145], v[198:201], v[26:29]
	v_mfma_f32_16x16x32_bf16 v[10:13], v[138:141], v[202:205], v[10:13]
	v_mfma_f32_16x16x32_bf16 v[10:13], v[142:145], v[206:209], v[10:13]
	s_waitcnt lgkmcnt(0)
	v_mfma_f32_16x16x32_bf16 v[14:17], v[130:133], v[202:205], v[14:17]
	v_mfma_f32_16x16x32_bf16 v[14:17], v[134:137], v[206:209], v[14:17]
	s_setprio 0
	s_setprio 1
	v_mfma_f32_16x16x32_bf16 v[54:57], v[150:153], v[166:169], v[54:57]
	v_mfma_f32_16x16x32_bf16 v[54:57], v[154:157], v[170:173], v[54:57]
	v_mfma_f32_16x16x32_bf16 v[50:53], v[158:161], v[166:169], v[50:53]
	v_mfma_f32_16x16x32_bf16 v[50:53], v[162:165], v[170:173], v[50:53]
	v_mfma_f32_16x16x32_bf16 v[34:37], v[158:161], v[186:189], v[34:37]
	v_mfma_f32_16x16x32_bf16 v[34:37], v[162:165], v[190:193], v[34:37]
	v_mfma_f32_16x16x32_bf16 v[38:41], v[150:153], v[186:189], v[38:41]
	v_mfma_f32_16x16x32_bf16 v[38:41], v[154:157], v[190:193], v[38:41]
	v_mfma_f32_16x16x32_bf16 v[22:25], v[150:153], v[194:197], v[22:25]
	v_mfma_f32_16x16x32_bf16 v[22:25], v[154:157], v[198:201], v[22:25]
	v_mfma_f32_16x16x32_bf16 v[18:21], v[158:161], v[194:197], v[18:21]
	v_mfma_f32_16x16x32_bf16 v[18:21], v[162:165], v[198:201], v[18:21]
	s_setprio 2
	s_barrier
	v_mfma_f32_16x16x32_bf16 v[2:5], v[158:161], v[202:205], v[2:5]
	v_mfma_f32_16x16x32_bf16 v[2:5], v[162:165], v[206:209], v[2:5]
	v_mfma_f32_16x16x32_bf16 v[6:9], v[150:153], v[202:205], v[6:9]
	v_mfma_f32_16x16x32_bf16 v[6:9], v[154:157], v[206:209], v[6:9]
	s_setprio 0
	ds_read_b128 v[130:133], v184
	ds_read_b128 v[134:137], v184 offset:1024
	ds_read_b128 v[138:141], v184 offset:2048
	ds_read_b128 v[142:145], v184 offset:3072
	ds_read_b128 v[150:153], v185
	ds_read_b128 v[154:157], v185 offset:1024
	ds_read_b128 v[158:161], v185 offset:2048
	ds_read_b128 v[162:165], v185 offset:3072
	ds_read_b128 v[166:169], v183 offset:32768
	ds_read_b128 v[170:173], v183 offset:33792
	ds_read_b128 v[186:189], v183 offset:34816
	ds_read_b128 v[190:193], v183 offset:35840
	ds_read_b128 v[194:197], v183 offset:36864
	ds_read_b128 v[198:201], v183 offset:37888
	ds_read_b128 v[202:205], v183 offset:38912
	ds_read_b128 v[206:209], v183 offset:39936
	s_mov_b32 s70, m0
	s_mov_b32 m0, s44
	s_nop 0
	global_load_lds_dwordx4 v1, s[34:35]
	s_mov_b32 m0, s70
	s_nop 0
	s_mov_b32 s70, m0
	s_mov_b32 m0, s48
	s_nop 0
	global_load_lds_dwordx4 v177, s[34:35]
	s_mov_b32 m0, s70
	s_add_u32 s34, s34, 0x4000
	s_addc_u32 s35, s35, 0
	s_mov_b32 s70, m0
	s_mov_b32 m0, s49
	s_nop 0
	global_load_lds_dwordx4 v1, s[34:35]
	s_mov_b32 m0, s70
	s_nop 0
	s_mov_b32 s70, m0
	s_mov_b32 m0, s50
	s_nop 0
	global_load_lds_dwordx4 v177, s[34:35]
	s_mov_b32 m0, s70
	s_waitcnt vmcnt(8)
	s_waitcnt lgkmcnt(0)
	s_barrier
	s_setprio 1
	s_waitcnt lgkmcnt(7)
	v_mfma_f32_16x16x32_bf16 v[126:129], v[130:133], v[166:169], v[126:129]
	v_mfma_f32_16x16x32_bf16 v[126:129], v[134:137], v[170:173], v[126:129]
	s_waitcnt lgkmcnt(5)
	v_mfma_f32_16x16x32_bf16 v[122:125], v[138:141], v[166:169], v[122:125]
	v_mfma_f32_16x16x32_bf16 v[122:125], v[142:145], v[170:173], v[122:125]
	s_waitcnt lgkmcnt(3)
	v_mfma_f32_16x16x32_bf16 v[110:113], v[138:141], v[186:189], v[110:113]
	v_mfma_f32_16x16x32_bf16 v[110:113], v[142:145], v[190:193], v[110:113]
	s_waitcnt lgkmcnt(1)
	v_mfma_f32_16x16x32_bf16 v[118:121], v[130:133], v[186:189], v[118:121]
	v_mfma_f32_16x16x32_bf16 v[118:121], v[134:137], v[190:193], v[118:121]
	v_mfma_f32_16x16x32_bf16 v[94:97], v[130:133], v[194:197], v[94:97]
	v_mfma_f32_16x16x32_bf16 v[94:97], v[134:137], v[198:201], v[94:97]
	v_mfma_f32_16x16x32_bf16 v[90:93], v[138:141], v[194:197], v[90:93]
	v_mfma_f32_16x16x32_bf16 v[90:93], v[142:145], v[198:201], v[90:93]
	v_mfma_f32_16x16x32_bf16 v[78:81], v[138:141], v[202:205], v[78:81]
	v_mfma_f32_16x16x32_bf16 v[78:81], v[142:145], v[206:209], v[78:81]
	s_waitcnt lgkmcnt(0)
	v_mfma_f32_16x16x32_bf16 v[86:89], v[130:133], v[202:205], v[86:89]
	v_mfma_f32_16x16x32_bf16 v[86:89], v[134:137], v[206:209], v[86:89]
	s_setprio 0
	s_setprio 1
	v_mfma_f32_16x16x32_bf16 v[114:117], v[150:153], v[166:169], v[114:117]
	v_mfma_f32_16x16x32_bf16 v[114:117], v[154:157], v[170:173], v[114:117]
	v_mfma_f32_16x16x32_bf16 v[106:109], v[158:161], v[166:169], v[106:109]
	v_mfma_f32_16x16x32_bf16 v[106:109], v[162:165], v[170:173], v[106:109]
	v_mfma_f32_16x16x32_bf16 v[98:101], v[158:161], v[186:189], v[98:101]
	v_mfma_f32_16x16x32_bf16 v[98:101], v[162:165], v[190:193], v[98:101]
	v_mfma_f32_16x16x32_bf16 v[102:105], v[150:153], v[186:189], v[102:105]
	v_mfma_f32_16x16x32_bf16 v[102:105], v[154:157], v[190:193], v[102:105]
	v_mfma_f32_16x16x32_bf16 v[82:85], v[150:153], v[194:197], v[82:85]
	v_mfma_f32_16x16x32_bf16 v[82:85], v[154:157], v[198:201], v[82:85]
	v_mfma_f32_16x16x32_bf16 v[74:77], v[158:161], v[194:197], v[74:77]
	v_mfma_f32_16x16x32_bf16 v[74:77], v[162:165], v[198:201], v[74:77]
	s_setprio 2
	s_barrier
	v_mfma_f32_16x16x32_bf16 v[66:69], v[158:161], v[202:205], v[66:69]
	v_mfma_f32_16x16x32_bf16 v[66:69], v[162:165], v[206:209], v[66:69]
	v_mfma_f32_16x16x32_bf16 v[70:73], v[150:153], v[202:205], v[70:73]
	v_mfma_f32_16x16x32_bf16 v[70:73], v[154:157], v[206:209], v[70:73]
	s_setprio 0
	ds_read_b128 v[166:169], v183 offset:49152
	ds_read_b128 v[170:173], v183 offset:50176
	ds_read_b128 v[186:189], v183 offset:51200
	ds_read_b128 v[190:193], v183 offset:52224
	ds_read_b128 v[194:197], v183 offset:53248
	ds_read_b128 v[198:201], v183 offset:54272
	ds_read_b128 v[202:205], v183 offset:55296
	ds_read_b128 v[206:209], v183 offset:56320
	s_add_u32 s34, s30, 0x40000
	s_addc_u32 s35, s31, 0
	s_mov_b32 s70, m0
	s_mov_b32 m0, s51
	s_nop 0
	global_load_lds_dwordx4 v176, s[34:35]
	s_mov_b32 m0, s70
	s_add_u32 s30, s30, 0x44000
	s_mov_b32 s70, m0
	s_mov_b32 m0, s52
	s_nop 0
	global_load_lds_dwordx4 v178, s[34:35]
	s_mov_b32 m0, s70
	s_addc_u32 s31, s31, 0
	s_mov_b32 s34, m0
	s_mov_b32 m0, s53
	s_nop 0
	global_load_lds_dwordx4 v176, s[30:31]
	s_mov_b32 m0, s34
	s_nop 0
	s_mov_b32 s34, m0
	s_mov_b32 m0, s54
	s_nop 0
	global_load_lds_dwordx4 v178, s[30:31]
	s_mov_b32 m0, s34
	s_waitcnt vmcnt(4)
	s_waitcnt lgkmcnt(0)
	s_barrier
	s_setprio 1
	s_waitcnt lgkmcnt(7)
	v_mfma_f32_16x16x32_bf16 v[62:65], v[130:133], v[166:169], v[62:65]
	v_mfma_f32_16x16x32_bf16 v[62:65], v[134:137], v[170:173], v[62:65]
	s_waitcnt lgkmcnt(5)
	v_mfma_f32_16x16x32_bf16 v[58:61], v[138:141], v[166:169], v[58:61]
	v_mfma_f32_16x16x32_bf16 v[58:61], v[142:145], v[170:173], v[58:61]
	s_waitcnt lgkmcnt(3)
	v_mfma_f32_16x16x32_bf16 v[42:45], v[138:141], v[186:189], v[42:45]
	v_mfma_f32_16x16x32_bf16 v[42:45], v[142:145], v[190:193], v[42:45]
	s_waitcnt lgkmcnt(1)
	v_mfma_f32_16x16x32_bf16 v[46:49], v[130:133], v[186:189], v[46:49]
	v_mfma_f32_16x16x32_bf16 v[46:49], v[134:137], v[190:193], v[46:49]
	v_mfma_f32_16x16x32_bf16 v[30:33], v[130:133], v[194:197], v[30:33]
	v_mfma_f32_16x16x32_bf16 v[30:33], v[134:137], v[198:201], v[30:33]
	v_mfma_f32_16x16x32_bf16 v[26:29], v[138:141], v[194:197], v[26:29]
	v_mfma_f32_16x16x32_bf16 v[26:29], v[142:145], v[198:201], v[26:29]
	v_mfma_f32_16x16x32_bf16 v[10:13], v[138:141], v[202:205], v[10:13]
	v_mfma_f32_16x16x32_bf16 v[10:13], v[142:145], v[206:209], v[10:13]
	s_waitcnt lgkmcnt(0)
	v_mfma_f32_16x16x32_bf16 v[14:17], v[130:133], v[202:205], v[14:17]
	v_mfma_f32_16x16x32_bf16 v[14:17], v[134:137], v[206:209], v[14:17]
	s_setprio 0
	s_setprio 1
	v_mfma_f32_16x16x32_bf16 v[54:57], v[150:153], v[166:169], v[54:57]
	v_mfma_f32_16x16x32_bf16 v[54:57], v[154:157], v[170:173], v[54:57]
	v_mfma_f32_16x16x32_bf16 v[50:53], v[158:161], v[166:169], v[50:53]
	v_mfma_f32_16x16x32_bf16 v[50:53], v[162:165], v[170:173], v[50:53]
	v_mfma_f32_16x16x32_bf16 v[34:37], v[158:161], v[186:189], v[34:37]
	v_mfma_f32_16x16x32_bf16 v[34:37], v[162:165], v[190:193], v[34:37]
	v_mfma_f32_16x16x32_bf16 v[38:41], v[150:153], v[186:189], v[38:41]
	v_mfma_f32_16x16x32_bf16 v[38:41], v[154:157], v[190:193], v[38:41]
	v_mfma_f32_16x16x32_bf16 v[22:25], v[150:153], v[194:197], v[22:25]
	v_mfma_f32_16x16x32_bf16 v[22:25], v[154:157], v[198:201], v[22:25]
	v_mfma_f32_16x16x32_bf16 v[18:21], v[158:161], v[194:197], v[18:21]
	v_mfma_f32_16x16x32_bf16 v[18:21], v[162:165], v[198:201], v[18:21]
	s_setprio 2
	s_barrier
	v_mfma_f32_16x16x32_bf16 v[2:5], v[158:161], v[202:205], v[2:5]
	v_mfma_f32_16x16x32_bf16 v[2:5], v[162:165], v[206:209], v[2:5]
	v_mfma_f32_16x16x32_bf16 v[6:9], v[150:153], v[202:205], v[6:9]
	v_mfma_f32_16x16x32_bf16 v[6:9], v[154:157], v[206:209], v[6:9]
	s_setprio 0
	s_add_i32 s69, s69, 2
	s_add_u32 s65, s65, 0x80000
	s_addc_u32 s66, s66, 0
	s_add_u32 s28, s28, 0x400000
	s_addc_u32 s29, s29, 0
	s_add_u32 s67, s67, 0x400000
	s_addc_u32 s68, s68, 0
	s_cmpk_gt_u32 s69, 0x53
	s_cbranch_scc0 .LBB0_2792
	s_and_b64 vcc, exec, s[8:9]
	s_cbranch_vccz .LBB0_2795
	s_barrier
